# baseline (speedup 1.0000x reference)
; #define PG8_STAGE(bufoff, gbase, voff) do { _Pragma("unroll") for (int _i = 0; _i < 2; ++_i) \
;         __builtin_amdgcn_global_load_lds((const unsigned*)((const char*)(gbase) + (voff)[_i]), (LAS unsigned*)(lds + (bufoff) + ldsw + _i * 8192), 16, 0, 0); } while (0)
; #define PG8_LDA(dst, b, h) do { _Pragma("unroll") for (int m = 0; m < 4; ++m) _Pragma("unroll") for (int k = 0; k < 2; ++k) dst[m][k] = *(const LAS bf16x8*)(lds + PG8_SA(b, h) + aoff + m * 2048 + k * 1024); } while (0)
; #define PG8_LDB(dst, b, h) do { _Pragma("unroll") for (int n = 0; n < 2; ++n) _Pragma("unroll") for (int k = 0; k < 2; ++k) dst[n][k] = *(const LAS bf16x8*)(lds + PG8_SB(b, h) + boff + n * 2048 + k * 1024); } while (0)
; #define PG8_MMA(ai, bj, At, Bt) do { __builtin_amdgcn_s_setprio(1); _Pragma("unroll") for (int m = 0; m < 4; ++m) _Pragma("unroll") for (int n = 0; n < 2; ++n) _Pragma("unroll") for (int k = 0; k < 2; ++k) \
;         acc[ai][bj][m][n] = __builtin_amdgcn_mfma_f32_16x16x32_bf16(Bt[n][k], At[m][k], acc[ai][bj][m][n], 0, 0, 0); __builtin_amdgcn_s_setprio(0); } while (0)
; #define PG8_WAIT_V(n) asm volatile("s_waitcnt vmcnt(" #n ")" ::: "memory")
; #define PG8_WAIT_L(n) asm volatile("s_waitcnt lgkmcnt(" #n ")" ::: "memory")
; #define PG8_BAR __builtin_amdgcn_s_barrier()
; #define PG8_SCHED __builtin_amdgcn_sched_barrier(0)
; template <class Epi, class Sched>
; DI void gemm_phase(LAS unsigned char* lds, const Gemm g, const Sched& S, const Epi& E) {
;     ...
;             PG8_LDB(B0, 0, 0); PG8_SCHED; PG8_LDA(At, 0, 0); PG8_STAGE(PG8_SA(1, 1), a1 + hstep, voffA);
;             PG8_WAIT_L(8); PG8_BAR; PG8_WAIT_L(0); PG8_MMA(0, 0, At, B0); PG8_BAR; PG8_SCHED;
;             PG8_LDB(B1, 0, 1); PG8_STAGE(PG8_SB(0, 0), b2, voffB);
;             PG8_BAR; PG8_WAIT_L(0); PG8_MMA(0, 1, At, B1); PG8_BAR;
;             PG8_LDA(At, 0, 1); PG8_STAGE(PG8_SA(0, 0), a2, voffA);
;             PG8_BAR; PG8_WAIT_L(0); PG8_MMA(1, 0, At, B0); PG8_BAR; PG8_SCHED;
;             PG8_STAGE(PG8_SB(0, 1), b2 + hstep, voffB);
;             PG8_WAIT_V(6); PG8_BAR; PG8_MMA(1, 1, At, B1); PG8_BAR;
.LBB0_218:
	s_ashr_i32 s17, s16, 31
	s_lshl_b64 s[0:1], s[16:17], 20
	v_cmp_lt_i64_e32 vcc, s[18:19], v[140:141]
	s_add_u32 s18, s47, s0
	s_addc_u32 s19, s48, s1
	s_and_b64 s[0:1], vcc, exec
	s_cselect_b32 s17, s19, s41
	s_cselect_b32 s65, s18, s40
	s_ashr_i32 s15, s14, 31
	s_lshl_b64 s[0:1], s[14:15], 20
	s_add_u32 s36, s49, s0
	s_addc_u32 s37, s50, s1
	s_and_b64 s[0:1], vcc, exec
	s_cselect_b32 s15, s37, s43
	s_cselect_b32 s66, s36, s42
	s_add_u32 s40, s40, 0x80080
	s_addc_u32 s41, s41, 0
	s_add_u32 s67, s42, 0x100
	v_mov_b32_e32 v0, 0
	s_addc_u32 s68, s43, 0
	s_mov_b32 s69, -2
	ds_read_b128 v[150:153], v147
	ds_read_b128 v[154:157], v147 offset:1024
	ds_read_b128 v[162:165], v147 offset:2048
	ds_read_b128 v[166:169], v147 offset:3072
	s_add_u32 s0, s40, 0xfff80080
	s_addc_u32 s1, s41, -1
	s_cmp_eq_u32 s69, 28
	s_cselect_b32 s45, s17, s1
	s_cselect_b32 s44, s65, s0
	s_cselect_b32 s43, s15, s68
	s_cselect_b32 s42, s66, s67
	v_lshl_add_u64 v[158:159], s[40:41], 0, v[136:137]
	s_add_i32 m0, s39, 0xc000
	ds_read_b128 v[170:173], v148
	ds_read_b128 v[174:177], v148 offset:1024
	ds_read_b128 v[178:181], v148 offset:2048
	ds_read_b128 v[188:191], v148 offset:3072
	ds_read_b128 v[194:197], v148 offset:4096
	ds_read_b128 v[198:201], v148 offset:5120
	ds_read_b128 v[202:205], v148 offset:6144
	ds_read_b128 v[206:209], v148 offset:7168
	global_load_lds_dwordx4 v[158:159], off
	v_lshl_add_u64 v[158:159], s[40:41], 0, v[138:139]
	s_add_i32 m0, s39, 0xe000
	s_nop 0
	global_load_lds_dwordx4 v[158:159], off
	s_waitcnt lgkmcnt(8)
	s_barrier
	s_waitcnt lgkmcnt(0)
	s_setprio 1
	s_waitcnt lgkmcnt(0)
	v_mfma_f32_16x16x32_bf16 v[124:127], v[150:153], v[170:173], 0
	v_mfma_f32_16x16x32_bf16 v[120:123], v[162:165], v[170:173], 0
	v_mfma_f32_16x16x32_bf16 v[108:111], v[150:153], v[178:181], 0
	v_mfma_f32_16x16x32_bf16 v[104:107], v[162:165], v[178:181], 0
	v_mfma_f32_16x16x32_bf16 v[92:95], v[150:153], v[194:197], 0
	v_mfma_f32_16x16x32_bf16 v[88:91], v[162:165], v[194:197], 0
	v_mfma_f32_16x16x32_bf16 v[76:79], v[150:153], v[202:205], 0
	v_mfma_f32_16x16x32_bf16 v[72:75], v[162:165], v[202:205], 0
	v_mfma_f32_16x16x32_bf16 v[124:127], v[154:157], v[174:177], v[124:127]
	v_mfma_f32_16x16x32_bf16 v[120:123], v[166:169], v[174:177], v[120:123]
	v_mfma_f32_16x16x32_bf16 v[108:111], v[154:157], v[188:191], v[108:111]
	v_mfma_f32_16x16x32_bf16 v[104:107], v[166:169], v[188:191], v[104:107]
	v_mfma_f32_16x16x32_bf16 v[92:95], v[154:157], v[198:201], v[92:95]
	v_mfma_f32_16x16x32_bf16 v[88:91], v[166:169], v[198:201], v[88:91]
	v_mfma_f32_16x16x32_bf16 v[76:79], v[154:157], v[206:209], v[76:79]
	v_mfma_f32_16x16x32_bf16 v[72:75], v[166:169], v[206:209], v[72:75]
	s_setprio 0
	s_barrier
	s_add_i32 s0, s34, s52
	v_lshl_add_u64 v[158:159], s[42:43], 0, v[130:131]
	s_mov_b32 m0, s0
	ds_read_b128 v[210:213], v149
	ds_read_b128 v[214:217], v149 offset:1024
	ds_read_b128 v[218:221], v149 offset:2048
	ds_read_b128 v[222:225], v149 offset:3072
	global_load_lds_dwordx4 v[158:159], off
	v_lshl_add_u64 v[182:183], s[42:43], 0, v[134:135]
	s_add_i32 m0, s0, 0x2000
	s_nop 0
	global_load_lds_dwordx4 v[182:183], off
	s_barrier
	s_waitcnt lgkmcnt(0)
	s_setprio 1
	s_waitcnt lgkmcnt(0)
	v_mfma_f32_16x16x32_bf16 v[116:119], v[210:213], v[170:173], 0
	v_mfma_f32_16x16x32_bf16 v[112:115], v[218:221], v[170:173], 0
	v_mfma_f32_16x16x32_bf16 v[100:103], v[210:213], v[178:181], 0
	v_mfma_f32_16x16x32_bf16 v[96:99], v[218:221], v[178:181], 0
	v_mfma_f32_16x16x32_bf16 v[84:87], v[210:213], v[194:197], 0
	v_mfma_f32_16x16x32_bf16 v[80:83], v[218:221], v[194:197], 0
	v_mfma_f32_16x16x32_bf16 v[68:71], v[210:213], v[202:205], 0
	v_mfma_f32_16x16x32_bf16 v[64:67], v[218:221], v[202:205], 0
	v_mfma_f32_16x16x32_bf16 v[116:119], v[214:217], v[174:177], v[116:119]
	v_mfma_f32_16x16x32_bf16 v[112:115], v[222:225], v[174:177], v[112:115]
	v_mfma_f32_16x16x32_bf16 v[100:103], v[214:217], v[188:191], v[100:103]
	v_mfma_f32_16x16x32_bf16 v[96:99], v[222:225], v[188:191], v[96:99]
	v_mfma_f32_16x16x32_bf16 v[84:87], v[214:217], v[198:201], v[84:87]
	v_mfma_f32_16x16x32_bf16 v[80:83], v[222:225], v[198:201], v[80:83]
	v_mfma_f32_16x16x32_bf16 v[68:71], v[214:217], v[206:209], v[68:71]
	v_mfma_f32_16x16x32_bf16 v[64:67], v[222:225], v[206:209], v[64:67]
	s_setprio 0
	s_mov_b32 m0, s39
	v_lshl_add_u64 v[226:227], s[44:45], 0, v[128:129]
	s_barrier
	ds_read_b128 v[170:173], v148 offset:16384
	ds_read_b128 v[174:177], v148 offset:17408
	ds_read_b128 v[178:181], v148 offset:18432
	ds_read_b128 v[188:191], v148 offset:19456
	ds_read_b128 v[194:197], v148 offset:20480
	ds_read_b128 v[198:201], v148 offset:21504
	ds_read_b128 v[202:205], v148 offset:22528
	ds_read_b128 v[206:209], v148 offset:23552
	global_load_lds_dwordx4 v[226:227], off
	v_lshl_add_u64 v[228:229], s[44:45], 0, v[132:133]
	s_mov_b32 m0, s53
	s_nop 0
	global_load_lds_dwordx4 v[228:229], off
	s_barrier
	s_waitcnt lgkmcnt(0)
	s_setprio 1
	s_waitcnt lgkmcnt(0)
	v_mfma_f32_16x16x32_bf16 v[60:63], v[150:153], v[170:173], 0
	v_mfma_f32_16x16x32_bf16 v[56:59], v[162:165], v[170:173], 0
	v_mfma_f32_16x16x32_bf16 v[44:47], v[150:153], v[178:181], 0
	v_mfma_f32_16x16x32_bf16 v[40:43], v[162:165], v[178:181], 0
	v_mfma_f32_16x16x32_bf16 v[28:31], v[150:153], v[194:197], 0
	v_mfma_f32_16x16x32_bf16 v[24:27], v[162:165], v[194:197], 0
	v_mfma_f32_16x16x32_bf16 v[12:15], v[150:153], v[202:205], 0
	v_mfma_f32_16x16x32_bf16 v[8:11], v[162:165], v[202:205], 0
	v_mfma_f32_16x16x32_bf16 v[60:63], v[154:157], v[174:177], v[60:63]
	v_mfma_f32_16x16x32_bf16 v[56:59], v[166:169], v[174:177], v[56:59]
	v_mfma_f32_16x16x32_bf16 v[44:47], v[154:157], v[188:191], v[44:47]
	v_mfma_f32_16x16x32_bf16 v[40:43], v[166:169], v[188:191], v[40:43]
	v_mfma_f32_16x16x32_bf16 v[28:31], v[154:157], v[198:201], v[28:31]
	v_mfma_f32_16x16x32_bf16 v[24:27], v[166:169], v[198:201], v[24:27]
	v_mfma_f32_16x16x32_bf16 v[12:15], v[154:157], v[206:209], v[12:15]
	v_mfma_f32_16x16x32_bf16 v[8:11], v[166:169], v[206:209], v[8:11]
	s_setprio 0
	s_barrier
; #define PG8_STAGE(bufoff, gbase, voff) do { _Pragma("unroll") for (int _i = 0; _i < 2; ++_i) \
;         __builtin_amdgcn_global_load_lds((const unsigned*)((const char*)(gbase) + (voff)[_i]), (LAS unsigned*)(lds + (bufoff) + ldsw + _i * 8192), 16, 0, 0); } while (0)
; #define PG8_LDA(dst, b, h) do { _Pragma("unroll") for (int m = 0; m < 4; ++m) _Pragma("unroll") for (int k = 0; k < 2; ++k) dst[m][k] = *(const LAS bf16x8*)(lds + PG8_SA(b, h) + aoff + m * 2048 + k * 1024); } while (0)
; #define PG8_LDB(dst, b, h) do { _Pragma("unroll") for (int n = 0; n < 2; ++n) _Pragma("unroll") for (int k = 0; k < 2; ++k) dst[n][k] = *(const LAS bf16x8*)(lds + PG8_SB(b, h) + boff + n * 2048 + k * 1024); } while (0)
; #define PG8_MMA(ai, bj, At, Bt) do { __builtin_amdgcn_s_setprio(1); _Pragma("unroll") for (int m = 0; m < 4; ++m) _Pragma("unroll") for (int n = 0; n < 2; ++n) _Pragma("unroll") for (int k = 0; k < 2; ++k) \
;         acc[ai][bj][m][n] = __builtin_amdgcn_mfma_f32_16x16x32_bf16(Bt[n][k], At[m][k], acc[ai][bj][m][n], 0, 0, 0); __builtin_amdgcn_s_setprio(0); } while (0)
; #define PG8_WAIT_V(n) asm volatile("s_waitcnt vmcnt(" #n ")" ::: "memory")
; #define PG8_WAIT_L(n) asm volatile("s_waitcnt lgkmcnt(" #n ")" ::: "memory")
; #define PG8_BAR __builtin_amdgcn_s_barrier()
; #define PG8_SCHED __builtin_amdgcn_sched_barrier(0)
; template <class Epi, class Sched>
; DI void gemm_phase(LAS unsigned char* lds, const Gemm g, const Sched& S, const Epi& E) {
;     ...
;             PG8_STAGE(PG8_SB(0, 1), b2 + hstep, voffB);
;             PG8_WAIT_V(6); PG8_BAR; PG8_MMA(1, 1, At, B1); PG8_BAR;
;             PG8_LDB(B0, 1, 0); PG8_SCHED; PG8_LDA(At, 1, 0); PG8_STAGE(PG8_SA(0, 1), a2 + hstep, voffA);
;             PG8_WAIT_L(8); PG8_BAR; PG8_WAIT_L(0); PG8_MMA(0, 0, At, B0); PG8_BAR; PG8_SCHED;
;             PG8_LDB(B1, 1, 1); PG8_STAGE(PG8_SB(1, 0), b3, voffB);
;             PG8_BAR; PG8_WAIT_L(0); PG8_MMA(0, 1, At, B1); PG8_BAR;
;             PG8_LDA(At, 1, 1); PG8_STAGE(PG8_SA(1, 0), a3, voffA);
	s_add_u32 s0, s42, 0x80000
	s_addc_u32 s1, s43, 0
	s_add_i32 s4, s35, s52
	v_lshl_add_u64 v[150:151], s[0:1], 0, v[130:131]
	s_mov_b32 m0, s4
	s_nop 0
	global_load_lds_dwordx4 v[150:151], off
	v_lshl_add_u64 v[150:151], s[0:1], 0, v[134:135]
	s_add_i32 m0, s4, 0x2000
	s_nop 0
	global_load_lds_dwordx4 v[150:151], off
	s_waitcnt vmcnt(6)
	s_barrier
	s_setprio 1
	v_mfma_f32_16x16x32_bf16 v[52:55], v[210:213], v[170:173], 0
	v_mfma_f32_16x16x32_bf16 v[48:51], v[218:221], v[170:173], 0
	v_mfma_f32_16x16x32_bf16 v[36:39], v[210:213], v[178:181], 0
	v_mfma_f32_16x16x32_bf16 v[32:35], v[218:221], v[178:181], 0
	v_mfma_f32_16x16x32_bf16 v[20:23], v[210:213], v[194:197], 0
	v_mfma_f32_16x16x32_bf16 v[16:19], v[218:221], v[194:197], 0
	v_mfma_f32_16x16x32_bf16 v[4:7], v[210:213], v[202:205], 0
	v_mfma_f32_16x16x32_bf16 v[0:3], v[218:221], v[202:205], 0
	v_mfma_f32_16x16x32_bf16 v[52:55], v[214:217], v[174:177], v[52:55]
	v_mfma_f32_16x16x32_bf16 v[48:51], v[222:225], v[174:177], v[48:51]
	v_mfma_f32_16x16x32_bf16 v[36:39], v[214:217], v[188:191], v[36:39]
	v_mfma_f32_16x16x32_bf16 v[32:35], v[222:225], v[188:191], v[32:35]
	v_mfma_f32_16x16x32_bf16 v[20:23], v[214:217], v[198:201], v[20:23]
	v_mfma_f32_16x16x32_bf16 v[16:19], v[222:225], v[198:201], v[16:19]
	v_mfma_f32_16x16x32_bf16 v[4:7], v[214:217], v[206:209], v[4:7]
	v_mfma_f32_16x16x32_bf16 v[0:3], v[222:225], v[206:209], v[0:3]
	s_setprio 0
	s_add_i32 s4, 0, 0x18000
	v_add_u32_e32 v161, s4, v146
	s_barrier
	ds_read_b128 v[150:153], v161
	ds_read_b128 v[154:157], v161 offset:1024
	ds_read_b128 v[162:165], v161 offset:2048
	ds_read_b128 v[166:169], v161 offset:3072
	s_add_u32 s0, s44, 0x80000
	s_addc_u32 s1, s45, 0
	s_mov_b32 m0, s54
	v_lshl_add_u64 v[210:211], s[0:1], 0, v[128:129]
	ds_read_b128 v[170:173], v148 offset:32768
	ds_read_b128 v[174:177], v148 offset:33792
	ds_read_b128 v[178:181], v148 offset:34816
	ds_read_b128 v[188:191], v148 offset:35840
	ds_read_b128 v[194:197], v148 offset:36864
	ds_read_b128 v[198:201], v148 offset:37888
	ds_read_b128 v[202:205], v148 offset:38912
	ds_read_b128 v[206:209], v148 offset:39936
	global_load_lds_dwordx4 v[210:211], off
	v_lshl_add_u64 v[210:211], s[0:1], 0, v[132:133]
	s_mov_b32 m0, s55
	s_nop 0
	global_load_lds_dwordx4 v[210:211], off
	s_waitcnt lgkmcnt(8)
	s_barrier
	s_waitcnt lgkmcnt(0)
	s_setprio 1
	s_waitcnt lgkmcnt(0)
	v_mfma_f32_16x16x32_bf16 v[124:127], v[150:153], v[170:173], v[124:127]
	v_mfma_f32_16x16x32_bf16 v[120:123], v[162:165], v[170:173], v[120:123]
	v_mfma_f32_16x16x32_bf16 v[108:111], v[150:153], v[178:181], v[108:111]
	v_mfma_f32_16x16x32_bf16 v[104:107], v[162:165], v[178:181], v[104:107]
	v_mfma_f32_16x16x32_bf16 v[92:95], v[150:153], v[194:197], v[92:95]
	v_mfma_f32_16x16x32_bf16 v[88:91], v[162:165], v[194:197], v[88:91]
	v_mfma_f32_16x16x32_bf16 v[76:79], v[150:153], v[202:205], v[76:79]
	v_mfma_f32_16x16x32_bf16 v[72:75], v[162:165], v[202:205], v[72:75]
	v_mfma_f32_16x16x32_bf16 v[124:127], v[154:157], v[174:177], v[124:127]
	v_mfma_f32_16x16x32_bf16 v[120:123], v[166:169], v[174:177], v[120:123]
	v_mfma_f32_16x16x32_bf16 v[108:111], v[154:157], v[188:191], v[108:111]
	v_mfma_f32_16x16x32_bf16 v[104:107], v[166:169], v[188:191], v[104:107]
	v_mfma_f32_16x16x32_bf16 v[92:95], v[154:157], v[198:201], v[92:95]
	v_mfma_f32_16x16x32_bf16 v[88:91], v[166:169], v[198:201], v[88:91]
	v_mfma_f32_16x16x32_bf16 v[76:79], v[154:157], v[206:209], v[76:79]
	v_mfma_f32_16x16x32_bf16 v[72:75], v[166:169], v[206:209], v[72:75]
	s_setprio 0
	s_barrier
	s_add_i32 s5, 0, 0x1c000
	s_add_i32 s0, s4, s52
	v_add_u32_e32 v161, s5, v146
	v_lshl_add_u64 v[158:159], v[158:159], 0, s[12:13]
	s_mov_b32 m0, s0
	ds_read_b128 v[210:213], v161
	ds_read_b128 v[214:217], v161 offset:1024
	ds_read_b128 v[218:221], v161 offset:2048
	ds_read_b128 v[222:225], v161 offset:3072
	global_load_lds_dwordx4 v[158:159], off
	v_lshl_add_u64 v[158:159], v[182:183], 0, s[12:13]
	s_add_i32 m0, s0, 0x2000
	s_nop 0
	global_load_lds_dwordx4 v[158:159], off
	s_barrier
; #define PG8_STAGE(bufoff, gbase, voff) do { _Pragma("unroll") for (int _i = 0; _i < 2; ++_i) \
;         __builtin_amdgcn_global_load_lds((const unsigned*)((const char*)(gbase) + (voff)[_i]), (LAS unsigned*)(lds + (bufoff) + ldsw + _i * 8192), 16, 0, 0); } while (0)
; #define PG8_LDA(dst, b, h) do { _Pragma("unroll") for (int m = 0; m < 4; ++m) _Pragma("unroll") for (int k = 0; k < 2; ++k) dst[m][k] = *(const LAS bf16x8*)(lds + PG8_SA(b, h) + aoff + m * 2048 + k * 1024); } while (0)
; #define PG8_MMA(ai, bj, At, Bt) do { __builtin_amdgcn_s_setprio(1); _Pragma("unroll") for (int m = 0; m < 4; ++m) _Pragma("unroll") for (int n = 0; n < 2; ++n) _Pragma("unroll") for (int k = 0; k < 2; ++k) \
;         acc[ai][bj][m][n] = __builtin_amdgcn_mfma_f32_16x16x32_bf16(Bt[n][k], At[m][k], acc[ai][bj][m][n], 0, 0, 0); __builtin_amdgcn_s_setprio(0); } while (0)
; #define PG8_WAIT_V(n) asm volatile("s_waitcnt vmcnt(" #n ")" ::: "memory")
; #define PG8_WAIT_L(n) asm volatile("s_waitcnt lgkmcnt(" #n ")" ::: "memory")
; #define PG8_BAR __builtin_amdgcn_s_barrier()
; #define PG8_SCHED __builtin_amdgcn_sched_barrier(0)
; template <class Epi, class Sched>
; DI void gemm_phase(LAS unsigned char* lds, const Gemm g, const Sched& S, const Epi& E) {
;     ...
;         for (int t = 0; t < nt; t += 2) {
;     ...
;             PG8_LDA(At, 1, 1); PG8_STAGE(PG8_SA(1, 0), a3, voffA);
;             PG8_BAR; PG8_WAIT_L(0); PG8_MMA(1, 0, At, B0); PG8_BAR; PG8_SCHED;
;             PG8_STAGE(PG8_SB(1, 1), b3 + hstep, voffB);
;             PG8_WAIT_V(6); PG8_BAR; PG8_MMA(1, 1, At, B1); PG8_BAR;
	s_waitcnt lgkmcnt(0)
	s_setprio 1
	s_waitcnt lgkmcnt(0)
	v_mfma_f32_16x16x32_bf16 v[116:119], v[210:213], v[170:173], v[116:119]
	v_mfma_f32_16x16x32_bf16 v[112:115], v[218:221], v[170:173], v[112:115]
	v_mfma_f32_16x16x32_bf16 v[100:103], v[210:213], v[178:181], v[100:103]
	v_mfma_f32_16x16x32_bf16 v[96:99], v[218:221], v[178:181], v[96:99]
	v_mfma_f32_16x16x32_bf16 v[84:87], v[210:213], v[194:197], v[84:87]
	v_mfma_f32_16x16x32_bf16 v[80:83], v[218:221], v[194:197], v[80:83]
	v_mfma_f32_16x16x32_bf16 v[68:71], v[210:213], v[202:205], v[68:71]
	v_mfma_f32_16x16x32_bf16 v[64:67], v[218:221], v[202:205], v[64:67]
	v_mfma_f32_16x16x32_bf16 v[116:119], v[214:217], v[174:177], v[116:119]
	v_mfma_f32_16x16x32_bf16 v[112:115], v[222:225], v[174:177], v[112:115]
	v_mfma_f32_16x16x32_bf16 v[100:103], v[214:217], v[188:191], v[100:103]
	v_mfma_f32_16x16x32_bf16 v[96:99], v[222:225], v[188:191], v[96:99]
	v_mfma_f32_16x16x32_bf16 v[84:87], v[214:217], v[198:201], v[84:87]
	v_mfma_f32_16x16x32_bf16 v[80:83], v[222:225], v[198:201], v[80:83]
	v_mfma_f32_16x16x32_bf16 v[68:71], v[214:217], v[206:209], v[68:71]
	v_mfma_f32_16x16x32_bf16 v[64:67], v[222:225], v[206:209], v[64:67]
	s_setprio 0
	s_mov_b32 m0, s59
	v_lshl_add_u64 v[158:159], v[226:227], 0, s[12:13]
	s_barrier
	ds_read_b128 v[170:173], v148 offset:49152
	ds_read_b128 v[174:177], v148 offset:50176
	ds_read_b128 v[178:181], v148 offset:51200
	ds_read_b128 v[188:191], v148 offset:52224
	ds_read_b128 v[194:197], v148 offset:53248
	ds_read_b128 v[198:201], v148 offset:54272
	ds_read_b128 v[202:205], v148 offset:55296
	ds_read_b128 v[206:209], v148 offset:56320
	global_load_lds_dwordx4 v[158:159], off
	v_lshl_add_u64 v[158:159], v[228:229], 0, s[12:13]
	s_mov_b32 m0, s60
	s_nop 0
	global_load_lds_dwordx4 v[158:159], off
	s_barrier
	s_waitcnt lgkmcnt(0)
	s_setprio 1
	s_waitcnt lgkmcnt(0)
	v_mfma_f32_16x16x32_bf16 v[60:63], v[150:153], v[170:173], v[60:63]
	v_mfma_f32_16x16x32_bf16 v[56:59], v[162:165], v[170:173], v[56:59]
	v_mfma_f32_16x16x32_bf16 v[44:47], v[150:153], v[178:181], v[44:47]
	v_mfma_f32_16x16x32_bf16 v[40:43], v[162:165], v[178:181], v[40:43]
	v_mfma_f32_16x16x32_bf16 v[28:31], v[150:153], v[194:197], v[28:31]
	v_mfma_f32_16x16x32_bf16 v[24:27], v[162:165], v[194:197], v[24:27]
	v_mfma_f32_16x16x32_bf16 v[12:15], v[150:153], v[202:205], v[12:15]
	v_mfma_f32_16x16x32_bf16 v[8:11], v[162:165], v[202:205], v[8:11]
	v_mfma_f32_16x16x32_bf16 v[60:63], v[154:157], v[174:177], v[60:63]
	v_mfma_f32_16x16x32_bf16 v[56:59], v[166:169], v[174:177], v[56:59]
	v_mfma_f32_16x16x32_bf16 v[44:47], v[154:157], v[188:191], v[44:47]
	v_mfma_f32_16x16x32_bf16 v[40:43], v[166:169], v[188:191], v[40:43]
	v_mfma_f32_16x16x32_bf16 v[28:31], v[154:157], v[198:201], v[28:31]
	v_mfma_f32_16x16x32_bf16 v[24:27], v[166:169], v[198:201], v[24:27]
	v_mfma_f32_16x16x32_bf16 v[12:15], v[154:157], v[206:209], v[12:15]
	v_mfma_f32_16x16x32_bf16 v[8:11], v[166:169], v[206:209], v[8:11]
	s_setprio 0
	s_barrier
	s_add_u32 s0, s42, 0x80080
	s_addc_u32 s1, s43, 0
	s_add_i32 s4, s5, s52
	v_lshl_add_u64 v[150:151], s[0:1], 0, v[130:131]
	s_mov_b32 m0, s4
	s_nop 0
	global_load_lds_dwordx4 v[150:151], off
	v_lshl_add_u64 v[150:151], s[0:1], 0, v[134:135]
	s_add_i32 m0, s4, 0x2000
	s_nop 0
	global_load_lds_dwordx4 v[150:151], off
	s_waitcnt vmcnt(6)
	s_barrier
	s_setprio 1
	v_mfma_f32_16x16x32_bf16 v[52:55], v[210:213], v[170:173], v[52:55]
	v_mfma_f32_16x16x32_bf16 v[48:51], v[218:221], v[170:173], v[48:51]
	v_mfma_f32_16x16x32_bf16 v[36:39], v[210:213], v[178:181], v[36:39]
	v_mfma_f32_16x16x32_bf16 v[32:35], v[218:221], v[178:181], v[32:35]
	v_mfma_f32_16x16x32_bf16 v[20:23], v[210:213], v[194:197], v[20:23]
	v_mfma_f32_16x16x32_bf16 v[16:19], v[218:221], v[194:197], v[16:19]
	v_mfma_f32_16x16x32_bf16 v[4:7], v[210:213], v[202:205], v[4:7]
	v_mfma_f32_16x16x32_bf16 v[0:3], v[218:221], v[202:205], v[0:3]
	v_mfma_f32_16x16x32_bf16 v[52:55], v[214:217], v[174:177], v[52:55]
	v_mfma_f32_16x16x32_bf16 v[48:51], v[222:225], v[174:177], v[48:51]
	v_mfma_f32_16x16x32_bf16 v[36:39], v[214:217], v[188:191], v[36:39]
	v_mfma_f32_16x16x32_bf16 v[32:35], v[222:225], v[188:191], v[32:35]
	v_mfma_f32_16x16x32_bf16 v[20:23], v[214:217], v[198:201], v[20:23]
	v_mfma_f32_16x16x32_bf16 v[16:19], v[222:225], v[198:201], v[16:19]
	v_mfma_f32_16x16x32_bf16 v[4:7], v[214:217], v[206:209], v[4:7]
	v_mfma_f32_16x16x32_bf16 v[0:3], v[222:225], v[206:209], v[0:3]
	s_setprio 0
	s_add_i32 s69, s69, 2
	s_add_u32 s40, s40, 0x100
	s_addc_u32 s41, s41, 0
	s_add_u32 s67, s67, 0x100
	s_addc_u32 s68, s68, 0
	s_cmp_gt_u32 s69, 29
	s_barrier
	s_cbranch_scc0 .LBB0_219
	s_branch .Lpeel_done_219

; DI float sigmoidf_(float x) { return __builtin_amdgcn_rcpf(1.0f + __builtin_amdgcn_exp2f(-x * LOG2E)); }
; DI float rs_of(const float* ss, int row) { return 1.0f / sqrtf(ss[row] * (1.0f / DM) + EPS); }
; DI u32x4 pack8(f32x4 a, f32x4 b) { u32x4 w; w.x = cvt_pk_bf16(a[0], a[1]); w.y = cvt_pk_bf16(a[2], a[3]); w.z = cvt_pk_bf16(b[0], b[1]); w.w = cvt_pk_bf16(b[2], b[3]); return w; }
;     DI void operator()(AccRef acc, const Unit& u, int wr, int wc, int fr, int fq) const {
;         const int row0 = u.pm * 256 + wr * 64 + fr, col0 = u.pn * 128 + wc * 32 + 8 * fq;
; #pragma unroll
;         for (int ai = 0; ai < 2; ++ai)
; #pragma unroll
;             for (int m = 0; m < 4; ++m) {
;                 f32x4 o[2]; const float r = ss ? rs_of(ss, row0 + ai * 128 + m * 16) : 1.0f;
; #pragma unroll
;                 for (int n = 0; n < 2; ++n)
; #pragma unroll
;                     for (int j = 0; j < 4; ++j) { const float gt = acc[ai][0][m][n][j] * r, up = acc[ai][1][m][n][j] * r; o[n][j] = gt * sigmoidf_(gt) * up; }
;                 *(u32x4*)(Hd + (size_t)(row0 + ai * 128 + m * 16) * DFF + col0) = pack8(o[0], o[1]);
;             }
.Lpeel_done_219:
	v_mul_f32_e32 v152, 0xbfb8aa3b, v124
	v_mov_b32_e32 v150, v144
	v_mov_b32_e32 v151, v145
	s_lshl_b32 s0, s38, 8
	v_exp_f32_e32 v153, v152
	v_mul_f32_e32 v152, 0xbfb8aa3b, v125
	s_add_i32 s0, s0, s57
	v_exp_f32_e32 v154, v152
	v_add_u32_e32 v150, s0, v150
	s_lshl_b32 s0, s64, 7
	s_or_b32 s0, s0, s58
	v_lshl_add_u32 v152, v151, 3, s0
	v_add_f32_e32 v151, 1.0, v153
	v_rcp_f32_e32 v151, v151
	v_add_f32_e32 v153, 1.0, v154
	v_rcp_f32_e32 v154, v153
	v_ashrrev_i32_e32 v153, 31, v152
	v_mul_f32_e32 v124, v124, v151
	v_mul_f32_e32 v116, v124, v116
	v_mul_f32_e32 v124, v125, v154
	v_mul_f32_e32 v125, 0xbfb8aa3b, v126
	v_exp_f32_e32 v125, v125
	v_mul_f32_e32 v151, 0xbfb8aa3b, v127
	v_exp_f32_e32 v151, v151
	v_mul_f32_e32 v117, v124, v117
	v_add_f32_e32 v124, 1.0, v125
	v_rcp_f32_e32 v124, v124
	v_add_f32_e32 v125, 1.0, v151
	v_mul_f32_e32 v151, 0xbfb8aa3b, v120
	v_rcp_f32_e32 v125, v125
	v_exp_f32_e32 v151, v151
	v_mul_f32_e32 v124, v126, v124
	v_mul_f32_e32 v118, v124, v118
	v_mul_f32_e32 v124, v127, v125
	v_add_f32_e32 v125, 1.0, v151
	v_rcp_f32_e32 v125, v125
	v_mul_f32_e32 v126, 0xbfb8aa3b, v121
	v_exp_f32_e32 v126, v126
	v_mul_f32_e32 v119, v124, v119
	v_mul_f32_e32 v120, v120, v125
	v_mul_f32_e32 v112, v120, v112
	v_add_f32_e32 v120, 1.0, v126
	v_mul_f32_e32 v124, 0xbfb8aa3b, v122
	v_rcp_f32_e32 v120, v120
	v_exp_f32_e32 v124, v124
	v_mul_f32_e32 v125, 0xbfb8aa3b, v123
	v_exp_f32_e32 v125, v125
	v_mul_f32_e32 v120, v121, v120
	v_add_f32_e32 v121, 1.0, v124
	v_rcp_f32_e32 v121, v121
	v_add_f32_e32 v124, 1.0, v125
	v_rcp_f32_e32 v124, v124
	v_mul_f32_e32 v113, v120, v113
	v_mul_f32_e32 v120, v122, v121
	v_mul_f32_e32 v122, 0xbfb8aa3b, v108
	v_mul_f32_e32 v114, v120, v114
	v_mul_f32_e32 v120, v123, v124
	v_exp_f32_e32 v122, v122
	v_mul_f32_e32 v123, 0xbfb8aa3b, v109
	v_mul_f32_e32 v115, v120, v115
	v_cvt_pk_bf16_f32 v116, v116, v117
	v_cvt_pk_bf16_f32 v117, v118, v119
	v_cvt_pk_bf16_f32 v118, v112, v113
	v_mov_b64_e32 v[112:113], s[10:11]
	v_exp_f32_e32 v123, v123
	v_cvt_pk_bf16_f32 v119, v114, v115
	v_mad_i64_i32 v[120:121], s[0:1], v150, s63, v[112:113]
	v_lshlrev_b64 v[114:115], 1, v[152:153]
	v_lshl_add_u64 v[120:121], v[120:121], 0, v[114:115]
	global_store_dwordx4 v[120:121], v[116:119], off
	s_and_b64 vcc, exec, s[6:7]
	s_mov_b32 s64, s14
	v_add_f32_e32 v116, 1.0, v122
	v_rcp_f32_e32 v116, v116
	v_add_f32_e32 v117, 1.0, v123
	v_rcp_f32_e32 v117, v117
	v_add_u32_e32 v118, 16, v150
	v_mul_f32_e32 v108, v108, v116
	v_mul_f32_e32 v100, v108, v100
	v_mul_f32_e32 v108, v109, v117
	v_mul_f32_e32 v109, 0xbfb8aa3b, v110
	v_exp_f32_e32 v109, v109
	v_mul_f32_e32 v116, 0xbfb8aa3b, v111
	v_exp_f32_e32 v116, v116
	v_mul_f32_e32 v101, v108, v101
	v_add_f32_e32 v108, 1.0, v109
	v_rcp_f32_e32 v108, v108
	v_add_f32_e32 v109, 1.0, v116
	v_mul_f32_e32 v116, 0xbfb8aa3b, v104
	v_rcp_f32_e32 v109, v109
	v_exp_f32_e32 v116, v116
	v_mul_f32_e32 v108, v110, v108
	v_mul_f32_e32 v102, v108, v102
	v_mul_f32_e32 v108, v111, v109
	v_add_f32_e32 v109, 1.0, v116
	v_rcp_f32_e32 v109, v109
	v_mul_f32_e32 v110, 0xbfb8aa3b, v105
	v_exp_f32_e32 v110, v110
	v_mul_f32_e32 v103, v108, v103
	v_mul_f32_e32 v104, v104, v109
	v_mul_f32_e32 v104, v104, v96
	v_add_f32_e32 v96, 1.0, v110
	v_mul_f32_e32 v108, 0xbfb8aa3b, v106
	v_rcp_f32_e32 v96, v96
	v_exp_f32_e32 v108, v108
	v_mul_f32_e32 v109, 0xbfb8aa3b, v107
	v_exp_f32_e32 v109, v109
	v_mul_f32_e32 v96, v105, v96
	v_add_f32_e32 v105, 1.0, v108
	v_rcp_f32_e32 v105, v105
	v_add_f32_e32 v108, 1.0, v109
	v_rcp_f32_e32 v108, v108
	v_mul_f32_e32 v109, v96, v97
	v_mul_f32_e32 v96, v106, v105
	v_mul_f32_e32 v105, v96, v98
	v_mul_f32_e32 v96, v107, v108
	v_mul_f32_e32 v99, v96, v99
	v_cvt_pk_bf16_f32 v96, v100, v101
	v_cvt_pk_bf16_f32 v97, v102, v103
	v_mul_f32_e32 v102, 0xbfb8aa3b, v92
	v_exp_f32_e32 v102, v102
	v_mul_f32_e32 v103, 0xbfb8aa3b, v93
	v_exp_f32_e32 v103, v103
	v_mad_i64_i32 v[100:101], s[0:1], v118, s63, v[112:113]
	v_lshl_add_u64 v[100:101], v[100:101], 0, v[114:115]
	v_cvt_pk_bf16_f32 v98, v104, v109
	v_cvt_pk_bf16_f32 v99, v105, v99
	global_store_dwordx4 v[100:101], v[96:99], off
	s_mov_b32 s38, s16
	s_mov_b64 s[42:43], s[36:37]
	v_add_f32_e32 v96, 1.0, v102
	v_rcp_f32_e32 v96, v96
	v_add_f32_e32 v97, 1.0, v103
	v_rcp_f32_e32 v97, v97
	v_add_u32_e32 v98, 32, v150
	v_mul_f32_e32 v92, v92, v96
	v_mul_f32_e32 v84, v92, v84
	v_mul_f32_e32 v92, v93, v97
	v_mul_f32_e32 v93, 0xbfb8aa3b, v94
	v_exp_f32_e32 v93, v93
	v_mul_f32_e32 v96, 0xbfb8aa3b, v95
	v_exp_f32_e32 v96, v96
	v_mul_f32_e32 v85, v92, v85
	v_add_f32_e32 v92, 1.0, v93
	v_rcp_f32_e32 v92, v92
	v_add_f32_e32 v93, 1.0, v96
	v_mul_f32_e32 v96, 0xbfb8aa3b, v88
	v_rcp_f32_e32 v93, v93
	v_exp_f32_e32 v96, v96
	v_mul_f32_e32 v92, v94, v92
	v_mul_f32_e32 v86, v92, v86
	v_mul_f32_e32 v92, v95, v93
	v_add_f32_e32 v93, 1.0, v96
	v_rcp_f32_e32 v93, v93
	v_mul_f32_e32 v94, 0xbfb8aa3b, v89
	v_exp_f32_e32 v94, v94
	v_mul_f32_e32 v87, v92, v87
	v_mul_f32_e32 v88, v88, v93
	v_mul_f32_e32 v88, v88, v80
	v_add_f32_e32 v80, 1.0, v94
	v_mul_f32_e32 v92, 0xbfb8aa3b, v90
	v_rcp_f32_e32 v80, v80
	v_exp_f32_e32 v92, v92
	v_mul_f32_e32 v93, 0xbfb8aa3b, v91
	v_exp_f32_e32 v93, v93
	v_mul_f32_e32 v80, v89, v80
	v_add_f32_e32 v89, 1.0, v92
	v_rcp_f32_e32 v89, v89
	v_add_f32_e32 v92, 1.0, v93
	v_rcp_f32_e32 v92, v92
	v_mul_f32_e32 v93, v80, v81
	v_mul_f32_e32 v80, v90, v89
	v_mul_f32_e32 v89, v80, v82
	v_mul_f32_e32 v80, v91, v92
	v_mul_f32_e32 v83, v80, v83
	v_cvt_pk_bf16_f32 v80, v84, v85
	v_cvt_pk_bf16_f32 v81, v86, v87
	v_mul_f32_e32 v86, 0xbfb8aa3b, v76
	v_exp_f32_e32 v86, v86
	v_mul_f32_e32 v87, 0xbfb8aa3b, v77
	v_exp_f32_e32 v87, v87
	v_mad_i64_i32 v[84:85], s[0:1], v98, s63, v[112:113]
; DI float sigmoidf_(float x) { return __builtin_amdgcn_rcpf(1.0f + __builtin_amdgcn_exp2f(-x * LOG2E)); }
; DI float rs_of(const float* ss, int row) { return 1.0f / sqrtf(ss[row] * (1.0f / DM) + EPS); }
; DI u32x4 pack8(f32x4 a, f32x4 b) { u32x4 w; w.x = cvt_pk_bf16(a[0], a[1]); w.y = cvt_pk_bf16(a[2], a[3]); w.z = cvt_pk_bf16(b[0], b[1]); w.w = cvt_pk_bf16(b[2], b[3]); return w; }
;     DI void operator()(AccRef acc, const Unit& u, int wr, int wc, int fr, int fq) const {
;     ...
;                 f32x4 o[2]; const float r = ss ? rs_of(ss, row0 + ai * 128 + m * 16) : 1.0f;
; #pragma unroll
;                 for (int n = 0; n < 2; ++n)
; #pragma unroll
;                     for (int j = 0; j < 4; ++j) { const float gt = acc[ai][0][m][n][j] * r, up = acc[ai][1][m][n][j] * r; o[n][j] = gt * sigmoidf_(gt) * up; }
;                 *(u32x4*)(Hd + (size_t)(row0 + ai * 128 + m * 16) * DFF + col0) = pack8(o[0], o[1]);
	v_lshl_add_u64 v[84:85], v[84:85], 0, v[114:115]
	v_cvt_pk_bf16_f32 v82, v88, v93
	v_cvt_pk_bf16_f32 v83, v89, v83
	global_store_dwordx4 v[84:85], v[80:83], off
	s_mov_b64 s[40:41], s[18:19]
	s_nop 0
	v_add_f32_e32 v80, 1.0, v86
	v_rcp_f32_e32 v80, v80
	v_add_f32_e32 v81, 1.0, v87
	v_rcp_f32_e32 v81, v81
	v_add_u32_e32 v82, 48, v150
	v_mul_f32_e32 v76, v76, v80
	v_mul_f32_e32 v68, v76, v68
	v_mul_f32_e32 v76, v77, v81
	v_mul_f32_e32 v77, 0xbfb8aa3b, v78
	v_exp_f32_e32 v77, v77
	v_mul_f32_e32 v80, 0xbfb8aa3b, v79
	v_exp_f32_e32 v80, v80
	v_mul_f32_e32 v69, v76, v69
	v_add_f32_e32 v76, 1.0, v77
	v_rcp_f32_e32 v76, v76
	v_add_f32_e32 v77, 1.0, v80
	v_mul_f32_e32 v80, 0xbfb8aa3b, v72
	v_rcp_f32_e32 v77, v77
	v_exp_f32_e32 v80, v80
	v_mul_f32_e32 v76, v78, v76
	v_mul_f32_e32 v70, v76, v70
	v_mul_f32_e32 v76, v79, v77
	v_add_f32_e32 v77, 1.0, v80
	v_rcp_f32_e32 v77, v77
	v_mul_f32_e32 v78, 0xbfb8aa3b, v73
	v_exp_f32_e32 v78, v78
	v_mul_f32_e32 v71, v76, v71
	v_mul_f32_e32 v72, v72, v77
	v_mul_f32_e32 v72, v72, v64
	v_add_f32_e32 v64, 1.0, v78
	v_mul_f32_e32 v76, 0xbfb8aa3b, v74
	v_rcp_f32_e32 v64, v64
	v_exp_f32_e32 v76, v76
	v_mul_f32_e32 v77, 0xbfb8aa3b, v75
	v_exp_f32_e32 v77, v77
	v_mul_f32_e32 v64, v73, v64
	v_add_f32_e32 v73, 1.0, v76
	v_rcp_f32_e32 v73, v73
	v_add_f32_e32 v76, 1.0, v77
	v_rcp_f32_e32 v76, v76
	v_mul_f32_e32 v77, v64, v65
	v_mul_f32_e32 v64, v74, v73
	v_mul_f32_e32 v73, v64, v66
	v_mul_f32_e32 v64, v75, v76
	v_mul_f32_e32 v67, v64, v67
	v_cvt_pk_bf16_f32 v64, v68, v69
	v_cvt_pk_bf16_f32 v65, v70, v71
	v_mul_f32_e32 v70, 0xbfb8aa3b, v60
	v_exp_f32_e32 v70, v70
	v_mul_f32_e32 v71, 0xbfb8aa3b, v61
	v_exp_f32_e32 v71, v71
	v_mad_i64_i32 v[68:69], s[0:1], v82, s63, v[112:113]
	v_lshl_add_u64 v[68:69], v[68:69], 0, v[114:115]
	v_cvt_pk_bf16_f32 v66, v72, v77
	v_cvt_pk_bf16_f32 v67, v73, v67
	global_store_dwordx4 v[68:69], v[64:67], off
	s_nop 1
	v_add_f32_e32 v64, 1.0, v70
	v_rcp_f32_e32 v64, v64
	v_add_f32_e32 v65, 1.0, v71
	v_rcp_f32_e32 v65, v65
	v_add_u32_e32 v66, 0x80, v150
	v_mul_f32_e32 v60, v60, v64
	v_mul_f32_e32 v52, v60, v52
	v_mul_f32_e32 v60, v61, v65
	v_mul_f32_e32 v61, 0xbfb8aa3b, v62
	v_exp_f32_e32 v61, v61
	v_mul_f32_e32 v64, 0xbfb8aa3b, v63
	v_exp_f32_e32 v64, v64
	v_mul_f32_e32 v53, v60, v53
	v_add_f32_e32 v60, 1.0, v61
	v_rcp_f32_e32 v60, v60
	v_add_f32_e32 v61, 1.0, v64
	v_mul_f32_e32 v64, 0xbfb8aa3b, v56
	v_rcp_f32_e32 v61, v61
	v_exp_f32_e32 v64, v64
	v_mul_f32_e32 v60, v62, v60
	v_mul_f32_e32 v54, v60, v54
	v_mul_f32_e32 v60, v63, v61
	v_add_f32_e32 v61, 1.0, v64
	v_rcp_f32_e32 v61, v61
	v_mul_f32_e32 v62, 0xbfb8aa3b, v57
	v_exp_f32_e32 v62, v62
	v_mul_f32_e32 v55, v60, v55
	v_mul_f32_e32 v56, v56, v61
	v_mul_f32_e32 v56, v56, v48
	v_add_f32_e32 v48, 1.0, v62
	v_mul_f32_e32 v60, 0xbfb8aa3b, v58
	v_rcp_f32_e32 v48, v48
	v_exp_f32_e32 v60, v60
	v_mul_f32_e32 v61, 0xbfb8aa3b, v59
	v_exp_f32_e32 v61, v61
	v_mul_f32_e32 v48, v57, v48
	v_add_f32_e32 v57, 1.0, v60
	v_rcp_f32_e32 v57, v57
	v_add_f32_e32 v60, 1.0, v61
	v_rcp_f32_e32 v60, v60
	v_mul_f32_e32 v61, v48, v49
	v_mul_f32_e32 v48, v58, v57
	v_mul_f32_e32 v57, v48, v50
	v_mul_f32_e32 v48, v59, v60
	v_mul_f32_e32 v51, v48, v51
	v_cvt_pk_bf16_f32 v48, v52, v53
	v_cvt_pk_bf16_f32 v49, v54, v55
	v_mul_f32_e32 v54, 0xbfb8aa3b, v44
	v_exp_f32_e32 v54, v54
	v_mul_f32_e32 v55, 0xbfb8aa3b, v45
	v_exp_f32_e32 v55, v55
	v_mad_i64_i32 v[52:53], s[0:1], v66, s63, v[112:113]
	v_lshl_add_u64 v[52:53], v[52:53], 0, v[114:115]
	v_cvt_pk_bf16_f32 v50, v56, v61
	v_cvt_pk_bf16_f32 v51, v57, v51
	global_store_dwordx4 v[52:53], v[48:51], off
	s_nop 1
	v_add_f32_e32 v48, 1.0, v54
	v_rcp_f32_e32 v48, v48
	v_add_f32_e32 v49, 1.0, v55
	v_rcp_f32_e32 v49, v49
	v_add_u32_e32 v50, 0x90, v150
	v_mul_f32_e32 v44, v44, v48
	v_mul_f32_e32 v36, v44, v36
	v_mul_f32_e32 v44, v45, v49
	v_mul_f32_e32 v45, 0xbfb8aa3b, v46
	v_exp_f32_e32 v45, v45
	v_mul_f32_e32 v48, 0xbfb8aa3b, v47
	v_exp_f32_e32 v48, v48
	v_mul_f32_e32 v37, v44, v37
	v_add_f32_e32 v44, 1.0, v45
	v_rcp_f32_e32 v44, v44
	v_add_f32_e32 v45, 1.0, v48
	v_mul_f32_e32 v48, 0xbfb8aa3b, v40
	v_rcp_f32_e32 v45, v45
	v_exp_f32_e32 v48, v48
	v_mul_f32_e32 v44, v46, v44
	v_mul_f32_e32 v38, v44, v38
	v_mul_f32_e32 v44, v47, v45
	v_add_f32_e32 v45, 1.0, v48
	v_rcp_f32_e32 v45, v45
	v_mul_f32_e32 v46, 0xbfb8aa3b, v41
; DI float sigmoidf_(float x) { return __builtin_amdgcn_rcpf(1.0f + __builtin_amdgcn_exp2f(-x * LOG2E)); }
; DI float rs_of(const float* ss, int row) { return 1.0f / sqrtf(ss[row] * (1.0f / DM) + EPS); }
; DI u32x4 pack8(f32x4 a, f32x4 b) { u32x4 w; w.x = cvt_pk_bf16(a[0], a[1]); w.y = cvt_pk_bf16(a[2], a[3]); w.z = cvt_pk_bf16(b[0], b[1]); w.w = cvt_pk_bf16(b[2], b[3]); return w; }
; #define PG8_WAIT_V(n) asm volatile("s_waitcnt vmcnt(" #n ")" ::: "memory")
; #define PG8_BAR __builtin_amdgcn_s_barrier()
; template <class Epi, class Sched>
; DI void gemm_phase(LAS unsigned char* lds, const Gemm g, const Sched& S, const Epi& E) {
;     ...
;     PG8_WAIT_V(0);
;     if (wr == 0) PG8_BAR;
;     PG8_BAR;
;     DI void operator()(AccRef acc, const Unit& u, int wr, int wc, int fr, int fq) const {
;     ...
;                 f32x4 o[2]; const float r = ss ? rs_of(ss, row0 + ai * 128 + m * 16) : 1.0f;
; #pragma unroll
;                 for (int n = 0; n < 2; ++n)
; #pragma unroll
;                     for (int j = 0; j < 4; ++j) { const float gt = acc[ai][0][m][n][j] * r, up = acc[ai][1][m][n][j] * r; o[n][j] = gt * sigmoidf_(gt) * up; }
;                 *(u32x4*)(Hd + (size_t)(row0 + ai * 128 + m * 16) * DFF + col0) = pack8(o[0], o[1]);
	v_exp_f32_e32 v46, v46
	v_mul_f32_e32 v39, v44, v39
	v_mul_f32_e32 v40, v40, v45
	v_mul_f32_e32 v40, v40, v32
	v_add_f32_e32 v32, 1.0, v46
	v_mul_f32_e32 v44, 0xbfb8aa3b, v42
	v_rcp_f32_e32 v32, v32
	v_exp_f32_e32 v44, v44
	v_mul_f32_e32 v45, 0xbfb8aa3b, v43
	v_exp_f32_e32 v45, v45
	v_mul_f32_e32 v32, v41, v32
	v_add_f32_e32 v41, 1.0, v44
	v_rcp_f32_e32 v41, v41
	v_add_f32_e32 v44, 1.0, v45
	v_rcp_f32_e32 v44, v44
	v_mul_f32_e32 v45, v32, v33
	v_mul_f32_e32 v32, v42, v41
	v_mul_f32_e32 v41, v32, v34
	v_mul_f32_e32 v32, v43, v44
	v_mul_f32_e32 v35, v32, v35
	v_cvt_pk_bf16_f32 v32, v36, v37
	v_cvt_pk_bf16_f32 v33, v38, v39
	v_mul_f32_e32 v38, 0xbfb8aa3b, v28
	v_exp_f32_e32 v38, v38
	v_mul_f32_e32 v39, 0xbfb8aa3b, v29
	v_exp_f32_e32 v39, v39
	v_mad_i64_i32 v[36:37], s[0:1], v50, s63, v[112:113]
	v_lshl_add_u64 v[36:37], v[36:37], 0, v[114:115]
	v_cvt_pk_bf16_f32 v34, v40, v45
	v_cvt_pk_bf16_f32 v35, v41, v35
	global_store_dwordx4 v[36:37], v[32:35], off
	s_nop 1
	v_add_f32_e32 v32, 1.0, v38
	v_rcp_f32_e32 v32, v32
	v_add_f32_e32 v33, 1.0, v39
	v_rcp_f32_e32 v33, v33
	v_add_u32_e32 v34, 0xa0, v150
	v_mul_f32_e32 v28, v28, v32
	v_mul_f32_e32 v20, v28, v20
	v_mul_f32_e32 v28, v29, v33
	v_mul_f32_e32 v29, 0xbfb8aa3b, v30
	v_exp_f32_e32 v29, v29
	v_mul_f32_e32 v32, 0xbfb8aa3b, v31
	v_exp_f32_e32 v32, v32
	v_mul_f32_e32 v21, v28, v21
	v_add_f32_e32 v28, 1.0, v29
	v_rcp_f32_e32 v28, v28
	v_add_f32_e32 v29, 1.0, v32
	v_mul_f32_e32 v32, 0xbfb8aa3b, v24
	v_rcp_f32_e32 v29, v29
	v_exp_f32_e32 v32, v32
	v_mul_f32_e32 v28, v30, v28
	v_mul_f32_e32 v22, v28, v22
	v_mul_f32_e32 v28, v31, v29
	v_add_f32_e32 v29, 1.0, v32
	v_rcp_f32_e32 v29, v29
	v_mul_f32_e32 v30, 0xbfb8aa3b, v25
	v_exp_f32_e32 v30, v30
	v_mul_f32_e32 v23, v28, v23
	v_mul_f32_e32 v24, v24, v29
	v_mul_f32_e32 v24, v24, v16
	v_add_f32_e32 v16, 1.0, v30
	v_mul_f32_e32 v28, 0xbfb8aa3b, v26
	v_rcp_f32_e32 v16, v16
	v_exp_f32_e32 v28, v28
	v_mul_f32_e32 v29, 0xbfb8aa3b, v27
	v_exp_f32_e32 v29, v29
	v_mul_f32_e32 v16, v25, v16
	v_add_f32_e32 v25, 1.0, v28
	v_rcp_f32_e32 v25, v25
	v_add_f32_e32 v28, 1.0, v29
	v_rcp_f32_e32 v28, v28
	v_mul_f32_e32 v29, v16, v17
	v_mul_f32_e32 v16, v26, v25
	v_mul_f32_e32 v25, v16, v18
	v_mul_f32_e32 v16, v27, v28
	v_mul_f32_e32 v19, v16, v19
	v_cvt_pk_bf16_f32 v16, v20, v21
	v_cvt_pk_bf16_f32 v17, v22, v23
	v_mul_f32_e32 v22, 0xbfb8aa3b, v12
	v_exp_f32_e32 v22, v22
	v_mul_f32_e32 v23, 0xbfb8aa3b, v13
	v_exp_f32_e32 v23, v23
	v_mad_i64_i32 v[20:21], s[0:1], v34, s63, v[112:113]
	v_lshl_add_u64 v[20:21], v[20:21], 0, v[114:115]
	v_cvt_pk_bf16_f32 v18, v24, v29
	v_cvt_pk_bf16_f32 v19, v25, v19
	global_store_dwordx4 v[20:21], v[16:19], off
	s_nop 1
	v_add_f32_e32 v16, 1.0, v22
	v_rcp_f32_e32 v16, v16
	v_add_f32_e32 v17, 1.0, v23
	v_rcp_f32_e32 v17, v17
	v_add_u32_e32 v18, 0xb0, v150
	v_mul_f32_e32 v12, v12, v16
	v_mul_f32_e32 v4, v12, v4
	v_mul_f32_e32 v12, v13, v17
	v_mul_f32_e32 v13, 0xbfb8aa3b, v14
	v_exp_f32_e32 v13, v13
	v_mul_f32_e32 v16, 0xbfb8aa3b, v15
	v_exp_f32_e32 v16, v16
	v_mul_f32_e32 v5, v12, v5
	v_add_f32_e32 v12, 1.0, v13
	v_rcp_f32_e32 v12, v12
	v_add_f32_e32 v13, 1.0, v16
	v_mul_f32_e32 v16, 0xbfb8aa3b, v8
	v_rcp_f32_e32 v13, v13
	v_exp_f32_e32 v16, v16
	v_mul_f32_e32 v12, v14, v12
	v_mul_f32_e32 v6, v12, v6
	v_mul_f32_e32 v12, v15, v13
	v_add_f32_e32 v13, 1.0, v16
	v_rcp_f32_e32 v13, v13
	v_mul_f32_e32 v14, 0xbfb8aa3b, v9
	v_exp_f32_e32 v14, v14
	v_mul_f32_e32 v7, v12, v7
	v_mul_f32_e32 v8, v8, v13
	v_mul_f32_e32 v8, v8, v0
	v_add_f32_e32 v0, 1.0, v14
	v_mul_f32_e32 v12, 0xbfb8aa3b, v10
	v_rcp_f32_e32 v0, v0
	v_exp_f32_e32 v12, v12
	v_mul_f32_e32 v13, 0xbfb8aa3b, v11
	v_exp_f32_e32 v13, v13
	v_mul_f32_e32 v0, v9, v0
	v_add_f32_e32 v9, 1.0, v12
	v_rcp_f32_e32 v9, v9
	v_add_f32_e32 v12, 1.0, v13
	v_rcp_f32_e32 v12, v12
	v_mul_f32_e32 v13, v0, v1
	v_mul_f32_e32 v0, v10, v9
	v_mul_f32_e32 v9, v0, v2
	v_mul_f32_e32 v0, v11, v12
	v_mul_f32_e32 v3, v0, v3
	v_cvt_pk_bf16_f32 v0, v4, v5
	v_mad_i64_i32 v[4:5], s[0:1], v18, s63, v[112:113]
	v_lshl_add_u64 v[4:5], v[4:5], 0, v[114:115]
	v_cvt_pk_bf16_f32 v1, v6, v7
	v_cvt_pk_bf16_f32 v2, v8, v13
	v_cvt_pk_bf16_f32 v3, v9, v3
	global_store_dwordx4 v[4:5], v[0:3], off
	s_cbranch_vccz .LBB0_212
	s_waitcnt vmcnt(0)
	s_cmpk_gt_u32 s3, 0xff
	s_cbranch_scc1 .LBB0_223
	s_barrier

; #define PG8_STAGE(bufoff, gbase, voff) do { _Pragma("unroll") for (int _i = 0; _i < 2; ++_i) \
;         __builtin_amdgcn_global_load_lds((const unsigned*)((const char*)(gbase) + (voff)[_i]), (LAS unsigned*)(lds + (bufoff) + ldsw + _i * 8192), 16, 0, 0); } while (0)
; #define PG8_LDA(dst, b, h) do { _Pragma("unroll") for (int m = 0; m < 4; ++m) _Pragma("unroll") for (int k = 0; k < 2; ++k) dst[m][k] = *(const LAS bf16x8*)(lds + PG8_SA(b, h) + aoff + m * 2048 + k * 1024); } while (0)
; #define PG8_LDB(dst, b, h) do { _Pragma("unroll") for (int n = 0; n < 2; ++n) _Pragma("unroll") for (int k = 0; k < 2; ++k) dst[n][k] = *(const LAS bf16x8*)(lds + PG8_SB(b, h) + boff + n * 2048 + k * 1024); } while (0)
; #define PG8_MMA(ai, bj, At, Bt) do { __builtin_amdgcn_s_setprio(1); _Pragma("unroll") for (int m = 0; m < 4; ++m) _Pragma("unroll") for (int n = 0; n < 2; ++n) _Pragma("unroll") for (int k = 0; k < 2; ++k) \
;         acc[ai][bj][m][n] = __builtin_amdgcn_mfma_f32_16x16x32_bf16(Bt[n][k], At[m][k], acc[ai][bj][m][n], 0, 0, 0); __builtin_amdgcn_s_setprio(0); } while (0)
; #define PG8_WAIT_V(n) asm volatile("s_waitcnt vmcnt(" #n ")" ::: "memory")
; #define PG8_WAIT_L(n) asm volatile("s_waitcnt lgkmcnt(" #n ")" ::: "memory")
; #define PG8_BAR __builtin_amdgcn_s_barrier()
; #define PG8_SCHED __builtin_amdgcn_sched_barrier(0)
; template <class Epi, class Sched>
; DI void gemm_phase(LAS unsigned char* lds, const Gemm g, const Sched& S, const Epi& E) {
;     ...
;             const bool last = (t == nt - 2);
;             const char* a1 = cA + (size_t)(t + 1) * kstep;
;             const char* a2 = last ? nA : cA + (size_t)(t + 2) * kstep; const char* b2 = last ? nB : cB + (size_t)(t + 2) * kstep;
;             const char* a3 = a2 + kstep; const char* b3 = b2 + kstep;
;             PG8_LDB(B0, 0, 0); PG8_SCHED; PG8_LDA(At, 0, 0); PG8_STAGE(PG8_SA(1, 1), a1 + hstep, voffA);
;             PG8_WAIT_L(8); PG8_BAR; PG8_WAIT_L(0); PG8_MMA(0, 0, At, B0); PG8_BAR; PG8_SCHED;
;             PG8_LDB(B1, 0, 1); PG8_STAGE(PG8_SB(0, 0), b2, voffB);
;             PG8_BAR; PG8_WAIT_L(0); PG8_MMA(0, 1, At, B1); PG8_BAR;
;             PG8_LDA(At, 0, 1); PG8_STAGE(PG8_SA(0, 0), a2, voffA);
;             PG8_BAR; PG8_WAIT_L(0); PG8_MMA(1, 0, At, B0); PG8_BAR; PG8_SCHED;
;             PG8_STAGE(PG8_SB(0, 1), b2 + hstep, voffB);
;             PG8_WAIT_V(6); PG8_BAR; PG8_MMA(1, 1, At, B1); PG8_BAR;
.LBB0_296:
	s_add_u32 s40, s40, 0x160080
	s_addc_u32 s41, s41, 0
	s_add_u32 s35, s42, 0x100
	v_mov_b32_e32 v0, 0
	s_addc_u32 s68, s43, 0
	s_mov_b32 s69, -2
	s_waitcnt lgkmcnt(0)
	ds_read_b128 v[144:147], v158
	ds_read_b128 v[164:167], v158 offset:1024
	ds_read_b128 v[168:171], v158 offset:2048
	ds_read_b128 v[172:175], v158 offset:3072
	s_add_u32 s0, s40, 0xffea0080
	s_addc_u32 s1, s41, -1
	s_cmpk_eq_i32 s69, 0x54
	s_cselect_b32 s45, s9, s1
	s_cselect_b32 s44, s8, s0
	s_cselect_b32 s43, s11, s68
	s_cselect_b32 s42, s10, s35
	v_lshl_add_u64 v[214:215], s[40:41], 0, v[136:137]
	s_add_i32 m0, s54, 0xc000
	ds_read_b128 v[176:179], v159
	ds_read_b128 v[180:183], v159 offset:1024
	ds_read_b128 v[188:191], v159 offset:2048
	ds_read_b128 v[194:197], v159 offset:3072
	ds_read_b128 v[198:201], v159 offset:4096
	ds_read_b128 v[202:205], v159 offset:5120
	ds_read_b128 v[206:209], v159 offset:6144
	ds_read_b128 v[210:213], v159 offset:7168
	global_load_lds_dwordx4 v[214:215], off
	v_lshl_add_u64 v[214:215], s[40:41], 0, v[138:139]
	s_add_i32 m0, s54, 0xe000
	s_nop 0
	global_load_lds_dwordx4 v[214:215], off
	s_waitcnt lgkmcnt(8)
	s_barrier
	s_waitcnt lgkmcnt(0)
	s_setprio 1
	s_waitcnt lgkmcnt(0)
	v_mfma_f32_16x16x32_bf16 v[124:127], v[144:147], v[176:179], 0
	v_mfma_f32_16x16x32_bf16 v[120:123], v[168:171], v[176:179], 0
	v_mfma_f32_16x16x32_bf16 v[108:111], v[144:147], v[188:191], 0
	v_mfma_f32_16x16x32_bf16 v[104:107], v[168:171], v[188:191], 0
	v_mfma_f32_16x16x32_bf16 v[92:95], v[144:147], v[198:201], 0
	v_mfma_f32_16x16x32_bf16 v[88:91], v[168:171], v[198:201], 0
	v_mfma_f32_16x16x32_bf16 v[76:79], v[144:147], v[206:209], 0
	v_mfma_f32_16x16x32_bf16 v[72:75], v[168:171], v[206:209], 0
	v_mfma_f32_16x16x32_bf16 v[124:127], v[164:167], v[180:183], v[124:127]
	v_mfma_f32_16x16x32_bf16 v[120:123], v[172:175], v[180:183], v[120:123]
	v_mfma_f32_16x16x32_bf16 v[108:111], v[164:167], v[194:197], v[108:111]
	v_mfma_f32_16x16x32_bf16 v[104:107], v[172:175], v[194:197], v[104:107]
	v_mfma_f32_16x16x32_bf16 v[92:95], v[164:167], v[202:205], v[92:95]
	v_mfma_f32_16x16x32_bf16 v[88:91], v[172:175], v[202:205], v[88:91]
	v_mfma_f32_16x16x32_bf16 v[76:79], v[164:167], v[210:213], v[76:79]
	v_mfma_f32_16x16x32_bf16 v[72:75], v[172:175], v[210:213], v[72:75]
	s_setprio 0
	s_barrier
	s_add_i32 s0, s63, s53
	v_lshl_add_u64 v[230:231], s[42:43], 0, v[130:131]
	s_mov_b32 m0, s0
	ds_read_b128 v[214:217], v161
	ds_read_b128 v[218:221], v161 offset:1024
	ds_read_b128 v[222:225], v161 offset:2048
	ds_read_b128 v[226:229], v161 offset:3072
	global_load_lds_dwordx4 v[230:231], off
	v_lshl_add_u64 v[232:233], s[42:43], 0, v[134:135]
	s_add_i32 m0, s0, 0x2000
	s_nop 0
	global_load_lds_dwordx4 v[232:233], off
	s_barrier
	s_waitcnt lgkmcnt(0)
	s_setprio 1
	s_waitcnt lgkmcnt(0)
	v_mfma_f32_16x16x32_bf16 v[116:119], v[214:217], v[176:179], 0
	v_mfma_f32_16x16x32_bf16 v[112:115], v[222:225], v[176:179], 0
	v_mfma_f32_16x16x32_bf16 v[100:103], v[214:217], v[188:191], 0
	v_mfma_f32_16x16x32_bf16 v[96:99], v[222:225], v[188:191], 0
	v_mfma_f32_16x16x32_bf16 v[84:87], v[214:217], v[198:201], 0
	v_mfma_f32_16x16x32_bf16 v[80:83], v[222:225], v[198:201], 0
	v_mfma_f32_16x16x32_bf16 v[68:71], v[214:217], v[206:209], 0
	v_mfma_f32_16x16x32_bf16 v[64:67], v[222:225], v[206:209], 0
	v_mfma_f32_16x16x32_bf16 v[116:119], v[218:221], v[180:183], v[116:119]
	v_mfma_f32_16x16x32_bf16 v[112:115], v[226:229], v[180:183], v[112:115]
	v_mfma_f32_16x16x32_bf16 v[100:103], v[218:221], v[194:197], v[100:103]
	v_mfma_f32_16x16x32_bf16 v[96:99], v[226:229], v[194:197], v[96:99]
	v_mfma_f32_16x16x32_bf16 v[84:87], v[218:221], v[202:205], v[84:87]
	v_mfma_f32_16x16x32_bf16 v[80:83], v[226:229], v[202:205], v[80:83]
	v_mfma_f32_16x16x32_bf16 v[68:71], v[218:221], v[210:213], v[68:71]
	v_mfma_f32_16x16x32_bf16 v[64:67], v[226:229], v[210:213], v[64:67]
	s_setprio 0
	s_mov_b32 m0, s54
	v_lshl_add_u64 v[234:235], s[44:45], 0, v[128:129]
	s_barrier
	ds_read_b128 v[176:179], v159 offset:16384
	ds_read_b128 v[180:183], v159 offset:17408
	ds_read_b128 v[188:191], v159 offset:18432
	ds_read_b128 v[194:197], v159 offset:19456
	ds_read_b128 v[198:201], v159 offset:20480
	ds_read_b128 v[202:205], v159 offset:21504
	ds_read_b128 v[206:209], v159 offset:22528
	ds_read_b128 v[210:213], v159 offset:23552
	global_load_lds_dwordx4 v[234:235], off
	v_lshl_add_u64 v[236:237], s[44:45], 0, v[132:133]
	s_mov_b32 m0, s55
	s_nop 0
	global_load_lds_dwordx4 v[236:237], off
	s_barrier
	s_waitcnt lgkmcnt(0)
	s_setprio 1
	s_waitcnt lgkmcnt(0)
	v_mfma_f32_16x16x32_bf16 v[60:63], v[144:147], v[176:179], 0
	v_mfma_f32_16x16x32_bf16 v[56:59], v[168:171], v[176:179], 0
	v_mfma_f32_16x16x32_bf16 v[44:47], v[144:147], v[188:191], 0
	v_mfma_f32_16x16x32_bf16 v[40:43], v[168:171], v[188:191], 0
	v_mfma_f32_16x16x32_bf16 v[28:31], v[144:147], v[198:201], 0
	v_mfma_f32_16x16x32_bf16 v[24:27], v[168:171], v[198:201], 0
	v_mfma_f32_16x16x32_bf16 v[12:15], v[144:147], v[206:209], 0
	v_mfma_f32_16x16x32_bf16 v[8:11], v[168:171], v[206:209], 0
	v_mfma_f32_16x16x32_bf16 v[60:63], v[164:167], v[180:183], v[60:63]
	v_mfma_f32_16x16x32_bf16 v[56:59], v[172:175], v[180:183], v[56:59]
	v_mfma_f32_16x16x32_bf16 v[44:47], v[164:167], v[194:197], v[44:47]
	v_mfma_f32_16x16x32_bf16 v[40:43], v[172:175], v[194:197], v[40:43]
	v_mfma_f32_16x16x32_bf16 v[28:31], v[164:167], v[202:205], v[28:31]
	v_mfma_f32_16x16x32_bf16 v[24:27], v[172:175], v[202:205], v[24:27]
	v_mfma_f32_16x16x32_bf16 v[12:15], v[164:167], v[210:213], v[12:15]
	v_mfma_f32_16x16x32_bf16 v[8:11], v[172:175], v[210:213], v[8:11]
	s_setprio 0
	s_barrier
; #define PG8_STAGE(bufoff, gbase, voff) do { _Pragma("unroll") for (int _i = 0; _i < 2; ++_i) \
;         __builtin_amdgcn_global_load_lds((const unsigned*)((const char*)(gbase) + (voff)[_i]), (LAS unsigned*)(lds + (bufoff) + ldsw + _i * 8192), 16, 0, 0); } while (0)
; #define PG8_LDA(dst, b, h) do { _Pragma("unroll") for (int m = 0; m < 4; ++m) _Pragma("unroll") for (int k = 0; k < 2; ++k) dst[m][k] = *(const LAS bf16x8*)(lds + PG8_SA(b, h) + aoff + m * 2048 + k * 1024); } while (0)
; #define PG8_LDB(dst, b, h) do { _Pragma("unroll") for (int n = 0; n < 2; ++n) _Pragma("unroll") for (int k = 0; k < 2; ++k) dst[n][k] = *(const LAS bf16x8*)(lds + PG8_SB(b, h) + boff + n * 2048 + k * 1024); } while (0)
; #define PG8_MMA(ai, bj, At, Bt) do { __builtin_amdgcn_s_setprio(1); _Pragma("unroll") for (int m = 0; m < 4; ++m) _Pragma("unroll") for (int n = 0; n < 2; ++n) _Pragma("unroll") for (int k = 0; k < 2; ++k) \
;         acc[ai][bj][m][n] = __builtin_amdgcn_mfma_f32_16x16x32_bf16(Bt[n][k], At[m][k], acc[ai][bj][m][n], 0, 0, 0); __builtin_amdgcn_s_setprio(0); } while (0)
; #define PG8_WAIT_V(n) asm volatile("s_waitcnt vmcnt(" #n ")" ::: "memory")
; #define PG8_WAIT_L(n) asm volatile("s_waitcnt lgkmcnt(" #n ")" ::: "memory")
; #define PG8_BAR __builtin_amdgcn_s_barrier()
; #define PG8_SCHED __builtin_amdgcn_sched_barrier(0)
; template <class Epi, class Sched>
; DI void gemm_phase(LAS unsigned char* lds, const Gemm g, const Sched& S, const Epi& E) {
;     ...
;             PG8_STAGE(PG8_SB(0, 1), b2 + hstep, voffB);
;             PG8_WAIT_V(6); PG8_BAR; PG8_MMA(1, 1, At, B1); PG8_BAR;
;             PG8_LDB(B0, 1, 0); PG8_SCHED; PG8_LDA(At, 1, 0); PG8_STAGE(PG8_SA(0, 1), a2 + hstep, voffA);
;             PG8_WAIT_L(8); PG8_BAR; PG8_WAIT_L(0); PG8_MMA(0, 0, At, B0); PG8_BAR; PG8_SCHED;
;             PG8_LDB(B1, 1, 1); PG8_STAGE(PG8_SB(1, 0), b3, voffB);
;             PG8_BAR; PG8_WAIT_L(0); PG8_MMA(0, 1, At, B1); PG8_BAR;
;             PG8_LDA(At, 1, 1); PG8_STAGE(PG8_SA(1, 0), a3, voffA);
;             PG8_BAR; PG8_WAIT_L(0); PG8_MMA(1, 0, At, B0); PG8_BAR; PG8_SCHED;
	s_add_u32 s0, s42, 0x160000
	s_addc_u32 s1, s43, 0
	s_add_i32 s4, s64, s53
	v_lshl_add_u64 v[144:145], s[0:1], 0, v[130:131]
	s_mov_b32 m0, s4
	s_nop 0
	global_load_lds_dwordx4 v[144:145], off
	v_lshl_add_u64 v[144:145], s[0:1], 0, v[134:135]
	s_add_i32 m0, s4, 0x2000
	s_nop 0
	global_load_lds_dwordx4 v[144:145], off
	s_waitcnt vmcnt(6)
	s_barrier
	s_setprio 1
	v_mfma_f32_16x16x32_bf16 v[52:55], v[214:217], v[176:179], 0
	v_mfma_f32_16x16x32_bf16 v[48:51], v[222:225], v[176:179], 0
	v_mfma_f32_16x16x32_bf16 v[36:39], v[214:217], v[188:191], 0
	v_mfma_f32_16x16x32_bf16 v[32:35], v[222:225], v[188:191], 0
	v_mfma_f32_16x16x32_bf16 v[20:23], v[214:217], v[198:201], 0
	v_mfma_f32_16x16x32_bf16 v[16:19], v[222:225], v[198:201], 0
	v_mfma_f32_16x16x32_bf16 v[4:7], v[214:217], v[206:209], 0
	v_mfma_f32_16x16x32_bf16 v[0:3], v[222:225], v[206:209], 0
	v_mfma_f32_16x16x32_bf16 v[52:55], v[218:221], v[180:183], v[52:55]
	v_mfma_f32_16x16x32_bf16 v[48:51], v[226:229], v[180:183], v[48:51]
	v_mfma_f32_16x16x32_bf16 v[36:39], v[218:221], v[194:197], v[36:39]
	v_mfma_f32_16x16x32_bf16 v[32:35], v[226:229], v[194:197], v[32:35]
	v_mfma_f32_16x16x32_bf16 v[20:23], v[218:221], v[202:205], v[20:23]
	v_mfma_f32_16x16x32_bf16 v[16:19], v[226:229], v[202:205], v[16:19]
	v_mfma_f32_16x16x32_bf16 v[4:7], v[218:221], v[210:213], v[4:7]
	v_mfma_f32_16x16x32_bf16 v[0:3], v[226:229], v[210:213], v[0:3]
	s_setprio 0
	s_add_i32 s4, 0, 0x18000
	v_add_u32_e32 v163, s4, v157
	s_barrier
	ds_read_b128 v[144:147], v163
	ds_read_b128 v[164:167], v163 offset:1024
	ds_read_b128 v[168:171], v163 offset:2048
	ds_read_b128 v[172:175], v163 offset:3072
	s_add_u32 s0, s44, 0x160000
	s_addc_u32 s1, s45, 0
	s_mov_b32 m0, s56
	v_lshl_add_u64 v[214:215], s[0:1], 0, v[128:129]
	ds_read_b128 v[176:179], v159 offset:32768
	ds_read_b128 v[180:183], v159 offset:33792
	ds_read_b128 v[188:191], v159 offset:34816
	ds_read_b128 v[194:197], v159 offset:35840
	ds_read_b128 v[198:201], v159 offset:36864
	ds_read_b128 v[202:205], v159 offset:37888
	ds_read_b128 v[206:209], v159 offset:38912
	ds_read_b128 v[210:213], v159 offset:39936
	global_load_lds_dwordx4 v[214:215], off
	v_lshl_add_u64 v[214:215], s[0:1], 0, v[132:133]
	s_mov_b32 m0, s57
	s_nop 0
	global_load_lds_dwordx4 v[214:215], off
	s_waitcnt lgkmcnt(8)
	s_barrier
	s_waitcnt lgkmcnt(0)
	s_setprio 1
	s_waitcnt lgkmcnt(0)
	v_mfma_f32_16x16x32_bf16 v[124:127], v[144:147], v[176:179], v[124:127]
	v_mfma_f32_16x16x32_bf16 v[120:123], v[168:171], v[176:179], v[120:123]
	v_mfma_f32_16x16x32_bf16 v[108:111], v[144:147], v[188:191], v[108:111]
	v_mfma_f32_16x16x32_bf16 v[104:107], v[168:171], v[188:191], v[104:107]
	v_mfma_f32_16x16x32_bf16 v[92:95], v[144:147], v[198:201], v[92:95]
	v_mfma_f32_16x16x32_bf16 v[88:91], v[168:171], v[198:201], v[88:91]
	v_mfma_f32_16x16x32_bf16 v[76:79], v[144:147], v[206:209], v[76:79]
	v_mfma_f32_16x16x32_bf16 v[72:75], v[168:171], v[206:209], v[72:75]
	v_mfma_f32_16x16x32_bf16 v[124:127], v[164:167], v[180:183], v[124:127]
	v_mfma_f32_16x16x32_bf16 v[120:123], v[172:175], v[180:183], v[120:123]
	v_mfma_f32_16x16x32_bf16 v[108:111], v[164:167], v[194:197], v[108:111]
	v_mfma_f32_16x16x32_bf16 v[104:107], v[172:175], v[194:197], v[104:107]
	v_mfma_f32_16x16x32_bf16 v[92:95], v[164:167], v[202:205], v[92:95]
	v_mfma_f32_16x16x32_bf16 v[88:91], v[172:175], v[202:205], v[88:91]
	v_mfma_f32_16x16x32_bf16 v[76:79], v[164:167], v[210:213], v[76:79]
	v_mfma_f32_16x16x32_bf16 v[72:75], v[172:175], v[210:213], v[72:75]
	s_setprio 0
	s_barrier
	s_add_i32 s5, 0, 0x1c000
	s_add_i32 s0, s4, s53
	v_add_u32_e32 v163, s5, v157
	v_lshl_add_u64 v[230:231], v[230:231], 0, s[38:39]
	s_mov_b32 m0, s0
	ds_read_b128 v[214:217], v163
	ds_read_b128 v[218:221], v163 offset:1024
	ds_read_b128 v[222:225], v163 offset:2048
	ds_read_b128 v[226:229], v163 offset:3072
	global_load_lds_dwordx4 v[230:231], off
	v_lshl_add_u64 v[230:231], v[232:233], 0, s[38:39]
	s_add_i32 m0, s0, 0x2000
	s_nop 0
	global_load_lds_dwordx4 v[230:231], off
	s_barrier
; #define PG8_STAGE(bufoff, gbase, voff) do { _Pragma("unroll") for (int _i = 0; _i < 2; ++_i) \
;         __builtin_amdgcn_global_load_lds((const unsigned*)((const char*)(gbase) + (voff)[_i]), (LAS unsigned*)(lds + (bufoff) + ldsw + _i * 8192), 16, 0, 0); } while (0)
; #define PG8_LDA(dst, b, h) do { _Pragma("unroll") for (int m = 0; m < 4; ++m) _Pragma("unroll") for (int k = 0; k < 2; ++k) dst[m][k] = *(const LAS bf16x8*)(lds + PG8_SA(b, h) + aoff + m * 2048 + k * 1024); } while (0)
; #define PG8_MMA(ai, bj, At, Bt) do { __builtin_amdgcn_s_setprio(1); _Pragma("unroll") for (int m = 0; m < 4; ++m) _Pragma("unroll") for (int n = 0; n < 2; ++n) _Pragma("unroll") for (int k = 0; k < 2; ++k) \
;         acc[ai][bj][m][n] = __builtin_amdgcn_mfma_f32_16x16x32_bf16(Bt[n][k], At[m][k], acc[ai][bj][m][n], 0, 0, 0); __builtin_amdgcn_s_setprio(0); } while (0)
; #define PG8_WAIT_V(n) asm volatile("s_waitcnt vmcnt(" #n ")" ::: "memory")
; #define PG8_WAIT_L(n) asm volatile("s_waitcnt lgkmcnt(" #n ")" ::: "memory")
; #define PG8_BAR __builtin_amdgcn_s_barrier()
; #define PG8_SCHED __builtin_amdgcn_sched_barrier(0)
; template <class Epi, class Sched>
; DI void gemm_phase(LAS unsigned char* lds, const Gemm g, const Sched& S, const Epi& E) {
;     ...
;             PG8_BAR; PG8_WAIT_L(0); PG8_MMA(0, 1, At, B1); PG8_BAR;
;             PG8_LDA(At, 1, 1); PG8_STAGE(PG8_SA(1, 0), a3, voffA);
;             PG8_BAR; PG8_WAIT_L(0); PG8_MMA(1, 0, At, B0); PG8_BAR; PG8_SCHED;
;             PG8_STAGE(PG8_SB(1, 1), b3 + hstep, voffB);
;             PG8_WAIT_V(6); PG8_BAR; PG8_MMA(1, 1, At, B1); PG8_BAR;
	s_waitcnt lgkmcnt(0)
	s_setprio 1
	s_waitcnt lgkmcnt(0)
	v_mfma_f32_16x16x32_bf16 v[116:119], v[214:217], v[176:179], v[116:119]
	v_mfma_f32_16x16x32_bf16 v[112:115], v[222:225], v[176:179], v[112:115]
	v_mfma_f32_16x16x32_bf16 v[100:103], v[214:217], v[188:191], v[100:103]
	v_mfma_f32_16x16x32_bf16 v[96:99], v[222:225], v[188:191], v[96:99]
	v_mfma_f32_16x16x32_bf16 v[84:87], v[214:217], v[198:201], v[84:87]
	v_mfma_f32_16x16x32_bf16 v[80:83], v[222:225], v[198:201], v[80:83]
	v_mfma_f32_16x16x32_bf16 v[68:71], v[214:217], v[206:209], v[68:71]
	v_mfma_f32_16x16x32_bf16 v[64:67], v[222:225], v[206:209], v[64:67]
	v_mfma_f32_16x16x32_bf16 v[116:119], v[218:221], v[180:183], v[116:119]
	v_mfma_f32_16x16x32_bf16 v[112:115], v[226:229], v[180:183], v[112:115]
	v_mfma_f32_16x16x32_bf16 v[100:103], v[218:221], v[194:197], v[100:103]
	v_mfma_f32_16x16x32_bf16 v[96:99], v[226:229], v[194:197], v[96:99]
	v_mfma_f32_16x16x32_bf16 v[84:87], v[218:221], v[202:205], v[84:87]
	v_mfma_f32_16x16x32_bf16 v[80:83], v[226:229], v[202:205], v[80:83]
	v_mfma_f32_16x16x32_bf16 v[68:71], v[218:221], v[210:213], v[68:71]
	v_mfma_f32_16x16x32_bf16 v[64:67], v[226:229], v[210:213], v[64:67]
	s_setprio 0
	s_mov_b32 m0, s61
	v_lshl_add_u64 v[230:231], v[234:235], 0, s[38:39]
	s_barrier
	ds_read_b128 v[176:179], v159 offset:49152
	ds_read_b128 v[180:183], v159 offset:50176
	ds_read_b128 v[188:191], v159 offset:51200
	ds_read_b128 v[194:197], v159 offset:52224
	ds_read_b128 v[198:201], v159 offset:53248
	ds_read_b128 v[202:205], v159 offset:54272
	ds_read_b128 v[206:209], v159 offset:55296
	ds_read_b128 v[210:213], v159 offset:56320
	global_load_lds_dwordx4 v[230:231], off
	v_lshl_add_u64 v[230:231], v[236:237], 0, s[38:39]
	s_mov_b32 m0, s62
	s_nop 0
	global_load_lds_dwordx4 v[230:231], off
	s_barrier
	s_waitcnt lgkmcnt(0)
	s_setprio 1
	s_waitcnt lgkmcnt(0)
	v_mfma_f32_16x16x32_bf16 v[60:63], v[144:147], v[176:179], v[60:63]
	v_mfma_f32_16x16x32_bf16 v[56:59], v[168:171], v[176:179], v[56:59]
	v_mfma_f32_16x16x32_bf16 v[44:47], v[144:147], v[188:191], v[44:47]
	v_mfma_f32_16x16x32_bf16 v[40:43], v[168:171], v[188:191], v[40:43]
	v_mfma_f32_16x16x32_bf16 v[28:31], v[144:147], v[198:201], v[28:31]
	v_mfma_f32_16x16x32_bf16 v[24:27], v[168:171], v[198:201], v[24:27]
	v_mfma_f32_16x16x32_bf16 v[12:15], v[144:147], v[206:209], v[12:15]
	v_mfma_f32_16x16x32_bf16 v[8:11], v[168:171], v[206:209], v[8:11]
	v_mfma_f32_16x16x32_bf16 v[60:63], v[164:167], v[180:183], v[60:63]
	v_mfma_f32_16x16x32_bf16 v[56:59], v[172:175], v[180:183], v[56:59]
	v_mfma_f32_16x16x32_bf16 v[44:47], v[164:167], v[194:197], v[44:47]
	v_mfma_f32_16x16x32_bf16 v[40:43], v[172:175], v[194:197], v[40:43]
	v_mfma_f32_16x16x32_bf16 v[28:31], v[164:167], v[202:205], v[28:31]
	v_mfma_f32_16x16x32_bf16 v[24:27], v[172:175], v[202:205], v[24:27]
	v_mfma_f32_16x16x32_bf16 v[12:15], v[164:167], v[210:213], v[12:15]
	v_mfma_f32_16x16x32_bf16 v[8:11], v[172:175], v[210:213], v[8:11]
	s_setprio 0
	s_barrier
	s_add_u32 s0, s42, 0x160080
	s_addc_u32 s1, s43, 0
	s_add_i32 s4, s5, s53
	v_lshl_add_u64 v[144:145], s[0:1], 0, v[130:131]
	s_mov_b32 m0, s4
	s_nop 0
	global_load_lds_dwordx4 v[144:145], off
	v_lshl_add_u64 v[144:145], s[0:1], 0, v[134:135]
	s_add_i32 m0, s4, 0x2000
	s_nop 0
	global_load_lds_dwordx4 v[144:145], off
	s_waitcnt vmcnt(6)
	s_barrier
	s_setprio 1
	v_mfma_f32_16x16x32_bf16 v[52:55], v[214:217], v[176:179], v[52:55]
	v_mfma_f32_16x16x32_bf16 v[48:51], v[222:225], v[176:179], v[48:51]
	v_mfma_f32_16x16x32_bf16 v[36:39], v[214:217], v[188:191], v[36:39]
	v_mfma_f32_16x16x32_bf16 v[32:35], v[222:225], v[188:191], v[32:35]
	v_mfma_f32_16x16x32_bf16 v[20:23], v[214:217], v[198:201], v[20:23]
	v_mfma_f32_16x16x32_bf16 v[16:19], v[222:225], v[198:201], v[16:19]
	v_mfma_f32_16x16x32_bf16 v[4:7], v[214:217], v[206:209], v[4:7]
	v_mfma_f32_16x16x32_bf16 v[0:3], v[222:225], v[206:209], v[0:3]
	v_mfma_f32_16x16x32_bf16 v[52:55], v[218:221], v[180:183], v[52:55]
	v_mfma_f32_16x16x32_bf16 v[48:51], v[226:229], v[180:183], v[48:51]
	v_mfma_f32_16x16x32_bf16 v[36:39], v[218:221], v[194:197], v[36:39]
	v_mfma_f32_16x16x32_bf16 v[32:35], v[226:229], v[194:197], v[32:35]
	v_mfma_f32_16x16x32_bf16 v[20:23], v[218:221], v[202:205], v[20:23]
	v_mfma_f32_16x16x32_bf16 v[16:19], v[226:229], v[202:205], v[16:19]
	v_mfma_f32_16x16x32_bf16 v[4:7], v[218:221], v[210:213], v[4:7]
	v_mfma_f32_16x16x32_bf16 v[0:3], v[226:229], v[210:213], v[0:3]
	s_setprio 0
	s_add_i32 s69, s69, 2
	s_add_u32 s40, s40, 0x100
	s_addc_u32 s41, s41, 0
	s_add_u32 s35, s35, 0x100
	s_addc_u32 s68, s68, 0
	s_cmpk_gt_u32 s69, 0x55
	s_barrier
	s_cbranch_scc0 .LBB0_297
	s_branch .Lpeel_done_297

; DI float bf_lo(unsigned u) { return __uint_as_float(u << 16); }
; DI float bf_hi(unsigned u) { return __uint_as_float(u & 0xffff0000u); }
; DI u32x4 pack8(f32x4 a, f32x4 b) { u32x4 w; w.x = cvt_pk_bf16(a[0], a[1]); w.y = cvt_pk_bf16(a[2], a[3]); w.z = cvt_pk_bf16(b[0], b[1]); w.w = cvt_pk_bf16(b[2], b[3]); return w; }
;     DI void operator()(AccRef acc, const Unit& u, int wr, int wc, int fr, int fq) const {
;         const int col0 = u.pn * 256 + wc * 32 + 8 * fq;
; #pragma unroll
;         for (int ai = 0; ai < 2; ++ai)
; #pragma unroll
;             for (int m = 0; m < 4; ++m) { const int row = u.pm * 256 + ai * 128 + wr * 64 + m * 16 + fr; const size_t off = (size_t)row * DM + col0; float q = 0.f;
; #pragma unroll
;                 for (int bj = 0; bj < 2; ++bj) {
;                     f32x4 b0, b1;
;                     if (F32BASE) { b0 = *(const f32x4*)(bp + off + bj * 128); b1 = *(const f32x4*)(bp + off + bj * 128 + 4); }
;                     else { const u32x4 uv = *(const u32x4*)(Ui + off + bj * 128); b0 = (f32x4){bf_lo(uv.x), bf_hi(uv.x), bf_lo(uv.y), bf_hi(uv.y)}; b1 = (f32x4){bf_lo(uv.z), bf_hi(uv.z), bf_lo(uv.w), bf_hi(uv.w)}; }
;                     const u32x4 w = pack8(b0 + acc[ai][bj][m][0] * (0.5f * S2), b1 + acc[ai][bj][m][1] * (0.5f * S2));
;                     *(u32x4*)(Uo + (size_t)row * ldo + col0 + bj * 128) = w;
;                     const float r0 = bf_lo(w.x), r1 = bf_hi(w.x), r2 = bf_lo(w.y), r3 = bf_hi(w.y), r4 = bf_lo(w.z), r5 = bf_hi(w.z), r6 = bf_lo(w.w), r7 = bf_hi(w.w);
;                     q += (r0 * r0 + r1 * r1) + (r2 * r2 + r3 * r3) + (r4 * r4 + r5 * r5) + (r6 * r6 + r7 * r7); }
;                 q += __shfl_xor(q, 16); q += __shfl_xor(q, 32); if (fq == 0) ssp[(size_t)row * 32 + u.pn * 4 + wc] = q; }
;     }
.Lpeel_done_297:
	s_lshl_b32 s0, s16, 8
	v_mov_b32_e32 v145, v148
	v_mov_b32_e32 v163, v149
	s_or_b32 s0, s0, s60
	s_lshl_b32 s40, s16, 2
	v_lshl_add_u32 v144, v163, 3, s0
	s_lshl_b32 s0, s34, 8
	s_add_i32 s0, s0, s59
	v_add_u32_e32 v146, s0, v145
	v_ashrrev_i32_e32 v147, 31, v146
	v_lshlrev_b64 v[164:165], 13, v[146:147]
	v_ashrrev_i32_e32 v145, 31, v144
	v_lshl_add_u64 v[164:165], s[28:29], 0, v[164:165]
	v_lshl_add_u64 v[172:173], v[144:145], 2, v[164:165]
	v_mov_b64_e32 v[240:241], v[172:173]
	s_mov_b32 s75, 0
	global_load_dwordx4 v[208:211], v[240:241], off
	global_load_dwordx4 v[212:215], v[240:241], off offset:16
	global_load_dwordx4 v[216:219], v[240:241], off offset:512
	global_load_dwordx4 v[220:223], v[240:241], off offset:528
	s_mov_b32 s74, 0x20000
	v_lshl_add_u64 v[240:241], v[240:241], 0, s[74:75]
	global_load_dwordx4 v[224:227], v[240:241], off
	global_load_dwordx4 v[228:231], v[240:241], off offset:16
	global_load_dwordx4 v[232:235], v[240:241], off offset:512
	global_load_dwordx4 v[236:239], v[240:241], off offset:528
	v_mov_b64_e32 v[242:243], v[240:241]
	s_mov_b32 s74, 0x20000
	v_lshl_add_u64 v[242:243], v[242:243], 0, s[74:75]
	global_load_dword v186, v[242:243], off
	global_load_dword v186, v[242:243], off offset:512
	s_mov_b32 s74, 0x20000
	v_lshl_add_u64 v[242:243], v[242:243], 0, s[74:75]
	global_load_dword v186, v[242:243], off
	global_load_dword v186, v[242:243], off offset:512
	s_mov_b32 s74, 0xa0000
	v_lshl_add_u64 v[242:243], v[242:243], 0, s[74:75]
	global_load_dword v186, v[242:243], off
	global_load_dword v186, v[242:243], off offset:512
	s_mov_b32 s74, 0x20000
	v_lshl_add_u64 v[242:243], v[242:243], 0, s[74:75]
	global_load_dword v186, v[242:243], off
	global_load_dword v186, v[242:243], off offset:512
	s_mov_b32 s74, 0x20000
	v_lshl_add_u64 v[242:243], v[242:243], 0, s[74:75]
	global_load_dword v186, v[242:243], off
	global_load_dword v186, v[242:243], off offset:512
	s_mov_b32 s74, 0x20000
	v_lshl_add_u64 v[242:243], v[242:243], 0, s[74:75]
	global_load_dword v186, v[242:243], off
	global_load_dword v186, v[242:243], off offset:512
	s_waitcnt vmcnt(19)
	v_mov_b64_e32 v[164:165], v[208:209]
	v_mov_b64_e32 v[166:167], v[210:211]
	s_mov_b32 s74, 0x20000
	v_lshl_add_u64 v[240:241], v[240:241], 0, s[74:75]
	global_load_dwordx4 v[208:211], v[240:241], off
	s_waitcnt vmcnt(19)
	v_mov_b64_e32 v[168:169], v[212:213]
	v_mov_b64_e32 v[170:171], v[214:215]
	global_load_dwordx4 v[212:215], v[240:241], off offset:16
	v_lshlrev_b64 v[174:175], 12, v[146:147]
	v_lshl_add_u64 v[174:175], s[18:19], 0, v[174:175]
	v_lshl_add_u64 v[174:175], v[144:145], 1, v[174:175]
	s_ashr_i32 s41, s40, 31
	v_pk_fma_f32 v[124:125], v[124:125], 0.5, v[164:165] op_sel_hi:[1,0,1]
	v_pk_fma_f32 v[126:127], v[126:127], 0.5, v[166:167] op_sel_hi:[1,0,1]
	v_pk_fma_f32 v[164:165], v[122:123], 0.5, v[170:171] op_sel_hi:[1,0,1]
	v_pk_fma_f32 v[120:121], v[120:121], 0.5, v[168:169] op_sel_hi:[1,0,1]
	v_cvt_pk_bf16_f32 v122, v124, v125
	v_cvt_pk_bf16_f32 v123, v126, v127
	s_nop 0
	v_cvt_pk_bf16_f32 v124, v120, v121
	v_cvt_pk_bf16_f32 v125, v164, v165
	global_store_dwordx4 v[174:175], v[122:125], off
	s_waitcnt vmcnt(20)
	v_mov_b64_e32 v[164:165], v[216:217]
	v_mov_b64_e32 v[166:167], v[218:219]
	global_load_dwordx4 v[216:219], v[240:241], off offset:512
	s_waitcnt vmcnt(20)
	v_mov_b64_e32 v[168:169], v[220:221]
	v_mov_b64_e32 v[170:171], v[222:223]
	global_load_dwordx4 v[220:223], v[240:241], off offset:528
	v_lshlrev_b32_e32 v126, 16, v122
	v_and_b32_e32 v122, 0xffff0000, v122
	v_lshlrev_b32_e32 v127, 16, v123
	v_and_b32_e32 v123, 0xffff0000, v123
	v_lshlrev_b32_e32 v172, 16, v124
	v_and_b32_e32 v124, 0xffff0000, v124
	v_mul_f32_e32 v122, v122, v122
	v_mul_f32_e32 v123, v123, v123
	v_mul_f32_e32 v124, v124, v124
	v_fmac_f32_e32 v122, v126, v126
	v_fmac_f32_e32 v123, v127, v127
	v_lshlrev_b32_e32 v173, 16, v125
	v_and_b32_e32 v125, 0xffff0000, v125
	v_fmac_f32_e32 v124, v172, v172
	v_add_f32_e32 v122, v122, v123
	v_mul_f32_e32 v125, v125, v125
	v_add_f32_e32 v122, v122, v124
	v_and_b32_e32 v121, 64, v162
	v_fmac_f32_e32 v125, v173, v173
	v_xor_b32_e32 v120, 16, v162
	v_add_u32_e32 v121, 64, v121
	v_add_f32_e32 v122, v122, v125
	v_cmp_lt_i32_e32 vcc, v120, v121
	v_pk_fma_f32 v[118:119], v[118:119], 0.5, v[166:167] op_sel_hi:[1,0,1]
	v_pk_fma_f32 v[116:117], v[116:117], 0.5, v[164:165] op_sel_hi:[1,0,1]
	v_pk_fma_f32 v[114:115], v[114:115], 0.5, v[170:171] op_sel_hi:[1,0,1]
	v_pk_fma_f32 v[112:113], v[112:113], 0.5, v[168:169] op_sel_hi:[1,0,1]
	v_cvt_pk_bf16_f32 v116, v116, v117
	v_cvt_pk_bf16_f32 v117, v118, v119
	v_cndmask_b32_e32 v120, v162, v120, vcc
	v_cvt_pk_bf16_f32 v118, v112, v113
	v_cvt_pk_bf16_f32 v119, v114, v115
	v_and_b32_e32 v113, 0xffff0000, v116
	v_and_b32_e32 v115, 0xffff0000, v117
	v_lshlrev_b32_e32 v112, 16, v116
	v_lshlrev_b32_e32 v114, 16, v117
	v_and_b32_e32 v124, 0xffff0000, v118
	v_mul_f32_e32 v113, v113, v113
	v_mul_f32_e32 v115, v115, v115
	v_lshlrev_b32_e32 v123, 16, v118
	v_and_b32_e32 v126, 0xffff0000, v119
	v_mul_f32_e32 v124, v124, v124
	v_fmac_f32_e32 v113, v112, v112
	v_fmac_f32_e32 v115, v114, v114
	v_lshlrev_b32_e32 v125, 16, v119
	v_mul_f32_e32 v126, v126, v126
	v_fmac_f32_e32 v124, v123, v123
	v_add_f32_e32 v112, v113, v115
	v_fmac_f32_e32 v126, v125, v125
	v_add_f32_e32 v112, v112, v124
	v_add_f32_e32 v112, v112, v126
	v_lshlrev_b32_e32 v120, 2, v120
	v_add_f32_e32 v112, v122, v112
	ds_bpermute_b32 v113, v120, v112
	v_xor_b32_e32 v114, 32, v162
	v_cmp_lt_i32_e32 vcc, v114, v121
	global_store_dwordx4 v[174:175], v[116:119], off offset:256
	s_waitcnt lgkmcnt(0)
	v_add_f32_e32 v112, v112, v113
	v_cndmask_b32_e32 v114, v162, v114, vcc
	v_lshlrev_b32_e32 v114, 2, v114
	ds_bpermute_b32 v113, v114, v112
	v_cmp_eq_u32_e32 vcc, 0, v163
	s_and_saveexec_b64 s[42:43], vcc
	s_cbranch_execz .LBB0_300
	v_lshlrev_b64 v[116:117], 7, v[146:147]
	v_lshl_add_u64 v[116:117], s[36:37], 0, v[116:117]
	v_lshl_add_u64 v[116:117], s[40:41], 2, v[116:117]
	s_lshl_b32 s16, s58, 2
	v_lshl_add_u64 v[116:117], v[116:117], 0, s[16:17]
	s_waitcnt lgkmcnt(0)
	v_add_f32_e32 v112, v112, v113
	global_store_dword v[116:117], v112, off

; #define PG8_STAGE(bufoff, gbase, voff) do { _Pragma("unroll") for (int _i = 0; _i < 2; ++_i) \
;         __builtin_amdgcn_global_load_lds((const unsigned*)((const char*)(gbase) + (voff)[_i]), (LAS unsigned*)(lds + (bufoff) + ldsw + _i * 8192), 16, 0, 0); } while (0)
; #define PG8_LDA(dst, b, h) do { _Pragma("unroll") for (int m = 0; m < 4; ++m) _Pragma("unroll") for (int k = 0; k < 2; ++k) dst[m][k] = *(const LAS bf16x8*)(lds + PG8_SA(b, h) + aoff + m * 2048 + k * 1024); } while (0)
; #define PG8_LDB(dst, b, h) do { _Pragma("unroll") for (int n = 0; n < 2; ++n) _Pragma("unroll") for (int k = 0; k < 2; ++k) dst[n][k] = *(const LAS bf16x8*)(lds + PG8_SB(b, h) + boff + n * 2048 + k * 1024); } while (0)
; #define PG8_MMA(ai, bj, At, Bt) do { __builtin_amdgcn_s_setprio(1); _Pragma("unroll") for (int m = 0; m < 4; ++m) _Pragma("unroll") for (int n = 0; n < 2; ++n) _Pragma("unroll") for (int k = 0; k < 2; ++k) \
;         acc[ai][bj][m][n] = __builtin_amdgcn_mfma_f32_16x16x32_bf16(Bt[n][k], At[m][k], acc[ai][bj][m][n], 0, 0, 0); __builtin_amdgcn_s_setprio(0); } while (0)
; #define PG8_WAIT_V(n) asm volatile("s_waitcnt vmcnt(" #n ")" ::: "memory")
; #define PG8_WAIT_L(n) asm volatile("s_waitcnt lgkmcnt(" #n ")" ::: "memory")
; #define PG8_BAR __builtin_amdgcn_s_barrier()
; #define PG8_SCHED __builtin_amdgcn_sched_barrier(0)
; template <class Epi, class Sched>
; DI void gemm_phase(LAS unsigned char* lds, const Gemm g, const Sched& S, const Epi& E) {
;     ...
;             const bool last = (t == nt - 2);
;             const char* a1 = cA + (size_t)(t + 1) * kstep;
;             const char* a2 = last ? nA : cA + (size_t)(t + 2) * kstep; const char* b2 = last ? nB : cB + (size_t)(t + 2) * kstep;
;             const char* a3 = a2 + kstep; const char* b3 = b2 + kstep;
;             PG8_LDB(B0, 0, 0); PG8_SCHED; PG8_LDA(At, 0, 0); PG8_STAGE(PG8_SA(1, 1), a1 + hstep, voffA);
;             PG8_WAIT_L(8); PG8_BAR; PG8_WAIT_L(0); PG8_MMA(0, 0, At, B0); PG8_BAR; PG8_SCHED;
;             PG8_LDB(B1, 0, 1); PG8_STAGE(PG8_SB(0, 0), b2, voffB);
;             PG8_BAR; PG8_WAIT_L(0); PG8_MMA(0, 1, At, B1); PG8_BAR;
;             PG8_LDA(At, 0, 1); PG8_STAGE(PG8_SA(0, 0), a2, voffA);
;             PG8_BAR; PG8_WAIT_L(0); PG8_MMA(1, 0, At, B0); PG8_BAR; PG8_SCHED;
;             PG8_STAGE(PG8_SB(0, 1), b2 + hstep, voffB);
;             PG8_WAIT_V(6); PG8_BAR; PG8_MMA(1, 1, At, B1); PG8_BAR;
.LBB0_325:
	s_add_u32 s28, s40, s28
	s_addc_u32 s29, s41, s29
	s_and_b64 s[0:1], s[8:9], exec
	s_cselect_b32 s15, s29, s39
	s_cselect_b32 s17, s28, s38
	s_add_u32 s8, s38, 0x160080
	s_addc_u32 s9, s39, 0
	s_add_u32 s66, s36, 0x100
	v_mov_b32_e32 v0, 0
	s_addc_u32 s67, s37, 0
	s_mov_b32 s68, -2
	ds_read_b128 v[150:153], v141
	ds_read_b128 v[154:157], v141 offset:1024
	ds_read_b128 v[162:165], v141 offset:2048
	ds_read_b128 v[166:169], v141 offset:3072
	s_add_u32 s0, s8, 0xffea0080
	s_addc_u32 s1, s9, -1
	s_cmp_eq_u32 s68, 4
	s_cselect_b32 s39, s15, s1
	s_cselect_b32 s38, s17, s0
	s_cselect_b32 s37, s19, s67
	s_cselect_b32 s36, s18, s66
	s_mov_b32 m0, s58
	v_lshl_add_u64 v[146:147], s[8:9], 0, v[132:133]
	ds_read_b128 v[170:173], v142
	ds_read_b128 v[174:177], v142 offset:1024
	ds_read_b128 v[178:181], v142 offset:2048
	ds_read_b128 v[188:191], v142 offset:3072
	ds_read_b128 v[194:197], v142 offset:4096
	ds_read_b128 v[198:201], v142 offset:5120
	ds_read_b128 v[202:205], v142 offset:6144
	ds_read_b128 v[206:209], v142 offset:7168
	global_load_lds_dwordx4 v[146:147], off
	v_lshl_add_u64 v[146:147], s[8:9], 0, v[134:135]
	s_mov_b32 m0, s59
	s_nop 0
	global_load_lds_dwordx4 v[146:147], off
	s_waitcnt lgkmcnt(8)
	s_barrier
	s_waitcnt lgkmcnt(0)
	s_setprio 1
	s_waitcnt lgkmcnt(0)
	v_mfma_f32_16x16x32_bf16 v[124:127], v[150:153], v[170:173], 0
	v_mfma_f32_16x16x32_bf16 v[120:123], v[162:165], v[170:173], 0
	v_mfma_f32_16x16x32_bf16 v[116:119], v[150:153], v[178:181], 0
	v_mfma_f32_16x16x32_bf16 v[112:115], v[162:165], v[178:181], 0
	v_mfma_f32_16x16x32_bf16 v[104:107], v[150:153], v[194:197], 0
	v_mfma_f32_16x16x32_bf16 v[96:99], v[162:165], v[194:197], 0
	v_mfma_f32_16x16x32_bf16 v[88:91], v[150:153], v[202:205], 0
	v_mfma_f32_16x16x32_bf16 v[80:83], v[162:165], v[202:205], 0
	v_mfma_f32_16x16x32_bf16 v[124:127], v[154:157], v[174:177], v[124:127]
	v_mfma_f32_16x16x32_bf16 v[120:123], v[166:169], v[174:177], v[120:123]
	v_mfma_f32_16x16x32_bf16 v[116:119], v[154:157], v[188:191], v[116:119]
	v_mfma_f32_16x16x32_bf16 v[112:115], v[166:169], v[188:191], v[112:115]
	v_mfma_f32_16x16x32_bf16 v[104:107], v[154:157], v[198:201], v[104:107]
	v_mfma_f32_16x16x32_bf16 v[96:99], v[166:169], v[198:201], v[96:99]
	v_mfma_f32_16x16x32_bf16 v[88:91], v[154:157], v[206:209], v[88:91]
	v_mfma_f32_16x16x32_bf16 v[80:83], v[166:169], v[206:209], v[80:83]
	s_setprio 0
	s_barrier
	s_mov_b32 m0, s60
	v_lshl_add_u64 v[146:147], s[36:37], 0, v[130:131]
	ds_read_b128 v[210:213], v143
	ds_read_b128 v[214:217], v143 offset:1024
	ds_read_b128 v[218:221], v143 offset:2048
	ds_read_b128 v[222:225], v143 offset:3072
	global_load_lds_dwordx4 v[146:147], off
	v_lshl_add_u64 v[158:159], s[36:37], 0, v[128:129]
	s_mov_b32 m0, s61
	s_nop 0
	global_load_lds_dwordx4 v[158:159], off
	s_barrier
	s_waitcnt lgkmcnt(0)
	s_setprio 1
	s_waitcnt lgkmcnt(0)
	v_mfma_f32_16x16x32_bf16 v[108:111], v[210:213], v[170:173], 0
	v_mfma_f32_16x16x32_bf16 v[100:103], v[218:221], v[170:173], 0
	v_mfma_f32_16x16x32_bf16 v[92:95], v[210:213], v[178:181], 0
	v_mfma_f32_16x16x32_bf16 v[84:87], v[218:221], v[178:181], 0
	v_mfma_f32_16x16x32_bf16 v[76:79], v[210:213], v[194:197], 0
	v_mfma_f32_16x16x32_bf16 v[72:75], v[218:221], v[194:197], 0
	v_mfma_f32_16x16x32_bf16 v[68:71], v[210:213], v[202:205], 0
	v_mfma_f32_16x16x32_bf16 v[64:67], v[218:221], v[202:205], 0
	v_mfma_f32_16x16x32_bf16 v[108:111], v[214:217], v[174:177], v[108:111]
	v_mfma_f32_16x16x32_bf16 v[100:103], v[222:225], v[174:177], v[100:103]
	v_mfma_f32_16x16x32_bf16 v[92:95], v[214:217], v[188:191], v[92:95]
	v_mfma_f32_16x16x32_bf16 v[84:87], v[222:225], v[188:191], v[84:87]
	v_mfma_f32_16x16x32_bf16 v[76:79], v[214:217], v[198:201], v[76:79]
	v_mfma_f32_16x16x32_bf16 v[72:75], v[222:225], v[198:201], v[72:75]
	v_mfma_f32_16x16x32_bf16 v[68:71], v[214:217], v[206:209], v[68:71]
	v_mfma_f32_16x16x32_bf16 v[64:67], v[222:225], v[206:209], v[64:67]
	s_setprio 0
	s_mov_b32 m0, s42
	v_lshl_add_u64 v[182:183], s[38:39], 0, v[130:131]
	s_barrier
	ds_read_b128 v[170:173], v142 offset:16384
	ds_read_b128 v[174:177], v142 offset:17408
	ds_read_b128 v[178:181], v142 offset:18432
	ds_read_b128 v[188:191], v142 offset:19456
	ds_read_b128 v[194:197], v142 offset:20480
	ds_read_b128 v[198:201], v142 offset:21504
	ds_read_b128 v[202:205], v142 offset:22528
	ds_read_b128 v[206:209], v142 offset:23552
	global_load_lds_dwordx4 v[182:183], off
	v_lshl_add_u64 v[226:227], s[38:39], 0, v[128:129]
	s_mov_b32 m0, s43
	s_nop 0
	global_load_lds_dwordx4 v[226:227], off
	s_barrier
	s_waitcnt lgkmcnt(0)
	s_setprio 1
	s_waitcnt lgkmcnt(0)
	v_mfma_f32_16x16x32_bf16 v[60:63], v[150:153], v[170:173], 0
	v_mfma_f32_16x16x32_bf16 v[56:59], v[162:165], v[170:173], 0
	v_mfma_f32_16x16x32_bf16 v[52:55], v[150:153], v[178:181], 0
	v_mfma_f32_16x16x32_bf16 v[48:51], v[162:165], v[178:181], 0
	v_mfma_f32_16x16x32_bf16 v[40:43], v[150:153], v[194:197], 0
	v_mfma_f32_16x16x32_bf16 v[32:35], v[162:165], v[194:197], 0
	v_mfma_f32_16x16x32_bf16 v[24:27], v[150:153], v[202:205], 0
	v_mfma_f32_16x16x32_bf16 v[16:19], v[162:165], v[202:205], 0
	v_mfma_f32_16x16x32_bf16 v[60:63], v[154:157], v[174:177], v[60:63]
	v_mfma_f32_16x16x32_bf16 v[56:59], v[166:169], v[174:177], v[56:59]
	v_mfma_f32_16x16x32_bf16 v[52:55], v[154:157], v[188:191], v[52:55]
	v_mfma_f32_16x16x32_bf16 v[48:51], v[166:169], v[188:191], v[48:51]
	v_mfma_f32_16x16x32_bf16 v[40:43], v[154:157], v[198:201], v[40:43]
	v_mfma_f32_16x16x32_bf16 v[32:35], v[166:169], v[198:201], v[32:35]
	v_mfma_f32_16x16x32_bf16 v[24:27], v[154:157], v[206:209], v[24:27]
	v_mfma_f32_16x16x32_bf16 v[16:19], v[166:169], v[206:209], v[16:19]
	s_setprio 0
	s_barrier
; #define PG8_STAGE(bufoff, gbase, voff) do { _Pragma("unroll") for (int _i = 0; _i < 2; ++_i) \
;         __builtin_amdgcn_global_load_lds((const unsigned*)((const char*)(gbase) + (voff)[_i]), (LAS unsigned*)(lds + (bufoff) + ldsw + _i * 8192), 16, 0, 0); } while (0)
; #define PG8_LDA(dst, b, h) do { _Pragma("unroll") for (int m = 0; m < 4; ++m) _Pragma("unroll") for (int k = 0; k < 2; ++k) dst[m][k] = *(const LAS bf16x8*)(lds + PG8_SA(b, h) + aoff + m * 2048 + k * 1024); } while (0)
; #define PG8_LDB(dst, b, h) do { _Pragma("unroll") for (int n = 0; n < 2; ++n) _Pragma("unroll") for (int k = 0; k < 2; ++k) dst[n][k] = *(const LAS bf16x8*)(lds + PG8_SB(b, h) + boff + n * 2048 + k * 1024); } while (0)
; #define PG8_MMA(ai, bj, At, Bt) do { __builtin_amdgcn_s_setprio(1); _Pragma("unroll") for (int m = 0; m < 4; ++m) _Pragma("unroll") for (int n = 0; n < 2; ++n) _Pragma("unroll") for (int k = 0; k < 2; ++k) \
;         acc[ai][bj][m][n] = __builtin_amdgcn_mfma_f32_16x16x32_bf16(Bt[n][k], At[m][k], acc[ai][bj][m][n], 0, 0, 0); __builtin_amdgcn_s_setprio(0); } while (0)
; #define PG8_WAIT_V(n) asm volatile("s_waitcnt vmcnt(" #n ")" ::: "memory")
; #define PG8_WAIT_L(n) asm volatile("s_waitcnt lgkmcnt(" #n ")" ::: "memory")
; #define PG8_BAR __builtin_amdgcn_s_barrier()
; #define PG8_SCHED __builtin_amdgcn_sched_barrier(0)
; template <class Epi, class Sched>
; DI void gemm_phase(LAS unsigned char* lds, const Gemm g, const Sched& S, const Epi& E) {
;     ...
;             PG8_STAGE(PG8_SB(0, 1), b2 + hstep, voffB);
;             PG8_WAIT_V(6); PG8_BAR; PG8_MMA(1, 1, At, B1); PG8_BAR;
;             PG8_LDB(B0, 1, 0); PG8_SCHED; PG8_LDA(At, 1, 0); PG8_STAGE(PG8_SA(0, 1), a2 + hstep, voffA);
;             PG8_WAIT_L(8); PG8_BAR; PG8_WAIT_L(0); PG8_MMA(0, 0, At, B0); PG8_BAR; PG8_SCHED;
;             PG8_LDB(B1, 1, 1); PG8_STAGE(PG8_SB(1, 0), b3, voffB);
;             PG8_BAR; PG8_WAIT_L(0); PG8_MMA(0, 1, At, B1); PG8_BAR;
;             PG8_LDA(At, 1, 1); PG8_STAGE(PG8_SA(1, 0), a3, voffA);
;             PG8_BAR; PG8_WAIT_L(0); PG8_MMA(1, 0, At, B0); PG8_BAR; PG8_SCHED;
	s_add_u32 s0, s36, 0x160000
	s_addc_u32 s1, s37, 0
	s_mov_b32 m0, s62
	v_lshl_add_u64 v[150:151], s[0:1], 0, v[130:131]
	global_load_lds_dwordx4 v[150:151], off
	v_lshl_add_u64 v[150:151], s[0:1], 0, v[128:129]
	s_mov_b32 m0, s63
	s_nop 0
	global_load_lds_dwordx4 v[150:151], off
	s_waitcnt vmcnt(6)
	s_barrier
	s_setprio 1
	v_mfma_f32_16x16x32_bf16 v[44:47], v[210:213], v[170:173], 0
	v_mfma_f32_16x16x32_bf16 v[36:39], v[218:221], v[170:173], 0
	v_mfma_f32_16x16x32_bf16 v[28:31], v[210:213], v[178:181], 0
	v_mfma_f32_16x16x32_bf16 v[20:23], v[218:221], v[178:181], 0
	v_mfma_f32_16x16x32_bf16 v[12:15], v[210:213], v[194:197], 0
	v_mfma_f32_16x16x32_bf16 v[8:11], v[218:221], v[194:197], 0
	v_mfma_f32_16x16x32_bf16 v[4:7], v[210:213], v[202:205], 0
	v_mfma_f32_16x16x32_bf16 v[0:3], v[218:221], v[202:205], 0
	v_mfma_f32_16x16x32_bf16 v[44:47], v[214:217], v[174:177], v[44:47]
	v_mfma_f32_16x16x32_bf16 v[36:39], v[222:225], v[174:177], v[36:39]
	v_mfma_f32_16x16x32_bf16 v[28:31], v[214:217], v[188:191], v[28:31]
	v_mfma_f32_16x16x32_bf16 v[20:23], v[222:225], v[188:191], v[20:23]
	v_mfma_f32_16x16x32_bf16 v[12:15], v[214:217], v[198:201], v[12:15]
	v_mfma_f32_16x16x32_bf16 v[8:11], v[222:225], v[198:201], v[8:11]
	v_mfma_f32_16x16x32_bf16 v[4:7], v[214:217], v[206:209], v[4:7]
	v_mfma_f32_16x16x32_bf16 v[0:3], v[222:225], v[206:209], v[0:3]
	s_setprio 0
	s_barrier
	ds_read_b128 v[150:153], v144
	ds_read_b128 v[154:157], v144 offset:1024
	ds_read_b128 v[162:165], v144 offset:2048
	ds_read_b128 v[166:169], v144 offset:3072
	s_add_u32 s0, s38, 0x160000
	s_addc_u32 s1, s39, 0
	s_mov_b32 m0, s44
	v_lshl_add_u64 v[210:211], s[0:1], 0, v[130:131]
	ds_read_b128 v[170:173], v142 offset:32768
	ds_read_b128 v[174:177], v142 offset:33792
	ds_read_b128 v[178:181], v142 offset:34816
	ds_read_b128 v[188:191], v142 offset:35840
	ds_read_b128 v[194:197], v142 offset:36864
	ds_read_b128 v[198:201], v142 offset:37888
	ds_read_b128 v[202:205], v142 offset:38912
	ds_read_b128 v[206:209], v142 offset:39936
	global_load_lds_dwordx4 v[210:211], off
	v_lshl_add_u64 v[210:211], s[0:1], 0, v[128:129]
	s_mov_b32 m0, s45
	s_nop 0
	global_load_lds_dwordx4 v[210:211], off
	s_waitcnt lgkmcnt(8)
	s_barrier
	s_waitcnt lgkmcnt(0)
	s_setprio 1
	s_waitcnt lgkmcnt(0)
	v_mfma_f32_16x16x32_bf16 v[124:127], v[150:153], v[170:173], v[124:127]
	v_mfma_f32_16x16x32_bf16 v[120:123], v[162:165], v[170:173], v[120:123]
	v_mfma_f32_16x16x32_bf16 v[116:119], v[150:153], v[178:181], v[116:119]
	v_mfma_f32_16x16x32_bf16 v[112:115], v[162:165], v[178:181], v[112:115]
	v_mfma_f32_16x16x32_bf16 v[104:107], v[150:153], v[194:197], v[104:107]
	v_mfma_f32_16x16x32_bf16 v[96:99], v[162:165], v[194:197], v[96:99]
	v_mfma_f32_16x16x32_bf16 v[88:91], v[150:153], v[202:205], v[88:91]
	v_mfma_f32_16x16x32_bf16 v[80:83], v[162:165], v[202:205], v[80:83]
	v_mfma_f32_16x16x32_bf16 v[124:127], v[154:157], v[174:177], v[124:127]
	v_mfma_f32_16x16x32_bf16 v[120:123], v[166:169], v[174:177], v[120:123]
	v_mfma_f32_16x16x32_bf16 v[116:119], v[154:157], v[188:191], v[116:119]
	v_mfma_f32_16x16x32_bf16 v[112:115], v[166:169], v[188:191], v[112:115]
	v_mfma_f32_16x16x32_bf16 v[104:107], v[154:157], v[198:201], v[104:107]
	v_mfma_f32_16x16x32_bf16 v[96:99], v[166:169], v[198:201], v[96:99]
	v_mfma_f32_16x16x32_bf16 v[88:91], v[154:157], v[206:209], v[88:91]
	v_mfma_f32_16x16x32_bf16 v[80:83], v[166:169], v[206:209], v[80:83]
	s_setprio 0
	s_barrier
	s_add_i32 s4, 0, 0x1c000
	s_add_i32 s0, s64, s35
	v_add_u32_e32 v145, s4, v140
	v_lshl_add_u64 v[146:147], v[146:147], 0, s[10:11]
	s_mov_b32 m0, s0
	ds_read_b128 v[210:213], v145
	ds_read_b128 v[214:217], v145 offset:1024
	ds_read_b128 v[218:221], v145 offset:2048
	ds_read_b128 v[222:225], v145 offset:3072
	global_load_lds_dwordx4 v[146:147], off
	v_lshl_add_u64 v[146:147], v[158:159], 0, s[10:11]
	s_add_i32 m0, s0, 0x2000
	s_nop 0
	global_load_lds_dwordx4 v[146:147], off
	s_barrier
; #define PG8_STAGE(bufoff, gbase, voff) do { _Pragma("unroll") for (int _i = 0; _i < 2; ++_i) \
;         __builtin_amdgcn_global_load_lds((const unsigned*)((const char*)(gbase) + (voff)[_i]), (LAS unsigned*)(lds + (bufoff) + ldsw + _i * 8192), 16, 0, 0); } while (0)
; #define PG8_LDA(dst, b, h) do { _Pragma("unroll") for (int m = 0; m < 4; ++m) _Pragma("unroll") for (int k = 0; k < 2; ++k) dst[m][k] = *(const LAS bf16x8*)(lds + PG8_SA(b, h) + aoff + m * 2048 + k * 1024); } while (0)
; #define PG8_MMA(ai, bj, At, Bt) do { __builtin_amdgcn_s_setprio(1); _Pragma("unroll") for (int m = 0; m < 4; ++m) _Pragma("unroll") for (int n = 0; n < 2; ++n) _Pragma("unroll") for (int k = 0; k < 2; ++k) \
;         acc[ai][bj][m][n] = __builtin_amdgcn_mfma_f32_16x16x32_bf16(Bt[n][k], At[m][k], acc[ai][bj][m][n], 0, 0, 0); __builtin_amdgcn_s_setprio(0); } while (0)
; #define PG8_WAIT_V(n) asm volatile("s_waitcnt vmcnt(" #n ")" ::: "memory")
; #define PG8_WAIT_L(n) asm volatile("s_waitcnt lgkmcnt(" #n ")" ::: "memory")
; #define PG8_BAR __builtin_amdgcn_s_barrier()
; #define PG8_SCHED __builtin_amdgcn_sched_barrier(0)
; template <class Epi, class Sched>
; DI void gemm_phase(LAS unsigned char* lds, const Gemm g, const Sched& S, const Epi& E) {
;     ...
;             PG8_BAR; PG8_WAIT_L(0); PG8_MMA(0, 1, At, B1); PG8_BAR;
;             PG8_LDA(At, 1, 1); PG8_STAGE(PG8_SA(1, 0), a3, voffA);
;             PG8_BAR; PG8_WAIT_L(0); PG8_MMA(1, 0, At, B0); PG8_BAR; PG8_SCHED;
;             PG8_STAGE(PG8_SB(1, 1), b3 + hstep, voffB);
;             PG8_WAIT_V(6); PG8_BAR; PG8_MMA(1, 1, At, B1); PG8_BAR;
	s_waitcnt lgkmcnt(0)
	s_setprio 1
	s_waitcnt lgkmcnt(0)
	v_mfma_f32_16x16x32_bf16 v[108:111], v[210:213], v[170:173], v[108:111]
	v_mfma_f32_16x16x32_bf16 v[100:103], v[218:221], v[170:173], v[100:103]
	v_mfma_f32_16x16x32_bf16 v[92:95], v[210:213], v[178:181], v[92:95]
	v_mfma_f32_16x16x32_bf16 v[84:87], v[218:221], v[178:181], v[84:87]
	v_mfma_f32_16x16x32_bf16 v[76:79], v[210:213], v[194:197], v[76:79]
	v_mfma_f32_16x16x32_bf16 v[72:75], v[218:221], v[194:197], v[72:75]
	v_mfma_f32_16x16x32_bf16 v[68:71], v[210:213], v[202:205], v[68:71]
	v_mfma_f32_16x16x32_bf16 v[64:67], v[218:221], v[202:205], v[64:67]
	v_mfma_f32_16x16x32_bf16 v[108:111], v[214:217], v[174:177], v[108:111]
	v_mfma_f32_16x16x32_bf16 v[100:103], v[222:225], v[174:177], v[100:103]
	v_mfma_f32_16x16x32_bf16 v[92:95], v[214:217], v[188:191], v[92:95]
	v_mfma_f32_16x16x32_bf16 v[84:87], v[222:225], v[188:191], v[84:87]
	v_mfma_f32_16x16x32_bf16 v[76:79], v[214:217], v[198:201], v[76:79]
	v_mfma_f32_16x16x32_bf16 v[72:75], v[222:225], v[198:201], v[72:75]
	v_mfma_f32_16x16x32_bf16 v[68:71], v[214:217], v[206:209], v[68:71]
	v_mfma_f32_16x16x32_bf16 v[64:67], v[222:225], v[206:209], v[64:67]
	s_setprio 0
	s_mov_b32 m0, s56
	v_lshl_add_u64 v[146:147], v[182:183], 0, s[10:11]
	s_barrier
	ds_read_b128 v[170:173], v142 offset:49152
	ds_read_b128 v[174:177], v142 offset:50176
	ds_read_b128 v[178:181], v142 offset:51200
	ds_read_b128 v[188:191], v142 offset:52224
	ds_read_b128 v[194:197], v142 offset:53248
	ds_read_b128 v[198:201], v142 offset:54272
	ds_read_b128 v[202:205], v142 offset:55296
	ds_read_b128 v[206:209], v142 offset:56320
	global_load_lds_dwordx4 v[146:147], off
	v_lshl_add_u64 v[146:147], v[226:227], 0, s[10:11]
	s_mov_b32 m0, s57
	s_nop 0
	global_load_lds_dwordx4 v[146:147], off
	s_barrier
	s_waitcnt lgkmcnt(0)
	s_setprio 1
	s_waitcnt lgkmcnt(0)
	v_mfma_f32_16x16x32_bf16 v[60:63], v[150:153], v[170:173], v[60:63]
	v_mfma_f32_16x16x32_bf16 v[56:59], v[162:165], v[170:173], v[56:59]
	v_mfma_f32_16x16x32_bf16 v[52:55], v[150:153], v[178:181], v[52:55]
	v_mfma_f32_16x16x32_bf16 v[48:51], v[162:165], v[178:181], v[48:51]
	v_mfma_f32_16x16x32_bf16 v[40:43], v[150:153], v[194:197], v[40:43]
	v_mfma_f32_16x16x32_bf16 v[32:35], v[162:165], v[194:197], v[32:35]
	v_mfma_f32_16x16x32_bf16 v[24:27], v[150:153], v[202:205], v[24:27]
	v_mfma_f32_16x16x32_bf16 v[16:19], v[162:165], v[202:205], v[16:19]
	v_mfma_f32_16x16x32_bf16 v[60:63], v[154:157], v[174:177], v[60:63]
	v_mfma_f32_16x16x32_bf16 v[56:59], v[166:169], v[174:177], v[56:59]
	v_mfma_f32_16x16x32_bf16 v[52:55], v[154:157], v[188:191], v[52:55]
	v_mfma_f32_16x16x32_bf16 v[48:51], v[166:169], v[188:191], v[48:51]
	v_mfma_f32_16x16x32_bf16 v[40:43], v[154:157], v[198:201], v[40:43]
	v_mfma_f32_16x16x32_bf16 v[32:35], v[166:169], v[198:201], v[32:35]
	v_mfma_f32_16x16x32_bf16 v[24:27], v[154:157], v[206:209], v[24:27]
	v_mfma_f32_16x16x32_bf16 v[16:19], v[166:169], v[206:209], v[16:19]
	s_setprio 0
	s_barrier
	s_add_u32 s0, s36, 0x160080
	s_addc_u32 s1, s37, 0
	s_add_i32 s4, s4, s35
	v_lshl_add_u64 v[146:147], s[0:1], 0, v[130:131]
	s_mov_b32 m0, s4
	s_nop 0
	global_load_lds_dwordx4 v[146:147], off
	v_lshl_add_u64 v[146:147], s[0:1], 0, v[128:129]
	s_add_i32 m0, s4, 0x2000
	s_nop 0
	global_load_lds_dwordx4 v[146:147], off
	s_waitcnt vmcnt(6)
	s_barrier
	s_setprio 1
	v_mfma_f32_16x16x32_bf16 v[44:47], v[210:213], v[170:173], v[44:47]
	v_mfma_f32_16x16x32_bf16 v[36:39], v[218:221], v[170:173], v[36:39]
	v_mfma_f32_16x16x32_bf16 v[28:31], v[210:213], v[178:181], v[28:31]
	v_mfma_f32_16x16x32_bf16 v[20:23], v[218:221], v[178:181], v[20:23]
	v_mfma_f32_16x16x32_bf16 v[12:15], v[210:213], v[194:197], v[12:15]
	v_mfma_f32_16x16x32_bf16 v[8:11], v[218:221], v[194:197], v[8:11]
	v_mfma_f32_16x16x32_bf16 v[4:7], v[210:213], v[202:205], v[4:7]
	v_mfma_f32_16x16x32_bf16 v[0:3], v[218:221], v[202:205], v[0:3]
	v_mfma_f32_16x16x32_bf16 v[44:47], v[214:217], v[174:177], v[44:47]
	v_mfma_f32_16x16x32_bf16 v[36:39], v[222:225], v[174:177], v[36:39]
	v_mfma_f32_16x16x32_bf16 v[28:31], v[214:217], v[188:191], v[28:31]
	v_mfma_f32_16x16x32_bf16 v[20:23], v[222:225], v[188:191], v[20:23]
	v_mfma_f32_16x16x32_bf16 v[12:15], v[214:217], v[198:201], v[12:15]
	v_mfma_f32_16x16x32_bf16 v[8:11], v[222:225], v[198:201], v[8:11]
	v_mfma_f32_16x16x32_bf16 v[4:7], v[214:217], v[206:209], v[4:7]
	v_mfma_f32_16x16x32_bf16 v[0:3], v[222:225], v[206:209], v[0:3]
	s_setprio 0
	s_add_i32 s68, s68, 2
	s_add_u32 s8, s8, 0x100
	s_addc_u32 s9, s9, 0
	s_add_u32 s66, s66, 0x100
	s_addc_u32 s67, s67, 0
	s_cmp_gt_u32 s68, 5
	s_barrier
	s_cbranch_scc0 .LBB0_326
	s_branch .Lpeel_done_326

; #define PG8_WAIT_V(n) asm volatile("s_waitcnt vmcnt(" #n ")" ::: "memory")
; #define PG8_BAR __builtin_amdgcn_s_barrier()
; template <class Epi, class Sched>
; DI void gemm_phase(LAS unsigned char* lds, const Gemm g, const Sched& S, const Epi& E) {
;     ...
;     PG8_WAIT_V(0);
;     if (wr == 0) PG8_BAR;
;     PG8_BAR;
;     DI void operator()(AccRef acc, const Unit& u, int wr, int wc, int fr, int fq) const {
;         float* base = P + (size_t)slot0 * 256 * DM + (size_t)u.ks * 256 * ld; const int col0 = u.pn * 256 + wc * 32 + 4 * fq;
; #pragma unroll
;         for (int ai = 0; ai < 2; ++ai)
; #pragma unroll
;             for (int m = 0; m < 4; ++m) { const size_t off = (size_t)(ai * 128 + wr * 64 + m * 16 + fr) * ld + col0;
; #pragma unroll
;                 for (int bj = 0; bj < 2; ++bj)
; #pragma unroll
;                     for (int n = 0; n < 2; ++n) *(f32x4*)(base + off + bj * 128 + n * 16) = acc[ai][bj][m][n]; }
;     }
.Lpeel_done_326:
	s_ashr_i32 s15, s14, 31
	s_lshl_b64 s[0:1], s[14:15], 21
	s_add_u32 s0, s54, s0
	s_addc_u32 s1, s55, s1
	s_lshl_b32 s4, s50, 8
	v_mov_b32_e32 v145, v149
	v_mov_b32_e32 v147, v148
	s_or_b32 s4, s4, s53
	s_and_b64 vcc, exec, s[6:7]
	v_lshl_add_u32 v146, v145, 2, s4
	v_add_u32_e32 v150, s52, v147
	v_ashrrev_i32_e32 v147, 31, v146
	v_ashrrev_i32_e32 v151, 31, v150
	v_lshl_add_u64 v[146:147], v[146:147], 2, s[0:1]
	v_lshlrev_b64 v[152:153], 13, v[150:151]
	v_lshl_add_u64 v[152:153], v[146:147], 0, v[152:153]
	global_store_dwordx4 v[152:153], v[124:127], off
	global_store_dwordx4 v[152:153], v[120:123], off offset:64
	global_store_dwordx4 v[152:153], v[108:111], off offset:512
	global_store_dwordx4 v[152:153], v[100:103], off offset:576
	s_mov_b32 s14, s16
	s_mov_b32 s50, s65
	v_add_u32_e32 v100, 16, v150
	v_ashrrev_i32_e32 v101, 31, v100
	v_lshlrev_b64 v[100:101], 13, v[100:101]
	v_lshl_add_u64 v[100:101], v[146:147], 0, v[100:101]
	global_store_dwordx4 v[100:101], v[116:119], off
	global_store_dwordx4 v[100:101], v[112:115], off offset:64
	global_store_dwordx4 v[100:101], v[92:95], off offset:512
	global_store_dwordx4 v[100:101], v[84:87], off offset:576
	s_mov_b64 s[36:37], s[18:19]
	s_mov_b64 s[38:39], s[28:29]
	v_add_u32_e32 v84, 32, v150
	v_ashrrev_i32_e32 v85, 31, v84
	v_lshlrev_b64 v[84:85], 13, v[84:85]
	v_lshl_add_u64 v[84:85], v[146:147], 0, v[84:85]
	global_store_dwordx4 v[84:85], v[104:107], off
	global_store_dwordx4 v[84:85], v[96:99], off offset:64
	global_store_dwordx4 v[84:85], v[76:79], off offset:512
	global_store_dwordx4 v[84:85], v[72:75], off offset:576
	s_nop 1
	v_add_u32_e32 v72, 48, v150
	v_ashrrev_i32_e32 v73, 31, v72
	v_lshlrev_b64 v[72:73], 13, v[72:73]
	v_lshl_add_u64 v[72:73], v[146:147], 0, v[72:73]
	global_store_dwordx4 v[72:73], v[88:91], off
	global_store_dwordx4 v[72:73], v[80:83], off offset:64
	global_store_dwordx4 v[72:73], v[68:71], off offset:512
	global_store_dwordx4 v[72:73], v[64:67], off offset:576
	s_nop 1
	v_add_u32_e32 v64, 0x80, v150
	v_ashrrev_i32_e32 v65, 31, v64
	v_lshlrev_b64 v[64:65], 13, v[64:65]
	v_lshl_add_u64 v[64:65], v[146:147], 0, v[64:65]
	global_store_dwordx4 v[64:65], v[60:63], off
	global_store_dwordx4 v[64:65], v[56:59], off offset:64
	global_store_dwordx4 v[64:65], v[44:47], off offset:512
	global_store_dwordx4 v[64:65], v[36:39], off offset:576
	s_nop 1
	v_add_u32_e32 v36, 0x90, v150
	v_ashrrev_i32_e32 v37, 31, v36
	v_lshlrev_b64 v[36:37], 13, v[36:37]
	v_lshl_add_u64 v[36:37], v[146:147], 0, v[36:37]
	global_store_dwordx4 v[36:37], v[52:55], off
	global_store_dwordx4 v[36:37], v[48:51], off offset:64
	global_store_dwordx4 v[36:37], v[28:31], off offset:512
	global_store_dwordx4 v[36:37], v[20:23], off offset:576
	s_nop 1
	v_add_u32_e32 v20, 0xa0, v150
	v_ashrrev_i32_e32 v21, 31, v20
	v_lshlrev_b64 v[20:21], 13, v[20:21]
	v_lshl_add_u64 v[20:21], v[146:147], 0, v[20:21]
	global_store_dwordx4 v[20:21], v[40:43], off
	global_store_dwordx4 v[20:21], v[32:35], off offset:64
	global_store_dwordx4 v[20:21], v[12:15], off offset:512
	global_store_dwordx4 v[20:21], v[8:11], off offset:576
	s_nop 1
	v_add_u32_e32 v8, 0xb0, v150
	v_ashrrev_i32_e32 v9, 31, v8
	v_lshlrev_b64 v[8:9], 13, v[8:9]
	v_lshl_add_u64 v[8:9], v[146:147], 0, v[8:9]
	global_store_dwordx4 v[8:9], v[24:27], off
	global_store_dwordx4 v[8:9], v[16:19], off offset:64
	global_store_dwordx4 v[8:9], v[4:7], off offset:512
	global_store_dwordx4 v[8:9], v[0:3], off offset:576
	s_cbranch_vccz .LBB0_321
	s_waitcnt vmcnt(0)
	s_cmpk_gt_u32 s34, 0xff
	s_cbranch_scc1 .LBB0_330
	s_barrier

; #define PG8_STAGE(bufoff, gbase, voff) do { _Pragma("unroll") for (int _i = 0; _i < 2; ++_i) \
;         __builtin_amdgcn_global_load_lds((const unsigned*)((const char*)(gbase) + (voff)[_i]), (LAS unsigned*)(lds + (bufoff) + ldsw + _i * 8192), 16, 0, 0); } while (0)
; #define PG8_LDA(dst, b, h) do { _Pragma("unroll") for (int m = 0; m < 4; ++m) _Pragma("unroll") for (int k = 0; k < 2; ++k) dst[m][k] = *(const LAS bf16x8*)(lds + PG8_SA(b, h) + aoff + m * 2048 + k * 1024); } while (0)
; #define PG8_LDB(dst, b, h) do { _Pragma("unroll") for (int n = 0; n < 2; ++n) _Pragma("unroll") for (int k = 0; k < 2; ++k) dst[n][k] = *(const LAS bf16x8*)(lds + PG8_SB(b, h) + boff + n * 2048 + k * 1024); } while (0)
; #define PG8_MMA(ai, bj, At, Bt) do { __builtin_amdgcn_s_setprio(1); _Pragma("unroll") for (int m = 0; m < 4; ++m) _Pragma("unroll") for (int n = 0; n < 2; ++n) _Pragma("unroll") for (int k = 0; k < 2; ++k) \
;         acc[ai][bj][m][n] = __builtin_amdgcn_mfma_f32_16x16x32_bf16(Bt[n][k], At[m][k], acc[ai][bj][m][n], 0, 0, 0); __builtin_amdgcn_s_setprio(0); } while (0)
; #define PG8_WAIT_V(n) asm volatile("s_waitcnt vmcnt(" #n ")" ::: "memory")
; #define PG8_WAIT_L(n) asm volatile("s_waitcnt lgkmcnt(" #n ")" ::: "memory")
; #define PG8_BAR __builtin_amdgcn_s_barrier()
; #define PG8_SCHED __builtin_amdgcn_sched_barrier(0)
; template <class Epi, class Sched>
; DI void gemm_phase(LAS unsigned char* lds, const Gemm g, const Sched& S, const Epi& E) {
;     ...
;             const bool last = (t == nt - 2);
;             const char* a1 = cA + (size_t)(t + 1) * kstep;
;             const char* a2 = last ? nA : cA + (size_t)(t + 2) * kstep; const char* b2 = last ? nB : cB + (size_t)(t + 2) * kstep;
;             const char* a3 = a2 + kstep; const char* b3 = b2 + kstep;
;             PG8_LDB(B0, 0, 0); PG8_SCHED; PG8_LDA(At, 0, 0); PG8_STAGE(PG8_SA(1, 1), a1 + hstep, voffA);
;             PG8_WAIT_L(8); PG8_BAR; PG8_WAIT_L(0); PG8_MMA(0, 0, At, B0); PG8_BAR; PG8_SCHED;
;             PG8_LDB(B1, 0, 1); PG8_STAGE(PG8_SB(0, 0), b2, voffB);
;             PG8_BAR; PG8_WAIT_L(0); PG8_MMA(0, 1, At, B1); PG8_BAR;
;             PG8_LDA(At, 0, 1); PG8_STAGE(PG8_SA(0, 0), a2, voffA);
;             PG8_BAR; PG8_WAIT_L(0); PG8_MMA(1, 0, At, B0); PG8_BAR; PG8_SCHED;
;             PG8_STAGE(PG8_SB(0, 1), b2 + hstep, voffB);
;             PG8_WAIT_V(6); PG8_BAR; PG8_MMA(1, 1, At, B1); PG8_BAR;
.LBB0_526:
	s_ashr_i32 s51, s50, 31
	s_lshl_b64 s[0:1], s[50:51], 20
	s_add_u32 s52, s70, s0
	v_cmp_lt_i64_e32 vcc, s[12:13], v[142:143]
	s_addc_u32 s53, s71, s1
	s_and_b64 s[0:1], vcc, exec
	s_cselect_b32 s14, s53, s9
	s_cselect_b32 s15, s52, s8
	s_ashr_i32 s49, s48, 31
	s_lshl_b64 s[0:1], s[48:49], 20
	s_add_u32 s54, s72, s0
	s_addc_u32 s55, s73, s1
	s_and_b64 s[0:1], vcc, exec
	s_cselect_b32 s16, s55, s11
	s_cselect_b32 s17, s54, s10
	s_add_u32 s8, s8, 0x80080
	s_addc_u32 s9, s9, 0
	s_add_u32 s28, s10, 0x100
	v_mov_b32_e32 v0, 0
	s_addc_u32 s34, s11, 0
	s_mov_b32 s35, -2
	ds_read_b128 v[146:149], v164
	ds_read_b128 v[150:153], v164 offset:1024
	ds_read_b128 v[154:157], v164 offset:2048
	ds_read_b128 v[170:173], v164 offset:3072
	s_add_u32 s0, s8, 0xfff80080
	s_addc_u32 s1, s9, -1
	s_cmp_eq_u32 s35, 28
	s_cselect_b32 s13, s14, s1
	s_cselect_b32 s12, s15, s0
	s_cselect_b32 s11, s16, s34
	s_cselect_b32 s10, s17, s28
	v_lshl_add_u64 v[158:159], s[8:9], 0, v[138:139]
	s_add_i32 m0, s59, 0xc000
	ds_read_b128 v[174:177], v165
	ds_read_b128 v[178:181], v165 offset:1024
	ds_read_b128 v[188:191], v165 offset:2048
	ds_read_b128 v[194:197], v165 offset:3072
	ds_read_b128 v[198:201], v165 offset:4096
	ds_read_b128 v[202:205], v165 offset:5120
	ds_read_b128 v[206:209], v165 offset:6144
	ds_read_b128 v[210:213], v165 offset:7168
	global_load_lds_dwordx4 v[158:159], off
	v_lshl_add_u64 v[158:159], s[8:9], 0, v[140:141]
	s_add_i32 m0, s59, 0xe000
	s_nop 0
	global_load_lds_dwordx4 v[158:159], off
	s_waitcnt lgkmcnt(8)
	s_barrier
	s_waitcnt lgkmcnt(0)
	s_setprio 1
	s_waitcnt lgkmcnt(0)
	v_mfma_f32_16x16x32_bf16 v[124:127], v[146:149], v[174:177], 0
	v_mfma_f32_16x16x32_bf16 v[120:123], v[154:157], v[174:177], 0
	v_mfma_f32_16x16x32_bf16 v[108:111], v[146:149], v[188:191], 0
	v_mfma_f32_16x16x32_bf16 v[104:107], v[154:157], v[188:191], 0
	v_mfma_f32_16x16x32_bf16 v[92:95], v[146:149], v[198:201], 0
	v_mfma_f32_16x16x32_bf16 v[88:91], v[154:157], v[198:201], 0
	v_mfma_f32_16x16x32_bf16 v[76:79], v[146:149], v[206:209], 0
	v_mfma_f32_16x16x32_bf16 v[72:75], v[154:157], v[206:209], 0
	v_mfma_f32_16x16x32_bf16 v[124:127], v[150:153], v[178:181], v[124:127]
	v_mfma_f32_16x16x32_bf16 v[120:123], v[170:173], v[178:181], v[120:123]
	v_mfma_f32_16x16x32_bf16 v[108:111], v[150:153], v[194:197], v[108:111]
	v_mfma_f32_16x16x32_bf16 v[104:107], v[170:173], v[194:197], v[104:107]
	v_mfma_f32_16x16x32_bf16 v[92:95], v[150:153], v[202:205], v[92:95]
	v_mfma_f32_16x16x32_bf16 v[88:91], v[170:173], v[202:205], v[88:91]
	v_mfma_f32_16x16x32_bf16 v[76:79], v[150:153], v[210:213], v[76:79]
	v_mfma_f32_16x16x32_bf16 v[72:75], v[170:173], v[210:213], v[72:75]
	s_setprio 0
	s_barrier
	s_add_i32 s0, s47, s74
	v_lshl_add_u64 v[158:159], s[10:11], 0, v[130:131]
	s_mov_b32 m0, s0
	ds_read_b128 v[214:217], v166
	ds_read_b128 v[218:221], v166 offset:1024
	ds_read_b128 v[222:225], v166 offset:2048
	ds_read_b128 v[226:229], v166 offset:3072
	global_load_lds_dwordx4 v[158:159], off
	v_lshl_add_u64 v[182:183], s[10:11], 0, v[134:135]
	s_add_i32 m0, s0, 0x2000
	s_nop 0
	global_load_lds_dwordx4 v[182:183], off
	s_barrier
	s_waitcnt lgkmcnt(0)
	s_setprio 1
	s_waitcnt lgkmcnt(0)
	v_mfma_f32_16x16x32_bf16 v[116:119], v[214:217], v[174:177], 0
	v_mfma_f32_16x16x32_bf16 v[112:115], v[222:225], v[174:177], 0
	v_mfma_f32_16x16x32_bf16 v[100:103], v[214:217], v[188:191], 0
	v_mfma_f32_16x16x32_bf16 v[96:99], v[222:225], v[188:191], 0
	v_mfma_f32_16x16x32_bf16 v[84:87], v[214:217], v[198:201], 0
	v_mfma_f32_16x16x32_bf16 v[80:83], v[222:225], v[198:201], 0
	v_mfma_f32_16x16x32_bf16 v[68:71], v[214:217], v[206:209], 0
	v_mfma_f32_16x16x32_bf16 v[64:67], v[222:225], v[206:209], 0
	v_mfma_f32_16x16x32_bf16 v[116:119], v[218:221], v[178:181], v[116:119]
	v_mfma_f32_16x16x32_bf16 v[112:115], v[226:229], v[178:181], v[112:115]
	v_mfma_f32_16x16x32_bf16 v[100:103], v[218:221], v[194:197], v[100:103]
	v_mfma_f32_16x16x32_bf16 v[96:99], v[226:229], v[194:197], v[96:99]
	v_mfma_f32_16x16x32_bf16 v[84:87], v[218:221], v[202:205], v[84:87]
	v_mfma_f32_16x16x32_bf16 v[80:83], v[226:229], v[202:205], v[80:83]
	v_mfma_f32_16x16x32_bf16 v[68:71], v[218:221], v[210:213], v[68:71]
	v_mfma_f32_16x16x32_bf16 v[64:67], v[226:229], v[210:213], v[64:67]
	s_setprio 0
	s_mov_b32 m0, s59
	v_lshl_add_u64 v[230:231], s[12:13], 0, v[128:129]
	s_barrier
	ds_read_b128 v[174:177], v165 offset:16384
	ds_read_b128 v[178:181], v165 offset:17408
	ds_read_b128 v[188:191], v165 offset:18432
	ds_read_b128 v[194:197], v165 offset:19456
	ds_read_b128 v[198:201], v165 offset:20480
	ds_read_b128 v[202:205], v165 offset:21504
	ds_read_b128 v[206:209], v165 offset:22528
	ds_read_b128 v[210:213], v165 offset:23552
	global_load_lds_dwordx4 v[230:231], off
	v_lshl_add_u64 v[232:233], s[12:13], 0, v[132:133]
	s_mov_b32 m0, s75
	s_nop 0
	global_load_lds_dwordx4 v[232:233], off
	s_barrier
	s_waitcnt lgkmcnt(0)
	s_setprio 1
	s_waitcnt lgkmcnt(0)
	v_mfma_f32_16x16x32_bf16 v[60:63], v[146:149], v[174:177], 0
	v_mfma_f32_16x16x32_bf16 v[56:59], v[154:157], v[174:177], 0
	v_mfma_f32_16x16x32_bf16 v[44:47], v[146:149], v[188:191], 0
	v_mfma_f32_16x16x32_bf16 v[40:43], v[154:157], v[188:191], 0
	v_mfma_f32_16x16x32_bf16 v[28:31], v[146:149], v[198:201], 0
	v_mfma_f32_16x16x32_bf16 v[24:27], v[154:157], v[198:201], 0
	v_mfma_f32_16x16x32_bf16 v[12:15], v[146:149], v[206:209], 0
	v_mfma_f32_16x16x32_bf16 v[8:11], v[154:157], v[206:209], 0
	v_mfma_f32_16x16x32_bf16 v[60:63], v[150:153], v[178:181], v[60:63]
	v_mfma_f32_16x16x32_bf16 v[56:59], v[170:173], v[178:181], v[56:59]
	v_mfma_f32_16x16x32_bf16 v[44:47], v[150:153], v[194:197], v[44:47]
	v_mfma_f32_16x16x32_bf16 v[40:43], v[170:173], v[194:197], v[40:43]
	v_mfma_f32_16x16x32_bf16 v[28:31], v[150:153], v[202:205], v[28:31]
	v_mfma_f32_16x16x32_bf16 v[24:27], v[170:173], v[202:205], v[24:27]
	v_mfma_f32_16x16x32_bf16 v[12:15], v[150:153], v[210:213], v[12:15]
	v_mfma_f32_16x16x32_bf16 v[8:11], v[170:173], v[210:213], v[8:11]
	s_setprio 0
	s_barrier
; #define PG8_STAGE(bufoff, gbase, voff) do { _Pragma("unroll") for (int _i = 0; _i < 2; ++_i) \
;         __builtin_amdgcn_global_load_lds((const unsigned*)((const char*)(gbase) + (voff)[_i]), (LAS unsigned*)(lds + (bufoff) + ldsw + _i * 8192), 16, 0, 0); } while (0)
; #define PG8_LDA(dst, b, h) do { _Pragma("unroll") for (int m = 0; m < 4; ++m) _Pragma("unroll") for (int k = 0; k < 2; ++k) dst[m][k] = *(const LAS bf16x8*)(lds + PG8_SA(b, h) + aoff + m * 2048 + k * 1024); } while (0)
; #define PG8_LDB(dst, b, h) do { _Pragma("unroll") for (int n = 0; n < 2; ++n) _Pragma("unroll") for (int k = 0; k < 2; ++k) dst[n][k] = *(const LAS bf16x8*)(lds + PG8_SB(b, h) + boff + n * 2048 + k * 1024); } while (0)
; #define PG8_MMA(ai, bj, At, Bt) do { __builtin_amdgcn_s_setprio(1); _Pragma("unroll") for (int m = 0; m < 4; ++m) _Pragma("unroll") for (int n = 0; n < 2; ++n) _Pragma("unroll") for (int k = 0; k < 2; ++k) \
;         acc[ai][bj][m][n] = __builtin_amdgcn_mfma_f32_16x16x32_bf16(Bt[n][k], At[m][k], acc[ai][bj][m][n], 0, 0, 0); __builtin_amdgcn_s_setprio(0); } while (0)
; #define PG8_WAIT_V(n) asm volatile("s_waitcnt vmcnt(" #n ")" ::: "memory")
; #define PG8_WAIT_L(n) asm volatile("s_waitcnt lgkmcnt(" #n ")" ::: "memory")
; #define PG8_BAR __builtin_amdgcn_s_barrier()
; #define PG8_SCHED __builtin_amdgcn_sched_barrier(0)
; template <class Epi, class Sched>
; DI void gemm_phase(LAS unsigned char* lds, const Gemm g, const Sched& S, const Epi& E) {
;     ...
;             PG8_STAGE(PG8_SB(0, 1), b2 + hstep, voffB);
;             PG8_WAIT_V(6); PG8_BAR; PG8_MMA(1, 1, At, B1); PG8_BAR;
;             PG8_LDB(B0, 1, 0); PG8_SCHED; PG8_LDA(At, 1, 0); PG8_STAGE(PG8_SA(0, 1), a2 + hstep, voffA);
;             PG8_WAIT_L(8); PG8_BAR; PG8_WAIT_L(0); PG8_MMA(0, 0, At, B0); PG8_BAR; PG8_SCHED;
;             PG8_LDB(B1, 1, 1); PG8_STAGE(PG8_SB(1, 0), b3, voffB);
;             PG8_BAR; PG8_WAIT_L(0); PG8_MMA(0, 1, At, B1); PG8_BAR;
;             PG8_LDA(At, 1, 1); PG8_STAGE(PG8_SA(1, 0), a3, voffA);
;             PG8_BAR; PG8_WAIT_L(0); PG8_MMA(1, 0, At, B0); PG8_BAR; PG8_SCHED;
	s_add_u32 s0, s10, 0x80000
	s_addc_u32 s1, s11, 0
	s_add_i32 s4, s87, s74
	v_lshl_add_u64 v[146:147], s[0:1], 0, v[130:131]
	s_mov_b32 m0, s4
	s_nop 0
	global_load_lds_dwordx4 v[146:147], off
	v_lshl_add_u64 v[146:147], s[0:1], 0, v[134:135]
	s_add_i32 m0, s4, 0x2000
	s_nop 0
	global_load_lds_dwordx4 v[146:147], off
	s_waitcnt vmcnt(6)
	s_barrier
	s_setprio 1
	v_mfma_f32_16x16x32_bf16 v[52:55], v[214:217], v[174:177], 0
	v_mfma_f32_16x16x32_bf16 v[48:51], v[222:225], v[174:177], 0
	v_mfma_f32_16x16x32_bf16 v[36:39], v[214:217], v[188:191], 0
	v_mfma_f32_16x16x32_bf16 v[32:35], v[222:225], v[188:191], 0
	v_mfma_f32_16x16x32_bf16 v[20:23], v[214:217], v[198:201], 0
	v_mfma_f32_16x16x32_bf16 v[16:19], v[222:225], v[198:201], 0
	v_mfma_f32_16x16x32_bf16 v[4:7], v[214:217], v[206:209], 0
	v_mfma_f32_16x16x32_bf16 v[0:3], v[222:225], v[206:209], 0
	v_mfma_f32_16x16x32_bf16 v[52:55], v[218:221], v[178:181], v[52:55]
	v_mfma_f32_16x16x32_bf16 v[48:51], v[226:229], v[178:181], v[48:51]
	v_mfma_f32_16x16x32_bf16 v[36:39], v[218:221], v[194:197], v[36:39]
	v_mfma_f32_16x16x32_bf16 v[32:35], v[226:229], v[194:197], v[32:35]
	v_mfma_f32_16x16x32_bf16 v[20:23], v[218:221], v[202:205], v[20:23]
	v_mfma_f32_16x16x32_bf16 v[16:19], v[226:229], v[202:205], v[16:19]
	v_mfma_f32_16x16x32_bf16 v[4:7], v[218:221], v[210:213], v[4:7]
	v_mfma_f32_16x16x32_bf16 v[0:3], v[226:229], v[210:213], v[0:3]
	s_setprio 0
	s_add_i32 s4, 0, 0x18000
	v_add_u32_e32 v137, s4, v163
	s_barrier
	ds_read_b128 v[146:149], v137
	ds_read_b128 v[150:153], v137 offset:1024
	ds_read_b128 v[154:157], v137 offset:2048
	ds_read_b128 v[170:173], v137 offset:3072
	s_add_u32 s0, s12, 0x80000
	s_addc_u32 s1, s13, 0
	s_mov_b32 m0, s76
	v_lshl_add_u64 v[214:215], s[0:1], 0, v[128:129]
	ds_read_b128 v[174:177], v165 offset:32768
	ds_read_b128 v[178:181], v165 offset:33792
	ds_read_b128 v[188:191], v165 offset:34816
	ds_read_b128 v[194:197], v165 offset:35840
	ds_read_b128 v[198:201], v165 offset:36864
	ds_read_b128 v[202:205], v165 offset:37888
	ds_read_b128 v[206:209], v165 offset:38912
	ds_read_b128 v[210:213], v165 offset:39936
	global_load_lds_dwordx4 v[214:215], off
	v_lshl_add_u64 v[214:215], s[0:1], 0, v[132:133]
	s_mov_b32 m0, s77
	s_nop 0
	global_load_lds_dwordx4 v[214:215], off
	s_waitcnt lgkmcnt(8)
	s_barrier
	s_waitcnt lgkmcnt(0)
	s_setprio 1
	s_waitcnt lgkmcnt(0)
	v_mfma_f32_16x16x32_bf16 v[124:127], v[146:149], v[174:177], v[124:127]
	v_mfma_f32_16x16x32_bf16 v[120:123], v[154:157], v[174:177], v[120:123]
	v_mfma_f32_16x16x32_bf16 v[108:111], v[146:149], v[188:191], v[108:111]
	v_mfma_f32_16x16x32_bf16 v[104:107], v[154:157], v[188:191], v[104:107]
	v_mfma_f32_16x16x32_bf16 v[92:95], v[146:149], v[198:201], v[92:95]
	v_mfma_f32_16x16x32_bf16 v[88:91], v[154:157], v[198:201], v[88:91]
	v_mfma_f32_16x16x32_bf16 v[76:79], v[146:149], v[206:209], v[76:79]
	v_mfma_f32_16x16x32_bf16 v[72:75], v[154:157], v[206:209], v[72:75]
	v_mfma_f32_16x16x32_bf16 v[124:127], v[150:153], v[178:181], v[124:127]
	v_mfma_f32_16x16x32_bf16 v[120:123], v[170:173], v[178:181], v[120:123]
	v_mfma_f32_16x16x32_bf16 v[108:111], v[150:153], v[194:197], v[108:111]
	v_mfma_f32_16x16x32_bf16 v[104:107], v[170:173], v[194:197], v[104:107]
	v_mfma_f32_16x16x32_bf16 v[92:95], v[150:153], v[202:205], v[92:95]
	v_mfma_f32_16x16x32_bf16 v[88:91], v[170:173], v[202:205], v[88:91]
	v_mfma_f32_16x16x32_bf16 v[76:79], v[150:153], v[210:213], v[76:79]
	v_mfma_f32_16x16x32_bf16 v[72:75], v[170:173], v[210:213], v[72:75]
	s_setprio 0
	s_barrier
	s_add_i32 s5, 0, 0x1c000
	s_add_i32 s0, s4, s74
	v_add_u32_e32 v137, s5, v163
	v_lshl_add_u64 v[158:159], v[158:159], 0, s[40:41]
	s_mov_b32 m0, s0
	ds_read_b128 v[214:217], v137
	ds_read_b128 v[218:221], v137 offset:1024
	ds_read_b128 v[222:225], v137 offset:2048
	ds_read_b128 v[226:229], v137 offset:3072
	global_load_lds_dwordx4 v[158:159], off
	v_lshl_add_u64 v[158:159], v[182:183], 0, s[40:41]
	s_add_i32 m0, s0, 0x2000
	s_nop 0
	global_load_lds_dwordx4 v[158:159], off
	s_barrier
; #define PG8_STAGE(bufoff, gbase, voff) do { _Pragma("unroll") for (int _i = 0; _i < 2; ++_i) \
;         __builtin_amdgcn_global_load_lds((const unsigned*)((const char*)(gbase) + (voff)[_i]), (LAS unsigned*)(lds + (bufoff) + ldsw + _i * 8192), 16, 0, 0); } while (0)
; #define PG8_LDA(dst, b, h) do { _Pragma("unroll") for (int m = 0; m < 4; ++m) _Pragma("unroll") for (int k = 0; k < 2; ++k) dst[m][k] = *(const LAS bf16x8*)(lds + PG8_SA(b, h) + aoff + m * 2048 + k * 1024); } while (0)
; #define PG8_MMA(ai, bj, At, Bt) do { __builtin_amdgcn_s_setprio(1); _Pragma("unroll") for (int m = 0; m < 4; ++m) _Pragma("unroll") for (int n = 0; n < 2; ++n) _Pragma("unroll") for (int k = 0; k < 2; ++k) \
;         acc[ai][bj][m][n] = __builtin_amdgcn_mfma_f32_16x16x32_bf16(Bt[n][k], At[m][k], acc[ai][bj][m][n], 0, 0, 0); __builtin_amdgcn_s_setprio(0); } while (0)
; #define PG8_WAIT_V(n) asm volatile("s_waitcnt vmcnt(" #n ")" ::: "memory")
; #define PG8_WAIT_L(n) asm volatile("s_waitcnt lgkmcnt(" #n ")" ::: "memory")
; #define PG8_BAR __builtin_amdgcn_s_barrier()
; #define PG8_SCHED __builtin_amdgcn_sched_barrier(0)
; template <class Epi, class Sched>
; DI void gemm_phase(LAS unsigned char* lds, const Gemm g, const Sched& S, const Epi& E) {
;     ...
;             PG8_BAR; PG8_WAIT_L(0); PG8_MMA(0, 1, At, B1); PG8_BAR;
;             PG8_LDA(At, 1, 1); PG8_STAGE(PG8_SA(1, 0), a3, voffA);
;             PG8_BAR; PG8_WAIT_L(0); PG8_MMA(1, 0, At, B0); PG8_BAR; PG8_SCHED;
;             PG8_STAGE(PG8_SB(1, 1), b3 + hstep, voffB);
;             PG8_WAIT_V(6); PG8_BAR; PG8_MMA(1, 1, At, B1); PG8_BAR;
	s_waitcnt lgkmcnt(0)
	s_setprio 1
	s_waitcnt lgkmcnt(0)
	v_mfma_f32_16x16x32_bf16 v[116:119], v[214:217], v[174:177], v[116:119]
	v_mfma_f32_16x16x32_bf16 v[112:115], v[222:225], v[174:177], v[112:115]
	v_mfma_f32_16x16x32_bf16 v[100:103], v[214:217], v[188:191], v[100:103]
	v_mfma_f32_16x16x32_bf16 v[96:99], v[222:225], v[188:191], v[96:99]
	v_mfma_f32_16x16x32_bf16 v[84:87], v[214:217], v[198:201], v[84:87]
	v_mfma_f32_16x16x32_bf16 v[80:83], v[222:225], v[198:201], v[80:83]
	v_mfma_f32_16x16x32_bf16 v[68:71], v[214:217], v[206:209], v[68:71]
	v_mfma_f32_16x16x32_bf16 v[64:67], v[222:225], v[206:209], v[64:67]
	v_mfma_f32_16x16x32_bf16 v[116:119], v[218:221], v[178:181], v[116:119]
	v_mfma_f32_16x16x32_bf16 v[112:115], v[226:229], v[178:181], v[112:115]
	v_mfma_f32_16x16x32_bf16 v[100:103], v[218:221], v[194:197], v[100:103]
	v_mfma_f32_16x16x32_bf16 v[96:99], v[226:229], v[194:197], v[96:99]
	v_mfma_f32_16x16x32_bf16 v[84:87], v[218:221], v[202:205], v[84:87]
	v_mfma_f32_16x16x32_bf16 v[80:83], v[226:229], v[202:205], v[80:83]
	v_mfma_f32_16x16x32_bf16 v[68:71], v[218:221], v[210:213], v[68:71]
	v_mfma_f32_16x16x32_bf16 v[64:67], v[226:229], v[210:213], v[64:67]
	s_setprio 0
	s_mov_b32 m0, s97
	v_lshl_add_u64 v[158:159], v[230:231], 0, s[40:41]
	s_barrier
	ds_read_b128 v[174:177], v165 offset:49152
	ds_read_b128 v[178:181], v165 offset:50176
	ds_read_b128 v[188:191], v165 offset:51200
	ds_read_b128 v[194:197], v165 offset:52224
	ds_read_b128 v[198:201], v165 offset:53248
	ds_read_b128 v[202:205], v165 offset:54272
	ds_read_b128 v[206:209], v165 offset:55296
	ds_read_b128 v[210:213], v165 offset:56320
	global_load_lds_dwordx4 v[158:159], off
	v_lshl_add_u64 v[158:159], v[232:233], 0, s[40:41]
	s_mov_b32 m0, s84
	s_nop 0
	global_load_lds_dwordx4 v[158:159], off
	s_barrier
	s_waitcnt lgkmcnt(0)
	s_setprio 1
	s_waitcnt lgkmcnt(0)
	v_mfma_f32_16x16x32_bf16 v[60:63], v[146:149], v[174:177], v[60:63]
	v_mfma_f32_16x16x32_bf16 v[56:59], v[154:157], v[174:177], v[56:59]
	v_mfma_f32_16x16x32_bf16 v[44:47], v[146:149], v[188:191], v[44:47]
	v_mfma_f32_16x16x32_bf16 v[40:43], v[154:157], v[188:191], v[40:43]
	v_mfma_f32_16x16x32_bf16 v[28:31], v[146:149], v[198:201], v[28:31]
	v_mfma_f32_16x16x32_bf16 v[24:27], v[154:157], v[198:201], v[24:27]
	v_mfma_f32_16x16x32_bf16 v[12:15], v[146:149], v[206:209], v[12:15]
	v_mfma_f32_16x16x32_bf16 v[8:11], v[154:157], v[206:209], v[8:11]
	v_mfma_f32_16x16x32_bf16 v[60:63], v[150:153], v[178:181], v[60:63]
	v_mfma_f32_16x16x32_bf16 v[56:59], v[170:173], v[178:181], v[56:59]
	v_mfma_f32_16x16x32_bf16 v[44:47], v[150:153], v[194:197], v[44:47]
	v_mfma_f32_16x16x32_bf16 v[40:43], v[170:173], v[194:197], v[40:43]
	v_mfma_f32_16x16x32_bf16 v[28:31], v[150:153], v[202:205], v[28:31]
	v_mfma_f32_16x16x32_bf16 v[24:27], v[170:173], v[202:205], v[24:27]
	v_mfma_f32_16x16x32_bf16 v[12:15], v[150:153], v[210:213], v[12:15]
	v_mfma_f32_16x16x32_bf16 v[8:11], v[170:173], v[210:213], v[8:11]
	s_setprio 0
	s_barrier
	s_add_u32 s0, s10, 0x80080
	s_addc_u32 s1, s11, 0
	s_add_i32 s4, s5, s74
	v_lshl_add_u64 v[146:147], s[0:1], 0, v[130:131]
	s_mov_b32 m0, s4
	s_nop 0
	global_load_lds_dwordx4 v[146:147], off
	v_lshl_add_u64 v[146:147], s[0:1], 0, v[134:135]
	s_add_i32 m0, s4, 0x2000
	s_nop 0
	global_load_lds_dwordx4 v[146:147], off
	s_waitcnt vmcnt(6)
	s_barrier
	s_setprio 1
	v_mfma_f32_16x16x32_bf16 v[52:55], v[214:217], v[174:177], v[52:55]
	v_mfma_f32_16x16x32_bf16 v[48:51], v[222:225], v[174:177], v[48:51]
	v_mfma_f32_16x16x32_bf16 v[36:39], v[214:217], v[188:191], v[36:39]
	v_mfma_f32_16x16x32_bf16 v[32:35], v[222:225], v[188:191], v[32:35]
	v_mfma_f32_16x16x32_bf16 v[20:23], v[214:217], v[198:201], v[20:23]
	v_mfma_f32_16x16x32_bf16 v[16:19], v[222:225], v[198:201], v[16:19]
	v_mfma_f32_16x16x32_bf16 v[4:7], v[214:217], v[206:209], v[4:7]
	v_mfma_f32_16x16x32_bf16 v[0:3], v[222:225], v[206:209], v[0:3]
	v_mfma_f32_16x16x32_bf16 v[52:55], v[218:221], v[178:181], v[52:55]
	v_mfma_f32_16x16x32_bf16 v[48:51], v[226:229], v[178:181], v[48:51]
	v_mfma_f32_16x16x32_bf16 v[36:39], v[218:221], v[194:197], v[36:39]
	v_mfma_f32_16x16x32_bf16 v[32:35], v[226:229], v[194:197], v[32:35]
	v_mfma_f32_16x16x32_bf16 v[20:23], v[218:221], v[202:205], v[20:23]
	v_mfma_f32_16x16x32_bf16 v[16:19], v[226:229], v[202:205], v[16:19]
	v_mfma_f32_16x16x32_bf16 v[4:7], v[218:221], v[210:213], v[4:7]
	v_mfma_f32_16x16x32_bf16 v[0:3], v[226:229], v[210:213], v[0:3]
	s_setprio 0
	s_add_i32 s35, s35, 2
	s_add_u32 s8, s8, 0x100
	s_addc_u32 s9, s9, 0
	s_add_u32 s28, s28, 0x100
	s_addc_u32 s34, s34, 0
	s_cmp_gt_u32 s35, 29
	s_barrier
	s_cbranch_scc0 .LBB0_527
	s_branch .Lpeel_done_527

; DI float rs_of(const float* ss, int row) { return 1.0f / sqrtf(ss[row] * (1.0f / DM) + EPS); }
;     DI void operator()(AccRef acc, const Unit& u, int wr, int wc, int fr, int fq) const {
;     ...
;         if (pn < 4 || (pn >= 12 && pn < 15)) {
;             bf16_t* dst = (pn < 4) ? QA + pn * 256 : CQ + (pn - 12) * 256; const int ld = (pn < 4) ? 1024 : 768;
; #pragma unroll
;             for (int ai = 0; ai < 2; ++ai)
; #pragma unroll
;                 for (int m = 0; m < 4; ++m) { const size_t row = (size_t)pm * 256 + rl0 + ai * 128 + m * 16; const float r = rs_of(ss, (int)row) * ((pn < 4) ? 0.08838834764831845f * LOG2E : 1.0f);
; #pragma unroll
;                     for (int bj = 0; bj < 2; ++bj) *(u32x4*)(dst + row * ld + cc0 + bj * 128) = pack8((acc[ai][bj][m][0] * r), (acc[ai][bj][m][1] * r)); }
;         } else if (pn < 12) {
;             const bool isv = pn >= 8; const int c0 = (pn - (isv ? 8 : 4)) * 256 + cc0;
;             const bool f32out = smp || ((pm & 15) >= 14);
;             float* fo = out + (smp ? (isv ? O_AVS : O_AKS) : (isv ? O_AVP : O_AKP));
; #pragma unroll
;             for (int ai = 0; ai < 2; ++ai)
; #pragma unroll
;                 for (int m = 0; m < 4; ++m) {
;                     const int rl = rl0 + ai * 128 + m * 16; const float r = rs_of(ss, pm * 256 + rl);
;                     int b, s; if (smp) { b = rl >> 5; s = rl & 31; } else { b = pm >> 4; s = (pm & 15) * 256 + rl; }
;                     if (f32out) { const size_t orow = smp ? (size_t)rl : (size_t)b * 512 + (s - 3584);
; #pragma unroll
;                         for (int bj = 0; bj < 2; ++bj) { float* p = fo + orow * 1024 + c0 + bj * 128; *(f32x4*)p = (acc[ai][bj][m][0] * r); *(f32x4*)(p + 4) = (acc[ai][bj][m][1] * r); } }
;                     if (!isv) { bf16_t* dst = smp ? KAs + ((size_t)b * LA + 512 + s) * 1024 : KA + ((size_t)pm * 256 + rl) * 1024;
; #pragma unroll
;                         for (int bj = 0; bj < 2; ++bj) *(u32x4*)(dst + c0 + bj * 128) = pack8((acc[ai][bj][m][0] * r), (acc[ai][bj][m][1] * r));
;                     } else { bf16_t* dst; size_t cs; if (smp) { dst = VtAs + (size_t)b * 1024 * LA + 512 + s; cs = LA; } else { dst = VtA + (size_t)b * 1024 * SEQ + s; cs = SEQ; }
; #pragma unroll
;                         for (int bj = 0; bj < 2; ++bj)
; #pragma unroll
.Lpeel_done_527:
	s_cmp_lt_i32 s58, 4
	s_cselect_b64 s[8:9], -1, 0
	s_add_i32 s0, s58, -12
	s_cmp_lt_u32 s0, 3
	v_mov_b32_e32 v146, v162
	v_mov_b32_e32 v137, v161
	s_cselect_b64 s[0:1], -1, 0
	s_or_b64 s[0:1], s[8:9], s[0:1]
	v_add_u32_e32 v148, s95, v137
	v_lshl_add_u32 v146, v146, 3, s96
	s_andn2_b64 vcc, exec, s[0:1]
	s_mov_b64 s[10:11], -1
	s_cbranch_vccz .LBB0_684
	s_cmpk_gt_i32 s56, 0x7f
	s_cselect_b64 s[12:13], -1, 0
	s_cmpk_lt_i32 s56, 0x80
	s_cselect_b64 s[16:17], -1, 0
	s_cmp_gt_u32 s58, 11
	s_cbranch_scc0 .LBB0_537
	s_cmp_gt_u32 s58, 16
	s_cbranch_scc0 .LBB0_534
	s_andn2_b64 vcc, exec, s[42:43]
	s_cbranch_vccnz .LBB0_533
	s_ashr_i32 s57, s56, 31
	s_lshl_b64 s[0:1], s[56:57], 16
	v_readlane_b32 s4, v244, 10
	s_add_u32 s4, s4, s0
	v_readlane_b32 s0, v244, 8
	s_addc_u32 s5, s0, s1
	s_and_b64 s[0:1], s[12:13], exec
	v_readlane_b32 s0, v244, 13
	v_readlane_b32 s1, v244, 9
	s_cselect_b32 s0, s0, s5
	s_cselect_b32 s1, s1, s4
	s_lshl_b32 s14, s56, 8
	v_add_u32_e32 v150, s14, v148
	v_ashrrev_i32_e32 v151, 31, v150
	v_lshl_add_u64 v[150:151], v[150:151], 2, s[38:39]
	v_mov_b64_e32 v[240:241], v[150:151]
	s_mov_b32 s61, 0
	global_load_dword v192, v[240:241], off
	s_mov_b32 s60, 0x40
	v_lshl_add_u64 v[240:241], v[240:241], 0, s[60:61]
	global_load_dword v236, v[240:241], off
	s_mov_b32 s60, 0x40
	v_lshl_add_u64 v[240:241], v[240:241], 0, s[60:61]
	global_load_dword v237, v[240:241], off
	s_mov_b32 s60, 0x40
	v_lshl_add_u64 v[240:241], v[240:241], 0, s[60:61]
	global_load_dword v238, v[240:241], off
	s_mov_b32 s60, 0x140
	v_lshl_add_u64 v[240:241], v[240:241], 0, s[60:61]
	global_load_dword v239, v[240:241], off
	s_mov_b32 s60, 0x40
	v_lshl_add_u64 v[240:241], v[240:241], 0, s[60:61]
	global_load_dword v232, v[240:241], off
	s_mov_b32 s60, 0x40
	v_lshl_add_u64 v[240:241], v[240:241], 0, s[60:61]
	global_load_dword v233, v[240:241], off
	s_mov_b32 s60, 0x40
	v_lshl_add_u64 v[240:241], v[240:241], 0, s[60:61]
	global_load_dword v234, v[240:241], off
	s_waitcnt vmcnt(7)
	v_mov_b32_e32 v153, v192
	v_ashrrev_i32_e32 v149, 31, v148
	v_lshlrev_b64 v[154:155], 8, v[148:149]
	v_ashrrev_i32_e32 v147, 31, v146
	v_mov_b32_e32 v150, s1
	v_mov_b32_e32 v151, s0
	v_lshl_add_u64 v[150:151], v[146:147], 2, v[150:151]
	v_lshl_add_u64 v[158:159], v[150:151], 0, v[154:155]
	v_add_u32_e32 v152, 16, v148
	v_add_u32_e32 v156, s14, v152
	v_ashrrev_i32_e32 v157, 31, v156
	v_lshl_add_u64 v[174:175], v[156:157], 2, s[38:39]
	s_nop 1
	s_nop 0
	s_nop 1
	s_nop 1
	s_nop 1
	v_mov_b32_e32 v170, v192
	v_pk_mul_f32 v[156:157], v[126:127], v[170:171] op_sel_hi:[1,0]
	v_pk_mul_f32 v[154:155], v[124:125], v[170:171] op_sel_hi:[1,0]
	v_pk_mul_f32 v[172:173], v[122:123], v[170:171] op_sel_hi:[1,0]
	v_pk_mul_f32 v[170:171], v[120:121], v[170:171] op_sel_hi:[1,0]
	global_store_dwordx4 v[158:159], v[154:157], off
	global_store_dwordx4 v[158:159], v[170:173], off offset:16
	s_waitcnt vmcnt(8)
	v_mov_b32_e32 v147, v236
	v_add_u32_e32 v154, 32, v148
	v_add_u32_e32 v156, s14, v154
	v_ashrrev_i32_e32 v157, 31, v156
	v_lshl_add_u64 v[174:175], v[156:157], 2, s[38:39]
	v_ashrrev_i32_e32 v153, 31, v152
	v_lshlrev_b64 v[152:153], 8, v[152:153]
	v_lshl_add_u64 v[152:153], v[150:151], 0, v[152:153]
	s_nop 1
	s_nop 0
	s_nop 1
	s_nop 1
	s_nop 1
	v_mov_b32_e32 v170, v236
	v_pk_mul_f32 v[158:159], v[110:111], v[170:171] op_sel_hi:[1,0]
	v_pk_mul_f32 v[156:157], v[108:109], v[170:171] op_sel_hi:[1,0]
	v_pk_mul_f32 v[172:173], v[106:107], v[170:171] op_sel_hi:[1,0]
	v_pk_mul_f32 v[170:171], v[104:105], v[170:171] op_sel_hi:[1,0]
	global_store_dwordx4 v[152:153], v[156:159], off
	global_store_dwordx4 v[152:153], v[170:173], off offset:16
	s_waitcnt vmcnt(9)
; DI float rs_of(const float* ss, int row) { return 1.0f / sqrtf(ss[row] * (1.0f / DM) + EPS); }
;     DI void operator()(AccRef acc, const Unit& u, int wr, int wc, int fr, int fq) const {
;     ...
;             if (wc < 2) { float* fo = smp ? out + O_KRS : out + O_KRP + (size_t)pm * 256 * 64;
; #pragma unroll
;                 for (int ai = 0; ai < 2; ++ai)
; #pragma unroll
;                     for (int m = 0; m < 4; ++m) { const int rl = rl0 + ai * 128 + m * 16; const float r = rs_of(ss, pm * 256 + rl); float* p = fo + (size_t)rl * 64 + cc0; *(f32x4*)p = (acc[ai][0][m][0] * r); *(f32x4*)(p + 4) = (acc[ai][0][m][1] * r); } }
	v_mov_b32_e32 v147, v237
	v_ashrrev_i32_e32 v155, 31, v154
	v_lshlrev_b64 v[154:155], 8, v[154:155]
	v_lshl_add_u64 v[158:159], v[150:151], 0, v[154:155]
	v_add_u32_e32 v152, 48, v148
	v_add_u32_e32 v156, s14, v152
	v_ashrrev_i32_e32 v157, 31, v156
	v_lshl_add_u64 v[174:175], v[156:157], 2, s[38:39]
	s_nop 1
	s_nop 0
	s_nop 1
	s_nop 1
	s_nop 1
	v_mov_b32_e32 v170, v237
	v_pk_mul_f32 v[156:157], v[94:95], v[170:171] op_sel_hi:[1,0]
	v_pk_mul_f32 v[154:155], v[92:93], v[170:171] op_sel_hi:[1,0]
	v_pk_mul_f32 v[172:173], v[90:91], v[170:171] op_sel_hi:[1,0]
	v_pk_mul_f32 v[170:171], v[88:89], v[170:171] op_sel_hi:[1,0]
	global_store_dwordx4 v[158:159], v[154:157], off
	global_store_dwordx4 v[158:159], v[170:173], off offset:16
	s_waitcnt vmcnt(10)
	v_mov_b32_e32 v147, v238
	v_add_u32_e32 v154, 0x80, v148
	v_add_u32_e32 v156, s14, v154
	v_ashrrev_i32_e32 v157, 31, v156
	v_lshl_add_u64 v[174:175], v[156:157], 2, s[38:39]
	v_ashrrev_i32_e32 v153, 31, v152
	v_lshlrev_b64 v[152:153], 8, v[152:153]
	v_lshl_add_u64 v[152:153], v[150:151], 0, v[152:153]
	s_nop 1
	s_nop 0
	s_nop 1
	s_nop 1
	s_nop 1
	v_mov_b32_e32 v170, v238
	v_pk_mul_f32 v[158:159], v[78:79], v[170:171] op_sel_hi:[1,0]
	v_pk_mul_f32 v[156:157], v[76:77], v[170:171] op_sel_hi:[1,0]
	v_pk_mul_f32 v[172:173], v[74:75], v[170:171] op_sel_hi:[1,0]
	v_pk_mul_f32 v[170:171], v[72:73], v[170:171] op_sel_hi:[1,0]
	global_store_dwordx4 v[152:153], v[156:159], off
	global_store_dwordx4 v[152:153], v[170:173], off offset:16
	s_waitcnt vmcnt(11)
	v_mov_b32_e32 v147, v239
	v_ashrrev_i32_e32 v155, 31, v154
	v_lshlrev_b64 v[154:155], 8, v[154:155]
	v_lshl_add_u64 v[158:159], v[150:151], 0, v[154:155]
	v_add_u32_e32 v152, 0x90, v148
	v_add_u32_e32 v156, s14, v152
	v_ashrrev_i32_e32 v157, 31, v156
	v_lshl_add_u64 v[174:175], v[156:157], 2, s[38:39]
	s_nop 1
	s_nop 0
	s_nop 1
	s_nop 1
	s_nop 1
	v_mov_b32_e32 v170, v239
	v_pk_mul_f32 v[156:157], v[62:63], v[170:171] op_sel_hi:[1,0]
	v_pk_mul_f32 v[154:155], v[60:61], v[170:171] op_sel_hi:[1,0]
	v_pk_mul_f32 v[172:173], v[58:59], v[170:171] op_sel_hi:[1,0]
	v_pk_mul_f32 v[170:171], v[56:57], v[170:171] op_sel_hi:[1,0]
	global_store_dwordx4 v[158:159], v[154:157], off
	global_store_dwordx4 v[158:159], v[170:173], off offset:16
	s_waitcnt vmcnt(12)
	v_mov_b32_e32 v147, v232
	v_add_u32_e32 v154, 0xa0, v148
	v_add_u32_e32 v156, s14, v154
	v_ashrrev_i32_e32 v157, 31, v156
	v_lshl_add_u64 v[174:175], v[156:157], 2, s[38:39]
	v_ashrrev_i32_e32 v153, 31, v152
	v_lshlrev_b64 v[152:153], 8, v[152:153]
	v_lshl_add_u64 v[152:153], v[150:151], 0, v[152:153]
	s_nop 1
	s_nop 0
	s_nop 1
	s_nop 1
	s_nop 1
	v_mov_b32_e32 v170, v232
	v_pk_mul_f32 v[158:159], v[46:47], v[170:171] op_sel_hi:[1,0]
	v_pk_mul_f32 v[156:157], v[44:45], v[170:171] op_sel_hi:[1,0]
	v_pk_mul_f32 v[172:173], v[42:43], v[170:171] op_sel_hi:[1,0]
	v_pk_mul_f32 v[170:171], v[40:41], v[170:171] op_sel_hi:[1,0]
	global_store_dwordx4 v[152:153], v[156:159], off
	global_store_dwordx4 v[152:153], v[170:173], off offset:16
	s_waitcnt vmcnt(13)
	v_mov_b32_e32 v147, v233
	v_ashrrev_i32_e32 v155, 31, v154
	v_lshlrev_b64 v[154:155], 8, v[154:155]
	v_lshl_add_u64 v[158:159], v[150:151], 0, v[154:155]
	v_add_u32_e32 v152, 0xb0, v148
	v_add_u32_e32 v156, s14, v152
	v_ashrrev_i32_e32 v157, 31, v156
	v_lshl_add_u64 v[174:175], v[156:157], 2, s[38:39]
	s_nop 1
	s_nop 0
	s_nop 1
	s_nop 1
	s_nop 1
	v_mov_b32_e32 v170, v233
	v_pk_mul_f32 v[156:157], v[30:31], v[170:171] op_sel_hi:[1,0]
	v_pk_mul_f32 v[154:155], v[28:29], v[170:171] op_sel_hi:[1,0]
	v_pk_mul_f32 v[172:173], v[26:27], v[170:171] op_sel_hi:[1,0]
	v_pk_mul_f32 v[170:171], v[24:25], v[170:171] op_sel_hi:[1,0]
	global_store_dwordx4 v[158:159], v[154:157], off
	global_store_dwordx4 v[158:159], v[170:173], off offset:16
	s_waitcnt vmcnt(14)
	v_mov_b32_e32 v147, v234
	v_ashrrev_i32_e32 v153, 31, v152
	v_lshlrev_b64 v[152:153], 8, v[152:153]
	v_lshl_add_u64 v[158:159], v[150:151], 0, v[152:153]
	s_nop 1
	s_nop 0
	s_nop 1
	s_nop 1
	s_nop 1
	v_mov_b32_e32 v154, v234
	v_pk_mul_f32 v[152:153], v[14:15], v[154:155] op_sel_hi:[1,0]
	v_pk_mul_f32 v[150:151], v[12:13], v[154:155] op_sel_hi:[1,0]
	v_pk_mul_f32 v[156:157], v[10:11], v[154:155] op_sel_hi:[1,0]
	v_pk_mul_f32 v[154:155], v[8:9], v[154:155] op_sel_hi:[1,0]
	global_store_dwordx4 v[158:159], v[150:153], off
	global_store_dwordx4 v[158:159], v[154:157], off offset:16

; #define PG8_STAGE(bufoff, gbase, voff) do { _Pragma("unroll") for (int _i = 0; _i < 2; ++_i) \
;         __builtin_amdgcn_global_load_lds((const unsigned*)((const char*)(gbase) + (voff)[_i]), (LAS unsigned*)(lds + (bufoff) + ldsw + _i * 8192), 16, 0, 0); } while (0)
; #define PG8_LDA(dst, b, h) do { _Pragma("unroll") for (int m = 0; m < 4; ++m) _Pragma("unroll") for (int k = 0; k < 2; ++k) dst[m][k] = *(const LAS bf16x8*)(lds + PG8_SA(b, h) + aoff + m * 2048 + k * 1024); } while (0)
; #define PG8_LDB(dst, b, h) do { _Pragma("unroll") for (int n = 0; n < 2; ++n) _Pragma("unroll") for (int k = 0; k < 2; ++k) dst[n][k] = *(const LAS bf16x8*)(lds + PG8_SB(b, h) + boff + n * 2048 + k * 1024); } while (0)
; #define PG8_MMA(ai, bj, At, Bt) do { __builtin_amdgcn_s_setprio(1); _Pragma("unroll") for (int m = 0; m < 4; ++m) _Pragma("unroll") for (int n = 0; n < 2; ++n) _Pragma("unroll") for (int k = 0; k < 2; ++k) \
;         acc[ai][bj][m][n] = __builtin_amdgcn_mfma_f32_16x16x32_bf16(Bt[n][k], At[m][k], acc[ai][bj][m][n], 0, 0, 0); __builtin_amdgcn_s_setprio(0); } while (0)
; #define PG8_WAIT_V(n) asm volatile("s_waitcnt vmcnt(" #n ")" ::: "memory")
; #define PG8_WAIT_L(n) asm volatile("s_waitcnt lgkmcnt(" #n ")" ::: "memory")
; #define PG8_BAR __builtin_amdgcn_s_barrier()
; #define PG8_SCHED __builtin_amdgcn_sched_barrier(0)
; template <class Epi, class Sched>
; DI void gemm_phase(LAS unsigned char* lds, const Gemm g, const Sched& S, const Epi& E) {
;     ...
;             const bool last = (t == nt - 2);
;             const char* a1 = cA + (size_t)(t + 1) * kstep;
;             const char* a2 = last ? nA : cA + (size_t)(t + 2) * kstep; const char* b2 = last ? nB : cB + (size_t)(t + 2) * kstep;
;             const char* a3 = a2 + kstep; const char* b3 = b2 + kstep;
;             PG8_LDB(B0, 0, 0); PG8_SCHED; PG8_LDA(At, 0, 0); PG8_STAGE(PG8_SA(1, 1), a1 + hstep, voffA);
;             PG8_WAIT_L(8); PG8_BAR; PG8_WAIT_L(0); PG8_MMA(0, 0, At, B0); PG8_BAR; PG8_SCHED;
;             PG8_LDB(B1, 0, 1); PG8_STAGE(PG8_SB(0, 0), b2, voffB);
;             PG8_BAR; PG8_WAIT_L(0); PG8_MMA(0, 1, At, B1); PG8_BAR;
;             PG8_LDA(At, 0, 1); PG8_STAGE(PG8_SA(0, 0), a2, voffA);
;             PG8_BAR; PG8_WAIT_L(0); PG8_MMA(1, 0, At, B0); PG8_BAR; PG8_SCHED;
;             PG8_STAGE(PG8_SB(0, 1), b2 + hstep, voffB);
;             PG8_WAIT_V(6); PG8_BAR; PG8_MMA(1, 1, At, B1); PG8_BAR;
.LBB0_937:
	s_add_u32 s8, s38, 0x30080
	s_addc_u32 s9, s39, 0
	s_add_u32 s35, s36, 0x100
	v_mov_b32_e32 v0, 0
	s_addc_u32 s40, s37, 0
	s_mov_b32 s41, -2
	ds_read_b128 v[144:147], v165
	ds_read_b128 v[168:171], v165 offset:1024
	ds_read_b128 v[172:175], v165 offset:2048
	ds_read_b128 v[176:179], v165 offset:3072
	s_add_u32 s0, s8, 0xfffd0080
	s_addc_u32 s1, s9, -1
	s_cmp_eq_u32 s41, 8
	s_cselect_b32 s39, s31, s1
	s_cselect_b32 s38, s30, s0
	s_cselect_b32 s37, s11, s40
	s_cselect_b32 s36, s10, s35
	v_lshl_add_u64 v[148:149], s[8:9], 0, v[136:137]
	s_add_i32 m0, s51, 0xc000
	ds_read_b128 v[180:183], v166
	ds_read_b128 v[188:191], v166 offset:1024
	ds_read_b128 v[194:197], v166 offset:2048
	ds_read_b128 v[198:201], v166 offset:3072
	ds_read_b128 v[202:205], v166 offset:4096
	ds_read_b128 v[206:209], v166 offset:5120
	ds_read_b128 v[210:213], v166 offset:6144
	ds_read_b128 v[214:217], v166 offset:7168
	global_load_lds_dwordx4 v[148:149], off
	v_lshl_add_u64 v[148:149], s[8:9], 0, v[138:139]
	s_add_i32 m0, s51, 0xe000
	s_nop 0
	global_load_lds_dwordx4 v[148:149], off
	s_waitcnt lgkmcnt(8)
	s_barrier
	s_waitcnt lgkmcnt(0)
	s_setprio 1
	s_waitcnt lgkmcnt(0)
	v_mfma_f32_16x16x32_bf16 v[124:127], v[144:147], v[180:183], 0
	v_mfma_f32_16x16x32_bf16 v[120:123], v[172:175], v[180:183], 0
	v_mfma_f32_16x16x32_bf16 v[108:111], v[144:147], v[194:197], 0
	v_mfma_f32_16x16x32_bf16 v[104:107], v[172:175], v[194:197], 0
	v_mfma_f32_16x16x32_bf16 v[92:95], v[144:147], v[202:205], 0
	v_mfma_f32_16x16x32_bf16 v[88:91], v[172:175], v[202:205], 0
	v_mfma_f32_16x16x32_bf16 v[76:79], v[144:147], v[210:213], 0
	v_mfma_f32_16x16x32_bf16 v[72:75], v[172:175], v[210:213], 0
	v_mfma_f32_16x16x32_bf16 v[124:127], v[168:171], v[188:191], v[124:127]
	v_mfma_f32_16x16x32_bf16 v[120:123], v[176:179], v[188:191], v[120:123]
	v_mfma_f32_16x16x32_bf16 v[108:111], v[168:171], v[198:201], v[108:111]
	v_mfma_f32_16x16x32_bf16 v[104:107], v[176:179], v[198:201], v[104:107]
	v_mfma_f32_16x16x32_bf16 v[92:95], v[168:171], v[206:209], v[92:95]
	v_mfma_f32_16x16x32_bf16 v[88:91], v[176:179], v[206:209], v[88:91]
	v_mfma_f32_16x16x32_bf16 v[76:79], v[168:171], v[214:217], v[76:79]
	v_mfma_f32_16x16x32_bf16 v[72:75], v[176:179], v[214:217], v[72:75]
	s_setprio 0
	s_barrier
	s_add_i32 s0, s61, s50
	v_lshl_add_u64 v[148:149], s[36:37], 0, v[130:131]
	s_mov_b32 m0, s0
	ds_read_b128 v[218:221], v167
	ds_read_b128 v[222:225], v167 offset:1024
	ds_read_b128 v[226:229], v167 offset:2048
	ds_read_b128 v[230:233], v167 offset:3072
	global_load_lds_dwordx4 v[148:149], off
	v_lshl_add_u64 v[234:235], s[36:37], 0, v[134:135]
	s_add_i32 m0, s0, 0x2000
	s_nop 0
	global_load_lds_dwordx4 v[234:235], off
	s_barrier
	s_waitcnt lgkmcnt(0)
	s_setprio 1
	s_waitcnt lgkmcnt(0)
	v_mfma_f32_16x16x32_bf16 v[116:119], v[218:221], v[180:183], 0
	v_mfma_f32_16x16x32_bf16 v[112:115], v[226:229], v[180:183], 0
	v_mfma_f32_16x16x32_bf16 v[100:103], v[218:221], v[194:197], 0
	v_mfma_f32_16x16x32_bf16 v[96:99], v[226:229], v[194:197], 0
	v_mfma_f32_16x16x32_bf16 v[84:87], v[218:221], v[202:205], 0
	v_mfma_f32_16x16x32_bf16 v[80:83], v[226:229], v[202:205], 0
	v_mfma_f32_16x16x32_bf16 v[68:71], v[218:221], v[210:213], 0
	v_mfma_f32_16x16x32_bf16 v[64:67], v[226:229], v[210:213], 0
	v_mfma_f32_16x16x32_bf16 v[116:119], v[222:225], v[188:191], v[116:119]
	v_mfma_f32_16x16x32_bf16 v[112:115], v[230:233], v[188:191], v[112:115]
	v_mfma_f32_16x16x32_bf16 v[100:103], v[222:225], v[198:201], v[100:103]
	v_mfma_f32_16x16x32_bf16 v[96:99], v[230:233], v[198:201], v[96:99]
	v_mfma_f32_16x16x32_bf16 v[84:87], v[222:225], v[206:209], v[84:87]
	v_mfma_f32_16x16x32_bf16 v[80:83], v[230:233], v[206:209], v[80:83]
	v_mfma_f32_16x16x32_bf16 v[68:71], v[222:225], v[214:217], v[68:71]
	v_mfma_f32_16x16x32_bf16 v[64:67], v[230:233], v[214:217], v[64:67]
	s_setprio 0
	s_mov_b32 m0, s51
	v_lshl_add_u64 v[236:237], s[38:39], 0, v[128:129]
	s_barrier
	ds_read_b128 v[180:183], v166 offset:16384
	ds_read_b128 v[188:191], v166 offset:17408
	ds_read_b128 v[194:197], v166 offset:18432
	ds_read_b128 v[198:201], v166 offset:19456
	ds_read_b128 v[202:205], v166 offset:20480
	ds_read_b128 v[206:209], v166 offset:21504
	ds_read_b128 v[210:213], v166 offset:22528
	ds_read_b128 v[214:217], v166 offset:23552
	global_load_lds_dwordx4 v[236:237], off
	v_lshl_add_u64 v[238:239], s[38:39], 0, v[132:133]
	s_mov_b32 m0, s52
	s_nop 0
	global_load_lds_dwordx4 v[238:239], off
	s_barrier
	s_waitcnt lgkmcnt(0)
	s_setprio 1
	s_waitcnt lgkmcnt(0)
	v_mfma_f32_16x16x32_bf16 v[60:63], v[144:147], v[180:183], 0
	v_mfma_f32_16x16x32_bf16 v[56:59], v[172:175], v[180:183], 0
	v_mfma_f32_16x16x32_bf16 v[44:47], v[144:147], v[194:197], 0
	v_mfma_f32_16x16x32_bf16 v[40:43], v[172:175], v[194:197], 0
	v_mfma_f32_16x16x32_bf16 v[28:31], v[144:147], v[202:205], 0
	v_mfma_f32_16x16x32_bf16 v[24:27], v[172:175], v[202:205], 0
	v_mfma_f32_16x16x32_bf16 v[12:15], v[144:147], v[210:213], 0
	v_mfma_f32_16x16x32_bf16 v[8:11], v[172:175], v[210:213], 0
	v_mfma_f32_16x16x32_bf16 v[60:63], v[168:171], v[188:191], v[60:63]
	v_mfma_f32_16x16x32_bf16 v[56:59], v[176:179], v[188:191], v[56:59]
	v_mfma_f32_16x16x32_bf16 v[44:47], v[168:171], v[198:201], v[44:47]
	v_mfma_f32_16x16x32_bf16 v[40:43], v[176:179], v[198:201], v[40:43]
	v_mfma_f32_16x16x32_bf16 v[28:31], v[168:171], v[206:209], v[28:31]
	v_mfma_f32_16x16x32_bf16 v[24:27], v[176:179], v[206:209], v[24:27]
	v_mfma_f32_16x16x32_bf16 v[12:15], v[168:171], v[214:217], v[12:15]
	v_mfma_f32_16x16x32_bf16 v[8:11], v[176:179], v[214:217], v[8:11]
	s_setprio 0
	s_barrier
; #define PG8_STAGE(bufoff, gbase, voff) do { _Pragma("unroll") for (int _i = 0; _i < 2; ++_i) \
;         __builtin_amdgcn_global_load_lds((const unsigned*)((const char*)(gbase) + (voff)[_i]), (LAS unsigned*)(lds + (bufoff) + ldsw + _i * 8192), 16, 0, 0); } while (0)
; #define PG8_LDA(dst, b, h) do { _Pragma("unroll") for (int m = 0; m < 4; ++m) _Pragma("unroll") for (int k = 0; k < 2; ++k) dst[m][k] = *(const LAS bf16x8*)(lds + PG8_SA(b, h) + aoff + m * 2048 + k * 1024); } while (0)
; #define PG8_LDB(dst, b, h) do { _Pragma("unroll") for (int n = 0; n < 2; ++n) _Pragma("unroll") for (int k = 0; k < 2; ++k) dst[n][k] = *(const LAS bf16x8*)(lds + PG8_SB(b, h) + boff + n * 2048 + k * 1024); } while (0)
; #define PG8_MMA(ai, bj, At, Bt) do { __builtin_amdgcn_s_setprio(1); _Pragma("unroll") for (int m = 0; m < 4; ++m) _Pragma("unroll") for (int n = 0; n < 2; ++n) _Pragma("unroll") for (int k = 0; k < 2; ++k) \
;         acc[ai][bj][m][n] = __builtin_amdgcn_mfma_f32_16x16x32_bf16(Bt[n][k], At[m][k], acc[ai][bj][m][n], 0, 0, 0); __builtin_amdgcn_s_setprio(0); } while (0)
; #define PG8_WAIT_V(n) asm volatile("s_waitcnt vmcnt(" #n ")" ::: "memory")
; #define PG8_WAIT_L(n) asm volatile("s_waitcnt lgkmcnt(" #n ")" ::: "memory")
; #define PG8_BAR __builtin_amdgcn_s_barrier()
; #define PG8_SCHED __builtin_amdgcn_sched_barrier(0)
; template <class Epi, class Sched>
; DI void gemm_phase(LAS unsigned char* lds, const Gemm g, const Sched& S, const Epi& E) {
;     ...
;             PG8_STAGE(PG8_SB(0, 1), b2 + hstep, voffB);
;             PG8_WAIT_V(6); PG8_BAR; PG8_MMA(1, 1, At, B1); PG8_BAR;
;             PG8_LDB(B0, 1, 0); PG8_SCHED; PG8_LDA(At, 1, 0); PG8_STAGE(PG8_SA(0, 1), a2 + hstep, voffA);
;             PG8_WAIT_L(8); PG8_BAR; PG8_WAIT_L(0); PG8_MMA(0, 0, At, B0); PG8_BAR; PG8_SCHED;
;             PG8_LDB(B1, 1, 1); PG8_STAGE(PG8_SB(1, 0), b3, voffB);
;             PG8_BAR; PG8_WAIT_L(0); PG8_MMA(0, 1, At, B1); PG8_BAR;
;             PG8_LDA(At, 1, 1); PG8_STAGE(PG8_SA(1, 0), a3, voffA);
;             PG8_BAR; PG8_WAIT_L(0); PG8_MMA(1, 0, At, B0); PG8_BAR; PG8_SCHED;
	s_add_u32 s0, s36, 0x30000
	s_addc_u32 s1, s37, 0
	s_add_i32 s4, s62, s50
	v_lshl_add_u64 v[144:145], s[0:1], 0, v[130:131]
	s_mov_b32 m0, s4
	s_nop 0
	global_load_lds_dwordx4 v[144:145], off
	v_lshl_add_u64 v[144:145], s[0:1], 0, v[134:135]
	s_add_i32 m0, s4, 0x2000
	s_nop 0
	global_load_lds_dwordx4 v[144:145], off
	s_waitcnt vmcnt(6)
	s_barrier
	s_setprio 1
	v_mfma_f32_16x16x32_bf16 v[52:55], v[218:221], v[180:183], 0
	v_mfma_f32_16x16x32_bf16 v[48:51], v[226:229], v[180:183], 0
	v_mfma_f32_16x16x32_bf16 v[36:39], v[218:221], v[194:197], 0
	v_mfma_f32_16x16x32_bf16 v[32:35], v[226:229], v[194:197], 0
	v_mfma_f32_16x16x32_bf16 v[20:23], v[218:221], v[202:205], 0
	v_mfma_f32_16x16x32_bf16 v[16:19], v[226:229], v[202:205], 0
	v_mfma_f32_16x16x32_bf16 v[4:7], v[218:221], v[210:213], 0
	v_mfma_f32_16x16x32_bf16 v[0:3], v[226:229], v[210:213], 0
	v_mfma_f32_16x16x32_bf16 v[52:55], v[222:225], v[188:191], v[52:55]
	v_mfma_f32_16x16x32_bf16 v[48:51], v[230:233], v[188:191], v[48:51]
	v_mfma_f32_16x16x32_bf16 v[36:39], v[222:225], v[198:201], v[36:39]
	v_mfma_f32_16x16x32_bf16 v[32:35], v[230:233], v[198:201], v[32:35]
	v_mfma_f32_16x16x32_bf16 v[20:23], v[222:225], v[206:209], v[20:23]
	v_mfma_f32_16x16x32_bf16 v[16:19], v[230:233], v[206:209], v[16:19]
	v_mfma_f32_16x16x32_bf16 v[4:7], v[222:225], v[214:217], v[4:7]
	v_mfma_f32_16x16x32_bf16 v[0:3], v[230:233], v[214:217], v[0:3]
	s_setprio 0
	s_add_i32 s4, 0, 0x18000
	v_add_u32_e32 v150, s4, v164
	s_barrier
	ds_read_b128 v[144:147], v150
	ds_read_b128 v[168:171], v150 offset:1024
	ds_read_b128 v[172:175], v150 offset:2048
	ds_read_b128 v[176:179], v150 offset:3072
	s_add_u32 s0, s38, 0x30000
	s_addc_u32 s1, s39, 0
	s_mov_b32 m0, s53
	v_lshl_add_u64 v[218:219], s[0:1], 0, v[128:129]
	ds_read_b128 v[180:183], v166 offset:32768
	ds_read_b128 v[188:191], v166 offset:33792
	ds_read_b128 v[194:197], v166 offset:34816
	ds_read_b128 v[198:201], v166 offset:35840
	ds_read_b128 v[202:205], v166 offset:36864
	ds_read_b128 v[206:209], v166 offset:37888
	ds_read_b128 v[210:213], v166 offset:38912
	ds_read_b128 v[214:217], v166 offset:39936
	global_load_lds_dwordx4 v[218:219], off
	v_lshl_add_u64 v[218:219], s[0:1], 0, v[132:133]
	s_mov_b32 m0, s54
	s_nop 0
	global_load_lds_dwordx4 v[218:219], off
	s_waitcnt lgkmcnt(8)
	s_barrier
	s_waitcnt lgkmcnt(0)
	s_setprio 1
	s_waitcnt lgkmcnt(0)
	v_mfma_f32_16x16x32_bf16 v[124:127], v[144:147], v[180:183], v[124:127]
	v_mfma_f32_16x16x32_bf16 v[120:123], v[172:175], v[180:183], v[120:123]
	v_mfma_f32_16x16x32_bf16 v[108:111], v[144:147], v[194:197], v[108:111]
	v_mfma_f32_16x16x32_bf16 v[104:107], v[172:175], v[194:197], v[104:107]
	v_mfma_f32_16x16x32_bf16 v[92:95], v[144:147], v[202:205], v[92:95]
	v_mfma_f32_16x16x32_bf16 v[88:91], v[172:175], v[202:205], v[88:91]
	v_mfma_f32_16x16x32_bf16 v[76:79], v[144:147], v[210:213], v[76:79]
	v_mfma_f32_16x16x32_bf16 v[72:75], v[172:175], v[210:213], v[72:75]
	v_mfma_f32_16x16x32_bf16 v[124:127], v[168:171], v[188:191], v[124:127]
	v_mfma_f32_16x16x32_bf16 v[120:123], v[176:179], v[188:191], v[120:123]
	v_mfma_f32_16x16x32_bf16 v[108:111], v[168:171], v[198:201], v[108:111]
	v_mfma_f32_16x16x32_bf16 v[104:107], v[176:179], v[198:201], v[104:107]
	v_mfma_f32_16x16x32_bf16 v[92:95], v[168:171], v[206:209], v[92:95]
	v_mfma_f32_16x16x32_bf16 v[88:91], v[176:179], v[206:209], v[88:91]
	v_mfma_f32_16x16x32_bf16 v[76:79], v[168:171], v[214:217], v[76:79]
	v_mfma_f32_16x16x32_bf16 v[72:75], v[176:179], v[214:217], v[72:75]
	s_setprio 0
	s_barrier
	s_add_i32 s5, 0, 0x1c000
	s_add_i32 s0, s4, s50
	v_add_u32_e32 v150, s5, v164
	v_lshl_add_u64 v[148:149], v[148:149], 0, s[28:29]
	s_mov_b32 m0, s0
	ds_read_b128 v[218:221], v150
	ds_read_b128 v[222:225], v150 offset:1024
	ds_read_b128 v[226:229], v150 offset:2048
	ds_read_b128 v[230:233], v150 offset:3072
	global_load_lds_dwordx4 v[148:149], off
	v_lshl_add_u64 v[148:149], v[234:235], 0, s[28:29]
	s_add_i32 m0, s0, 0x2000
	s_nop 0
	global_load_lds_dwordx4 v[148:149], off
	s_barrier
; #define PG8_STAGE(bufoff, gbase, voff) do { _Pragma("unroll") for (int _i = 0; _i < 2; ++_i) \
;         __builtin_amdgcn_global_load_lds((const unsigned*)((const char*)(gbase) + (voff)[_i]), (LAS unsigned*)(lds + (bufoff) + ldsw + _i * 8192), 16, 0, 0); } while (0)
; #define PG8_LDA(dst, b, h) do { _Pragma("unroll") for (int m = 0; m < 4; ++m) _Pragma("unroll") for (int k = 0; k < 2; ++k) dst[m][k] = *(const LAS bf16x8*)(lds + PG8_SA(b, h) + aoff + m * 2048 + k * 1024); } while (0)
; #define PG8_MMA(ai, bj, At, Bt) do { __builtin_amdgcn_s_setprio(1); _Pragma("unroll") for (int m = 0; m < 4; ++m) _Pragma("unroll") for (int n = 0; n < 2; ++n) _Pragma("unroll") for (int k = 0; k < 2; ++k) \
;         acc[ai][bj][m][n] = __builtin_amdgcn_mfma_f32_16x16x32_bf16(Bt[n][k], At[m][k], acc[ai][bj][m][n], 0, 0, 0); __builtin_amdgcn_s_setprio(0); } while (0)
; #define PG8_WAIT_V(n) asm volatile("s_waitcnt vmcnt(" #n ")" ::: "memory")
; #define PG8_WAIT_L(n) asm volatile("s_waitcnt lgkmcnt(" #n ")" ::: "memory")
; #define PG8_BAR __builtin_amdgcn_s_barrier()
; #define PG8_SCHED __builtin_amdgcn_sched_barrier(0)
; template <class Epi, class Sched>
; DI void gemm_phase(LAS unsigned char* lds, const Gemm g, const Sched& S, const Epi& E) {
;     ...
;             PG8_BAR; PG8_WAIT_L(0); PG8_MMA(0, 1, At, B1); PG8_BAR;
;             PG8_LDA(At, 1, 1); PG8_STAGE(PG8_SA(1, 0), a3, voffA);
;             PG8_BAR; PG8_WAIT_L(0); PG8_MMA(1, 0, At, B0); PG8_BAR; PG8_SCHED;
;             PG8_STAGE(PG8_SB(1, 1), b3 + hstep, voffB);
;             PG8_WAIT_V(6); PG8_BAR; PG8_MMA(1, 1, At, B1); PG8_BAR;
	s_waitcnt lgkmcnt(0)
	s_setprio 1
	s_waitcnt lgkmcnt(0)
	v_mfma_f32_16x16x32_bf16 v[116:119], v[218:221], v[180:183], v[116:119]
	v_mfma_f32_16x16x32_bf16 v[112:115], v[226:229], v[180:183], v[112:115]
	v_mfma_f32_16x16x32_bf16 v[100:103], v[218:221], v[194:197], v[100:103]
	v_mfma_f32_16x16x32_bf16 v[96:99], v[226:229], v[194:197], v[96:99]
	v_mfma_f32_16x16x32_bf16 v[84:87], v[218:221], v[202:205], v[84:87]
	v_mfma_f32_16x16x32_bf16 v[80:83], v[226:229], v[202:205], v[80:83]
	v_mfma_f32_16x16x32_bf16 v[68:71], v[218:221], v[210:213], v[68:71]
	v_mfma_f32_16x16x32_bf16 v[64:67], v[226:229], v[210:213], v[64:67]
	v_mfma_f32_16x16x32_bf16 v[116:119], v[222:225], v[188:191], v[116:119]
	v_mfma_f32_16x16x32_bf16 v[112:115], v[230:233], v[188:191], v[112:115]
	v_mfma_f32_16x16x32_bf16 v[100:103], v[222:225], v[198:201], v[100:103]
	v_mfma_f32_16x16x32_bf16 v[96:99], v[230:233], v[198:201], v[96:99]
	v_mfma_f32_16x16x32_bf16 v[84:87], v[222:225], v[206:209], v[84:87]
	v_mfma_f32_16x16x32_bf16 v[80:83], v[230:233], v[206:209], v[80:83]
	v_mfma_f32_16x16x32_bf16 v[68:71], v[222:225], v[214:217], v[68:71]
	v_mfma_f32_16x16x32_bf16 v[64:67], v[230:233], v[214:217], v[64:67]
	s_setprio 0
	s_mov_b32 m0, s57
	v_lshl_add_u64 v[148:149], v[236:237], 0, s[28:29]
	s_barrier
	ds_read_b128 v[180:183], v166 offset:49152
	ds_read_b128 v[188:191], v166 offset:50176
	ds_read_b128 v[194:197], v166 offset:51200
	ds_read_b128 v[198:201], v166 offset:52224
	ds_read_b128 v[202:205], v166 offset:53248
	ds_read_b128 v[206:209], v166 offset:54272
	ds_read_b128 v[210:213], v166 offset:55296
	ds_read_b128 v[214:217], v166 offset:56320
	global_load_lds_dwordx4 v[148:149], off
	v_lshl_add_u64 v[148:149], v[238:239], 0, s[28:29]
	s_mov_b32 m0, s58
	s_nop 0
	global_load_lds_dwordx4 v[148:149], off
	s_barrier
	s_waitcnt lgkmcnt(0)
	s_setprio 1
	s_waitcnt lgkmcnt(0)
	v_mfma_f32_16x16x32_bf16 v[60:63], v[144:147], v[180:183], v[60:63]
	v_mfma_f32_16x16x32_bf16 v[56:59], v[172:175], v[180:183], v[56:59]
	v_mfma_f32_16x16x32_bf16 v[44:47], v[144:147], v[194:197], v[44:47]
	v_mfma_f32_16x16x32_bf16 v[40:43], v[172:175], v[194:197], v[40:43]
	v_mfma_f32_16x16x32_bf16 v[28:31], v[144:147], v[202:205], v[28:31]
	v_mfma_f32_16x16x32_bf16 v[24:27], v[172:175], v[202:205], v[24:27]
	v_mfma_f32_16x16x32_bf16 v[12:15], v[144:147], v[210:213], v[12:15]
	v_mfma_f32_16x16x32_bf16 v[8:11], v[172:175], v[210:213], v[8:11]
	v_mfma_f32_16x16x32_bf16 v[60:63], v[168:171], v[188:191], v[60:63]
	v_mfma_f32_16x16x32_bf16 v[56:59], v[176:179], v[188:191], v[56:59]
	v_mfma_f32_16x16x32_bf16 v[44:47], v[168:171], v[198:201], v[44:47]
	v_mfma_f32_16x16x32_bf16 v[40:43], v[176:179], v[198:201], v[40:43]
	v_mfma_f32_16x16x32_bf16 v[28:31], v[168:171], v[206:209], v[28:31]
	v_mfma_f32_16x16x32_bf16 v[24:27], v[176:179], v[206:209], v[24:27]
	v_mfma_f32_16x16x32_bf16 v[12:15], v[168:171], v[214:217], v[12:15]
	v_mfma_f32_16x16x32_bf16 v[8:11], v[176:179], v[214:217], v[8:11]
	s_setprio 0
	s_barrier
	s_add_u32 s0, s36, 0x30080
	s_addc_u32 s1, s37, 0
	s_add_i32 s4, s5, s50
	v_lshl_add_u64 v[144:145], s[0:1], 0, v[130:131]
	s_mov_b32 m0, s4
	s_nop 0
	global_load_lds_dwordx4 v[144:145], off
	v_lshl_add_u64 v[144:145], s[0:1], 0, v[134:135]
	s_add_i32 m0, s4, 0x2000
	s_nop 0
	global_load_lds_dwordx4 v[144:145], off
	s_waitcnt vmcnt(6)
	s_barrier
	s_setprio 1
	v_mfma_f32_16x16x32_bf16 v[52:55], v[218:221], v[180:183], v[52:55]
	v_mfma_f32_16x16x32_bf16 v[48:51], v[226:229], v[180:183], v[48:51]
	v_mfma_f32_16x16x32_bf16 v[36:39], v[218:221], v[194:197], v[36:39]
	v_mfma_f32_16x16x32_bf16 v[32:35], v[226:229], v[194:197], v[32:35]
	v_mfma_f32_16x16x32_bf16 v[20:23], v[218:221], v[202:205], v[20:23]
	v_mfma_f32_16x16x32_bf16 v[16:19], v[226:229], v[202:205], v[16:19]
	v_mfma_f32_16x16x32_bf16 v[4:7], v[218:221], v[210:213], v[4:7]
	v_mfma_f32_16x16x32_bf16 v[0:3], v[226:229], v[210:213], v[0:3]
	v_mfma_f32_16x16x32_bf16 v[52:55], v[222:225], v[188:191], v[52:55]
	v_mfma_f32_16x16x32_bf16 v[48:51], v[230:233], v[188:191], v[48:51]
	v_mfma_f32_16x16x32_bf16 v[36:39], v[222:225], v[198:201], v[36:39]
	v_mfma_f32_16x16x32_bf16 v[32:35], v[230:233], v[198:201], v[32:35]
	v_mfma_f32_16x16x32_bf16 v[20:23], v[222:225], v[206:209], v[20:23]
	v_mfma_f32_16x16x32_bf16 v[16:19], v[230:233], v[206:209], v[16:19]
	v_mfma_f32_16x16x32_bf16 v[4:7], v[222:225], v[214:217], v[4:7]
	v_mfma_f32_16x16x32_bf16 v[0:3], v[230:233], v[214:217], v[0:3]
	s_setprio 0
	s_add_i32 s41, s41, 2
	s_add_u32 s8, s8, 0x100
	s_addc_u32 s9, s9, 0
	s_add_u32 s35, s35, 0x100
	s_addc_u32 s40, s40, 0
	s_cmp_gt_u32 s41, 9
	s_barrier
	s_cbranch_scc0 .LBB0_938
	s_branch .Lpeel_done_938

; DI u32x4 pack8(f32x4 a, f32x4 b) { u32x4 w; w.x = cvt_pk_bf16(a[0], a[1]); w.y = cvt_pk_bf16(a[2], a[3]); w.z = cvt_pk_bf16(b[0], b[1]); w.w = cvt_pk_bf16(b[2], b[3]); return w; }
;     DI void operator()(AccRef acc, const Unit& u, int wr, int wc, int fr, int fq) const {
;         const int pn = u.pn, pm = u.pm;
; #pragma unroll
;         for (int ai = 0; ai < 2; ++ai)
; #pragma unroll
;             for (int m = 0; m < 4; ++m) {
;                 const int row = pm * 256 + wr * 64 + fr + ai * 128 + m * 16; const float r = rcq[row] * (0.07216878364870323f * LOG2E);
;                 if (pn < 4) {
; #pragma unroll
;                     for (int bj = 0; bj < 2; ++bj) { const int hh = pn * 2 + bj;
;                         *(u32x4*)(Qm + (size_t)row * 1536 + hh * 192 + wc * 32 + 8 * fq) = pack8(acc[ai][bj][m][0] * r, acc[ai][bj][m][1] * r); }
;                 } else {
;                     const int hh = (pn - 4) * 4 + wc; const int pos = (row < RP) ? (row & 4095) : PAST + ((row - RP) & 31);
;                     f32x4 o1[2], o2[2];
; #pragma unroll
;                     for (int n = 0; n < 2; ++n)
; #pragma unroll
;                         for (int j = 0; j < 4; ++j) { const f32x2 c = cs[pos * 32 + 8 * fq + 4 * n + j]; const float x1 = acc[ai][0][m][n][j] * r, x2 = acc[ai][1][m][n][j] * r;
;                             o1[n][j] = x1 * c.x - x2 * c.y; o2[n][j] = x2 * c.x + x1 * c.y; }
;                     bf16_t* p = Qm + (size_t)row * 1536 + hh * 192 + 128 + 8 * fq;
;                     *(u32x4*)p = pack8(o1[0], o1[1]); *(u32x4*)(p + 32) = pack8(o2[0], o2[1]);
;                 }
.Lpeel_done_938:
	s_lshl_b32 s0, s14, 8
	v_mov_b32_e32 v145, v154
	v_mov_b32_e32 v144, v155
	s_add_i32 s0, s0, s55
	s_cmp_gt_i32 s34, 3
	v_add_u32_e32 v146, s0, v145
	v_ashrrev_i32_e32 v147, 31, v146
	v_lshl_add_u64 v[148:149], v[146:147], 2, s[18:19]
	global_load_dword v150, v[148:149], off
	s_cselect_b64 s[38:39], -1, 0
	s_lshl_b32 s0, s34, 2
	v_lshlrev_b32_e32 v144, 3, v144
	v_and_b32_e32 v168, 31, v145
	s_add_i32 s0, s60, s0
	s_mov_b64 s[8:9], -1
	v_ashrrev_i32_e32 v145, 31, v144
	v_or_b32_e32 v147, 0x1000, v168
	s_and_b64 vcc, exec, s[38:39]
	s_mul_i32 s14, s0, 0xc0
	s_waitcnt vmcnt(0)
	v_mul_f32_e32 v150, 0x3dd53b94, v150
	s_cbranch_vccz .LBB0_941
	v_and_b32_e32 v169, 0xfff, v146
	v_cmp_gt_i32_e32 vcc, s59, v146
	v_mov_b32_e32 v194, v125
	v_mov_b32_e32 v195, v117
	v_cndmask_b32_e32 v169, v147, v169, vcc
	v_lshl_add_u32 v170, v169, 5, v144
	v_ashrrev_i32_e32 v171, 31, v170
	v_lshl_add_u64 v[182:183], v[170:171], 3, s[22:23]
	global_load_dwordx4 v[170:173], v[182:183], off
	global_load_dwordx4 v[174:177], v[182:183], off offset:16
	global_load_dwordx4 v[178:181], v[182:183], off offset:32
	global_load_dwordx4 v[188:191], v[182:183], off offset:48
	v_mov_b32_e32 v182, v124
	v_mov_b32_e32 v183, v116
	v_mov_b32_e32 v196, v126
	v_mov_b32_e32 v197, v118
	v_mov_b32_e32 v198, v127
	v_mov_b32_e32 v199, v119
	v_mov_b32_e32 v200, v120
	v_mov_b32_e32 v201, v112
	v_mov_b32_e32 v202, v121
	v_mov_b32_e32 v203, v113
	v_mov_b32_e32 v204, v122
	v_mov_b32_e32 v205, v114
	v_mov_b32_e32 v206, v123
	v_mov_b32_e32 v207, v115
	v_mov_b64_e32 v[208:209], s[16:17]
	v_pk_mul_f32 v[182:183], v[182:183], v[150:151] op_sel_hi:[1,0]
	v_pk_mul_f32 v[194:195], v[194:195], v[150:151] op_sel_hi:[1,0]
	v_pk_mul_f32 v[196:197], v[196:197], v[150:151] op_sel_hi:[1,0]
	v_pk_mul_f32 v[198:199], v[198:199], v[150:151] op_sel_hi:[1,0]
	v_pk_mul_f32 v[200:201], v[200:201], v[150:151] op_sel_hi:[1,0]
	v_pk_mul_f32 v[202:203], v[202:203], v[150:151] op_sel_hi:[1,0]
	v_pk_mul_f32 v[204:205], v[204:205], v[150:151] op_sel_hi:[1,0]
	v_pk_mul_f32 v[206:207], v[206:207], v[150:151] op_sel_hi:[1,0]
	v_mad_i64_i32 v[208:209], s[0:1], v146, s63, v[208:209]
	v_lshl_add_u64 v[208:209], s[14:15], 1, v[208:209]
	v_lshl_add_u64 v[208:209], v[144:145], 1, v[208:209]
	s_mov_b64 s[8:9], 0
	s_waitcnt vmcnt(0)
	v_pk_mul_f32 v[210:211], v[182:183], v[170:171]
	v_pk_mul_f32 v[170:171], v[182:183], v[170:171] op_sel:[0,1] op_sel_hi:[1,0]
	v_pk_mul_f32 v[182:183], v[194:195], v[172:173]
	v_pk_mul_f32 v[172:173], v[194:195], v[172:173] op_sel:[0,1] op_sel_hi:[1,0]
	v_pk_mul_f32 v[194:195], v[196:197], v[174:175]
	v_pk_mul_f32 v[174:175], v[196:197], v[174:175] op_sel:[0,1] op_sel_hi:[1,0]
	v_pk_mul_f32 v[196:197], v[198:199], v[176:177]
	v_pk_mul_f32 v[176:177], v[198:199], v[176:177] op_sel:[0,1] op_sel_hi:[1,0]
	v_pk_mul_f32 v[198:199], v[200:201], v[178:179]
	v_pk_mul_f32 v[178:179], v[200:201], v[178:179] op_sel:[0,1] op_sel_hi:[1,0]
	v_pk_mul_f32 v[200:201], v[202:203], v[180:181]
	v_pk_mul_f32 v[180:181], v[202:203], v[180:181] op_sel:[0,1] op_sel_hi:[1,0]
	v_pk_mul_f32 v[202:203], v[204:205], v[188:189]
	v_pk_mul_f32 v[188:189], v[204:205], v[188:189] op_sel:[0,1] op_sel_hi:[1,0]
	v_pk_mul_f32 v[204:205], v[206:207], v[190:191]
	v_add_f32_e32 v192, v170, v171
	v_sub_f32_e32 v170, v182, v183
	v_add_f32_e32 v182, v172, v173
	v_sub_f32_e32 v171, v194, v195
	v_sub_f32_e32 v172, v196, v197
	v_sub_f32_e32 v173, v198, v199
	v_pk_mul_f32 v[190:191], v[206:207], v[190:191] op_sel:[0,1] op_sel_hi:[1,0]
	v_sub_f32_e32 v169, v210, v211
	v_add_f32_e32 v174, v174, v175
	v_add_f32_e32 v175, v176, v177
	v_add_f32_e32 v176, v178, v179
	v_sub_f32_e32 v177, v200, v201
	v_add_f32_e32 v178, v180, v181
	v_sub_f32_e32 v179, v202, v203
	v_sub_f32_e32 v181, v204, v205
	v_cvt_pk_bf16_f32 v170, v169, v170
	v_cvt_pk_bf16_f32 v171, v171, v172
	v_cvt_pk_bf16_f32 v172, v173, v177
	v_cvt_pk_bf16_f32 v173, v179, v181
	v_add_f32_e32 v180, v188, v189
	v_add_f32_e32 v183, v190, v191
	global_store_dwordx4 v[208:209], v[170:173], off offset:256
	s_nop 1
	v_cvt_pk_bf16_f32 v170, v192, v182
	v_cvt_pk_bf16_f32 v171, v174, v175
	v_cvt_pk_bf16_f32 v172, v176, v178
	v_cvt_pk_bf16_f32 v173, v180, v183
	global_store_dwordx4 v[208:209], v[170:173], off offset:320

; #define PG8_STAGE(bufoff, gbase, voff) do { _Pragma("unroll") for (int _i = 0; _i < 2; ++_i) \
;         __builtin_amdgcn_global_load_lds((const unsigned*)((const char*)(gbase) + (voff)[_i]), (LAS unsigned*)(lds + (bufoff) + ldsw + _i * 8192), 16, 0, 0); } while (0)
; #define PG8_LDA(dst, b, h) do { _Pragma("unroll") for (int m = 0; m < 4; ++m) _Pragma("unroll") for (int k = 0; k < 2; ++k) dst[m][k] = *(const LAS bf16x8*)(lds + PG8_SA(b, h) + aoff + m * 2048 + k * 1024); } while (0)
; #define PG8_LDB(dst, b, h) do { _Pragma("unroll") for (int n = 0; n < 2; ++n) _Pragma("unroll") for (int k = 0; k < 2; ++k) dst[n][k] = *(const LAS bf16x8*)(lds + PG8_SB(b, h) + boff + n * 2048 + k * 1024); } while (0)
; #define PG8_MMA(ai, bj, At, Bt) do { __builtin_amdgcn_s_setprio(1); _Pragma("unroll") for (int m = 0; m < 4; ++m) _Pragma("unroll") for (int n = 0; n < 2; ++n) _Pragma("unroll") for (int k = 0; k < 2; ++k) \
;         acc[ai][bj][m][n] = __builtin_amdgcn_mfma_f32_16x16x32_bf16(Bt[n][k], At[m][k], acc[ai][bj][m][n], 0, 0, 0); __builtin_amdgcn_s_setprio(0); } while (0)
; #define PG8_WAIT_V(n) asm volatile("s_waitcnt vmcnt(" #n ")" ::: "memory")
; #define PG8_WAIT_L(n) asm volatile("s_waitcnt lgkmcnt(" #n ")" ::: "memory")
; #define PG8_BAR __builtin_amdgcn_s_barrier()
; #define PG8_SCHED __builtin_amdgcn_sched_barrier(0)
; template <class Epi, class Sched>
; DI void gemm_phase(LAS unsigned char* lds, const Gemm g, const Sched& S, const Epi& E) {
;     ...
;             const bool last = (t == nt - 2);
;             const char* a1 = cA + (size_t)(t + 1) * kstep;
;             const char* a2 = last ? nA : cA + (size_t)(t + 2) * kstep; const char* b2 = last ? nB : cB + (size_t)(t + 2) * kstep;
;             const char* a3 = a2 + kstep; const char* b3 = b2 + kstep;
;             PG8_LDB(B0, 0, 0); PG8_SCHED; PG8_LDA(At, 0, 0); PG8_STAGE(PG8_SA(1, 1), a1 + hstep, voffA);
;             PG8_WAIT_L(8); PG8_BAR; PG8_WAIT_L(0); PG8_MMA(0, 0, At, B0); PG8_BAR; PG8_SCHED;
;             PG8_LDB(B1, 0, 1); PG8_STAGE(PG8_SB(0, 0), b2, voffB);
;             PG8_BAR; PG8_WAIT_L(0); PG8_MMA(0, 1, At, B1); PG8_BAR;
;             PG8_LDA(At, 0, 1); PG8_STAGE(PG8_SA(0, 0), a2, voffA);
;             PG8_BAR; PG8_WAIT_L(0); PG8_MMA(1, 0, At, B0); PG8_BAR; PG8_SCHED;
;             PG8_STAGE(PG8_SB(0, 1), b2 + hstep, voffB);
;             PG8_WAIT_V(6); PG8_BAR; PG8_MMA(1, 1, At, B1); PG8_BAR;
.LBB0_983:
	s_ashr_i32 s31, s30, 31
	s_lshl_b64 s[0:1], s[30:31], 18
	v_cmp_lt_i64_e32 vcc, s[36:37], v[142:143]
	s_add_u32 s36, s51, s0
	s_addc_u32 s37, s52, s1
	s_and_b64 s[0:1], vcc, exec
	s_cselect_b32 s9, s37, s43
	s_cselect_b32 s31, s36, s42
	s_ashr_i32 s29, s28, 31
	s_lshl_b64 s[0:1], s[28:29], 18
	s_add_u32 s38, s53, s0
	s_addc_u32 s39, s54, s1
	s_and_b64 s[0:1], vcc, exec
	s_cselect_b32 s29, s39, s45
	s_cselect_b32 s34, s38, s44
	s_add_u32 s42, s42, 0x20080
	s_addc_u32 s43, s43, 0
	s_add_u32 s35, s44, 0x100
	v_mov_b32_e32 v0, 0
	s_addc_u32 s41, s45, 0
	s_mov_b32 s79, -2
	ds_read_b128 v[146:149], v156
	ds_read_b128 v[150:153], v156 offset:1024
	ds_read_b128 v[160:163], v156 offset:2048
	ds_read_b128 v[164:167], v156 offset:3072
	s_add_u32 s0, s42, 0xfffe0080
	s_addc_u32 s1, s43, -1
	s_cmp_eq_u32 s79, 4
	s_cselect_b32 s47, s9, s1
	s_cselect_b32 s46, s31, s0
	s_cselect_b32 s45, s29, s41
	s_cselect_b32 s44, s34, s35
	v_lshl_add_u64 v[206:207], s[42:43], 0, v[138:139]
	s_add_i32 m0, s55, 0xc000
	ds_read_b128 v[168:171], v158
	ds_read_b128 v[172:175], v158 offset:1024
	ds_read_b128 v[176:179], v158 offset:2048
	ds_read_b128 v[180:183], v158 offset:3072
	ds_read_b128 v[188:191], v158 offset:4096
	ds_read_b128 v[194:197], v158 offset:5120
	ds_read_b128 v[198:201], v158 offset:6144
	ds_read_b128 v[202:205], v158 offset:7168
	global_load_lds_dwordx4 v[206:207], off
	v_lshl_add_u64 v[206:207], s[42:43], 0, v[140:141]
	s_add_i32 m0, s55, 0xe000
	s_nop 0
	global_load_lds_dwordx4 v[206:207], off
	s_waitcnt lgkmcnt(8)
	s_barrier
	s_waitcnt lgkmcnt(0)
	s_setprio 1
	s_waitcnt lgkmcnt(0)
	v_mfma_f32_16x16x32_bf16 v[124:127], v[146:149], v[168:171], 0
	v_mfma_f32_16x16x32_bf16 v[120:123], v[160:163], v[168:171], 0
	v_mfma_f32_16x16x32_bf16 v[108:111], v[146:149], v[176:179], 0
	v_mfma_f32_16x16x32_bf16 v[104:107], v[160:163], v[176:179], 0
	v_mfma_f32_16x16x32_bf16 v[92:95], v[146:149], v[188:191], 0
	v_mfma_f32_16x16x32_bf16 v[88:91], v[160:163], v[188:191], 0
	v_mfma_f32_16x16x32_bf16 v[76:79], v[146:149], v[198:201], 0
	v_mfma_f32_16x16x32_bf16 v[72:75], v[160:163], v[198:201], 0
	v_mfma_f32_16x16x32_bf16 v[124:127], v[150:153], v[172:175], v[124:127]
	v_mfma_f32_16x16x32_bf16 v[120:123], v[164:167], v[172:175], v[120:123]
	v_mfma_f32_16x16x32_bf16 v[108:111], v[150:153], v[180:183], v[108:111]
	v_mfma_f32_16x16x32_bf16 v[104:107], v[164:167], v[180:183], v[104:107]
	v_mfma_f32_16x16x32_bf16 v[92:95], v[150:153], v[194:197], v[92:95]
	v_mfma_f32_16x16x32_bf16 v[88:91], v[164:167], v[194:197], v[88:91]
	v_mfma_f32_16x16x32_bf16 v[76:79], v[150:153], v[202:205], v[76:79]
	v_mfma_f32_16x16x32_bf16 v[72:75], v[164:167], v[202:205], v[72:75]
	s_setprio 0
	s_barrier
	s_add_i32 s0, s66, s50
	v_lshl_add_u64 v[222:223], s[44:45], 0, v[130:131]
	s_mov_b32 m0, s0
	ds_read_b128 v[206:209], v159
	ds_read_b128 v[210:213], v159 offset:1024
	ds_read_b128 v[214:217], v159 offset:2048
	ds_read_b128 v[218:221], v159 offset:3072
	global_load_lds_dwordx4 v[222:223], off
	v_lshl_add_u64 v[224:225], s[44:45], 0, v[134:135]
	s_add_i32 m0, s0, 0x2000
	s_nop 0
	global_load_lds_dwordx4 v[224:225], off
	s_barrier
	s_waitcnt lgkmcnt(0)
	s_setprio 1
	s_waitcnt lgkmcnt(0)
	v_mfma_f32_16x16x32_bf16 v[116:119], v[206:209], v[168:171], 0
	v_mfma_f32_16x16x32_bf16 v[112:115], v[214:217], v[168:171], 0
	v_mfma_f32_16x16x32_bf16 v[100:103], v[206:209], v[176:179], 0
	v_mfma_f32_16x16x32_bf16 v[96:99], v[214:217], v[176:179], 0
	v_mfma_f32_16x16x32_bf16 v[84:87], v[206:209], v[188:191], 0
	v_mfma_f32_16x16x32_bf16 v[80:83], v[214:217], v[188:191], 0
	v_mfma_f32_16x16x32_bf16 v[68:71], v[206:209], v[198:201], 0
	v_mfma_f32_16x16x32_bf16 v[64:67], v[214:217], v[198:201], 0
	v_mfma_f32_16x16x32_bf16 v[116:119], v[210:213], v[172:175], v[116:119]
	v_mfma_f32_16x16x32_bf16 v[112:115], v[218:221], v[172:175], v[112:115]
	v_mfma_f32_16x16x32_bf16 v[100:103], v[210:213], v[180:183], v[100:103]
	v_mfma_f32_16x16x32_bf16 v[96:99], v[218:221], v[180:183], v[96:99]
	v_mfma_f32_16x16x32_bf16 v[84:87], v[210:213], v[194:197], v[84:87]
	v_mfma_f32_16x16x32_bf16 v[80:83], v[218:221], v[194:197], v[80:83]
	v_mfma_f32_16x16x32_bf16 v[68:71], v[210:213], v[202:205], v[68:71]
	v_mfma_f32_16x16x32_bf16 v[64:67], v[218:221], v[202:205], v[64:67]
	s_setprio 0
	s_mov_b32 m0, s55
	v_lshl_add_u64 v[226:227], s[46:47], 0, v[128:129]
	s_barrier
	ds_read_b128 v[168:171], v158 offset:16384
	ds_read_b128 v[172:175], v158 offset:17408
	ds_read_b128 v[176:179], v158 offset:18432
	ds_read_b128 v[180:183], v158 offset:19456
	ds_read_b128 v[188:191], v158 offset:20480
	ds_read_b128 v[194:197], v158 offset:21504
	ds_read_b128 v[198:201], v158 offset:22528
	ds_read_b128 v[202:205], v158 offset:23552
	global_load_lds_dwordx4 v[226:227], off
	v_lshl_add_u64 v[228:229], s[46:47], 0, v[132:133]
	s_mov_b32 m0, s56
	s_nop 0
	global_load_lds_dwordx4 v[228:229], off
	s_barrier
	s_waitcnt lgkmcnt(0)
	s_setprio 1
	s_waitcnt lgkmcnt(0)
	v_mfma_f32_16x16x32_bf16 v[60:63], v[146:149], v[168:171], 0
	v_mfma_f32_16x16x32_bf16 v[56:59], v[160:163], v[168:171], 0
	v_mfma_f32_16x16x32_bf16 v[44:47], v[146:149], v[176:179], 0
	v_mfma_f32_16x16x32_bf16 v[40:43], v[160:163], v[176:179], 0
	v_mfma_f32_16x16x32_bf16 v[28:31], v[146:149], v[188:191], 0
	v_mfma_f32_16x16x32_bf16 v[24:27], v[160:163], v[188:191], 0
	v_mfma_f32_16x16x32_bf16 v[12:15], v[146:149], v[198:201], 0
	v_mfma_f32_16x16x32_bf16 v[8:11], v[160:163], v[198:201], 0
	v_mfma_f32_16x16x32_bf16 v[60:63], v[150:153], v[172:175], v[60:63]
	v_mfma_f32_16x16x32_bf16 v[56:59], v[164:167], v[172:175], v[56:59]
	v_mfma_f32_16x16x32_bf16 v[44:47], v[150:153], v[180:183], v[44:47]
	v_mfma_f32_16x16x32_bf16 v[40:43], v[164:167], v[180:183], v[40:43]
	v_mfma_f32_16x16x32_bf16 v[28:31], v[150:153], v[194:197], v[28:31]
	v_mfma_f32_16x16x32_bf16 v[24:27], v[164:167], v[194:197], v[24:27]
	v_mfma_f32_16x16x32_bf16 v[12:15], v[150:153], v[202:205], v[12:15]
	v_mfma_f32_16x16x32_bf16 v[8:11], v[164:167], v[202:205], v[8:11]
	s_setprio 0
	s_barrier
; #define PG8_STAGE(bufoff, gbase, voff) do { _Pragma("unroll") for (int _i = 0; _i < 2; ++_i) \
;         __builtin_amdgcn_global_load_lds((const unsigned*)((const char*)(gbase) + (voff)[_i]), (LAS unsigned*)(lds + (bufoff) + ldsw + _i * 8192), 16, 0, 0); } while (0)
; #define PG8_LDA(dst, b, h) do { _Pragma("unroll") for (int m = 0; m < 4; ++m) _Pragma("unroll") for (int k = 0; k < 2; ++k) dst[m][k] = *(const LAS bf16x8*)(lds + PG8_SA(b, h) + aoff + m * 2048 + k * 1024); } while (0)
; #define PG8_LDB(dst, b, h) do { _Pragma("unroll") for (int n = 0; n < 2; ++n) _Pragma("unroll") for (int k = 0; k < 2; ++k) dst[n][k] = *(const LAS bf16x8*)(lds + PG8_SB(b, h) + boff + n * 2048 + k * 1024); } while (0)
; #define PG8_MMA(ai, bj, At, Bt) do { __builtin_amdgcn_s_setprio(1); _Pragma("unroll") for (int m = 0; m < 4; ++m) _Pragma("unroll") for (int n = 0; n < 2; ++n) _Pragma("unroll") for (int k = 0; k < 2; ++k) \
;         acc[ai][bj][m][n] = __builtin_amdgcn_mfma_f32_16x16x32_bf16(Bt[n][k], At[m][k], acc[ai][bj][m][n], 0, 0, 0); __builtin_amdgcn_s_setprio(0); } while (0)
; #define PG8_WAIT_V(n) asm volatile("s_waitcnt vmcnt(" #n ")" ::: "memory")
; #define PG8_WAIT_L(n) asm volatile("s_waitcnt lgkmcnt(" #n ")" ::: "memory")
; #define PG8_BAR __builtin_amdgcn_s_barrier()
; #define PG8_SCHED __builtin_amdgcn_sched_barrier(0)
; template <class Epi, class Sched>
; DI void gemm_phase(LAS unsigned char* lds, const Gemm g, const Sched& S, const Epi& E) {
;     ...
;             PG8_STAGE(PG8_SB(0, 1), b2 + hstep, voffB);
;             PG8_WAIT_V(6); PG8_BAR; PG8_MMA(1, 1, At, B1); PG8_BAR;
;             PG8_LDB(B0, 1, 0); PG8_SCHED; PG8_LDA(At, 1, 0); PG8_STAGE(PG8_SA(0, 1), a2 + hstep, voffA);
;             PG8_WAIT_L(8); PG8_BAR; PG8_WAIT_L(0); PG8_MMA(0, 0, At, B0); PG8_BAR; PG8_SCHED;
;             PG8_LDB(B1, 1, 1); PG8_STAGE(PG8_SB(1, 0), b3, voffB);
;             PG8_BAR; PG8_WAIT_L(0); PG8_MMA(0, 1, At, B1); PG8_BAR;
;             PG8_LDA(At, 1, 1); PG8_STAGE(PG8_SA(1, 0), a3, voffA);
;             PG8_BAR; PG8_WAIT_L(0); PG8_MMA(1, 0, At, B0); PG8_BAR; PG8_SCHED;
	s_add_u32 s0, s44, 0x20000
	s_addc_u32 s1, s45, 0
	s_add_i32 s4, s67, s50
	v_lshl_add_u64 v[146:147], s[0:1], 0, v[130:131]
	s_mov_b32 m0, s4
	s_nop 0
	global_load_lds_dwordx4 v[146:147], off
	v_lshl_add_u64 v[146:147], s[0:1], 0, v[134:135]
	s_add_i32 m0, s4, 0x2000
	s_nop 0
	global_load_lds_dwordx4 v[146:147], off
	s_waitcnt vmcnt(6)
	s_barrier
	s_setprio 1
	v_mfma_f32_16x16x32_bf16 v[52:55], v[206:209], v[168:171], 0
	v_mfma_f32_16x16x32_bf16 v[48:51], v[214:217], v[168:171], 0
	v_mfma_f32_16x16x32_bf16 v[36:39], v[206:209], v[176:179], 0
	v_mfma_f32_16x16x32_bf16 v[32:35], v[214:217], v[176:179], 0
	v_mfma_f32_16x16x32_bf16 v[20:23], v[206:209], v[188:191], 0
	v_mfma_f32_16x16x32_bf16 v[16:19], v[214:217], v[188:191], 0
	v_mfma_f32_16x16x32_bf16 v[4:7], v[206:209], v[198:201], 0
	v_mfma_f32_16x16x32_bf16 v[0:3], v[214:217], v[198:201], 0
	v_mfma_f32_16x16x32_bf16 v[52:55], v[210:213], v[172:175], v[52:55]
	v_mfma_f32_16x16x32_bf16 v[48:51], v[218:221], v[172:175], v[48:51]
	v_mfma_f32_16x16x32_bf16 v[36:39], v[210:213], v[180:183], v[36:39]
	v_mfma_f32_16x16x32_bf16 v[32:35], v[218:221], v[180:183], v[32:35]
	v_mfma_f32_16x16x32_bf16 v[20:23], v[210:213], v[194:197], v[20:23]
	v_mfma_f32_16x16x32_bf16 v[16:19], v[218:221], v[194:197], v[16:19]
	v_mfma_f32_16x16x32_bf16 v[4:7], v[210:213], v[202:205], v[4:7]
	v_mfma_f32_16x16x32_bf16 v[0:3], v[218:221], v[202:205], v[0:3]
	s_setprio 0
	s_add_i32 s4, 0, 0x18000
	v_add_u32_e32 v136, s4, v157
	s_barrier
	ds_read_b128 v[146:149], v136
	ds_read_b128 v[150:153], v136 offset:1024
	ds_read_b128 v[160:163], v136 offset:2048
	ds_read_b128 v[164:167], v136 offset:3072
	s_add_u32 s0, s46, 0x20000
	s_addc_u32 s1, s47, 0
	s_mov_b32 m0, s57
	v_lshl_add_u64 v[206:207], s[0:1], 0, v[128:129]
	ds_read_b128 v[168:171], v158 offset:32768
	ds_read_b128 v[172:175], v158 offset:33792
	ds_read_b128 v[176:179], v158 offset:34816
	ds_read_b128 v[180:183], v158 offset:35840
	ds_read_b128 v[188:191], v158 offset:36864
	ds_read_b128 v[194:197], v158 offset:37888
	ds_read_b128 v[198:201], v158 offset:38912
	ds_read_b128 v[202:205], v158 offset:39936
	global_load_lds_dwordx4 v[206:207], off
	v_lshl_add_u64 v[206:207], s[0:1], 0, v[132:133]
	s_mov_b32 m0, s58
	s_nop 0
	global_load_lds_dwordx4 v[206:207], off
	s_waitcnt lgkmcnt(8)
	s_barrier
	s_waitcnt lgkmcnt(0)
	s_setprio 1
	s_waitcnt lgkmcnt(0)
	v_mfma_f32_16x16x32_bf16 v[124:127], v[146:149], v[168:171], v[124:127]
	v_mfma_f32_16x16x32_bf16 v[120:123], v[160:163], v[168:171], v[120:123]
	v_mfma_f32_16x16x32_bf16 v[108:111], v[146:149], v[176:179], v[108:111]
	v_mfma_f32_16x16x32_bf16 v[104:107], v[160:163], v[176:179], v[104:107]
	v_mfma_f32_16x16x32_bf16 v[92:95], v[146:149], v[188:191], v[92:95]
	v_mfma_f32_16x16x32_bf16 v[88:91], v[160:163], v[188:191], v[88:91]
	v_mfma_f32_16x16x32_bf16 v[76:79], v[146:149], v[198:201], v[76:79]
	v_mfma_f32_16x16x32_bf16 v[72:75], v[160:163], v[198:201], v[72:75]
	v_mfma_f32_16x16x32_bf16 v[124:127], v[150:153], v[172:175], v[124:127]
	v_mfma_f32_16x16x32_bf16 v[120:123], v[164:167], v[172:175], v[120:123]
	v_mfma_f32_16x16x32_bf16 v[108:111], v[150:153], v[180:183], v[108:111]
	v_mfma_f32_16x16x32_bf16 v[104:107], v[164:167], v[180:183], v[104:107]
	v_mfma_f32_16x16x32_bf16 v[92:95], v[150:153], v[194:197], v[92:95]
	v_mfma_f32_16x16x32_bf16 v[88:91], v[164:167], v[194:197], v[88:91]
	v_mfma_f32_16x16x32_bf16 v[76:79], v[150:153], v[202:205], v[76:79]
	v_mfma_f32_16x16x32_bf16 v[72:75], v[164:167], v[202:205], v[72:75]
	s_setprio 0
	s_barrier
	s_add_i32 s5, 0, 0x1c000
	s_add_i32 s0, s4, s50
	v_add_u32_e32 v136, s5, v157
	v_lshl_add_u64 v[222:223], v[222:223], 0, s[18:19]
	s_mov_b32 m0, s0
	ds_read_b128 v[206:209], v136
	ds_read_b128 v[210:213], v136 offset:1024
	ds_read_b128 v[214:217], v136 offset:2048
	ds_read_b128 v[218:221], v136 offset:3072
	global_load_lds_dwordx4 v[222:223], off
	v_lshl_add_u64 v[222:223], v[224:225], 0, s[18:19]
	s_add_i32 m0, s0, 0x2000
	s_nop 0
	global_load_lds_dwordx4 v[222:223], off
	s_barrier
; #define PG8_STAGE(bufoff, gbase, voff) do { _Pragma("unroll") for (int _i = 0; _i < 2; ++_i) \
;         __builtin_amdgcn_global_load_lds((const unsigned*)((const char*)(gbase) + (voff)[_i]), (LAS unsigned*)(lds + (bufoff) + ldsw + _i * 8192), 16, 0, 0); } while (0)
; #define PG8_LDA(dst, b, h) do { _Pragma("unroll") for (int m = 0; m < 4; ++m) _Pragma("unroll") for (int k = 0; k < 2; ++k) dst[m][k] = *(const LAS bf16x8*)(lds + PG8_SA(b, h) + aoff + m * 2048 + k * 1024); } while (0)
; #define PG8_MMA(ai, bj, At, Bt) do { __builtin_amdgcn_s_setprio(1); _Pragma("unroll") for (int m = 0; m < 4; ++m) _Pragma("unroll") for (int n = 0; n < 2; ++n) _Pragma("unroll") for (int k = 0; k < 2; ++k) \
;         acc[ai][bj][m][n] = __builtin_amdgcn_mfma_f32_16x16x32_bf16(Bt[n][k], At[m][k], acc[ai][bj][m][n], 0, 0, 0); __builtin_amdgcn_s_setprio(0); } while (0)
; #define PG8_WAIT_V(n) asm volatile("s_waitcnt vmcnt(" #n ")" ::: "memory")
; #define PG8_WAIT_L(n) asm volatile("s_waitcnt lgkmcnt(" #n ")" ::: "memory")
; #define PG8_BAR __builtin_amdgcn_s_barrier()
; #define PG8_SCHED __builtin_amdgcn_sched_barrier(0)
; template <class Epi, class Sched>
; DI void gemm_phase(LAS unsigned char* lds, const Gemm g, const Sched& S, const Epi& E) {
;     ...
;             PG8_BAR; PG8_WAIT_L(0); PG8_MMA(0, 1, At, B1); PG8_BAR;
;             PG8_LDA(At, 1, 1); PG8_STAGE(PG8_SA(1, 0), a3, voffA);
;             PG8_BAR; PG8_WAIT_L(0); PG8_MMA(1, 0, At, B0); PG8_BAR; PG8_SCHED;
;             PG8_STAGE(PG8_SB(1, 1), b3 + hstep, voffB);
;             PG8_WAIT_V(6); PG8_BAR; PG8_MMA(1, 1, At, B1); PG8_BAR;
	s_waitcnt lgkmcnt(0)
	s_setprio 1
	s_waitcnt lgkmcnt(0)
	v_mfma_f32_16x16x32_bf16 v[116:119], v[206:209], v[168:171], v[116:119]
	v_mfma_f32_16x16x32_bf16 v[112:115], v[214:217], v[168:171], v[112:115]
	v_mfma_f32_16x16x32_bf16 v[100:103], v[206:209], v[176:179], v[100:103]
	v_mfma_f32_16x16x32_bf16 v[96:99], v[214:217], v[176:179], v[96:99]
	v_mfma_f32_16x16x32_bf16 v[84:87], v[206:209], v[188:191], v[84:87]
	v_mfma_f32_16x16x32_bf16 v[80:83], v[214:217], v[188:191], v[80:83]
	v_mfma_f32_16x16x32_bf16 v[68:71], v[206:209], v[198:201], v[68:71]
	v_mfma_f32_16x16x32_bf16 v[64:67], v[214:217], v[198:201], v[64:67]
	v_mfma_f32_16x16x32_bf16 v[116:119], v[210:213], v[172:175], v[116:119]
	v_mfma_f32_16x16x32_bf16 v[112:115], v[218:221], v[172:175], v[112:115]
	v_mfma_f32_16x16x32_bf16 v[100:103], v[210:213], v[180:183], v[100:103]
	v_mfma_f32_16x16x32_bf16 v[96:99], v[218:221], v[180:183], v[96:99]
	v_mfma_f32_16x16x32_bf16 v[84:87], v[210:213], v[194:197], v[84:87]
	v_mfma_f32_16x16x32_bf16 v[80:83], v[218:221], v[194:197], v[80:83]
	v_mfma_f32_16x16x32_bf16 v[68:71], v[210:213], v[202:205], v[68:71]
	v_mfma_f32_16x16x32_bf16 v[64:67], v[218:221], v[202:205], v[64:67]
	s_setprio 0
	s_mov_b32 m0, s62
	v_lshl_add_u64 v[222:223], v[226:227], 0, s[18:19]
	s_barrier
	ds_read_b128 v[168:171], v158 offset:49152
	ds_read_b128 v[172:175], v158 offset:50176
	ds_read_b128 v[176:179], v158 offset:51200
	ds_read_b128 v[180:183], v158 offset:52224
	ds_read_b128 v[188:191], v158 offset:53248
	ds_read_b128 v[194:197], v158 offset:54272
	ds_read_b128 v[198:201], v158 offset:55296
	ds_read_b128 v[202:205], v158 offset:56320
	global_load_lds_dwordx4 v[222:223], off
	v_lshl_add_u64 v[222:223], v[228:229], 0, s[18:19]
	s_mov_b32 m0, s63
	s_nop 0
	global_load_lds_dwordx4 v[222:223], off
	s_barrier
	s_waitcnt lgkmcnt(0)
	s_setprio 1
	s_waitcnt lgkmcnt(0)
	v_mfma_f32_16x16x32_bf16 v[60:63], v[146:149], v[168:171], v[60:63]
	v_mfma_f32_16x16x32_bf16 v[56:59], v[160:163], v[168:171], v[56:59]
	v_mfma_f32_16x16x32_bf16 v[44:47], v[146:149], v[176:179], v[44:47]
	v_mfma_f32_16x16x32_bf16 v[40:43], v[160:163], v[176:179], v[40:43]
	v_mfma_f32_16x16x32_bf16 v[28:31], v[146:149], v[188:191], v[28:31]
	v_mfma_f32_16x16x32_bf16 v[24:27], v[160:163], v[188:191], v[24:27]
	v_mfma_f32_16x16x32_bf16 v[12:15], v[146:149], v[198:201], v[12:15]
	v_mfma_f32_16x16x32_bf16 v[8:11], v[160:163], v[198:201], v[8:11]
	v_mfma_f32_16x16x32_bf16 v[60:63], v[150:153], v[172:175], v[60:63]
	v_mfma_f32_16x16x32_bf16 v[56:59], v[164:167], v[172:175], v[56:59]
	v_mfma_f32_16x16x32_bf16 v[44:47], v[150:153], v[180:183], v[44:47]
	v_mfma_f32_16x16x32_bf16 v[40:43], v[164:167], v[180:183], v[40:43]
	v_mfma_f32_16x16x32_bf16 v[28:31], v[150:153], v[194:197], v[28:31]
	v_mfma_f32_16x16x32_bf16 v[24:27], v[164:167], v[194:197], v[24:27]
	v_mfma_f32_16x16x32_bf16 v[12:15], v[150:153], v[202:205], v[12:15]
	v_mfma_f32_16x16x32_bf16 v[8:11], v[164:167], v[202:205], v[8:11]
	s_setprio 0
	s_barrier
	s_add_u32 s0, s44, 0x20080
	s_addc_u32 s1, s45, 0
	s_add_i32 s4, s5, s50
	v_lshl_add_u64 v[146:147], s[0:1], 0, v[130:131]
	s_mov_b32 m0, s4
	s_nop 0
	global_load_lds_dwordx4 v[146:147], off
	v_lshl_add_u64 v[146:147], s[0:1], 0, v[134:135]
	s_add_i32 m0, s4, 0x2000
	s_nop 0
	global_load_lds_dwordx4 v[146:147], off
	s_waitcnt vmcnt(6)
	s_barrier
	s_setprio 1
	v_mfma_f32_16x16x32_bf16 v[52:55], v[206:209], v[168:171], v[52:55]
	v_mfma_f32_16x16x32_bf16 v[48:51], v[214:217], v[168:171], v[48:51]
	v_mfma_f32_16x16x32_bf16 v[36:39], v[206:209], v[176:179], v[36:39]
	v_mfma_f32_16x16x32_bf16 v[32:35], v[214:217], v[176:179], v[32:35]
	v_mfma_f32_16x16x32_bf16 v[20:23], v[206:209], v[188:191], v[20:23]
	v_mfma_f32_16x16x32_bf16 v[16:19], v[214:217], v[188:191], v[16:19]
	v_mfma_f32_16x16x32_bf16 v[4:7], v[206:209], v[198:201], v[4:7]
	v_mfma_f32_16x16x32_bf16 v[0:3], v[214:217], v[198:201], v[0:3]
	v_mfma_f32_16x16x32_bf16 v[52:55], v[210:213], v[172:175], v[52:55]
	v_mfma_f32_16x16x32_bf16 v[48:51], v[218:221], v[172:175], v[48:51]
	v_mfma_f32_16x16x32_bf16 v[36:39], v[210:213], v[180:183], v[36:39]
	v_mfma_f32_16x16x32_bf16 v[32:35], v[218:221], v[180:183], v[32:35]
	v_mfma_f32_16x16x32_bf16 v[20:23], v[210:213], v[194:197], v[20:23]
	v_mfma_f32_16x16x32_bf16 v[16:19], v[218:221], v[194:197], v[16:19]
	v_mfma_f32_16x16x32_bf16 v[4:7], v[210:213], v[202:205], v[4:7]
	v_mfma_f32_16x16x32_bf16 v[0:3], v[218:221], v[202:205], v[0:3]
	s_setprio 0
	s_add_i32 s79, s79, 2
	s_add_u32 s42, s42, 0x100
	s_addc_u32 s43, s43, 0
	s_add_u32 s35, s35, 0x100
	s_addc_u32 s41, s41, 0
	s_cmp_gt_u32 s79, 5
	s_barrier
	s_cbranch_scc0 .LBB0_984
	s_branch .Lpeel_done_984

; DI unsigned cvt_pk_bf16(float lo, float hi) { unsigned r; asm volatile("v_cvt_pk_bf16_f32 %0, %1, %2" : "=v"(r) : "v"(lo), "v"(hi)); return r; }
; DI u32x4 pack8(f32x4 a, f32x4 b) { u32x4 w; w.x = cvt_pk_bf16(a[0], a[1]); w.y = cvt_pk_bf16(a[2], a[3]); w.z = cvt_pk_bf16(b[0], b[1]); w.w = cvt_pk_bf16(b[2], b[3]); return w; }
;     DI void operator()(AccRef acc, const Unit& u, int wr, int wc, int fr, int fq) const {
;         const int pn = u.pn, pm = u.pm; const int cc0 = wc * 32 + 8 * fq;
; #pragma unroll
;         for (int ai = 0; ai < 2; ++ai)
; #pragma unroll
;             for (int m = 0; m < 4; ++m) {
;                 const int row = pm * 256 + wr * 64 + fr + ai * 128 + m * 16;
;                 if (pn < 4) {
; #pragma unroll
;                     for (int bj = 0; bj < 2; ++bj) *(u32x4*)(Kn + (size_t)row * 1024 + pn * 256 + cc0 + bj * 128) = pack8(acc[ai][bj][m][0], acc[ai][bj][m][1]);
;                 } else {
;                     bf16_t* dst; size_t cs;
;                     if (row < RP) { dst = VtMp + (size_t)(row >> 12) * 1024 * SEQ + (row & 4095); cs = SEQ; }
;                     else { const int ip = row - RP, b = ip / LM, key = ip - b * LM; dst = VtMs + (size_t)b * 1024 * LM + key; cs = LM; }
;                     const int c0 = (pn - 4) * 256 + cc0;
; #pragma unroll
;                     for (int bj = 0; bj < 2; ++bj)
; #pragma unroll
;                         for (int n = 0; n < 2; ++n) { const unsigned w0 = cvt_pk_bf16(acc[ai][bj][m][n][0], acc[ai][bj][m][n][1]), w1 = cvt_pk_bf16(acc[ai][bj][m][n][2], acc[ai][bj][m][n][3]);
;                             bf16_t* p = dst + (size_t)(c0 + bj * 128 + 4 * n) * cs;
;                             p[0] = (bf16_t)(w0 & 0xffff); p[cs] = (bf16_t)(w0 >> 16); p[2 * cs] = (bf16_t)(w1 & 0xffff); p[3 * cs] = (bf16_t)(w1 >> 16); asm volatile("" ::: "memory"); }
;                 }
;                 asm volatile("" ::: "memory");
;             }
;     }
.Lpeel_done_984:
	s_lshl_b32 s0, s40, 8
	s_add_i32 s0, s0, s60
	v_mov_b32_e32 v136, v154
	v_mov_b32_e32 v146, v155
	s_cmp_gt_i32 s8, 3
	s_cselect_b64 s[42:43], -1, 0
	s_lshl_b32 s40, s8, 8
	v_lshl_add_u32 v146, v146, 3, s61
	v_add_u32_e32 v148, s0, v136
	s_add_i32 s0, s40, 0xfffffc00
	v_add_u32_e32 v160, s0, v146
	s_mov_b64 s[8:9], -1
	s_and_b64 vcc, exec, s[42:43]
	s_cbranch_vccz .LBB0_991
	v_cmp_lt_i32_e32 vcc, s68, v148
	s_and_saveexec_b64 s[0:1], vcc
	s_xor_b64 s[8:9], exec, s[0:1]
	v_add_u32_e32 v136, 0xffff8000, v148
	v_mul_hi_u32 v147, v136, s69
	v_lshrrev_b32_e32 v147, 8, v147
	v_mad_i32_i24 v150, v147, s70, v136
	v_lshlrev_b32_e32 v136, 10, v147
	v_mov_b64_e32 v[152:153], s[16:17]
	v_mad_u64_u32 v[152:153], s[0:1], v136, s71, v[152:153]
	v_ashrrev_i32_e32 v151, 31, v150
	v_lshl_add_u64 v[150:151], v[150:151], 1, v[152:153]
	s_or_saveexec_b64 s[8:9], s[8:9]
	v_mov_b64_e32 v[152:153], 0x1020
	s_xor_b64 exec, exec, s[8:9]
	v_ashrrev_i32_e32 v150, 12, v148
	v_ashrrev_i32_e32 v151, 31, v150
	v_lshlrev_b64 v[150:151], 23, v[150:151]
	v_and_b32_e32 v136, 0xfff, v148
	v_lshl_add_u64 v[150:151], s[14:15], 0, v[150:151]
	v_lshlrev_b32_e32 v136, 1, v136
	v_lshl_add_u64 v[150:151], v[150:151], 0, v[136:137]
	v_mov_b64_e32 v[152:153], 0x1000
	s_or_b64 exec, exec, s[8:9]
	v_mad_i64_i32 v[162:163], s[0:1], v152, v160, 0
	v_lshl_add_u64 v[162:163], v[162:163], 1, v[150:151]
	v_lshlrev_b32_e32 v136, 1, v152
	v_cvt_pk_bf16_f32 v147, v124, v125
	v_cvt_pk_bf16_f32 v149, v126, v127
	global_store_short v[162:163], v147, off
	v_lshl_add_u64 v[162:163], v[162:163], 0, v[136:137]
	global_store_short_d16_hi v[162:163], v147, off
	v_lshl_add_u64 v[162:163], v[162:163], 0, v[136:137]
	global_store_short v[162:163], v149, off
	v_lshl_add_u64 v[162:163], v[162:163], 0, v[136:137]
	v_or_b32_e32 v153, 4, v160
	global_store_short_d16_hi v[162:163], v149, off
	v_mad_i64_i32 v[162:163], s[0:1], v152, v153, 0
	v_lshl_add_u64 v[162:163], v[162:163], 1, v[150:151]
	v_cvt_pk_bf16_f32 v147, v120, v121
	v_cvt_pk_bf16_f32 v149, v122, v123
	global_store_short v[162:163], v147, off
	v_lshl_add_u64 v[162:163], v[162:163], 0, v[136:137]
	global_store_short_d16_hi v[162:163], v147, off
	v_lshl_add_u64 v[162:163], v[162:163], 0, v[136:137]
	global_store_short v[162:163], v149, off
	v_lshl_add_u64 v[162:163], v[162:163], 0, v[136:137]
	v_add_u32_e32 v147, 0x80, v160
	global_store_short_d16_hi v[162:163], v149, off
	v_mad_i64_i32 v[162:163], s[0:1], v152, v147, 0
	v_lshl_add_u64 v[162:163], v[162:163], 1, v[150:151]
	v_cvt_pk_bf16_f32 v149, v116, v117
	v_cvt_pk_bf16_f32 v153, v118, v119
	global_store_short v[162:163], v149, off
	v_lshl_add_u64 v[162:163], v[162:163], 0, v[136:137]
	global_store_short_d16_hi v[162:163], v149, off
	v_lshl_add_u64 v[162:163], v[162:163], 0, v[136:137]
	global_store_short v[162:163], v153, off
	v_lshl_add_u64 v[162:163], v[162:163], 0, v[136:137]
	global_store_short_d16_hi v[162:163], v153, off
	v_add_u32_e32 v153, 0x84, v160
	v_mad_i64_i32 v[152:153], s[0:1], v152, v153, 0
	v_lshl_add_u64 v[150:151], v[152:153], 1, v[150:151]
	v_cvt_pk_bf16_f32 v147, v112, v113
	v_cvt_pk_bf16_f32 v149, v114, v115
	global_store_short v[150:151], v147, off
	v_lshl_add_u64 v[150:151], v[150:151], 0, v[136:137]
	global_store_short_d16_hi v[150:151], v147, off
	v_lshl_add_u64 v[150:151], v[150:151], 0, v[136:137]
	global_store_short v[150:151], v149, off
	v_lshl_add_u64 v[150:151], v[150:151], 0, v[136:137]
	global_store_short_d16_hi v[150:151], v149, off
	s_mov_b64 s[8:9], 0

; #define PG8_STAGE(bufoff, gbase, voff) do { _Pragma("unroll") for (int _i = 0; _i < 2; ++_i) \
;         __builtin_amdgcn_global_load_lds((const unsigned*)((const char*)(gbase) + (voff)[_i]), (LAS unsigned*)(lds + (bufoff) + ldsw + _i * 8192), 16, 0, 0); } while (0)
; #define PG8_LDA(dst, b, h) do { _Pragma("unroll") for (int m = 0; m < 4; ++m) _Pragma("unroll") for (int k = 0; k < 2; ++k) dst[m][k] = *(const LAS bf16x8*)(lds + PG8_SA(b, h) + aoff + m * 2048 + k * 1024); } while (0)
; #define PG8_LDB(dst, b, h) do { _Pragma("unroll") for (int n = 0; n < 2; ++n) _Pragma("unroll") for (int k = 0; k < 2; ++k) dst[n][k] = *(const LAS bf16x8*)(lds + PG8_SB(b, h) + boff + n * 2048 + k * 1024); } while (0)
; #define PG8_MMA(ai, bj, At, Bt) do { __builtin_amdgcn_s_setprio(1); _Pragma("unroll") for (int m = 0; m < 4; ++m) _Pragma("unroll") for (int n = 0; n < 2; ++n) _Pragma("unroll") for (int k = 0; k < 2; ++k) \
;         acc[ai][bj][m][n] = __builtin_amdgcn_mfma_f32_16x16x32_bf16(Bt[n][k], At[m][k], acc[ai][bj][m][n], 0, 0, 0); __builtin_amdgcn_s_setprio(0); } while (0)
; #define PG8_WAIT_V(n) asm volatile("s_waitcnt vmcnt(" #n ")" ::: "memory")
; #define PG8_WAIT_L(n) asm volatile("s_waitcnt lgkmcnt(" #n ")" ::: "memory")
; #define PG8_BAR __builtin_amdgcn_s_barrier()
; #define PG8_SCHED __builtin_amdgcn_sched_barrier(0)
; template <class Epi, class Sched>
; DI void gemm_phase(LAS unsigned char* lds, const Gemm g, const Sched& S, const Epi& E) {
;     ...
;             const bool last = (t == nt - 2);
;             const char* a1 = cA + (size_t)(t + 1) * kstep;
;             const char* a2 = last ? nA : cA + (size_t)(t + 2) * kstep; const char* b2 = last ? nB : cB + (size_t)(t + 2) * kstep;
;             const char* a3 = a2 + kstep; const char* b3 = b2 + kstep;
;             PG8_LDB(B0, 0, 0); PG8_SCHED; PG8_LDA(At, 0, 0); PG8_STAGE(PG8_SA(1, 1), a1 + hstep, voffA);
;             PG8_WAIT_L(8); PG8_BAR; PG8_WAIT_L(0); PG8_MMA(0, 0, At, B0); PG8_BAR; PG8_SCHED;
;             PG8_LDB(B1, 0, 1); PG8_STAGE(PG8_SB(0, 0), b2, voffB);
;             PG8_BAR; PG8_WAIT_L(0); PG8_MMA(0, 1, At, B1); PG8_BAR;
;             PG8_LDA(At, 0, 1); PG8_STAGE(PG8_SA(0, 0), a2, voffA);
;             PG8_BAR; PG8_WAIT_L(0); PG8_MMA(1, 0, At, B0); PG8_BAR; PG8_SCHED;
;             PG8_STAGE(PG8_SB(0, 1), b2 + hstep, voffB);
;             PG8_WAIT_V(6); PG8_BAR; PG8_MMA(1, 1, At, B1); PG8_BAR;
.LBB0_1507:
	s_ashr_i32 s37, s36, 31
	s_lshl_b64 s[0:1], s[36:37], 20
	v_cmp_lt_i64_e32 vcc, s[38:39], v[140:141]
	s_add_u32 s38, s13, s0
	s_addc_u32 s39, s50, s1
	s_and_b64 s[0:1], vcc, exec
	s_cselect_b32 s34, s39, s45
	s_cselect_b32 s35, s38, s44
	s_ashr_i32 s31, s30, 31
	s_lshl_b64 s[0:1], s[30:31], 20
	s_add_u32 s40, s55, s0
	s_addc_u32 s41, s56, s1
	s_and_b64 s[0:1], vcc, exec
	s_cselect_b32 s31, s41, s47
	s_cselect_b32 s37, s40, s46
	s_add_u32 s44, s44, 0x80080
	s_addc_u32 s45, s45, 0
	s_add_u32 s43, s46, 0x100
	v_mov_b32_e32 v0, 0
	s_addc_u32 s68, s47, 0
	s_mov_b32 s69, -2
	s_waitcnt lgkmcnt(0)
	ds_read_b128 v[144:147], v150
	ds_read_b128 v[154:157], v150 offset:1024
	ds_read_b128 v[158:161], v150 offset:2048
	ds_read_b128 v[162:165], v150 offset:3072
	s_add_u32 s0, s44, 0xfff80080
	s_addc_u32 s1, s45, -1
	s_cmp_eq_u32 s69, 28
	s_cselect_b32 s49, s34, s1
	s_cselect_b32 s48, s35, s0
	s_cselect_b32 s47, s31, s68
	s_cselect_b32 s46, s37, s43
	v_lshl_add_u64 v[182:183], s[44:45], 0, v[136:137]
	s_add_i32 m0, s52, 0xc000
	ds_read_b128 v[166:169], v151
	ds_read_b128 v[170:173], v151 offset:1024
	ds_read_b128 v[174:177], v151 offset:2048
	ds_read_b128 v[178:181], v151 offset:3072
	ds_read_b128 v[188:191], v151 offset:4096
	ds_read_b128 v[206:209], v151 offset:5120
	ds_read_b128 v[210:213], v151 offset:6144
	ds_read_b128 v[214:217], v151 offset:7168
	global_load_lds_dwordx4 v[182:183], off
	v_lshl_add_u64 v[182:183], s[44:45], 0, v[138:139]
	s_add_i32 m0, s52, 0xe000
	s_nop 0
	global_load_lds_dwordx4 v[182:183], off
	s_waitcnt lgkmcnt(8)
	s_barrier
	s_waitcnt lgkmcnt(0)
	s_setprio 1
	s_waitcnt lgkmcnt(0)
	v_mfma_f32_16x16x32_bf16 v[124:127], v[144:147], v[166:169], 0
	v_mfma_f32_16x16x32_bf16 v[120:123], v[158:161], v[166:169], 0
	v_mfma_f32_16x16x32_bf16 v[108:111], v[144:147], v[174:177], 0
	v_mfma_f32_16x16x32_bf16 v[104:107], v[158:161], v[174:177], 0
	v_mfma_f32_16x16x32_bf16 v[92:95], v[144:147], v[188:191], 0
	v_mfma_f32_16x16x32_bf16 v[88:91], v[158:161], v[188:191], 0
	v_mfma_f32_16x16x32_bf16 v[76:79], v[144:147], v[210:213], 0
	v_mfma_f32_16x16x32_bf16 v[72:75], v[158:161], v[210:213], 0
	v_mfma_f32_16x16x32_bf16 v[124:127], v[154:157], v[170:173], v[124:127]
	v_mfma_f32_16x16x32_bf16 v[120:123], v[162:165], v[170:173], v[120:123]
	v_mfma_f32_16x16x32_bf16 v[108:111], v[154:157], v[178:181], v[108:111]
	v_mfma_f32_16x16x32_bf16 v[104:107], v[162:165], v[178:181], v[104:107]
	v_mfma_f32_16x16x32_bf16 v[92:95], v[154:157], v[206:209], v[92:95]
	v_mfma_f32_16x16x32_bf16 v[88:91], v[162:165], v[206:209], v[88:91]
	v_mfma_f32_16x16x32_bf16 v[76:79], v[154:157], v[214:217], v[76:79]
	v_mfma_f32_16x16x32_bf16 v[72:75], v[162:165], v[214:217], v[72:75]
	s_setprio 0
	s_barrier
	s_add_i32 s0, s65, s51
	v_lshl_add_u64 v[182:183], s[46:47], 0, v[132:133]
	s_mov_b32 m0, s0
	ds_read_b128 v[218:221], v152
	ds_read_b128 v[222:225], v152 offset:1024
	ds_read_b128 v[226:229], v152 offset:2048
	ds_read_b128 v[230:233], v152 offset:3072
	global_load_lds_dwordx4 v[182:183], off
	v_lshl_add_u64 v[202:203], s[46:47], 0, v[134:135]
	s_add_i32 m0, s0, 0x2000
	s_nop 0
	global_load_lds_dwordx4 v[202:203], off
	s_barrier
	s_waitcnt lgkmcnt(0)
	s_setprio 1
	s_waitcnt lgkmcnt(0)
	v_mfma_f32_16x16x32_bf16 v[116:119], v[218:221], v[166:169], 0
	v_mfma_f32_16x16x32_bf16 v[112:115], v[226:229], v[166:169], 0
	v_mfma_f32_16x16x32_bf16 v[100:103], v[218:221], v[174:177], 0
	v_mfma_f32_16x16x32_bf16 v[96:99], v[226:229], v[174:177], 0
	v_mfma_f32_16x16x32_bf16 v[84:87], v[218:221], v[188:191], 0
	v_mfma_f32_16x16x32_bf16 v[80:83], v[226:229], v[188:191], 0
	v_mfma_f32_16x16x32_bf16 v[68:71], v[218:221], v[210:213], 0
	v_mfma_f32_16x16x32_bf16 v[64:67], v[226:229], v[210:213], 0
	v_mfma_f32_16x16x32_bf16 v[116:119], v[222:225], v[170:173], v[116:119]
	v_mfma_f32_16x16x32_bf16 v[112:115], v[230:233], v[170:173], v[112:115]
	v_mfma_f32_16x16x32_bf16 v[100:103], v[222:225], v[178:181], v[100:103]
	v_mfma_f32_16x16x32_bf16 v[96:99], v[230:233], v[178:181], v[96:99]
	v_mfma_f32_16x16x32_bf16 v[84:87], v[222:225], v[206:209], v[84:87]
	v_mfma_f32_16x16x32_bf16 v[80:83], v[230:233], v[206:209], v[80:83]
	v_mfma_f32_16x16x32_bf16 v[68:71], v[222:225], v[214:217], v[68:71]
	v_mfma_f32_16x16x32_bf16 v[64:67], v[230:233], v[214:217], v[64:67]
	s_setprio 0
	s_mov_b32 m0, s52
	v_lshl_add_u64 v[234:235], s[48:49], 0, v[128:129]
	s_barrier
	ds_read_b128 v[166:169], v151 offset:16384
	ds_read_b128 v[170:173], v151 offset:17408
	ds_read_b128 v[174:177], v151 offset:18432
	ds_read_b128 v[178:181], v151 offset:19456
	ds_read_b128 v[188:191], v151 offset:20480
	ds_read_b128 v[206:209], v151 offset:21504
	ds_read_b128 v[210:213], v151 offset:22528
	ds_read_b128 v[214:217], v151 offset:23552
	global_load_lds_dwordx4 v[234:235], off
	v_lshl_add_u64 v[236:237], s[48:49], 0, v[130:131]
	s_mov_b32 m0, s53
	s_nop 0
	global_load_lds_dwordx4 v[236:237], off
	s_barrier
	s_waitcnt lgkmcnt(0)
	s_setprio 1
	s_waitcnt lgkmcnt(0)
	v_mfma_f32_16x16x32_bf16 v[60:63], v[144:147], v[166:169], 0
	v_mfma_f32_16x16x32_bf16 v[56:59], v[158:161], v[166:169], 0
	v_mfma_f32_16x16x32_bf16 v[44:47], v[144:147], v[174:177], 0
	v_mfma_f32_16x16x32_bf16 v[40:43], v[158:161], v[174:177], 0
	v_mfma_f32_16x16x32_bf16 v[28:31], v[144:147], v[188:191], 0
	v_mfma_f32_16x16x32_bf16 v[24:27], v[158:161], v[188:191], 0
	v_mfma_f32_16x16x32_bf16 v[12:15], v[144:147], v[210:213], 0
	v_mfma_f32_16x16x32_bf16 v[8:11], v[158:161], v[210:213], 0
	v_mfma_f32_16x16x32_bf16 v[60:63], v[154:157], v[170:173], v[60:63]
	v_mfma_f32_16x16x32_bf16 v[56:59], v[162:165], v[170:173], v[56:59]
	v_mfma_f32_16x16x32_bf16 v[44:47], v[154:157], v[178:181], v[44:47]
	v_mfma_f32_16x16x32_bf16 v[40:43], v[162:165], v[178:181], v[40:43]
	v_mfma_f32_16x16x32_bf16 v[28:31], v[154:157], v[206:209], v[28:31]
	v_mfma_f32_16x16x32_bf16 v[24:27], v[162:165], v[206:209], v[24:27]
	v_mfma_f32_16x16x32_bf16 v[12:15], v[154:157], v[214:217], v[12:15]
	v_mfma_f32_16x16x32_bf16 v[8:11], v[162:165], v[214:217], v[8:11]
	s_setprio 0
	s_barrier
; #define PG8_STAGE(bufoff, gbase, voff) do { _Pragma("unroll") for (int _i = 0; _i < 2; ++_i) \
;         __builtin_amdgcn_global_load_lds((const unsigned*)((const char*)(gbase) + (voff)[_i]), (LAS unsigned*)(lds + (bufoff) + ldsw + _i * 8192), 16, 0, 0); } while (0)
; #define PG8_LDA(dst, b, h) do { _Pragma("unroll") for (int m = 0; m < 4; ++m) _Pragma("unroll") for (int k = 0; k < 2; ++k) dst[m][k] = *(const LAS bf16x8*)(lds + PG8_SA(b, h) + aoff + m * 2048 + k * 1024); } while (0)
; #define PG8_LDB(dst, b, h) do { _Pragma("unroll") for (int n = 0; n < 2; ++n) _Pragma("unroll") for (int k = 0; k < 2; ++k) dst[n][k] = *(const LAS bf16x8*)(lds + PG8_SB(b, h) + boff + n * 2048 + k * 1024); } while (0)
; #define PG8_MMA(ai, bj, At, Bt) do { __builtin_amdgcn_s_setprio(1); _Pragma("unroll") for (int m = 0; m < 4; ++m) _Pragma("unroll") for (int n = 0; n < 2; ++n) _Pragma("unroll") for (int k = 0; k < 2; ++k) \
;         acc[ai][bj][m][n] = __builtin_amdgcn_mfma_f32_16x16x32_bf16(Bt[n][k], At[m][k], acc[ai][bj][m][n], 0, 0, 0); __builtin_amdgcn_s_setprio(0); } while (0)
; #define PG8_WAIT_V(n) asm volatile("s_waitcnt vmcnt(" #n ")" ::: "memory")
; #define PG8_WAIT_L(n) asm volatile("s_waitcnt lgkmcnt(" #n ")" ::: "memory")
; #define PG8_BAR __builtin_amdgcn_s_barrier()
; #define PG8_SCHED __builtin_amdgcn_sched_barrier(0)
; template <class Epi, class Sched>
; DI void gemm_phase(LAS unsigned char* lds, const Gemm g, const Sched& S, const Epi& E) {
;     ...
;             PG8_STAGE(PG8_SB(0, 1), b2 + hstep, voffB);
;             PG8_WAIT_V(6); PG8_BAR; PG8_MMA(1, 1, At, B1); PG8_BAR;
;             PG8_LDB(B0, 1, 0); PG8_SCHED; PG8_LDA(At, 1, 0); PG8_STAGE(PG8_SA(0, 1), a2 + hstep, voffA);
;             PG8_WAIT_L(8); PG8_BAR; PG8_WAIT_L(0); PG8_MMA(0, 0, At, B0); PG8_BAR; PG8_SCHED;
;             PG8_LDB(B1, 1, 1); PG8_STAGE(PG8_SB(1, 0), b3, voffB);
;             PG8_BAR; PG8_WAIT_L(0); PG8_MMA(0, 1, At, B1); PG8_BAR;
;             PG8_LDA(At, 1, 1); PG8_STAGE(PG8_SA(1, 0), a3, voffA);
;             PG8_BAR; PG8_WAIT_L(0); PG8_MMA(1, 0, At, B0); PG8_BAR; PG8_SCHED;
	s_add_u32 s0, s46, 0x80000
	s_addc_u32 s1, s47, 0
	s_add_i32 s4, s66, s51
	v_lshl_add_u64 v[144:145], s[0:1], 0, v[132:133]
	s_mov_b32 m0, s4
	s_nop 0
	global_load_lds_dwordx4 v[144:145], off
	v_lshl_add_u64 v[144:145], s[0:1], 0, v[134:135]
	s_add_i32 m0, s4, 0x2000
	s_nop 0
	global_load_lds_dwordx4 v[144:145], off
	s_waitcnt vmcnt(6)
	s_barrier
	s_setprio 1
	v_mfma_f32_16x16x32_bf16 v[52:55], v[218:221], v[166:169], 0
	v_mfma_f32_16x16x32_bf16 v[48:51], v[226:229], v[166:169], 0
	v_mfma_f32_16x16x32_bf16 v[36:39], v[218:221], v[174:177], 0
	v_mfma_f32_16x16x32_bf16 v[32:35], v[226:229], v[174:177], 0
	v_mfma_f32_16x16x32_bf16 v[20:23], v[218:221], v[188:191], 0
	v_mfma_f32_16x16x32_bf16 v[16:19], v[226:229], v[188:191], 0
	v_mfma_f32_16x16x32_bf16 v[4:7], v[218:221], v[210:213], 0
	v_mfma_f32_16x16x32_bf16 v[0:3], v[226:229], v[210:213], 0
	v_mfma_f32_16x16x32_bf16 v[52:55], v[222:225], v[170:173], v[52:55]
	v_mfma_f32_16x16x32_bf16 v[48:51], v[230:233], v[170:173], v[48:51]
	v_mfma_f32_16x16x32_bf16 v[36:39], v[222:225], v[178:181], v[36:39]
	v_mfma_f32_16x16x32_bf16 v[32:35], v[230:233], v[178:181], v[32:35]
	v_mfma_f32_16x16x32_bf16 v[20:23], v[222:225], v[206:209], v[20:23]
	v_mfma_f32_16x16x32_bf16 v[16:19], v[230:233], v[206:209], v[16:19]
	v_mfma_f32_16x16x32_bf16 v[4:7], v[222:225], v[214:217], v[4:7]
	v_mfma_f32_16x16x32_bf16 v[0:3], v[230:233], v[214:217], v[0:3]
	s_setprio 0
	s_add_i32 s4, 0, 0x18000
	v_add_u32_e32 v162, s4, v149
	s_barrier
	ds_read_b128 v[144:147], v162
	ds_read_b128 v[154:157], v162 offset:1024
	ds_read_b128 v[158:161], v162 offset:2048
	ds_read_b128 v[162:165], v162 offset:3072
	s_add_u32 s0, s48, 0x80000
	s_addc_u32 s1, s49, 0
	s_mov_b32 m0, s58
	v_lshl_add_u64 v[218:219], s[0:1], 0, v[128:129]
	ds_read_b128 v[166:169], v151 offset:32768
	ds_read_b128 v[170:173], v151 offset:33792
	ds_read_b128 v[174:177], v151 offset:34816
	ds_read_b128 v[178:181], v151 offset:35840
	ds_read_b128 v[188:191], v151 offset:36864
	ds_read_b128 v[206:209], v151 offset:37888
	ds_read_b128 v[210:213], v151 offset:38912
	ds_read_b128 v[214:217], v151 offset:39936
	global_load_lds_dwordx4 v[218:219], off
	v_lshl_add_u64 v[218:219], s[0:1], 0, v[130:131]
	s_mov_b32 m0, s59
	s_nop 0
	global_load_lds_dwordx4 v[218:219], off
	s_waitcnt lgkmcnt(8)
	s_barrier
	s_waitcnt lgkmcnt(0)
	s_setprio 1
	s_waitcnt lgkmcnt(0)
	v_mfma_f32_16x16x32_bf16 v[124:127], v[144:147], v[166:169], v[124:127]
	v_mfma_f32_16x16x32_bf16 v[120:123], v[158:161], v[166:169], v[120:123]
	v_mfma_f32_16x16x32_bf16 v[108:111], v[144:147], v[174:177], v[108:111]
	v_mfma_f32_16x16x32_bf16 v[104:107], v[158:161], v[174:177], v[104:107]
	v_mfma_f32_16x16x32_bf16 v[92:95], v[144:147], v[188:191], v[92:95]
	v_mfma_f32_16x16x32_bf16 v[88:91], v[158:161], v[188:191], v[88:91]
	v_mfma_f32_16x16x32_bf16 v[76:79], v[144:147], v[210:213], v[76:79]
	v_mfma_f32_16x16x32_bf16 v[72:75], v[158:161], v[210:213], v[72:75]
	v_mfma_f32_16x16x32_bf16 v[124:127], v[154:157], v[170:173], v[124:127]
	v_mfma_f32_16x16x32_bf16 v[120:123], v[162:165], v[170:173], v[120:123]
	v_mfma_f32_16x16x32_bf16 v[108:111], v[154:157], v[178:181], v[108:111]
	v_mfma_f32_16x16x32_bf16 v[104:107], v[162:165], v[178:181], v[104:107]
	v_mfma_f32_16x16x32_bf16 v[92:95], v[154:157], v[206:209], v[92:95]
	v_mfma_f32_16x16x32_bf16 v[88:91], v[162:165], v[206:209], v[88:91]
	v_mfma_f32_16x16x32_bf16 v[76:79], v[154:157], v[214:217], v[76:79]
	v_mfma_f32_16x16x32_bf16 v[72:75], v[162:165], v[214:217], v[72:75]
	s_setprio 0
	s_barrier
	s_add_i32 s5, 0, 0x1c000
	s_add_i32 s0, s4, s51
	v_add_u32_e32 v201, s5, v149
	v_lshl_add_u64 v[182:183], v[182:183], 0, s[28:29]
	s_mov_b32 m0, s0
	ds_read_b128 v[218:221], v201
	ds_read_b128 v[222:225], v201 offset:1024
	ds_read_b128 v[226:229], v201 offset:2048
	ds_read_b128 v[230:233], v201 offset:3072
	global_load_lds_dwordx4 v[182:183], off
	v_lshl_add_u64 v[182:183], v[202:203], 0, s[28:29]
	s_add_i32 m0, s0, 0x2000
	s_nop 0
	global_load_lds_dwordx4 v[182:183], off
	s_barrier
; #define PG8_STAGE(bufoff, gbase, voff) do { _Pragma("unroll") for (int _i = 0; _i < 2; ++_i) \
;         __builtin_amdgcn_global_load_lds((const unsigned*)((const char*)(gbase) + (voff)[_i]), (LAS unsigned*)(lds + (bufoff) + ldsw + _i * 8192), 16, 0, 0); } while (0)
; #define PG8_LDA(dst, b, h) do { _Pragma("unroll") for (int m = 0; m < 4; ++m) _Pragma("unroll") for (int k = 0; k < 2; ++k) dst[m][k] = *(const LAS bf16x8*)(lds + PG8_SA(b, h) + aoff + m * 2048 + k * 1024); } while (0)
; #define PG8_MMA(ai, bj, At, Bt) do { __builtin_amdgcn_s_setprio(1); _Pragma("unroll") for (int m = 0; m < 4; ++m) _Pragma("unroll") for (int n = 0; n < 2; ++n) _Pragma("unroll") for (int k = 0; k < 2; ++k) \
;         acc[ai][bj][m][n] = __builtin_amdgcn_mfma_f32_16x16x32_bf16(Bt[n][k], At[m][k], acc[ai][bj][m][n], 0, 0, 0); __builtin_amdgcn_s_setprio(0); } while (0)
; #define PG8_WAIT_V(n) asm volatile("s_waitcnt vmcnt(" #n ")" ::: "memory")
; #define PG8_WAIT_L(n) asm volatile("s_waitcnt lgkmcnt(" #n ")" ::: "memory")
; #define PG8_BAR __builtin_amdgcn_s_barrier()
; #define PG8_SCHED __builtin_amdgcn_sched_barrier(0)
; template <class Epi, class Sched>
; DI void gemm_phase(LAS unsigned char* lds, const Gemm g, const Sched& S, const Epi& E) {
;     ...
;             PG8_BAR; PG8_WAIT_L(0); PG8_MMA(0, 1, At, B1); PG8_BAR;
;             PG8_LDA(At, 1, 1); PG8_STAGE(PG8_SA(1, 0), a3, voffA);
;             PG8_BAR; PG8_WAIT_L(0); PG8_MMA(1, 0, At, B0); PG8_BAR; PG8_SCHED;
;             PG8_STAGE(PG8_SB(1, 1), b3 + hstep, voffB);
;             PG8_WAIT_V(6); PG8_BAR; PG8_MMA(1, 1, At, B1); PG8_BAR;
	s_waitcnt lgkmcnt(0)
	s_setprio 1
	s_waitcnt lgkmcnt(0)
	v_mfma_f32_16x16x32_bf16 v[116:119], v[218:221], v[166:169], v[116:119]
	v_mfma_f32_16x16x32_bf16 v[112:115], v[226:229], v[166:169], v[112:115]
	v_mfma_f32_16x16x32_bf16 v[100:103], v[218:221], v[174:177], v[100:103]
	v_mfma_f32_16x16x32_bf16 v[96:99], v[226:229], v[174:177], v[96:99]
	v_mfma_f32_16x16x32_bf16 v[84:87], v[218:221], v[188:191], v[84:87]
	v_mfma_f32_16x16x32_bf16 v[80:83], v[226:229], v[188:191], v[80:83]
	v_mfma_f32_16x16x32_bf16 v[68:71], v[218:221], v[210:213], v[68:71]
	v_mfma_f32_16x16x32_bf16 v[64:67], v[226:229], v[210:213], v[64:67]
	v_mfma_f32_16x16x32_bf16 v[116:119], v[222:225], v[170:173], v[116:119]
	v_mfma_f32_16x16x32_bf16 v[112:115], v[230:233], v[170:173], v[112:115]
	v_mfma_f32_16x16x32_bf16 v[100:103], v[222:225], v[178:181], v[100:103]
	v_mfma_f32_16x16x32_bf16 v[96:99], v[230:233], v[178:181], v[96:99]
	v_mfma_f32_16x16x32_bf16 v[84:87], v[222:225], v[206:209], v[84:87]
	v_mfma_f32_16x16x32_bf16 v[80:83], v[230:233], v[206:209], v[80:83]
	v_mfma_f32_16x16x32_bf16 v[68:71], v[222:225], v[214:217], v[68:71]
	v_mfma_f32_16x16x32_bf16 v[64:67], v[230:233], v[214:217], v[64:67]
	s_setprio 0
	s_mov_b32 m0, s63
	v_lshl_add_u64 v[182:183], v[234:235], 0, s[28:29]
	s_barrier
	ds_read_b128 v[166:169], v151 offset:49152
	ds_read_b128 v[170:173], v151 offset:50176
	ds_read_b128 v[174:177], v151 offset:51200
	ds_read_b128 v[178:181], v151 offset:52224
	ds_read_b128 v[188:191], v151 offset:53248
	ds_read_b128 v[206:209], v151 offset:54272
	ds_read_b128 v[210:213], v151 offset:55296
	ds_read_b128 v[214:217], v151 offset:56320
	global_load_lds_dwordx4 v[182:183], off
	v_lshl_add_u64 v[182:183], v[236:237], 0, s[28:29]
	s_mov_b32 m0, s64
	s_nop 0
	global_load_lds_dwordx4 v[182:183], off
	s_barrier
	s_waitcnt lgkmcnt(0)
	s_setprio 1
	s_waitcnt lgkmcnt(0)
	v_mfma_f32_16x16x32_bf16 v[60:63], v[144:147], v[166:169], v[60:63]
	v_mfma_f32_16x16x32_bf16 v[56:59], v[158:161], v[166:169], v[56:59]
	v_mfma_f32_16x16x32_bf16 v[44:47], v[144:147], v[174:177], v[44:47]
	v_mfma_f32_16x16x32_bf16 v[40:43], v[158:161], v[174:177], v[40:43]
	v_mfma_f32_16x16x32_bf16 v[28:31], v[144:147], v[188:191], v[28:31]
	v_mfma_f32_16x16x32_bf16 v[24:27], v[158:161], v[188:191], v[24:27]
	v_mfma_f32_16x16x32_bf16 v[12:15], v[144:147], v[210:213], v[12:15]
	v_mfma_f32_16x16x32_bf16 v[8:11], v[158:161], v[210:213], v[8:11]
	v_mfma_f32_16x16x32_bf16 v[60:63], v[154:157], v[170:173], v[60:63]
	v_mfma_f32_16x16x32_bf16 v[56:59], v[162:165], v[170:173], v[56:59]
	v_mfma_f32_16x16x32_bf16 v[44:47], v[154:157], v[178:181], v[44:47]
	v_mfma_f32_16x16x32_bf16 v[40:43], v[162:165], v[178:181], v[40:43]
	v_mfma_f32_16x16x32_bf16 v[28:31], v[154:157], v[206:209], v[28:31]
	v_mfma_f32_16x16x32_bf16 v[24:27], v[162:165], v[206:209], v[24:27]
	v_mfma_f32_16x16x32_bf16 v[12:15], v[154:157], v[214:217], v[12:15]
	v_mfma_f32_16x16x32_bf16 v[8:11], v[162:165], v[214:217], v[8:11]
	s_setprio 0
	s_barrier
	s_add_u32 s0, s46, 0x80080
	s_addc_u32 s1, s47, 0
	s_add_i32 s4, s5, s51
	v_lshl_add_u64 v[144:145], s[0:1], 0, v[132:133]
	s_mov_b32 m0, s4
	s_nop 0
	global_load_lds_dwordx4 v[144:145], off
	v_lshl_add_u64 v[144:145], s[0:1], 0, v[134:135]
	s_add_i32 m0, s4, 0x2000
	s_nop 0
	global_load_lds_dwordx4 v[144:145], off
	s_waitcnt vmcnt(6)
	s_barrier
	s_setprio 1
	v_mfma_f32_16x16x32_bf16 v[52:55], v[218:221], v[166:169], v[52:55]
	v_mfma_f32_16x16x32_bf16 v[48:51], v[226:229], v[166:169], v[48:51]
	v_mfma_f32_16x16x32_bf16 v[36:39], v[218:221], v[174:177], v[36:39]
	v_mfma_f32_16x16x32_bf16 v[32:35], v[226:229], v[174:177], v[32:35]
	v_mfma_f32_16x16x32_bf16 v[20:23], v[218:221], v[188:191], v[20:23]
	v_mfma_f32_16x16x32_bf16 v[16:19], v[226:229], v[188:191], v[16:19]
	v_mfma_f32_16x16x32_bf16 v[4:7], v[218:221], v[210:213], v[4:7]
	v_mfma_f32_16x16x32_bf16 v[0:3], v[226:229], v[210:213], v[0:3]
	v_mfma_f32_16x16x32_bf16 v[52:55], v[222:225], v[170:173], v[52:55]
	v_mfma_f32_16x16x32_bf16 v[48:51], v[230:233], v[170:173], v[48:51]
	v_mfma_f32_16x16x32_bf16 v[36:39], v[222:225], v[178:181], v[36:39]
	v_mfma_f32_16x16x32_bf16 v[32:35], v[230:233], v[178:181], v[32:35]
	v_mfma_f32_16x16x32_bf16 v[20:23], v[222:225], v[206:209], v[20:23]
	v_mfma_f32_16x16x32_bf16 v[16:19], v[230:233], v[206:209], v[16:19]
	v_mfma_f32_16x16x32_bf16 v[4:7], v[222:225], v[214:217], v[4:7]
	v_mfma_f32_16x16x32_bf16 v[0:3], v[230:233], v[214:217], v[0:3]
	s_setprio 0
	s_add_i32 s69, s69, 2
	s_add_u32 s44, s44, 0x100
	s_addc_u32 s45, s45, 0
	s_add_u32 s43, s43, 0x100
	s_addc_u32 s68, s68, 0
	s_cmp_gt_u32 s69, 29
	s_barrier
	s_cbranch_scc0 .LBB0_1508
	s_branch .Lpeel_done_1508

; DI float bf_lo(unsigned u) { return __uint_as_float(u << 16); }
; DI float bf_hi(unsigned u) { return __uint_as_float(u & 0xffff0000u); }
; DI u32x4 pack8(f32x4 a, f32x4 b) { u32x4 w; w.x = cvt_pk_bf16(a[0], a[1]); w.y = cvt_pk_bf16(a[2], a[3]); w.z = cvt_pk_bf16(b[0], b[1]); w.w = cvt_pk_bf16(b[2], b[3]); return w; }
;     DI void operator()(AccRef acc, const Unit& u, int wr, int wc, int fr, int fq) const {
;         const int col0 = u.pn * 256 + wc * 32 + 8 * fq;
; #pragma unroll
;         for (int ai = 0; ai < 2; ++ai)
; #pragma unroll
;             for (int m = 0; m < 4; ++m) { const int row = u.pm * 256 + ai * 128 + wr * 64 + m * 16 + fr; const size_t off = (size_t)row * DM + col0; float q = 0.f;
; #pragma unroll
;                 for (int bj = 0; bj < 2; ++bj) {
;                     f32x4 b0, b1;
;                     if (F32BASE) { b0 = *(const f32x4*)(bp + off + bj * 128); b1 = *(const f32x4*)(bp + off + bj * 128 + 4); }
;                     else { const u32x4 uv = *(const u32x4*)(Ui + off + bj * 128); b0 = (f32x4){bf_lo(uv.x), bf_hi(uv.x), bf_lo(uv.y), bf_hi(uv.y)}; b1 = (f32x4){bf_lo(uv.z), bf_hi(uv.z), bf_lo(uv.w), bf_hi(uv.w)}; }
;                     const u32x4 w = pack8(b0 + acc[ai][bj][m][0] * (0.5f * S2), b1 + acc[ai][bj][m][1] * (0.5f * S2));
;                     *(u32x4*)(Uo + (size_t)row * ldo + col0 + bj * 128) = w;
;                     const float r0 = bf_lo(w.x), r1 = bf_hi(w.x), r2 = bf_lo(w.y), r3 = bf_hi(w.y), r4 = bf_lo(w.z), r5 = bf_hi(w.z), r6 = bf_lo(w.w), r7 = bf_hi(w.w);
;                     q += (r0 * r0 + r1 * r1) + (r2 * r2 + r3 * r3) + (r4 * r4 + r5 * r5) + (r6 * r6 + r7 * r7); }
;                 q += __shfl_xor(q, 16); q += __shfl_xor(q, 32); if (fq == 0) ssp[(size_t)row * 32 + u.pn * 4 + wc] = q; }
;     }
.Lpeel_done_1508:
	s_lshl_b32 s0, s14, 8
	v_mov_b32_e32 v145, v194
	v_mov_b32_e32 v164, v192
	s_or_b32 s0, s0, s62
	s_nop 0
	v_lshl_add_u32 v144, v164, 3, s0
	s_lshl_b32 s0, s42, 8
	s_add_i32 s0, s0, s61
	v_add_u32_e32 v146, s0, v145
	v_ashrrev_i32_e32 v147, 31, v146
	v_lshlrev_b64 v[154:155], 12, v[146:147]
	v_ashrrev_i32_e32 v145, 31, v144
	v_lshl_add_u64 v[154:155], s[16:17], 0, v[154:155]
	v_lshl_add_u64 v[158:159], v[144:145], 1, v[154:155]
	v_mov_b64_e32 v[182:183], v[158:159]
	s_mov_b32 s47, 0
	global_load_dwordx4 v[166:169], v[182:183], off
	global_load_dwordx4 v[170:173], v[182:183], off offset:256
	s_mov_b32 s46, 0x10000
	v_lshl_add_u64 v[182:183], v[182:183], 0, s[46:47]
	global_load_dwordx4 v[174:177], v[182:183], off
	global_load_dwordx4 v[178:181], v[182:183], off offset:256
	s_mov_b32 s46, 0x10000
	v_lshl_add_u64 v[182:183], v[182:183], 0, s[46:47]
	global_load_dwordx4 v[188:191], v[182:183], off
	global_load_dwordx4 v[206:209], v[182:183], off offset:256
	s_mov_b32 s46, 0x10000
	v_lshl_add_u64 v[182:183], v[182:183], 0, s[46:47]
	global_load_dwordx4 v[210:213], v[182:183], off
	global_load_dwordx4 v[214:217], v[182:183], off offset:256
	s_mov_b32 s46, 0x50000
	v_lshl_add_u64 v[182:183], v[182:183], 0, s[46:47]
	global_load_dwordx4 v[218:221], v[182:183], off
	global_load_dwordx4 v[222:225], v[182:183], off offset:256
	s_mov_b32 s46, 0x10000
	v_lshl_add_u64 v[182:183], v[182:183], 0, s[46:47]
	global_load_dwordx4 v[226:229], v[182:183], off
	global_load_dwordx4 v[230:233], v[182:183], off offset:256
	s_mov_b32 s46, 0x10000
	v_lshl_add_u64 v[182:183], v[182:183], 0, s[46:47]
	global_load_dwordx4 v[234:237], v[182:183], off
	global_load_dwordx4 v[238:241], v[182:183], off offset:256
	v_mov_b64_e32 v[202:203], v[182:183]
	s_mov_b32 s46, 0x10000
	v_lshl_add_u64 v[202:203], v[202:203], 0, s[46:47]
	global_load_dword v165, v[202:203], off
	global_load_dword v165, v[202:203], off offset:256
	s_waitcnt vmcnt(15)
	v_mov_b64_e32 v[154:155], v[166:167]
	v_mov_b64_e32 v[156:157], v[168:169]
	s_mov_b32 s46, 0x10000
	v_lshl_add_u64 v[182:183], v[182:183], 0, s[46:47]
	global_load_dwordx4 v[166:169], v[182:183], off
	s_lshl_b32 s42, s14, 2
	s_ashr_i32 s43, s42, 31
	v_lshlrev_b32_e32 v160, 16, v154
	v_and_b32_e32 v161, 0xffff0000, v154
	v_lshlrev_b32_e32 v154, 16, v155
	v_and_b32_e32 v155, 0xffff0000, v155
	v_lshlrev_b32_e32 v162, 16, v156
	v_and_b32_e32 v163, 0xffff0000, v156
	v_lshlrev_b32_e32 v156, 16, v157
	v_and_b32_e32 v157, 0xffff0000, v157
	v_pk_add_f32 v[126:127], v[126:127], v[154:155]
	v_pk_add_f32 v[124:125], v[124:125], v[160:161]
	v_pk_add_f32 v[154:155], v[122:123], v[156:157]
	v_pk_add_f32 v[120:121], v[120:121], v[162:163]
	v_cvt_pk_bf16_f32 v122, v124, v125
	v_cvt_pk_bf16_f32 v123, v126, v127
	s_nop 0
	v_cvt_pk_bf16_f32 v124, v120, v121
	v_cvt_pk_bf16_f32 v125, v154, v155
	s_waitcnt vmcnt(15)
	v_mov_b64_e32 v[154:155], v[170:171]
	v_mov_b64_e32 v[156:157], v[172:173]
	global_load_dwordx4 v[170:173], v[182:183], off offset:256
	v_lshlrev_b32_e32 v126, 16, v122
	global_store_dwordx4 v[158:159], v[122:125], off
	v_lshlrev_b32_e32 v127, 16, v123
	v_lshlrev_b32_e32 v160, 16, v124
	v_and_b32_e32 v122, 0xffff0000, v122
	v_and_b32_e32 v123, 0xffff0000, v123
	v_and_b32_e32 v124, 0xffff0000, v124
	v_mul_f32_e32 v122, v122, v122
	v_mul_f32_e32 v123, v123, v123
	v_lshlrev_b32_e32 v161, 16, v125
	v_and_b32_e32 v125, 0xffff0000, v125
	v_mul_f32_e32 v124, v124, v124
	v_fmac_f32_e32 v122, v126, v126
	v_fmac_f32_e32 v123, v127, v127
	v_mul_f32_e32 v125, v125, v125
	v_fmac_f32_e32 v124, v160, v160
	v_add_f32_e32 v122, v122, v123
	v_fmac_f32_e32 v125, v161, v161
	v_add_f32_e32 v122, v122, v124
	v_add_f32_e32 v160, v122, v125
	v_and_b32_e32 v121, 64, v153
	v_xor_b32_e32 v120, 16, v153
	v_add_u32_e32 v121, 64, v121
	v_cmp_lt_i32_e32 vcc, v120, v121
	v_lshlrev_b32_e32 v122, 16, v154
	v_and_b32_e32 v123, 0xffff0000, v154
	v_lshlrev_b32_e32 v124, 16, v155
	v_and_b32_e32 v125, 0xffff0000, v155
	v_lshlrev_b32_e32 v126, 16, v156
	v_and_b32_e32 v127, 0xffff0000, v156
	v_lshlrev_b32_e32 v154, 16, v157
	v_and_b32_e32 v155, 0xffff0000, v157
	v_pk_add_f32 v[118:119], v[118:119], v[124:125]
	v_pk_add_f32 v[116:117], v[116:117], v[122:123]
	v_pk_add_f32 v[114:115], v[114:115], v[154:155]
	v_pk_add_f32 v[112:113], v[112:113], v[126:127]
	v_cvt_pk_bf16_f32 v116, v116, v117
	v_cvt_pk_bf16_f32 v117, v118, v119
	v_cndmask_b32_e32 v120, v153, v120, vcc
	v_cvt_pk_bf16_f32 v118, v112, v113
	v_cvt_pk_bf16_f32 v119, v114, v115
	v_and_b32_e32 v113, 0xffff0000, v116
	v_and_b32_e32 v115, 0xffff0000, v117
	v_lshlrev_b32_e32 v112, 16, v116
	v_lshlrev_b32_e32 v114, 16, v117
	v_and_b32_e32 v123, 0xffff0000, v118
	v_mul_f32_e32 v113, v113, v113
	v_mul_f32_e32 v115, v115, v115
	v_lshlrev_b32_e32 v122, 16, v118
	v_and_b32_e32 v125, 0xffff0000, v119
	v_mul_f32_e32 v123, v123, v123
	v_fmac_f32_e32 v113, v112, v112
	v_fmac_f32_e32 v115, v114, v114
	v_lshlrev_b32_e32 v124, 16, v119
	v_mul_f32_e32 v125, v125, v125
	v_fmac_f32_e32 v123, v122, v122
	v_add_f32_e32 v112, v113, v115
	v_fmac_f32_e32 v125, v124, v124
	v_add_f32_e32 v112, v112, v123
	v_add_f32_e32 v112, v112, v125
	v_lshlrev_b32_e32 v120, 2, v120
	v_add_f32_e32 v112, v160, v112
	ds_bpermute_b32 v113, v120, v112
	v_xor_b32_e32 v114, 32, v153
	v_cmp_lt_i32_e32 vcc, v114, v121
	global_store_dwordx4 v[158:159], v[116:119], off offset:256
	s_waitcnt lgkmcnt(0)
	v_add_f32_e32 v112, v112, v113
	v_cndmask_b32_e32 v114, v153, v114, vcc
	v_lshlrev_b32_e32 v114, 2, v114
	ds_bpermute_b32 v113, v114, v112
	v_cmp_eq_u32_e32 vcc, 0, v164
	s_and_saveexec_b64 s[44:45], vcc
	s_cbranch_execz .LBB0_1511
	v_lshlrev_b64 v[116:117], 7, v[146:147]
	v_lshl_add_u64 v[116:117], s[18:19], 0, v[116:117]
	v_lshl_add_u64 v[116:117], s[42:43], 2, v[116:117]
	s_lshl_b32 s14, s60, 2
	v_lshl_add_u64 v[116:117], v[116:117], 0, s[14:15]
	s_waitcnt lgkmcnt(0)
	v_add_f32_e32 v112, v112, v113
	global_store_dword v[116:117], v112, off

;     DI size_t aoff(const Unit& u, size_t tstep) const { return (size_t)u.pm * tstep; }
;     DI size_t boff(const Unit& u, size_t tstep) const { return (size_t)u.pn * tstep; }
;     DI size_t aoff(const Unit& u, size_t) const { return (size_t)u.ks * kbytes; }
; template <class Epi, class Sched>
; DI void gemm_phase(LAS unsigned char* lds, const Gemm g, const Sched& S, const Epi& E) {
;     ...
;         const bool has_next = S.next(ui + 1, nxt);
;         const char* nA = has_next ? (const char*)g.A + S.aoff(nxt, tstep) : cA; const char* nB = has_next ? (const char*)g.Bt + S.boff(nxt, tstep) : cB;
;         for (int t = 0; t < nt; t += 2) {
;             if constexpr (Epi::HAS_MID) { if (t == E.mid_t(nt)) { int fr3 = fr, fq3 = fq; asm volatile("" : "+v"(fr3), "+v"(fq3)); E.mid(acc, cur, wr, wc, fr3, fq3); } }
;             const bool last = (t == nt - 2);
;             const char* a1 = cA + (size_t)(t + 1) * kstep;
;             const char* a2 = last ? nA : cA + (size_t)(t + 2) * kstep; const char* b2 = last ? nB : cB + (size_t)(t + 2) * kstep;
;             const char* a3 = a2 + kstep; const char* b3 = b2 + kstep;
;             PG8_LDB(B0, 0, 0); PG8_SCHED; PG8_LDA(At, 0, 0); PG8_STAGE(PG8_SA(1, 1), a1 + hstep, voffA);
;             PG8_WAIT_L(8); PG8_BAR; PG8_WAIT_L(0); PG8_MMA(0, 0, At, B0); PG8_BAR; PG8_SCHED;
;             PG8_LDB(B1, 0, 1); PG8_STAGE(PG8_SB(0, 0), b2, voffB);
;             PG8_BAR; PG8_WAIT_L(0); PG8_MMA(0, 1, At, B1); PG8_BAR;
;             PG8_LDA(At, 0, 1); PG8_STAGE(PG8_SA(0, 0), a2, voffA);
;             PG8_BAR; PG8_WAIT_L(0); PG8_MMA(1, 0, At, B0); PG8_BAR; PG8_SCHED;
;             PG8_STAGE(PG8_SB(0, 1), b2 + hstep, voffB);
;             PG8_WAIT_V(6); PG8_BAR; PG8_MMA(1, 1, At, B1); PG8_BAR;
;             PG8_LDB(B0, 1, 0); PG8_SCHED; PG8_LDA(At, 1, 0); PG8_STAGE(PG8_SA(0, 1), a2 + hstep, voffA);
;             PG8_WAIT_L(8); PG8_BAR; PG8_WAIT_L(0); PG8_MMA(0, 0, At, B0); PG8_BAR; PG8_SCHED;
;             PG8_LDB(B1, 1, 1); PG8_STAGE(PG8_SB(1, 0), b3, voffB);
;             PG8_BAR; PG8_WAIT_L(0); PG8_MMA(0, 1, At, B1); PG8_BAR;
;             PG8_LDA(At, 1, 1); PG8_STAGE(PG8_SA(1, 0), a3, voffA);
;             PG8_BAR; PG8_WAIT_L(0); PG8_MMA(1, 0, At, B0); PG8_BAR; PG8_SCHED;
;             PG8_STAGE(PG8_SB(1, 1), b3 + hstep, voffB);
;             PG8_WAIT_V(6); PG8_BAR; PG8_MMA(1, 1, At, B1); PG8_BAR;
.LBB0_1667:
	s_ashr_i32 s29, s28, 31
	s_lshl_b64 s[0:1], s[28:29], 20
	s_add_u32 s30, s45, s0
	v_cmp_lt_i64_e32 vcc, s[8:9], v[140:141]
	s_addc_u32 s31, s46, s1
	s_and_b64 s[0:1], vcc, exec
	s_cselect_b32 s29, s31, s43
	s_cselect_b32 s35, s30, s42
	s_ashr_i32 s19, s18, 31
	s_lshl_b64 s[0:1], s[18:19], 20
	s_add_u32 s36, s47, s0
	s_addc_u32 s37, s48, s1
	s_and_b64 s[0:1], vcc, exec
	s_cselect_b32 s19, s37, s41
	s_cselect_b32 s65, s36, s40
	s_add_u32 s8, s42, 0x80080
	s_addc_u32 s9, s43, 0
	s_add_u32 s66, s40, 0x100
	v_mov_b32_e32 v8, 0
	s_addc_u32 s67, s41, 0
	s_mov_b32 s68, -2
	ds_read_b128 v[144:147], v149
	ds_read_b128 v[156:159], v149 offset:1024
	ds_read_b128 v[160:163], v149 offset:2048
	ds_read_b128 v[164:167], v149 offset:3072
	s_add_u32 s0, s8, 0xfff80080
	s_addc_u32 s1, s9, -1
	s_cmp_eq_u32 s68, 28
	s_cselect_b32 s43, s29, s1
	s_cselect_b32 s42, s35, s0
	s_cselect_b32 s41, s19, s67
	s_cselect_b32 s40, s65, s66
	v_lshl_add_u64 v[202:203], s[8:9], 0, v[136:137]
	s_add_i32 m0, s39, 0xc000
	ds_read_b128 v[168:171], v150
	ds_read_b128 v[172:175], v150 offset:1024
	ds_read_b128 v[176:179], v150 offset:2048
	ds_read_b128 v[180:183], v150 offset:3072
	ds_read_b128 v[188:191], v150 offset:4096
	ds_read_b128 v[206:209], v150 offset:5120
	ds_read_b128 v[210:213], v150 offset:6144
	ds_read_b128 v[214:217], v150 offset:7168
	global_load_lds_dwordx4 v[202:203], off
	v_lshl_add_u64 v[202:203], s[8:9], 0, v[138:139]
	s_add_i32 m0, s39, 0xe000
	s_nop 0
	global_load_lds_dwordx4 v[202:203], off
	s_waitcnt lgkmcnt(8)
	s_barrier
	s_waitcnt lgkmcnt(0)
	s_setprio 1
	s_waitcnt lgkmcnt(0)
	v_mfma_f32_16x16x32_bf16 v[116:119], v[144:147], v[168:171], 0
	v_mfma_f32_16x16x32_bf16 v[112:115], v[160:163], v[168:171], 0
	v_mfma_f32_16x16x32_bf16 v[100:103], v[144:147], v[176:179], 0
	v_mfma_f32_16x16x32_bf16 v[96:99], v[160:163], v[176:179], 0
	v_mfma_f32_16x16x32_bf16 v[84:87], v[144:147], v[188:191], 0
	v_mfma_f32_16x16x32_bf16 v[80:83], v[160:163], v[188:191], 0
	v_mfma_f32_16x16x32_bf16 v[68:71], v[144:147], v[210:213], 0
	v_mfma_f32_16x16x32_bf16 v[64:67], v[160:163], v[210:213], 0
	v_mfma_f32_16x16x32_bf16 v[116:119], v[156:159], v[172:175], v[116:119]
	v_mfma_f32_16x16x32_bf16 v[112:115], v[164:167], v[172:175], v[112:115]
	v_mfma_f32_16x16x32_bf16 v[100:103], v[156:159], v[180:183], v[100:103]
	v_mfma_f32_16x16x32_bf16 v[96:99], v[164:167], v[180:183], v[96:99]
	v_mfma_f32_16x16x32_bf16 v[84:87], v[156:159], v[206:209], v[84:87]
	v_mfma_f32_16x16x32_bf16 v[80:83], v[164:167], v[206:209], v[80:83]
	v_mfma_f32_16x16x32_bf16 v[68:71], v[156:159], v[214:217], v[68:71]
	v_mfma_f32_16x16x32_bf16 v[64:67], v[164:167], v[214:217], v[64:67]
	s_setprio 0
	s_barrier
	s_add_i32 s0, s61, s50
	v_lshl_add_u64 v[202:203], s[40:41], 0, v[130:131]
	s_mov_b32 m0, s0
	ds_read_b128 v[218:221], v151
	ds_read_b128 v[222:225], v151 offset:1024
	ds_read_b128 v[226:229], v151 offset:2048
	ds_read_b128 v[230:233], v151 offset:3072
	global_load_lds_dwordx4 v[202:203], off
	v_lshl_add_u64 v[234:235], s[40:41], 0, v[134:135]
	s_add_i32 m0, s0, 0x2000
	s_nop 0
	global_load_lds_dwordx4 v[234:235], off
	s_barrier
	s_waitcnt lgkmcnt(0)
	s_setprio 1
	s_waitcnt lgkmcnt(0)
	v_mfma_f32_16x16x32_bf16 v[124:127], v[218:221], v[168:171], 0
	v_mfma_f32_16x16x32_bf16 v[120:123], v[226:229], v[168:171], 0
	v_mfma_f32_16x16x32_bf16 v[108:111], v[218:221], v[176:179], 0
	v_mfma_f32_16x16x32_bf16 v[104:107], v[226:229], v[176:179], 0
	v_mfma_f32_16x16x32_bf16 v[92:95], v[218:221], v[188:191], 0
	v_mfma_f32_16x16x32_bf16 v[88:91], v[226:229], v[188:191], 0
	v_mfma_f32_16x16x32_bf16 v[76:79], v[218:221], v[210:213], 0
	v_mfma_f32_16x16x32_bf16 v[72:75], v[226:229], v[210:213], 0
	v_mfma_f32_16x16x32_bf16 v[124:127], v[222:225], v[172:175], v[124:127]
	v_mfma_f32_16x16x32_bf16 v[120:123], v[230:233], v[172:175], v[120:123]
	v_mfma_f32_16x16x32_bf16 v[108:111], v[222:225], v[180:183], v[108:111]
	v_mfma_f32_16x16x32_bf16 v[104:107], v[230:233], v[180:183], v[104:107]
	v_mfma_f32_16x16x32_bf16 v[92:95], v[222:225], v[206:209], v[92:95]
	v_mfma_f32_16x16x32_bf16 v[88:91], v[230:233], v[206:209], v[88:91]
	v_mfma_f32_16x16x32_bf16 v[76:79], v[222:225], v[214:217], v[76:79]
	v_mfma_f32_16x16x32_bf16 v[72:75], v[230:233], v[214:217], v[72:75]
	s_setprio 0
	s_mov_b32 m0, s39
	v_lshl_add_u64 v[236:237], s[42:43], 0, v[128:129]
	s_barrier
	ds_read_b128 v[168:171], v150 offset:16384
	ds_read_b128 v[172:175], v150 offset:17408
	ds_read_b128 v[176:179], v150 offset:18432
	ds_read_b128 v[180:183], v150 offset:19456
	ds_read_b128 v[188:191], v150 offset:20480
	ds_read_b128 v[206:209], v150 offset:21504
	ds_read_b128 v[210:213], v150 offset:22528
	ds_read_b128 v[214:217], v150 offset:23552
	global_load_lds_dwordx4 v[236:237], off
	v_lshl_add_u64 v[238:239], s[42:43], 0, v[132:133]
	s_mov_b32 m0, s51
	s_nop 0
	global_load_lds_dwordx4 v[238:239], off
	s_barrier
	s_waitcnt lgkmcnt(0)
	s_setprio 1
	s_waitcnt lgkmcnt(0)
	v_mfma_f32_16x16x32_bf16 v[52:55], v[144:147], v[168:171], 0
	v_mfma_f32_16x16x32_bf16 v[48:51], v[160:163], v[168:171], 0
	v_mfma_f32_16x16x32_bf16 v[36:39], v[144:147], v[176:179], 0
	v_mfma_f32_16x16x32_bf16 v[32:35], v[160:163], v[176:179], 0
	v_mfma_f32_16x16x32_bf16 v[20:23], v[144:147], v[188:191], 0
	v_mfma_f32_16x16x32_bf16 v[16:19], v[160:163], v[188:191], 0
	v_mfma_f32_16x16x32_bf16 v[4:7], v[144:147], v[210:213], 0
	v_mfma_f32_16x16x32_bf16 v[0:3], v[160:163], v[210:213], 0
	v_mfma_f32_16x16x32_bf16 v[52:55], v[156:159], v[172:175], v[52:55]
	v_mfma_f32_16x16x32_bf16 v[48:51], v[164:167], v[172:175], v[48:51]
	v_mfma_f32_16x16x32_bf16 v[36:39], v[156:159], v[180:183], v[36:39]
	v_mfma_f32_16x16x32_bf16 v[32:35], v[164:167], v[180:183], v[32:35]
	v_mfma_f32_16x16x32_bf16 v[20:23], v[156:159], v[206:209], v[20:23]
	v_mfma_f32_16x16x32_bf16 v[16:19], v[164:167], v[206:209], v[16:19]
	v_mfma_f32_16x16x32_bf16 v[4:7], v[156:159], v[214:217], v[4:7]
	v_mfma_f32_16x16x32_bf16 v[0:3], v[164:167], v[214:217], v[0:3]
	s_setprio 0
	s_barrier
; #define PG8_STAGE(bufoff, gbase, voff) do { _Pragma("unroll") for (int _i = 0; _i < 2; ++_i) \
;         __builtin_amdgcn_global_load_lds((const unsigned*)((const char*)(gbase) + (voff)[_i]), (LAS unsigned*)(lds + (bufoff) + ldsw + _i * 8192), 16, 0, 0); } while (0)
; #define PG8_LDA(dst, b, h) do { _Pragma("unroll") for (int m = 0; m < 4; ++m) _Pragma("unroll") for (int k = 0; k < 2; ++k) dst[m][k] = *(const LAS bf16x8*)(lds + PG8_SA(b, h) + aoff + m * 2048 + k * 1024); } while (0)
; #define PG8_LDB(dst, b, h) do { _Pragma("unroll") for (int n = 0; n < 2; ++n) _Pragma("unroll") for (int k = 0; k < 2; ++k) dst[n][k] = *(const LAS bf16x8*)(lds + PG8_SB(b, h) + boff + n * 2048 + k * 1024); } while (0)
; #define PG8_WAIT_V(n) asm volatile("s_waitcnt vmcnt(" #n ")" ::: "memory")
; #define PG8_WAIT_L(n) asm volatile("s_waitcnt lgkmcnt(" #n ")" ::: "memory")
; #define PG8_BAR __builtin_amdgcn_s_barrier()
; #define PG8_SCHED __builtin_amdgcn_sched_barrier(0)
; template <class Epi, class Sched>
; DI void gemm_phase(LAS unsigned char* lds, const Gemm g, const Sched& S, const Epi& E) {
;     ...
;             PG8_LDB(B0, 0, 0); PG8_SCHED; PG8_LDA(At, 0, 0); PG8_STAGE(PG8_SA(1, 1), a1 + hstep, voffA);
;             PG8_WAIT_L(8); PG8_BAR; PG8_WAIT_L(0); PG8_MMA(0, 0, At, B0); PG8_BAR; PG8_SCHED;
;             PG8_LDB(B1, 0, 1); PG8_STAGE(PG8_SB(0, 0), b2, voffB);
;             PG8_BAR; PG8_WAIT_L(0); PG8_MMA(0, 1, At, B1); PG8_BAR;
;             PG8_LDA(At, 0, 1); PG8_STAGE(PG8_SA(0, 0), a2, voffA);
;             PG8_BAR; PG8_WAIT_L(0); PG8_MMA(1, 0, At, B0); PG8_BAR; PG8_SCHED;
;             PG8_STAGE(PG8_SB(0, 1), b2 + hstep, voffB);
;             PG8_WAIT_V(6); PG8_BAR; PG8_MMA(1, 1, At, B1); PG8_BAR;
;             PG8_LDB(B0, 1, 0); PG8_SCHED; PG8_LDA(At, 1, 0); PG8_STAGE(PG8_SA(0, 1), a2 + hstep, voffA);
;             PG8_WAIT_L(8); PG8_BAR; PG8_WAIT_L(0); PG8_MMA(0, 0, At, B0); PG8_BAR; PG8_SCHED;
;             PG8_LDB(B1, 1, 1); PG8_STAGE(PG8_SB(1, 0), b3, voffB);
;             PG8_BAR; PG8_WAIT_L(0); PG8_MMA(0, 1, At, B1); PG8_BAR;
;             PG8_LDA(At, 1, 1); PG8_STAGE(PG8_SA(1, 0), a3, voffA);
;             PG8_BAR; PG8_WAIT_L(0); PG8_MMA(1, 0, At, B0); PG8_BAR; PG8_SCHED;
;             PG8_STAGE(PG8_SB(1, 1), b3 + hstep, voffB);
;             PG8_WAIT_V(6); PG8_BAR; PG8_MMA(1, 1, At, B1); PG8_BAR;
	s_add_u32 s0, s40, 0x80000
	s_addc_u32 s1, s41, 0
	s_add_i32 s4, s62, s50
	v_lshl_add_u64 v[144:145], s[0:1], 0, v[130:131]
	s_mov_b32 m0, s4
	s_nop 0
	global_load_lds_dwordx4 v[144:145], off
	v_lshl_add_u64 v[144:145], s[0:1], 0, v[134:135]
	s_add_i32 m0, s4, 0x2000
	s_nop 0
	global_load_lds_dwordx4 v[144:145], off
	s_waitcnt vmcnt(6)
	s_barrier
	s_setprio 1
	v_mfma_f32_16x16x32_bf16 v[60:63], v[218:221], v[168:171], 0
	v_mfma_f32_16x16x32_bf16 v[56:59], v[226:229], v[168:171], 0
	v_mfma_f32_16x16x32_bf16 v[44:47], v[218:221], v[176:179], 0
	v_mfma_f32_16x16x32_bf16 v[40:43], v[226:229], v[176:179], 0
	v_mfma_f32_16x16x32_bf16 v[28:31], v[218:221], v[188:191], 0
	v_mfma_f32_16x16x32_bf16 v[24:27], v[226:229], v[188:191], 0
	v_mfma_f32_16x16x32_bf16 v[12:15], v[218:221], v[210:213], 0
	v_mfma_f32_16x16x32_bf16 v[8:11], v[226:229], v[210:213], 0
	v_mfma_f32_16x16x32_bf16 v[60:63], v[222:225], v[172:175], v[60:63]
	v_mfma_f32_16x16x32_bf16 v[56:59], v[230:233], v[172:175], v[56:59]
	v_mfma_f32_16x16x32_bf16 v[44:47], v[222:225], v[180:183], v[44:47]
	v_mfma_f32_16x16x32_bf16 v[40:43], v[230:233], v[180:183], v[40:43]
	v_mfma_f32_16x16x32_bf16 v[28:31], v[222:225], v[206:209], v[28:31]
	v_mfma_f32_16x16x32_bf16 v[24:27], v[230:233], v[206:209], v[24:27]
	v_mfma_f32_16x16x32_bf16 v[12:15], v[222:225], v[214:217], v[12:15]
	v_mfma_f32_16x16x32_bf16 v[8:11], v[230:233], v[214:217], v[8:11]
	s_setprio 0
	s_add_i32 s4, 0, 0x18000
	v_add_u32_e32 v155, s4, v148
	s_barrier
	ds_read_b128 v[144:147], v155
	ds_read_b128 v[156:159], v155 offset:1024
	ds_read_b128 v[160:163], v155 offset:2048
	ds_read_b128 v[164:167], v155 offset:3072
	s_add_u32 s0, s42, 0x80000
	s_addc_u32 s1, s43, 0
	s_mov_b32 m0, s52
	v_lshl_add_u64 v[218:219], s[0:1], 0, v[128:129]
	ds_read_b128 v[168:171], v150 offset:32768
	ds_read_b128 v[172:175], v150 offset:33792
	ds_read_b128 v[176:179], v150 offset:34816
	ds_read_b128 v[180:183], v150 offset:35840
	ds_read_b128 v[188:191], v150 offset:36864
	ds_read_b128 v[206:209], v150 offset:37888
	ds_read_b128 v[210:213], v150 offset:38912
	ds_read_b128 v[214:217], v150 offset:39936
	global_load_lds_dwordx4 v[218:219], off
	v_lshl_add_u64 v[218:219], s[0:1], 0, v[132:133]
	s_mov_b32 m0, s53
	s_nop 0
	global_load_lds_dwordx4 v[218:219], off
	s_waitcnt lgkmcnt(8)
	s_barrier
	s_waitcnt lgkmcnt(0)
	s_setprio 1
	s_waitcnt lgkmcnt(0)
	v_mfma_f32_16x16x32_bf16 v[116:119], v[144:147], v[168:171], v[116:119]
	v_mfma_f32_16x16x32_bf16 v[112:115], v[160:163], v[168:171], v[112:115]
	v_mfma_f32_16x16x32_bf16 v[100:103], v[144:147], v[176:179], v[100:103]
	v_mfma_f32_16x16x32_bf16 v[96:99], v[160:163], v[176:179], v[96:99]
	v_mfma_f32_16x16x32_bf16 v[84:87], v[144:147], v[188:191], v[84:87]
	v_mfma_f32_16x16x32_bf16 v[80:83], v[160:163], v[188:191], v[80:83]
	v_mfma_f32_16x16x32_bf16 v[68:71], v[144:147], v[210:213], v[68:71]
	v_mfma_f32_16x16x32_bf16 v[64:67], v[160:163], v[210:213], v[64:67]
	v_mfma_f32_16x16x32_bf16 v[116:119], v[156:159], v[172:175], v[116:119]
	v_mfma_f32_16x16x32_bf16 v[112:115], v[164:167], v[172:175], v[112:115]
	v_mfma_f32_16x16x32_bf16 v[100:103], v[156:159], v[180:183], v[100:103]
	v_mfma_f32_16x16x32_bf16 v[96:99], v[164:167], v[180:183], v[96:99]
	v_mfma_f32_16x16x32_bf16 v[84:87], v[156:159], v[206:209], v[84:87]
	v_mfma_f32_16x16x32_bf16 v[80:83], v[164:167], v[206:209], v[80:83]
	v_mfma_f32_16x16x32_bf16 v[68:71], v[156:159], v[214:217], v[68:71]
	v_mfma_f32_16x16x32_bf16 v[64:67], v[164:167], v[214:217], v[64:67]
	s_setprio 0
	s_barrier
	s_add_i32 s5, 0, 0x1c000
	s_add_i32 s0, s4, s50
	v_add_u32_e32 v155, s5, v148
	v_lshl_add_u64 v[202:203], v[202:203], 0, s[16:17]
	s_mov_b32 m0, s0
	ds_read_b128 v[218:221], v155
	ds_read_b128 v[222:225], v155 offset:1024
	ds_read_b128 v[226:229], v155 offset:2048
	ds_read_b128 v[230:233], v155 offset:3072
	global_load_lds_dwordx4 v[202:203], off
	v_lshl_add_u64 v[202:203], v[234:235], 0, s[16:17]
	s_add_i32 m0, s0, 0x2000
	s_nop 0
	global_load_lds_dwordx4 v[202:203], off
	s_barrier
; #define PG8_STAGE(bufoff, gbase, voff) do { _Pragma("unroll") for (int _i = 0; _i < 2; ++_i) \
;         __builtin_amdgcn_global_load_lds((const unsigned*)((const char*)(gbase) + (voff)[_i]), (LAS unsigned*)(lds + (bufoff) + ldsw + _i * 8192), 16, 0, 0); } while (0)
; #define PG8_LDA(dst, b, h) do { _Pragma("unroll") for (int m = 0; m < 4; ++m) _Pragma("unroll") for (int k = 0; k < 2; ++k) dst[m][k] = *(const LAS bf16x8*)(lds + PG8_SA(b, h) + aoff + m * 2048 + k * 1024); } while (0)
; #define PG8_LDB(dst, b, h) do { _Pragma("unroll") for (int n = 0; n < 2; ++n) _Pragma("unroll") for (int k = 0; k < 2; ++k) dst[n][k] = *(const LAS bf16x8*)(lds + PG8_SB(b, h) + boff + n * 2048 + k * 1024); } while (0)
; #define PG8_MMA(ai, bj, At, Bt) do { __builtin_amdgcn_s_setprio(1); _Pragma("unroll") for (int m = 0; m < 4; ++m) _Pragma("unroll") for (int n = 0; n < 2; ++n) _Pragma("unroll") for (int k = 0; k < 2; ++k) \
;         acc[ai][bj][m][n] = __builtin_amdgcn_mfma_f32_16x16x32_bf16(Bt[n][k], At[m][k], acc[ai][bj][m][n], 0, 0, 0); __builtin_amdgcn_s_setprio(0); } while (0)
; #define PG8_WAIT_V(n) asm volatile("s_waitcnt vmcnt(" #n ")" ::: "memory")
; #define PG8_WAIT_L(n) asm volatile("s_waitcnt lgkmcnt(" #n ")" ::: "memory")
; #define PG8_BAR __builtin_amdgcn_s_barrier()
; #define PG8_SCHED __builtin_amdgcn_sched_barrier(0)
; template <class Epi, class Sched>
; DI void gemm_phase(LAS unsigned char* lds, const Gemm g, const Sched& S, const Epi& E) {
;     ...
;             PG8_LDB(B1, 1, 1); PG8_STAGE(PG8_SB(1, 0), b3, voffB);
;             PG8_BAR; PG8_WAIT_L(0); PG8_MMA(0, 1, At, B1); PG8_BAR;
;             PG8_LDA(At, 1, 1); PG8_STAGE(PG8_SA(1, 0), a3, voffA);
;             PG8_BAR; PG8_WAIT_L(0); PG8_MMA(1, 0, At, B0); PG8_BAR; PG8_SCHED;
;             PG8_STAGE(PG8_SB(1, 1), b3 + hstep, voffB);
;             PG8_WAIT_V(6); PG8_BAR; PG8_MMA(1, 1, At, B1); PG8_BAR;
	s_waitcnt lgkmcnt(0)
	s_setprio 1
	s_waitcnt lgkmcnt(0)
	v_mfma_f32_16x16x32_bf16 v[124:127], v[218:221], v[168:171], v[124:127]
	v_mfma_f32_16x16x32_bf16 v[120:123], v[226:229], v[168:171], v[120:123]
	v_mfma_f32_16x16x32_bf16 v[108:111], v[218:221], v[176:179], v[108:111]
	v_mfma_f32_16x16x32_bf16 v[104:107], v[226:229], v[176:179], v[104:107]
	v_mfma_f32_16x16x32_bf16 v[92:95], v[218:221], v[188:191], v[92:95]
	v_mfma_f32_16x16x32_bf16 v[88:91], v[226:229], v[188:191], v[88:91]
	v_mfma_f32_16x16x32_bf16 v[76:79], v[218:221], v[210:213], v[76:79]
	v_mfma_f32_16x16x32_bf16 v[72:75], v[226:229], v[210:213], v[72:75]
	v_mfma_f32_16x16x32_bf16 v[124:127], v[222:225], v[172:175], v[124:127]
	v_mfma_f32_16x16x32_bf16 v[120:123], v[230:233], v[172:175], v[120:123]
	v_mfma_f32_16x16x32_bf16 v[108:111], v[222:225], v[180:183], v[108:111]
	v_mfma_f32_16x16x32_bf16 v[104:107], v[230:233], v[180:183], v[104:107]
	v_mfma_f32_16x16x32_bf16 v[92:95], v[222:225], v[206:209], v[92:95]
	v_mfma_f32_16x16x32_bf16 v[88:91], v[230:233], v[206:209], v[88:91]
	v_mfma_f32_16x16x32_bf16 v[76:79], v[222:225], v[214:217], v[76:79]
	v_mfma_f32_16x16x32_bf16 v[72:75], v[230:233], v[214:217], v[72:75]
	s_setprio 0
	s_mov_b32 m0, s57
	v_lshl_add_u64 v[202:203], v[236:237], 0, s[16:17]
	s_barrier
	ds_read_b128 v[168:171], v150 offset:49152
	ds_read_b128 v[172:175], v150 offset:50176
	ds_read_b128 v[176:179], v150 offset:51200
	ds_read_b128 v[180:183], v150 offset:52224
	ds_read_b128 v[188:191], v150 offset:53248
	ds_read_b128 v[206:209], v150 offset:54272
	ds_read_b128 v[210:213], v150 offset:55296
	ds_read_b128 v[214:217], v150 offset:56320
	global_load_lds_dwordx4 v[202:203], off
	v_lshl_add_u64 v[202:203], v[238:239], 0, s[16:17]
	s_mov_b32 m0, s58
	s_nop 0
	global_load_lds_dwordx4 v[202:203], off
	s_barrier
	s_waitcnt lgkmcnt(0)
	s_setprio 1
	s_waitcnt lgkmcnt(0)
	v_mfma_f32_16x16x32_bf16 v[52:55], v[144:147], v[168:171], v[52:55]
	v_mfma_f32_16x16x32_bf16 v[48:51], v[160:163], v[168:171], v[48:51]
	v_mfma_f32_16x16x32_bf16 v[36:39], v[144:147], v[176:179], v[36:39]
	v_mfma_f32_16x16x32_bf16 v[32:35], v[160:163], v[176:179], v[32:35]
	v_mfma_f32_16x16x32_bf16 v[20:23], v[144:147], v[188:191], v[20:23]
	v_mfma_f32_16x16x32_bf16 v[16:19], v[160:163], v[188:191], v[16:19]
	v_mfma_f32_16x16x32_bf16 v[4:7], v[144:147], v[210:213], v[4:7]
	v_mfma_f32_16x16x32_bf16 v[0:3], v[160:163], v[210:213], v[0:3]
	v_mfma_f32_16x16x32_bf16 v[52:55], v[156:159], v[172:175], v[52:55]
	v_mfma_f32_16x16x32_bf16 v[48:51], v[164:167], v[172:175], v[48:51]
	v_mfma_f32_16x16x32_bf16 v[36:39], v[156:159], v[180:183], v[36:39]
	v_mfma_f32_16x16x32_bf16 v[32:35], v[164:167], v[180:183], v[32:35]
	v_mfma_f32_16x16x32_bf16 v[20:23], v[156:159], v[206:209], v[20:23]
	v_mfma_f32_16x16x32_bf16 v[16:19], v[164:167], v[206:209], v[16:19]
	v_mfma_f32_16x16x32_bf16 v[4:7], v[156:159], v[214:217], v[4:7]
	v_mfma_f32_16x16x32_bf16 v[0:3], v[164:167], v[214:217], v[0:3]
	s_setprio 0
	s_barrier
	s_add_u32 s0, s40, 0x80080
	s_addc_u32 s1, s41, 0
	s_add_i32 s4, s5, s50
	v_lshl_add_u64 v[144:145], s[0:1], 0, v[130:131]
	s_mov_b32 m0, s4
	s_nop 0
	global_load_lds_dwordx4 v[144:145], off
	v_lshl_add_u64 v[144:145], s[0:1], 0, v[134:135]
	s_add_i32 m0, s4, 0x2000
	s_nop 0
	global_load_lds_dwordx4 v[144:145], off
	s_waitcnt vmcnt(6)
	s_barrier
	s_setprio 1
	v_mfma_f32_16x16x32_bf16 v[60:63], v[218:221], v[168:171], v[60:63]
	v_mfma_f32_16x16x32_bf16 v[56:59], v[226:229], v[168:171], v[56:59]
	v_mfma_f32_16x16x32_bf16 v[44:47], v[218:221], v[176:179], v[44:47]
	v_mfma_f32_16x16x32_bf16 v[40:43], v[226:229], v[176:179], v[40:43]
	v_mfma_f32_16x16x32_bf16 v[28:31], v[218:221], v[188:191], v[28:31]
	v_mfma_f32_16x16x32_bf16 v[24:27], v[226:229], v[188:191], v[24:27]
	v_mfma_f32_16x16x32_bf16 v[12:15], v[218:221], v[210:213], v[12:15]
	v_mfma_f32_16x16x32_bf16 v[8:11], v[226:229], v[210:213], v[8:11]
	v_mfma_f32_16x16x32_bf16 v[60:63], v[222:225], v[172:175], v[60:63]
	v_mfma_f32_16x16x32_bf16 v[56:59], v[230:233], v[172:175], v[56:59]
	v_mfma_f32_16x16x32_bf16 v[44:47], v[222:225], v[180:183], v[44:47]
	v_mfma_f32_16x16x32_bf16 v[40:43], v[230:233], v[180:183], v[40:43]
	v_mfma_f32_16x16x32_bf16 v[28:31], v[222:225], v[206:209], v[28:31]
	v_mfma_f32_16x16x32_bf16 v[24:27], v[230:233], v[206:209], v[24:27]
	v_mfma_f32_16x16x32_bf16 v[12:15], v[222:225], v[214:217], v[12:15]
	v_mfma_f32_16x16x32_bf16 v[8:11], v[230:233], v[214:217], v[8:11]
	s_setprio 0
	s_add_i32 s68, s68, 2
	s_add_u32 s8, s8, 0x100
	s_addc_u32 s9, s9, 0
	s_add_u32 s66, s66, 0x100
	s_addc_u32 s67, s67, 0
	s_cmp_gt_u32 s68, 29
	s_barrier
	s_cbranch_scc0 .LBB0_1668
	s_branch .Lpeel_done_1668

; DI float sigmoidf_(float x) { return __builtin_amdgcn_rcpf(1.0f + __builtin_amdgcn_exp2f(-x * LOG2E)); }
; DI float rs_of(const float* ss, int row) { return 1.0f / sqrtf(ss[row] * (1.0f / DM) + EPS); }
; DI u32x4 pack8(f32x4 a, f32x4 b) { u32x4 w; w.x = cvt_pk_bf16(a[0], a[1]); w.y = cvt_pk_bf16(a[2], a[3]); w.z = cvt_pk_bf16(b[0], b[1]); w.w = cvt_pk_bf16(b[2], b[3]); return w; }
;     DI void operator()(AccRef acc, const Unit& u, int wr, int wc, int fr, int fq) const {
;         const int row0 = u.pm * 256 + wr * 64 + fr, col0 = u.pn * 128 + wc * 32 + 8 * fq;
; #pragma unroll
;         for (int ai = 0; ai < 2; ++ai)
; #pragma unroll
;             for (int m = 0; m < 4; ++m) {
;                 f32x4 o[2]; const float r = ss ? rs_of(ss, row0 + ai * 128 + m * 16) : 1.0f;
; #pragma unroll
;                 for (int n = 0; n < 2; ++n)
; #pragma unroll
;                     for (int j = 0; j < 4; ++j) { const float gt = acc[ai][0][m][n][j] * r, up = acc[ai][1][m][n][j] * r; o[n][j] = gt * sigmoidf_(gt) * up; }
;                 *(u32x4*)(Hd + (size_t)(row0 + ai * 128 + m * 16) * DFF + col0) = pack8(o[0], o[1]);
;             }
.Lpeel_done_1668:
	v_mov_b32_e32 v144, v194
	v_mov_b32_e32 v155, v192
	s_lshl_b32 s0, s38, 8
	s_add_i32 s0, s0, s55
	v_add_u32_e32 v144, s0, v144
	v_ashrrev_i32_e32 v145, 31, v144
	v_lshl_add_u64 v[146:147], v[144:145], 2, s[14:15]
	v_mov_b64_e32 v[202:203], v[146:147]
	s_mov_b32 s69, 0
	global_load_dword v201, v[202:203], off
	global_load_dword v205, v[202:203], off offset:64
	global_load_dword v242, v[202:203], off offset:128
	global_load_dword v243, v[202:203], off offset:192
	global_load_dword v238, v[202:203], off offset:512
	global_load_dword v239, v[202:203], off offset:576
	global_load_dword v240, v[202:203], off offset:640
	global_load_dword v241, v[202:203], off offset:704
	s_waitcnt vmcnt(7)
	v_mov_b32_e32 v145, v201
	s_lshl_b32 s0, s34, 7
	s_or_b32 s0, s0, s56
	v_mov_b32_e32 v156, v124
	v_mov_b32_e32 v124, v126
	v_mov_b32_e32 v126, v120
	v_lshl_add_u32 v120, v155, 3, s0
	v_mov_b32_e32 v159, v114
	v_mov_b32_e32 v114, v123
	v_mov_b32_e32 v157, v116
	v_mov_b32_e32 v116, v125
	v_mov_b32_e32 v125, v118
	v_mov_b32_e32 v118, v127
	v_mov_b32_e32 v127, v112
	v_mov_b32_e32 v112, v121
	v_mov_b32_e32 v158, v122
	v_mov_b64_e32 v[122:123], s[12:13]
	v_ashrrev_i32_e32 v121, 31, v120
	v_mad_i64_i32 v[160:161], s[0:1], v144, s64, v[122:123]
	v_lshlrev_b64 v[120:121], 1, v[120:121]
	v_lshl_add_u64 v[160:161], v[160:161], 0, v[120:121]
	s_and_b64 s[6:7], exec, s[6:7]
	s_mov_b32 s34, s18
	s_mov_b32 s38, s28
	s_mov_b64 s[40:41], s[36:37]
	s_mov_b64 s[42:43], s[30:31]
	v_mov_b32_e32 v162, v145
	s_nop 1
	s_nop 0
	s_nop 1
	s_nop 1
	s_nop 1
	v_pk_mul_f32 v[114:115], v[114:115], v[162:163] op_sel_hi:[1,0]
	v_pk_mul_f32 v[156:157], v[156:157], v[162:163] op_sel_hi:[1,0]
	v_pk_mul_f32 v[116:117], v[116:117], v[162:163] op_sel_hi:[1,0]
	v_pk_mul_f32 v[124:125], v[124:125], v[162:163] op_sel_hi:[1,0]
	v_pk_mul_f32 v[118:119], v[118:119], v[162:163] op_sel_hi:[1,0]
	v_pk_mul_f32 v[126:127], v[126:127], v[162:163] op_sel_hi:[1,0]
	v_pk_mul_f32 v[112:113], v[112:113], v[162:163] op_sel_hi:[1,0]
	v_pk_mul_f32 v[158:159], v[158:159], v[162:163] op_sel_hi:[1,0]
	v_mul_f32_e32 v167, 0xbfb8aa3b, v115
	v_mul_f32_e32 v145, 0xbfb8aa3b, v157
	v_mul_f32_e32 v155, 0xbfb8aa3b, v117
	v_mul_f32_e32 v162, 0xbfb8aa3b, v125
	v_mul_f32_e32 v163, 0xbfb8aa3b, v119
	v_mul_f32_e32 v164, 0xbfb8aa3b, v127
	v_mul_f32_e32 v165, 0xbfb8aa3b, v113
	v_mul_f32_e32 v166, 0xbfb8aa3b, v159
	v_exp_f32_e32 v167, v167
	v_exp_f32_e32 v145, v145
	v_exp_f32_e32 v155, v155
	v_exp_f32_e32 v162, v162
	v_exp_f32_e32 v163, v163
	v_exp_f32_e32 v164, v164
	v_exp_f32_e32 v165, v165
	v_exp_f32_e32 v166, v166
	v_add_f32_e32 v167, 1.0, v167
	v_add_f32_e32 v145, 1.0, v145
	v_add_f32_e32 v155, 1.0, v155
	v_add_f32_e32 v162, 1.0, v162
	v_add_f32_e32 v163, 1.0, v163
	v_add_f32_e32 v164, 1.0, v164
	v_add_f32_e32 v165, 1.0, v165
	v_add_f32_e32 v166, 1.0, v166
	v_rcp_f32_e32 v167, v167
	v_rcp_f32_e32 v145, v145
	v_rcp_f32_e32 v155, v155
	v_rcp_f32_e32 v162, v162
	v_rcp_f32_e32 v163, v163
	v_rcp_f32_e32 v164, v164
	v_rcp_f32_e32 v165, v165
	v_rcp_f32_e32 v166, v166
	v_mul_f32_e32 v115, v115, v167
	v_mul_f32_e32 v145, v157, v145
	v_mul_f32_e32 v117, v117, v155
	v_mul_f32_e32 v125, v125, v162
	v_mul_f32_e32 v119, v119, v163
	v_mul_f32_e32 v127, v127, v164
	v_mul_f32_e32 v113, v113, v165
	v_mul_f32_e32 v155, v159, v166
	v_mul_f32_e32 v115, v114, v115
	v_mul_f32_e32 v145, v156, v145
	v_mul_f32_e32 v116, v116, v117
	v_mul_f32_e32 v117, v124, v125
	v_mul_f32_e32 v118, v118, v119
	v_mul_f32_e32 v119, v126, v127
	v_mul_f32_e32 v124, v112, v113
	v_mul_f32_e32 v125, v158, v155
	v_cvt_pk_bf16_f32 v112, v145, v116
	v_cvt_pk_bf16_f32 v113, v117, v118
	v_cvt_pk_bf16_f32 v114, v119, v124
	v_cvt_pk_bf16_f32 v115, v125, v115
	global_store_dwordx4 v[160:161], v[112:115], off
	s_waitcnt vmcnt(7)
	s_nop 1
	v_mov_b32_e32 v114, v205
	s_nop 0
	v_mov_b32_e32 v112, v108
	v_mov_b32_e32 v108, v110
	v_mov_b32_e32 v110, v104
	v_mov_b32_e32 v104, v106
	v_mov_b32_e32 v113, v100
	v_mov_b32_e32 v100, v109
	v_mov_b32_e32 v109, v102
	v_mov_b32_e32 v102, v111
	v_mov_b32_e32 v111, v96
	v_mov_b32_e32 v96, v105
	v_mov_b32_e32 v105, v98
	v_mov_b32_e32 v98, v107
	v_mov_b32_e32 v114, v114
	s_nop 1
	v_add_u32_e32 v106, 16, v144
	v_mad_i64_i32 v[106:107], s[0:1], v106, s64, v[122:123]
	v_lshl_add_u64 v[106:107], v[106:107], 0, v[120:121]
	s_nop 0
	s_nop 1
	s_nop 1
	v_pk_mul_f32 v[98:99], v[98:99], v[114:115] op_sel_hi:[1,0]
	v_pk_mul_f32 v[112:113], v[112:113], v[114:115] op_sel_hi:[1,0]
	v_pk_mul_f32 v[100:101], v[100:101], v[114:115] op_sel_hi:[1,0]
	v_pk_mul_f32 v[108:109], v[108:109], v[114:115] op_sel_hi:[1,0]
	v_pk_mul_f32 v[102:103], v[102:103], v[114:115] op_sel_hi:[1,0]
	v_pk_mul_f32 v[110:111], v[110:111], v[114:115] op_sel_hi:[1,0]
	v_pk_mul_f32 v[96:97], v[96:97], v[114:115] op_sel_hi:[1,0]
	v_pk_mul_f32 v[104:105], v[104:105], v[114:115] op_sel_hi:[1,0]
	v_mul_f32_e32 v125, 0xbfb8aa3b, v99
	v_mul_f32_e32 v114, 0xbfb8aa3b, v113
	v_mul_f32_e32 v115, 0xbfb8aa3b, v101
	v_mul_f32_e32 v116, 0xbfb8aa3b, v109
	v_mul_f32_e32 v117, 0xbfb8aa3b, v103
	v_mul_f32_e32 v118, 0xbfb8aa3b, v111
	v_mul_f32_e32 v119, 0xbfb8aa3b, v97
	v_mul_f32_e32 v124, 0xbfb8aa3b, v105
	v_exp_f32_e32 v125, v125
	v_exp_f32_e32 v114, v114
	v_exp_f32_e32 v115, v115
	v_exp_f32_e32 v116, v116
	v_exp_f32_e32 v117, v117
	v_exp_f32_e32 v118, v118
	v_exp_f32_e32 v119, v119
	v_exp_f32_e32 v124, v124
	v_add_f32_e32 v125, 1.0, v125
	v_add_f32_e32 v114, 1.0, v114
	v_add_f32_e32 v115, 1.0, v115
	v_add_f32_e32 v116, 1.0, v116
	v_add_f32_e32 v117, 1.0, v117
	v_add_f32_e32 v118, 1.0, v118
	v_add_f32_e32 v119, 1.0, v119
	v_add_f32_e32 v124, 1.0, v124
	v_rcp_f32_e32 v125, v125
	v_rcp_f32_e32 v114, v114
	v_rcp_f32_e32 v115, v115
	v_rcp_f32_e32 v116, v116
	v_rcp_f32_e32 v117, v117
	v_rcp_f32_e32 v118, v118
	v_rcp_f32_e32 v119, v119
	v_rcp_f32_e32 v124, v124
	v_mul_f32_e32 v99, v99, v125
	v_mul_f32_e32 v113, v113, v114
	v_mul_f32_e32 v101, v101, v115
	v_mul_f32_e32 v109, v109, v116
	v_mul_f32_e32 v103, v103, v117
	v_mul_f32_e32 v111, v111, v118
	v_mul_f32_e32 v97, v97, v119
	v_mul_f32_e32 v105, v105, v124
	v_mul_f32_e32 v99, v98, v99
	v_mul_f32_e32 v112, v112, v113
	v_mul_f32_e32 v100, v100, v101
	v_mul_f32_e32 v101, v108, v109
	v_mul_f32_e32 v102, v102, v103
	v_mul_f32_e32 v103, v110, v111
	v_mul_f32_e32 v108, v96, v97
	v_mul_f32_e32 v104, v104, v105
	v_cvt_pk_bf16_f32 v96, v112, v100
	v_cvt_pk_bf16_f32 v97, v101, v102
	v_cvt_pk_bf16_f32 v98, v103, v108
	v_cvt_pk_bf16_f32 v99, v104, v99
	global_store_dwordx4 v[106:107], v[96:99], off
	s_waitcnt vmcnt(7)
; DI float sigmoidf_(float x) { return __builtin_amdgcn_rcpf(1.0f + __builtin_amdgcn_exp2f(-x * LOG2E)); }
; DI float rs_of(const float* ss, int row) { return 1.0f / sqrtf(ss[row] * (1.0f / DM) + EPS); }
; DI u32x4 pack8(f32x4 a, f32x4 b) { u32x4 w; w.x = cvt_pk_bf16(a[0], a[1]); w.y = cvt_pk_bf16(a[2], a[3]); w.z = cvt_pk_bf16(b[0], b[1]); w.w = cvt_pk_bf16(b[2], b[3]); return w; }
;     DI void operator()(AccRef acc, const Unit& u, int wr, int wc, int fr, int fq) const {
;     ...
;             for (int m = 0; m < 4; ++m) {
;                 f32x4 o[2]; const float r = ss ? rs_of(ss, row0 + ai * 128 + m * 16) : 1.0f;
; #pragma unroll
;                 for (int n = 0; n < 2; ++n)
; #pragma unroll
;                     for (int j = 0; j < 4; ++j) { const float gt = acc[ai][0][m][n][j] * r, up = acc[ai][1][m][n][j] * r; o[n][j] = gt * sigmoidf_(gt) * up; }
;                 *(u32x4*)(Hd + (size_t)(row0 + ai * 128 + m * 16) * DFF + col0) = pack8(o[0], o[1]);
;             }
	s_nop 1
	v_mov_b32_e32 v98, v242
	s_nop 0
	v_mov_b32_e32 v96, v92
	v_mov_b32_e32 v92, v94
	v_mov_b32_e32 v94, v88
	v_mov_b32_e32 v88, v90
	v_mov_b32_e32 v97, v84
	v_mov_b32_e32 v84, v93
	v_mov_b32_e32 v93, v86
	v_mov_b32_e32 v86, v95
	v_mov_b32_e32 v95, v80
	v_mov_b32_e32 v80, v89
	v_mov_b32_e32 v89, v82
	v_mov_b32_e32 v82, v91
	v_mov_b32_e32 v98, v98
	s_nop 1
	v_add_u32_e32 v90, 32, v144
	v_mad_i64_i32 v[90:91], s[0:1], v90, s64, v[122:123]
	v_lshl_add_u64 v[90:91], v[90:91], 0, v[120:121]
	s_nop 0
	s_nop 1
	s_nop 1
	v_pk_mul_f32 v[82:83], v[82:83], v[98:99] op_sel_hi:[1,0]
	v_pk_mul_f32 v[96:97], v[96:97], v[98:99] op_sel_hi:[1,0]
	v_pk_mul_f32 v[84:85], v[84:85], v[98:99] op_sel_hi:[1,0]
	v_pk_mul_f32 v[92:93], v[92:93], v[98:99] op_sel_hi:[1,0]
	v_pk_mul_f32 v[86:87], v[86:87], v[98:99] op_sel_hi:[1,0]
	v_pk_mul_f32 v[94:95], v[94:95], v[98:99] op_sel_hi:[1,0]
	v_pk_mul_f32 v[80:81], v[80:81], v[98:99] op_sel_hi:[1,0]
	v_pk_mul_f32 v[88:89], v[88:89], v[98:99] op_sel_hi:[1,0]
	v_mul_f32_e32 v105, 0xbfb8aa3b, v83
	v_mul_f32_e32 v98, 0xbfb8aa3b, v97
	v_mul_f32_e32 v99, 0xbfb8aa3b, v85
	v_mul_f32_e32 v100, 0xbfb8aa3b, v93
	v_mul_f32_e32 v101, 0xbfb8aa3b, v87
	v_mul_f32_e32 v102, 0xbfb8aa3b, v95
	v_mul_f32_e32 v103, 0xbfb8aa3b, v81
	v_mul_f32_e32 v104, 0xbfb8aa3b, v89
	v_exp_f32_e32 v105, v105
	v_exp_f32_e32 v98, v98
	v_exp_f32_e32 v99, v99
	v_exp_f32_e32 v100, v100
	v_exp_f32_e32 v101, v101
	v_exp_f32_e32 v102, v102
	v_exp_f32_e32 v103, v103
	v_exp_f32_e32 v104, v104
	v_add_f32_e32 v105, 1.0, v105
	v_add_f32_e32 v98, 1.0, v98
	v_add_f32_e32 v99, 1.0, v99
	v_add_f32_e32 v100, 1.0, v100
	v_add_f32_e32 v101, 1.0, v101
	v_add_f32_e32 v102, 1.0, v102
	v_add_f32_e32 v103, 1.0, v103
	v_add_f32_e32 v104, 1.0, v104
	v_rcp_f32_e32 v105, v105
	v_rcp_f32_e32 v98, v98
	v_rcp_f32_e32 v99, v99
	v_rcp_f32_e32 v100, v100
	v_rcp_f32_e32 v101, v101
	v_rcp_f32_e32 v102, v102
	v_rcp_f32_e32 v103, v103
	v_rcp_f32_e32 v104, v104
	v_mul_f32_e32 v83, v83, v105
	v_mul_f32_e32 v97, v97, v98
	v_mul_f32_e32 v85, v85, v99
	v_mul_f32_e32 v93, v93, v100
	v_mul_f32_e32 v87, v87, v101
	v_mul_f32_e32 v95, v95, v102
	v_mul_f32_e32 v81, v81, v103
	v_mul_f32_e32 v89, v89, v104
	v_mul_f32_e32 v83, v82, v83
	v_mul_f32_e32 v96, v96, v97
	v_mul_f32_e32 v84, v84, v85
	v_mul_f32_e32 v85, v92, v93
	v_mul_f32_e32 v86, v86, v87
	v_mul_f32_e32 v87, v94, v95
	v_mul_f32_e32 v92, v80, v81
	v_mul_f32_e32 v88, v88, v89
	v_cvt_pk_bf16_f32 v80, v96, v84
	v_cvt_pk_bf16_f32 v81, v85, v86
	v_cvt_pk_bf16_f32 v82, v87, v92
	v_cvt_pk_bf16_f32 v83, v88, v83
	global_store_dwordx4 v[90:91], v[80:83], off
	s_waitcnt vmcnt(7)
	s_nop 1
	v_mov_b32_e32 v82, v243
	s_nop 0
	v_mov_b32_e32 v80, v76
	v_mov_b32_e32 v76, v78
	v_mov_b32_e32 v78, v72
	v_mov_b32_e32 v72, v74
	v_mov_b32_e32 v81, v68
	v_mov_b32_e32 v68, v77
	v_mov_b32_e32 v77, v70
	v_mov_b32_e32 v70, v79
	v_mov_b32_e32 v79, v64
	v_mov_b32_e32 v64, v73
	v_mov_b32_e32 v73, v66
	v_mov_b32_e32 v66, v75
	v_mov_b32_e32 v82, v82
	s_nop 1
	v_add_u32_e32 v74, 48, v144
	v_mad_i64_i32 v[74:75], s[0:1], v74, s64, v[122:123]
	v_lshl_add_u64 v[74:75], v[74:75], 0, v[120:121]
	s_nop 0
	s_nop 1
	s_nop 1
	v_pk_mul_f32 v[66:67], v[66:67], v[82:83] op_sel_hi:[1,0]
	v_pk_mul_f32 v[80:81], v[80:81], v[82:83] op_sel_hi:[1,0]
	v_pk_mul_f32 v[68:69], v[68:69], v[82:83] op_sel_hi:[1,0]
	v_pk_mul_f32 v[76:77], v[76:77], v[82:83] op_sel_hi:[1,0]
	v_pk_mul_f32 v[70:71], v[70:71], v[82:83] op_sel_hi:[1,0]
	v_pk_mul_f32 v[78:79], v[78:79], v[82:83] op_sel_hi:[1,0]
	v_pk_mul_f32 v[64:65], v[64:65], v[82:83] op_sel_hi:[1,0]
	v_pk_mul_f32 v[72:73], v[72:73], v[82:83] op_sel_hi:[1,0]
	v_mul_f32_e32 v89, 0xbfb8aa3b, v67
	v_mul_f32_e32 v82, 0xbfb8aa3b, v81
	v_mul_f32_e32 v83, 0xbfb8aa3b, v69
	v_mul_f32_e32 v84, 0xbfb8aa3b, v77
	v_mul_f32_e32 v85, 0xbfb8aa3b, v71
	v_mul_f32_e32 v86, 0xbfb8aa3b, v79
	v_mul_f32_e32 v87, 0xbfb8aa3b, v65
	v_mul_f32_e32 v88, 0xbfb8aa3b, v73
	v_exp_f32_e32 v89, v89
	v_exp_f32_e32 v82, v82
	v_exp_f32_e32 v83, v83
	v_exp_f32_e32 v84, v84
	v_exp_f32_e32 v85, v85
	v_exp_f32_e32 v86, v86
	v_exp_f32_e32 v87, v87
	v_exp_f32_e32 v88, v88
	v_add_f32_e32 v89, 1.0, v89
	v_add_f32_e32 v82, 1.0, v82
	v_add_f32_e32 v83, 1.0, v83
	v_add_f32_e32 v84, 1.0, v84
	v_add_f32_e32 v85, 1.0, v85
	v_add_f32_e32 v86, 1.0, v86
	v_add_f32_e32 v87, 1.0, v87
	v_add_f32_e32 v88, 1.0, v88
	v_rcp_f32_e32 v89, v89
	v_rcp_f32_e32 v82, v82
	v_rcp_f32_e32 v83, v83
	v_rcp_f32_e32 v84, v84
	v_rcp_f32_e32 v85, v85
	v_rcp_f32_e32 v86, v86
	v_rcp_f32_e32 v87, v87
	v_rcp_f32_e32 v88, v88
	v_mul_f32_e32 v67, v67, v89
	v_mul_f32_e32 v81, v81, v82
	v_mul_f32_e32 v69, v69, v83
	v_mul_f32_e32 v77, v77, v84
	v_mul_f32_e32 v71, v71, v85
	v_mul_f32_e32 v79, v79, v86
	v_mul_f32_e32 v65, v65, v87
	v_mul_f32_e32 v73, v73, v88
	v_mul_f32_e32 v67, v66, v67
	v_mul_f32_e32 v80, v80, v81
	v_mul_f32_e32 v68, v68, v69
	v_mul_f32_e32 v69, v76, v77
	v_mul_f32_e32 v70, v70, v71
	v_mul_f32_e32 v71, v78, v79
	v_mul_f32_e32 v76, v64, v65
	v_mul_f32_e32 v72, v72, v73
	v_cvt_pk_bf16_f32 v64, v80, v68
	v_cvt_pk_bf16_f32 v65, v69, v70
	v_cvt_pk_bf16_f32 v66, v71, v76
	v_cvt_pk_bf16_f32 v67, v72, v67
	global_store_dwordx4 v[74:75], v[64:67], off
	s_waitcnt vmcnt(7)
; DI float sigmoidf_(float x) { return __builtin_amdgcn_rcpf(1.0f + __builtin_amdgcn_exp2f(-x * LOG2E)); }
; DI float rs_of(const float* ss, int row) { return 1.0f / sqrtf(ss[row] * (1.0f / DM) + EPS); }
; DI u32x4 pack8(f32x4 a, f32x4 b) { u32x4 w; w.x = cvt_pk_bf16(a[0], a[1]); w.y = cvt_pk_bf16(a[2], a[3]); w.z = cvt_pk_bf16(b[0], b[1]); w.w = cvt_pk_bf16(b[2], b[3]); return w; }
;     DI void operator()(AccRef acc, const Unit& u, int wr, int wc, int fr, int fq) const {
;     ...
;             for (int m = 0; m < 4; ++m) {
;                 f32x4 o[2]; const float r = ss ? rs_of(ss, row0 + ai * 128 + m * 16) : 1.0f;
; #pragma unroll
;                 for (int n = 0; n < 2; ++n)
; #pragma unroll
;                     for (int j = 0; j < 4; ++j) { const float gt = acc[ai][0][m][n][j] * r, up = acc[ai][1][m][n][j] * r; o[n][j] = gt * sigmoidf_(gt) * up; }
;                 *(u32x4*)(Hd + (size_t)(row0 + ai * 128 + m * 16) * DFF + col0) = pack8(o[0], o[1]);
;             }
	s_nop 1
	v_mov_b32_e32 v66, v238
	s_nop 0
	v_mov_b32_e32 v64, v60
	v_mov_b32_e32 v60, v62
	v_mov_b32_e32 v62, v56
	v_mov_b32_e32 v56, v58
	v_mov_b32_e32 v65, v52
	v_mov_b32_e32 v52, v61
	v_mov_b32_e32 v61, v54
	v_mov_b32_e32 v54, v63
	v_mov_b32_e32 v63, v48
	v_mov_b32_e32 v48, v57
	v_mov_b32_e32 v57, v50
	v_mov_b32_e32 v50, v59
	v_mov_b32_e32 v66, v66
	s_nop 1
	v_add_u32_e32 v58, 0x80, v144
	v_mad_i64_i32 v[58:59], s[0:1], v58, s64, v[122:123]
	v_lshl_add_u64 v[58:59], v[58:59], 0, v[120:121]
	s_nop 0
	s_nop 1
	s_nop 1
	v_pk_mul_f32 v[50:51], v[50:51], v[66:67] op_sel_hi:[1,0]
	v_pk_mul_f32 v[64:65], v[64:65], v[66:67] op_sel_hi:[1,0]
	v_pk_mul_f32 v[52:53], v[52:53], v[66:67] op_sel_hi:[1,0]
	v_pk_mul_f32 v[60:61], v[60:61], v[66:67] op_sel_hi:[1,0]
	v_pk_mul_f32 v[54:55], v[54:55], v[66:67] op_sel_hi:[1,0]
	v_pk_mul_f32 v[62:63], v[62:63], v[66:67] op_sel_hi:[1,0]
	v_pk_mul_f32 v[48:49], v[48:49], v[66:67] op_sel_hi:[1,0]
	v_pk_mul_f32 v[56:57], v[56:57], v[66:67] op_sel_hi:[1,0]
	v_mul_f32_e32 v73, 0xbfb8aa3b, v51
	v_mul_f32_e32 v66, 0xbfb8aa3b, v65
	v_mul_f32_e32 v67, 0xbfb8aa3b, v53
	v_mul_f32_e32 v68, 0xbfb8aa3b, v61
	v_mul_f32_e32 v69, 0xbfb8aa3b, v55
	v_mul_f32_e32 v70, 0xbfb8aa3b, v63
	v_mul_f32_e32 v71, 0xbfb8aa3b, v49
	v_mul_f32_e32 v72, 0xbfb8aa3b, v57
	v_exp_f32_e32 v73, v73
	v_exp_f32_e32 v66, v66
	v_exp_f32_e32 v67, v67
	v_exp_f32_e32 v68, v68
	v_exp_f32_e32 v69, v69
	v_exp_f32_e32 v70, v70
	v_exp_f32_e32 v71, v71
	v_exp_f32_e32 v72, v72
	v_add_f32_e32 v73, 1.0, v73
	v_add_f32_e32 v66, 1.0, v66
	v_add_f32_e32 v67, 1.0, v67
	v_add_f32_e32 v68, 1.0, v68
	v_add_f32_e32 v69, 1.0, v69
	v_add_f32_e32 v70, 1.0, v70
	v_add_f32_e32 v71, 1.0, v71
	v_add_f32_e32 v72, 1.0, v72
	v_rcp_f32_e32 v73, v73
	v_rcp_f32_e32 v66, v66
	v_rcp_f32_e32 v67, v67
	v_rcp_f32_e32 v68, v68
	v_rcp_f32_e32 v69, v69
	v_rcp_f32_e32 v70, v70
	v_rcp_f32_e32 v71, v71
	v_rcp_f32_e32 v72, v72
	v_mul_f32_e32 v51, v51, v73
	v_mul_f32_e32 v65, v65, v66
	v_mul_f32_e32 v53, v53, v67
	v_mul_f32_e32 v61, v61, v68
	v_mul_f32_e32 v55, v55, v69
	v_mul_f32_e32 v63, v63, v70
	v_mul_f32_e32 v49, v49, v71
	v_mul_f32_e32 v57, v57, v72
	v_mul_f32_e32 v51, v50, v51
	v_mul_f32_e32 v64, v64, v65
	v_mul_f32_e32 v52, v52, v53
	v_mul_f32_e32 v53, v60, v61
	v_mul_f32_e32 v54, v54, v55
	v_mul_f32_e32 v55, v62, v63
	v_mul_f32_e32 v60, v48, v49
	v_mul_f32_e32 v56, v56, v57
	v_cvt_pk_bf16_f32 v48, v64, v52
	v_cvt_pk_bf16_f32 v49, v53, v54
	v_cvt_pk_bf16_f32 v50, v55, v60
	v_cvt_pk_bf16_f32 v51, v56, v51
	global_store_dwordx4 v[58:59], v[48:51], off
	s_waitcnt vmcnt(7)
	s_nop 1
	v_mov_b32_e32 v50, v239
	s_nop 0
	v_mov_b32_e32 v48, v44
	v_mov_b32_e32 v44, v46
	v_mov_b32_e32 v46, v40
	v_mov_b32_e32 v40, v42
	v_mov_b32_e32 v49, v36
	v_mov_b32_e32 v36, v45
	v_mov_b32_e32 v45, v38
	v_mov_b32_e32 v38, v47
	v_mov_b32_e32 v47, v32
	v_mov_b32_e32 v32, v41
	v_mov_b32_e32 v41, v34
	v_mov_b32_e32 v34, v43
	v_mov_b32_e32 v50, v50
	s_nop 1
	v_add_u32_e32 v42, 0x90, v144
	v_mad_i64_i32 v[42:43], s[0:1], v42, s64, v[122:123]
	v_lshl_add_u64 v[42:43], v[42:43], 0, v[120:121]
	s_nop 0
	s_nop 1
	s_nop 1
	v_pk_mul_f32 v[34:35], v[34:35], v[50:51] op_sel_hi:[1,0]
	v_pk_mul_f32 v[48:49], v[48:49], v[50:51] op_sel_hi:[1,0]
	v_pk_mul_f32 v[36:37], v[36:37], v[50:51] op_sel_hi:[1,0]
	v_pk_mul_f32 v[44:45], v[44:45], v[50:51] op_sel_hi:[1,0]
	v_pk_mul_f32 v[38:39], v[38:39], v[50:51] op_sel_hi:[1,0]
	v_pk_mul_f32 v[46:47], v[46:47], v[50:51] op_sel_hi:[1,0]
	v_pk_mul_f32 v[32:33], v[32:33], v[50:51] op_sel_hi:[1,0]
	v_pk_mul_f32 v[40:41], v[40:41], v[50:51] op_sel_hi:[1,0]
	v_mul_f32_e32 v57, 0xbfb8aa3b, v35
	v_mul_f32_e32 v50, 0xbfb8aa3b, v49
	v_mul_f32_e32 v51, 0xbfb8aa3b, v37
	v_mul_f32_e32 v52, 0xbfb8aa3b, v45
	v_mul_f32_e32 v53, 0xbfb8aa3b, v39
	v_mul_f32_e32 v54, 0xbfb8aa3b, v47
	v_mul_f32_e32 v55, 0xbfb8aa3b, v33
	v_mul_f32_e32 v56, 0xbfb8aa3b, v41
	v_exp_f32_e32 v57, v57
	v_exp_f32_e32 v50, v50
	v_exp_f32_e32 v51, v51
	v_exp_f32_e32 v52, v52
	v_exp_f32_e32 v53, v53
	v_exp_f32_e32 v54, v54
	v_exp_f32_e32 v55, v55
	v_exp_f32_e32 v56, v56
	v_add_f32_e32 v57, 1.0, v57
	v_add_f32_e32 v50, 1.0, v50
	v_add_f32_e32 v51, 1.0, v51
	v_add_f32_e32 v52, 1.0, v52
	v_add_f32_e32 v53, 1.0, v53
	v_add_f32_e32 v54, 1.0, v54
	v_add_f32_e32 v55, 1.0, v55
	v_add_f32_e32 v56, 1.0, v56
	v_rcp_f32_e32 v57, v57
	v_rcp_f32_e32 v50, v50
	v_rcp_f32_e32 v51, v51
	v_rcp_f32_e32 v52, v52
	v_rcp_f32_e32 v53, v53
	v_rcp_f32_e32 v54, v54
	v_rcp_f32_e32 v55, v55
	v_rcp_f32_e32 v56, v56
	v_mul_f32_e32 v35, v35, v57
	v_mul_f32_e32 v49, v49, v50
	v_mul_f32_e32 v37, v37, v51
	v_mul_f32_e32 v45, v45, v52
	v_mul_f32_e32 v39, v39, v53
	v_mul_f32_e32 v47, v47, v54
	v_mul_f32_e32 v33, v33, v55
	v_mul_f32_e32 v41, v41, v56
	v_mul_f32_e32 v35, v34, v35
	v_mul_f32_e32 v48, v48, v49
	v_mul_f32_e32 v36, v36, v37
	v_mul_f32_e32 v37, v44, v45
	v_mul_f32_e32 v38, v38, v39
	v_mul_f32_e32 v39, v46, v47
	v_mul_f32_e32 v44, v32, v33
	v_mul_f32_e32 v40, v40, v41
	v_cvt_pk_bf16_f32 v32, v48, v36
	v_cvt_pk_bf16_f32 v33, v37, v38
	v_cvt_pk_bf16_f32 v34, v39, v44
	v_cvt_pk_bf16_f32 v35, v40, v35
	global_store_dwordx4 v[42:43], v[32:35], off
	s_waitcnt vmcnt(7)
; DI float sigmoidf_(float x) { return __builtin_amdgcn_rcpf(1.0f + __builtin_amdgcn_exp2f(-x * LOG2E)); }
; DI float rs_of(const float* ss, int row) { return 1.0f / sqrtf(ss[row] * (1.0f / DM) + EPS); }
; DI u32x4 pack8(f32x4 a, f32x4 b) { u32x4 w; w.x = cvt_pk_bf16(a[0], a[1]); w.y = cvt_pk_bf16(a[2], a[3]); w.z = cvt_pk_bf16(b[0], b[1]); w.w = cvt_pk_bf16(b[2], b[3]); return w; }
;     DI void operator()(AccRef acc, const Unit& u, int wr, int wc, int fr, int fq) const {
;     ...
;             for (int m = 0; m < 4; ++m) {
;                 f32x4 o[2]; const float r = ss ? rs_of(ss, row0 + ai * 128 + m * 16) : 1.0f;
; #pragma unroll
;                 for (int n = 0; n < 2; ++n)
; #pragma unroll
;                     for (int j = 0; j < 4; ++j) { const float gt = acc[ai][0][m][n][j] * r, up = acc[ai][1][m][n][j] * r; o[n][j] = gt * sigmoidf_(gt) * up; }
;                 *(u32x4*)(Hd + (size_t)(row0 + ai * 128 + m * 16) * DFF + col0) = pack8(o[0], o[1]);
;             }
	s_nop 1
	v_mov_b32_e32 v34, v240
	s_nop 0
	v_mov_b32_e32 v32, v28
	v_mov_b32_e32 v28, v30
	v_mov_b32_e32 v30, v24
	v_mov_b32_e32 v24, v26
	v_mov_b32_e32 v33, v20
	v_mov_b32_e32 v20, v29
	v_mov_b32_e32 v29, v22
	v_mov_b32_e32 v22, v31
	v_mov_b32_e32 v31, v16
	v_mov_b32_e32 v16, v25
	v_mov_b32_e32 v25, v18
	v_mov_b32_e32 v18, v27
	v_mov_b32_e32 v34, v34
	s_nop 1
	v_add_u32_e32 v26, 0xa0, v144
	v_mad_i64_i32 v[26:27], s[0:1], v26, s64, v[122:123]
	v_lshl_add_u64 v[26:27], v[26:27], 0, v[120:121]
	s_nop 0
	s_nop 1
	s_nop 1
	v_pk_mul_f32 v[18:19], v[18:19], v[34:35] op_sel_hi:[1,0]
	v_pk_mul_f32 v[32:33], v[32:33], v[34:35] op_sel_hi:[1,0]
	v_pk_mul_f32 v[20:21], v[20:21], v[34:35] op_sel_hi:[1,0]
	v_pk_mul_f32 v[28:29], v[28:29], v[34:35] op_sel_hi:[1,0]
	v_pk_mul_f32 v[22:23], v[22:23], v[34:35] op_sel_hi:[1,0]
	v_pk_mul_f32 v[30:31], v[30:31], v[34:35] op_sel_hi:[1,0]
	v_pk_mul_f32 v[16:17], v[16:17], v[34:35] op_sel_hi:[1,0]
	v_pk_mul_f32 v[24:25], v[24:25], v[34:35] op_sel_hi:[1,0]
	v_mul_f32_e32 v41, 0xbfb8aa3b, v19
	v_mul_f32_e32 v34, 0xbfb8aa3b, v33
	v_mul_f32_e32 v35, 0xbfb8aa3b, v21
	v_mul_f32_e32 v36, 0xbfb8aa3b, v29
	v_mul_f32_e32 v37, 0xbfb8aa3b, v23
	v_mul_f32_e32 v38, 0xbfb8aa3b, v31
	v_mul_f32_e32 v39, 0xbfb8aa3b, v17
	v_mul_f32_e32 v40, 0xbfb8aa3b, v25
	v_exp_f32_e32 v41, v41
	v_exp_f32_e32 v34, v34
	v_exp_f32_e32 v35, v35
	v_exp_f32_e32 v36, v36
	v_exp_f32_e32 v37, v37
	v_exp_f32_e32 v38, v38
	v_exp_f32_e32 v39, v39
	v_exp_f32_e32 v40, v40
	v_add_f32_e32 v41, 1.0, v41
	v_add_f32_e32 v34, 1.0, v34
	v_add_f32_e32 v35, 1.0, v35
	v_add_f32_e32 v36, 1.0, v36
	v_add_f32_e32 v37, 1.0, v37
	v_add_f32_e32 v38, 1.0, v38
	v_add_f32_e32 v39, 1.0, v39
	v_add_f32_e32 v40, 1.0, v40
	v_rcp_f32_e32 v41, v41
	v_rcp_f32_e32 v34, v34
	v_rcp_f32_e32 v35, v35
	v_rcp_f32_e32 v36, v36
	v_rcp_f32_e32 v37, v37
	v_rcp_f32_e32 v38, v38
	v_rcp_f32_e32 v39, v39
	v_rcp_f32_e32 v40, v40
	v_mul_f32_e32 v19, v19, v41
	v_mul_f32_e32 v33, v33, v34
	v_mul_f32_e32 v21, v21, v35
	v_mul_f32_e32 v29, v29, v36
	v_mul_f32_e32 v23, v23, v37
	v_mul_f32_e32 v31, v31, v38
	v_mul_f32_e32 v17, v17, v39
	v_mul_f32_e32 v25, v25, v40
	v_mul_f32_e32 v19, v18, v19
	v_mul_f32_e32 v32, v32, v33
	v_mul_f32_e32 v20, v20, v21
	v_mul_f32_e32 v21, v28, v29
	v_mul_f32_e32 v22, v22, v23
	v_mul_f32_e32 v23, v30, v31
	v_mul_f32_e32 v28, v16, v17
	v_mul_f32_e32 v24, v24, v25
	v_cvt_pk_bf16_f32 v16, v32, v20
	v_cvt_pk_bf16_f32 v17, v21, v22
	v_cvt_pk_bf16_f32 v18, v23, v28
	v_cvt_pk_bf16_f32 v19, v24, v19
	global_store_dwordx4 v[26:27], v[16:19], off
	s_waitcnt vmcnt(7)
	s_nop 1
	v_mov_b32_e32 v18, v241
	s_nop 0
	v_mov_b32_e32 v16, v12
	v_mov_b32_e32 v12, v14
	v_mov_b32_e32 v14, v8
	v_mov_b32_e32 v8, v10
	v_mov_b32_e32 v17, v4
	v_mov_b32_e32 v4, v13
	v_mov_b32_e32 v13, v6
	v_mov_b32_e32 v6, v15
	v_mov_b32_e32 v15, v0
	v_mov_b32_e32 v0, v9
	v_mov_b32_e32 v9, v2
	v_mov_b32_e32 v2, v11
	v_mov_b32_e32 v18, v18
	s_nop 1
	v_add_u32_e32 v10, 0xb0, v144
	v_mad_i64_i32 v[10:11], s[0:1], v10, s64, v[122:123]
	v_lshl_add_u64 v[10:11], v[10:11], 0, v[120:121]
	s_nop 0
	s_nop 1
	s_nop 1
	v_pk_mul_f32 v[2:3], v[2:3], v[18:19] op_sel_hi:[1,0]
	v_pk_mul_f32 v[16:17], v[16:17], v[18:19] op_sel_hi:[1,0]
	v_pk_mul_f32 v[4:5], v[4:5], v[18:19] op_sel_hi:[1,0]
	v_pk_mul_f32 v[12:13], v[12:13], v[18:19] op_sel_hi:[1,0]
	v_pk_mul_f32 v[6:7], v[6:7], v[18:19] op_sel_hi:[1,0]
	v_pk_mul_f32 v[14:15], v[14:15], v[18:19] op_sel_hi:[1,0]
	v_pk_mul_f32 v[0:1], v[0:1], v[18:19] op_sel_hi:[1,0]
	v_pk_mul_f32 v[8:9], v[8:9], v[18:19] op_sel_hi:[1,0]
	v_mul_f32_e32 v25, 0xbfb8aa3b, v3
	v_mul_f32_e32 v18, 0xbfb8aa3b, v17
	v_mul_f32_e32 v19, 0xbfb8aa3b, v5
	v_mul_f32_e32 v20, 0xbfb8aa3b, v13
	v_mul_f32_e32 v21, 0xbfb8aa3b, v7
	v_mul_f32_e32 v22, 0xbfb8aa3b, v15
	v_mul_f32_e32 v23, 0xbfb8aa3b, v1
	v_mul_f32_e32 v24, 0xbfb8aa3b, v9
	v_exp_f32_e32 v25, v25
	v_exp_f32_e32 v18, v18
	v_exp_f32_e32 v19, v19
	v_exp_f32_e32 v20, v20
	v_exp_f32_e32 v21, v21
	v_exp_f32_e32 v22, v22
	v_exp_f32_e32 v23, v23
	v_exp_f32_e32 v24, v24
	v_add_f32_e32 v25, 1.0, v25
	v_add_f32_e32 v18, 1.0, v18
	v_add_f32_e32 v19, 1.0, v19
	v_add_f32_e32 v20, 1.0, v20
	v_add_f32_e32 v21, 1.0, v21
	v_add_f32_e32 v22, 1.0, v22
	v_add_f32_e32 v23, 1.0, v23
	v_add_f32_e32 v24, 1.0, v24
	v_rcp_f32_e32 v25, v25
	v_rcp_f32_e32 v18, v18
	v_rcp_f32_e32 v19, v19
	v_rcp_f32_e32 v20, v20
	v_rcp_f32_e32 v21, v21
	v_rcp_f32_e32 v22, v22
	v_rcp_f32_e32 v23, v23
	v_rcp_f32_e32 v24, v24
	v_mul_f32_e32 v3, v3, v25
	v_mul_f32_e32 v17, v17, v18
	v_mul_f32_e32 v5, v5, v19
	v_mul_f32_e32 v13, v13, v20
	v_mul_f32_e32 v7, v7, v21
	v_mul_f32_e32 v15, v15, v22
	v_mul_f32_e32 v1, v1, v23
	v_mul_f32_e32 v9, v9, v24
	v_mul_f32_e32 v3, v2, v3
	s_mov_b64 vcc, s[6:7]
	v_mul_f32_e32 v16, v16, v17
	v_mul_f32_e32 v4, v4, v5
	v_mul_f32_e32 v5, v12, v13
	v_mul_f32_e32 v6, v6, v7
	v_mul_f32_e32 v7, v14, v15
	v_mul_f32_e32 v12, v0, v1
	v_mul_f32_e32 v8, v8, v9
	v_cvt_pk_bf16_f32 v0, v16, v4
	v_cvt_pk_bf16_f32 v1, v5, v6
	v_cvt_pk_bf16_f32 v2, v7, v12
	v_cvt_pk_bf16_f32 v3, v8, v3
	global_store_dwordx4 v[10:11], v[0:3], off
	s_cbranch_vccz .LBB0_1661
	s_waitcnt vmcnt(0)
	s_cmpk_gt_u32 s3, 0xff
	s_cbranch_scc1 .LBB0_1672
	s_barrier

;     DI size_t aoff(const Unit& u, size_t tstep) const { return (size_t)u.pm * tstep; }
;     DI size_t boff(const Unit& u, size_t tstep) const { return (size_t)u.pn * tstep; }
;     DI size_t aoff(const Unit& u, size_t) const { return (size_t)u.ks * kbytes; }
; template <class Epi, class Sched>
; DI void gemm_phase(LAS unsigned char* lds, const Gemm g, const Sched& S, const Epi& E) {
;     ...
;         const bool has_next = S.next(ui + 1, nxt);
;         const char* nA = has_next ? (const char*)g.A + S.aoff(nxt, tstep) : cA; const char* nB = has_next ? (const char*)g.Bt + S.boff(nxt, tstep) : cB;
;         for (int t = 0; t < nt; t += 2) {
;             if constexpr (Epi::HAS_MID) { if (t == E.mid_t(nt)) { int fr3 = fr, fq3 = fq; asm volatile("" : "+v"(fr3), "+v"(fq3)); E.mid(acc, cur, wr, wc, fr3, fq3); } }
;             const bool last = (t == nt - 2);
;             const char* a1 = cA + (size_t)(t + 1) * kstep;
;             const char* a2 = last ? nA : cA + (size_t)(t + 2) * kstep; const char* b2 = last ? nB : cB + (size_t)(t + 2) * kstep;
;             const char* a3 = a2 + kstep; const char* b3 = b2 + kstep;
;             PG8_LDB(B0, 0, 0); PG8_SCHED; PG8_LDA(At, 0, 0); PG8_STAGE(PG8_SA(1, 1), a1 + hstep, voffA);
;             PG8_WAIT_L(8); PG8_BAR; PG8_WAIT_L(0); PG8_MMA(0, 0, At, B0); PG8_BAR; PG8_SCHED;
;             PG8_LDB(B1, 0, 1); PG8_STAGE(PG8_SB(0, 0), b2, voffB);
;             PG8_BAR; PG8_WAIT_L(0); PG8_MMA(0, 1, At, B1); PG8_BAR;
;             PG8_LDA(At, 0, 1); PG8_STAGE(PG8_SA(0, 0), a2, voffA);
;             PG8_BAR; PG8_WAIT_L(0); PG8_MMA(1, 0, At, B0); PG8_BAR; PG8_SCHED;
;             PG8_STAGE(PG8_SB(0, 1), b2 + hstep, voffB);
;             PG8_WAIT_V(6); PG8_BAR; PG8_MMA(1, 1, At, B1); PG8_BAR;
;             PG8_LDB(B0, 1, 0); PG8_SCHED; PG8_LDA(At, 1, 0); PG8_STAGE(PG8_SA(0, 1), a2 + hstep, voffA);
;             PG8_WAIT_L(8); PG8_BAR; PG8_WAIT_L(0); PG8_MMA(0, 0, At, B0); PG8_BAR; PG8_SCHED;
;             PG8_LDB(B1, 1, 1); PG8_STAGE(PG8_SB(1, 0), b3, voffB);
;             PG8_BAR; PG8_WAIT_L(0); PG8_MMA(0, 1, At, B1); PG8_BAR;
;             PG8_LDA(At, 1, 1); PG8_STAGE(PG8_SA(1, 0), a3, voffA);
;             PG8_BAR; PG8_WAIT_L(0); PG8_MMA(1, 0, At, B0); PG8_BAR; PG8_SCHED;
;             PG8_STAGE(PG8_SB(1, 1), b3 + hstep, voffB);
;             PG8_WAIT_V(6); PG8_BAR; PG8_MMA(1, 1, At, B1); PG8_BAR;
.LBB0_1745:
	s_add_u32 s38, s38, 0x160080
	s_addc_u32 s39, s39, 0
	s_add_u32 s35, s40, 0x100
	v_mov_b32_e32 v0, 0
	s_addc_u32 s67, s41, 0
	s_mov_b32 s68, -2
	s_waitcnt lgkmcnt(0)
	ds_read_b128 v[144:147], v155
	ds_read_b128 v[160:163], v155 offset:1024
	ds_read_b128 v[164:167], v155 offset:2048
	ds_read_b128 v[168:171], v155 offset:3072
	s_add_u32 s0, s38, 0xffea0080
	s_addc_u32 s1, s39, -1
	s_cmpk_eq_i32 s68, 0x54
	s_cselect_b32 s43, s9, s1
	s_cselect_b32 s42, s8, s0
	s_cselect_b32 s41, s11, s67
	s_cselect_b32 s40, s10, s35
	v_lshl_add_u64 v[202:203], s[38:39], 0, v[136:137]
	s_add_i32 m0, s52, 0xc000
	ds_read_b128 v[172:175], v156
	ds_read_b128 v[176:179], v156 offset:1024
	ds_read_b128 v[180:183], v156 offset:2048
	ds_read_b128 v[188:191], v156 offset:3072
	ds_read_b128 v[206:209], v156 offset:4096
	ds_read_b128 v[210:213], v156 offset:5120
	ds_read_b128 v[214:217], v156 offset:6144
	ds_read_b128 v[218:221], v156 offset:7168
	global_load_lds_dwordx4 v[202:203], off
	v_lshl_add_u64 v[202:203], s[38:39], 0, v[138:139]
	s_add_i32 m0, s52, 0xe000
	s_nop 0
	global_load_lds_dwordx4 v[202:203], off
	s_waitcnt lgkmcnt(8)
	s_barrier
	s_waitcnt lgkmcnt(0)
	s_setprio 1
	s_waitcnt lgkmcnt(0)
	v_mfma_f32_16x16x32_bf16 v[124:127], v[144:147], v[172:175], 0
	v_mfma_f32_16x16x32_bf16 v[120:123], v[164:167], v[172:175], 0
	v_mfma_f32_16x16x32_bf16 v[108:111], v[144:147], v[180:183], 0
	v_mfma_f32_16x16x32_bf16 v[104:107], v[164:167], v[180:183], 0
	v_mfma_f32_16x16x32_bf16 v[92:95], v[144:147], v[206:209], 0
	v_mfma_f32_16x16x32_bf16 v[88:91], v[164:167], v[206:209], 0
	v_mfma_f32_16x16x32_bf16 v[76:79], v[144:147], v[214:217], 0
	v_mfma_f32_16x16x32_bf16 v[72:75], v[164:167], v[214:217], 0
	v_mfma_f32_16x16x32_bf16 v[124:127], v[160:163], v[176:179], v[124:127]
	v_mfma_f32_16x16x32_bf16 v[120:123], v[168:171], v[176:179], v[120:123]
	v_mfma_f32_16x16x32_bf16 v[108:111], v[160:163], v[188:191], v[108:111]
	v_mfma_f32_16x16x32_bf16 v[104:107], v[168:171], v[188:191], v[104:107]
	v_mfma_f32_16x16x32_bf16 v[92:95], v[160:163], v[210:213], v[92:95]
	v_mfma_f32_16x16x32_bf16 v[88:91], v[168:171], v[210:213], v[88:91]
	v_mfma_f32_16x16x32_bf16 v[76:79], v[160:163], v[218:221], v[76:79]
	v_mfma_f32_16x16x32_bf16 v[72:75], v[168:171], v[218:221], v[72:75]
	s_setprio 0
	s_barrier
	s_add_i32 s0, s61, s51
	v_lshl_add_u64 v[202:203], s[40:41], 0, v[130:131]
	s_mov_b32 m0, s0
	ds_read_b128 v[222:225], v157
	ds_read_b128 v[226:229], v157 offset:1024
	ds_read_b128 v[230:233], v157 offset:2048
	ds_read_b128 v[234:237], v157 offset:3072
	global_load_lds_dwordx4 v[202:203], off
	v_lshl_add_u64 v[238:239], s[40:41], 0, v[134:135]
	s_add_i32 m0, s0, 0x2000
	s_nop 0
	global_load_lds_dwordx4 v[238:239], off
	s_barrier
	s_waitcnt lgkmcnt(0)
	s_setprio 1
	s_waitcnt lgkmcnt(0)
	v_mfma_f32_16x16x32_bf16 v[116:119], v[222:225], v[172:175], 0
	v_mfma_f32_16x16x32_bf16 v[112:115], v[230:233], v[172:175], 0
	v_mfma_f32_16x16x32_bf16 v[100:103], v[222:225], v[180:183], 0
	v_mfma_f32_16x16x32_bf16 v[96:99], v[230:233], v[180:183], 0
	v_mfma_f32_16x16x32_bf16 v[84:87], v[222:225], v[206:209], 0
	v_mfma_f32_16x16x32_bf16 v[80:83], v[230:233], v[206:209], 0
	v_mfma_f32_16x16x32_bf16 v[68:71], v[222:225], v[214:217], 0
	v_mfma_f32_16x16x32_bf16 v[64:67], v[230:233], v[214:217], 0
	v_mfma_f32_16x16x32_bf16 v[116:119], v[226:229], v[176:179], v[116:119]
	v_mfma_f32_16x16x32_bf16 v[112:115], v[234:237], v[176:179], v[112:115]
	v_mfma_f32_16x16x32_bf16 v[100:103], v[226:229], v[188:191], v[100:103]
	v_mfma_f32_16x16x32_bf16 v[96:99], v[234:237], v[188:191], v[96:99]
	v_mfma_f32_16x16x32_bf16 v[84:87], v[226:229], v[210:213], v[84:87]
	v_mfma_f32_16x16x32_bf16 v[80:83], v[234:237], v[210:213], v[80:83]
	v_mfma_f32_16x16x32_bf16 v[68:71], v[226:229], v[218:221], v[68:71]
	v_mfma_f32_16x16x32_bf16 v[64:67], v[234:237], v[218:221], v[64:67]
	s_setprio 0
	s_mov_b32 m0, s52
	v_lshl_add_u64 v[240:241], s[42:43], 0, v[128:129]
	s_barrier
	ds_read_b128 v[172:175], v156 offset:16384
	ds_read_b128 v[176:179], v156 offset:17408
	ds_read_b128 v[180:183], v156 offset:18432
	ds_read_b128 v[188:191], v156 offset:19456
	ds_read_b128 v[206:209], v156 offset:20480
	ds_read_b128 v[210:213], v156 offset:21504
	ds_read_b128 v[214:217], v156 offset:22528
	ds_read_b128 v[218:221], v156 offset:23552
	global_load_lds_dwordx4 v[240:241], off
	v_lshl_add_u64 v[242:243], s[42:43], 0, v[132:133]
	s_mov_b32 m0, s53
	s_nop 0
	global_load_lds_dwordx4 v[242:243], off
	s_barrier
	s_waitcnt lgkmcnt(0)
	s_setprio 1
	s_waitcnt lgkmcnt(0)
	v_mfma_f32_16x16x32_bf16 v[60:63], v[144:147], v[172:175], 0
	v_mfma_f32_16x16x32_bf16 v[56:59], v[164:167], v[172:175], 0
	v_mfma_f32_16x16x32_bf16 v[44:47], v[144:147], v[180:183], 0
	v_mfma_f32_16x16x32_bf16 v[40:43], v[164:167], v[180:183], 0
	v_mfma_f32_16x16x32_bf16 v[28:31], v[144:147], v[206:209], 0
	v_mfma_f32_16x16x32_bf16 v[24:27], v[164:167], v[206:209], 0
	v_mfma_f32_16x16x32_bf16 v[12:15], v[144:147], v[214:217], 0
	v_mfma_f32_16x16x32_bf16 v[8:11], v[164:167], v[214:217], 0
	v_mfma_f32_16x16x32_bf16 v[60:63], v[160:163], v[176:179], v[60:63]
	v_mfma_f32_16x16x32_bf16 v[56:59], v[168:171], v[176:179], v[56:59]
	v_mfma_f32_16x16x32_bf16 v[44:47], v[160:163], v[188:191], v[44:47]
	v_mfma_f32_16x16x32_bf16 v[40:43], v[168:171], v[188:191], v[40:43]
	v_mfma_f32_16x16x32_bf16 v[28:31], v[160:163], v[210:213], v[28:31]
	v_mfma_f32_16x16x32_bf16 v[24:27], v[168:171], v[210:213], v[24:27]
	v_mfma_f32_16x16x32_bf16 v[12:15], v[160:163], v[218:221], v[12:15]
	v_mfma_f32_16x16x32_bf16 v[8:11], v[168:171], v[218:221], v[8:11]
	s_setprio 0
	s_barrier
; #define PG8_STAGE(bufoff, gbase, voff) do { _Pragma("unroll") for (int _i = 0; _i < 2; ++_i) \
;         __builtin_amdgcn_global_load_lds((const unsigned*)((const char*)(gbase) + (voff)[_i]), (LAS unsigned*)(lds + (bufoff) + ldsw + _i * 8192), 16, 0, 0); } while (0)
; #define PG8_LDA(dst, b, h) do { _Pragma("unroll") for (int m = 0; m < 4; ++m) _Pragma("unroll") for (int k = 0; k < 2; ++k) dst[m][k] = *(const LAS bf16x8*)(lds + PG8_SA(b, h) + aoff + m * 2048 + k * 1024); } while (0)
; #define PG8_LDB(dst, b, h) do { _Pragma("unroll") for (int n = 0; n < 2; ++n) _Pragma("unroll") for (int k = 0; k < 2; ++k) dst[n][k] = *(const LAS bf16x8*)(lds + PG8_SB(b, h) + boff + n * 2048 + k * 1024); } while (0)
; #define PG8_WAIT_V(n) asm volatile("s_waitcnt vmcnt(" #n ")" ::: "memory")
; #define PG8_WAIT_L(n) asm volatile("s_waitcnt lgkmcnt(" #n ")" ::: "memory")
; #define PG8_BAR __builtin_amdgcn_s_barrier()
; #define PG8_SCHED __builtin_amdgcn_sched_barrier(0)
; template <class Epi, class Sched>
; DI void gemm_phase(LAS unsigned char* lds, const Gemm g, const Sched& S, const Epi& E) {
;     ...
;             PG8_LDB(B0, 0, 0); PG8_SCHED; PG8_LDA(At, 0, 0); PG8_STAGE(PG8_SA(1, 1), a1 + hstep, voffA);
;             PG8_WAIT_L(8); PG8_BAR; PG8_WAIT_L(0); PG8_MMA(0, 0, At, B0); PG8_BAR; PG8_SCHED;
;             PG8_LDB(B1, 0, 1); PG8_STAGE(PG8_SB(0, 0), b2, voffB);
;             PG8_BAR; PG8_WAIT_L(0); PG8_MMA(0, 1, At, B1); PG8_BAR;
;             PG8_LDA(At, 0, 1); PG8_STAGE(PG8_SA(0, 0), a2, voffA);
;             PG8_BAR; PG8_WAIT_L(0); PG8_MMA(1, 0, At, B0); PG8_BAR; PG8_SCHED;
;             PG8_STAGE(PG8_SB(0, 1), b2 + hstep, voffB);
;             PG8_WAIT_V(6); PG8_BAR; PG8_MMA(1, 1, At, B1); PG8_BAR;
;             PG8_LDB(B0, 1, 0); PG8_SCHED; PG8_LDA(At, 1, 0); PG8_STAGE(PG8_SA(0, 1), a2 + hstep, voffA);
;             PG8_WAIT_L(8); PG8_BAR; PG8_WAIT_L(0); PG8_MMA(0, 0, At, B0); PG8_BAR; PG8_SCHED;
;             PG8_LDB(B1, 1, 1); PG8_STAGE(PG8_SB(1, 0), b3, voffB);
;             PG8_BAR; PG8_WAIT_L(0); PG8_MMA(0, 1, At, B1); PG8_BAR;
;             PG8_LDA(At, 1, 1); PG8_STAGE(PG8_SA(1, 0), a3, voffA);
;             PG8_BAR; PG8_WAIT_L(0); PG8_MMA(1, 0, At, B0); PG8_BAR; PG8_SCHED;
;             PG8_STAGE(PG8_SB(1, 1), b3 + hstep, voffB);
;             PG8_WAIT_V(6); PG8_BAR; PG8_MMA(1, 1, At, B1); PG8_BAR;
	s_add_u32 s0, s40, 0x160000
	s_addc_u32 s1, s41, 0
	s_add_i32 s4, s62, s51
	v_lshl_add_u64 v[144:145], s[0:1], 0, v[130:131]
	s_mov_b32 m0, s4
	s_nop 0
	global_load_lds_dwordx4 v[144:145], off
	v_lshl_add_u64 v[144:145], s[0:1], 0, v[134:135]
	s_add_i32 m0, s4, 0x2000
	s_nop 0
	global_load_lds_dwordx4 v[144:145], off
	s_waitcnt vmcnt(6)
	s_barrier
	s_setprio 1
	v_mfma_f32_16x16x32_bf16 v[52:55], v[222:225], v[172:175], 0
	v_mfma_f32_16x16x32_bf16 v[48:51], v[230:233], v[172:175], 0
	v_mfma_f32_16x16x32_bf16 v[36:39], v[222:225], v[180:183], 0
	v_mfma_f32_16x16x32_bf16 v[32:35], v[230:233], v[180:183], 0
	v_mfma_f32_16x16x32_bf16 v[20:23], v[222:225], v[206:209], 0
	v_mfma_f32_16x16x32_bf16 v[16:19], v[230:233], v[206:209], 0
	v_mfma_f32_16x16x32_bf16 v[4:7], v[222:225], v[214:217], 0
	v_mfma_f32_16x16x32_bf16 v[0:3], v[230:233], v[214:217], 0
	v_mfma_f32_16x16x32_bf16 v[52:55], v[226:229], v[176:179], v[52:55]
	v_mfma_f32_16x16x32_bf16 v[48:51], v[234:237], v[176:179], v[48:51]
	v_mfma_f32_16x16x32_bf16 v[36:39], v[226:229], v[188:191], v[36:39]
	v_mfma_f32_16x16x32_bf16 v[32:35], v[234:237], v[188:191], v[32:35]
	v_mfma_f32_16x16x32_bf16 v[20:23], v[226:229], v[210:213], v[20:23]
	v_mfma_f32_16x16x32_bf16 v[16:19], v[234:237], v[210:213], v[16:19]
	v_mfma_f32_16x16x32_bf16 v[4:7], v[226:229], v[218:221], v[4:7]
	v_mfma_f32_16x16x32_bf16 v[0:3], v[234:237], v[218:221], v[0:3]
	s_setprio 0
	s_add_i32 s4, 0, 0x18000
	v_add_u32_e32 v159, s4, v154
	s_barrier
	ds_read_b128 v[144:147], v159
	ds_read_b128 v[160:163], v159 offset:1024
	ds_read_b128 v[164:167], v159 offset:2048
	ds_read_b128 v[168:171], v159 offset:3072
	s_add_u32 s0, s42, 0x160000
	s_addc_u32 s1, s43, 0
	s_mov_b32 m0, s54
	v_lshl_add_u64 v[222:223], s[0:1], 0, v[128:129]
	ds_read_b128 v[172:175], v156 offset:32768
	ds_read_b128 v[176:179], v156 offset:33792
	ds_read_b128 v[180:183], v156 offset:34816
	ds_read_b128 v[188:191], v156 offset:35840
	ds_read_b128 v[206:209], v156 offset:36864
	ds_read_b128 v[210:213], v156 offset:37888
	ds_read_b128 v[214:217], v156 offset:38912
	ds_read_b128 v[218:221], v156 offset:39936
	global_load_lds_dwordx4 v[222:223], off
	v_lshl_add_u64 v[222:223], s[0:1], 0, v[132:133]
	s_mov_b32 m0, s55
	s_nop 0
	global_load_lds_dwordx4 v[222:223], off
	s_waitcnt lgkmcnt(8)
	s_barrier
	s_waitcnt lgkmcnt(0)
	s_setprio 1
	s_waitcnt lgkmcnt(0)
	v_mfma_f32_16x16x32_bf16 v[124:127], v[144:147], v[172:175], v[124:127]
	v_mfma_f32_16x16x32_bf16 v[120:123], v[164:167], v[172:175], v[120:123]
	v_mfma_f32_16x16x32_bf16 v[108:111], v[144:147], v[180:183], v[108:111]
	v_mfma_f32_16x16x32_bf16 v[104:107], v[164:167], v[180:183], v[104:107]
	v_mfma_f32_16x16x32_bf16 v[92:95], v[144:147], v[206:209], v[92:95]
	v_mfma_f32_16x16x32_bf16 v[88:91], v[164:167], v[206:209], v[88:91]
	v_mfma_f32_16x16x32_bf16 v[76:79], v[144:147], v[214:217], v[76:79]
	v_mfma_f32_16x16x32_bf16 v[72:75], v[164:167], v[214:217], v[72:75]
	v_mfma_f32_16x16x32_bf16 v[124:127], v[160:163], v[176:179], v[124:127]
	v_mfma_f32_16x16x32_bf16 v[120:123], v[168:171], v[176:179], v[120:123]
	v_mfma_f32_16x16x32_bf16 v[108:111], v[160:163], v[188:191], v[108:111]
	v_mfma_f32_16x16x32_bf16 v[104:107], v[168:171], v[188:191], v[104:107]
	v_mfma_f32_16x16x32_bf16 v[92:95], v[160:163], v[210:213], v[92:95]
	v_mfma_f32_16x16x32_bf16 v[88:91], v[168:171], v[210:213], v[88:91]
	v_mfma_f32_16x16x32_bf16 v[76:79], v[160:163], v[218:221], v[76:79]
	v_mfma_f32_16x16x32_bf16 v[72:75], v[168:171], v[218:221], v[72:75]
	s_setprio 0
	s_barrier
	s_add_i32 s5, 0, 0x1c000
	s_add_i32 s0, s4, s51
	v_add_u32_e32 v159, s5, v154
	v_lshl_add_u64 v[202:203], v[202:203], 0, s[36:37]
	s_mov_b32 m0, s0
	ds_read_b128 v[222:225], v159
	ds_read_b128 v[226:229], v159 offset:1024
	ds_read_b128 v[230:233], v159 offset:2048
	ds_read_b128 v[234:237], v159 offset:3072
	global_load_lds_dwordx4 v[202:203], off
	v_lshl_add_u64 v[202:203], v[238:239], 0, s[36:37]
	s_add_i32 m0, s0, 0x2000
	s_nop 0
	global_load_lds_dwordx4 v[202:203], off
	s_barrier
; #define PG8_STAGE(bufoff, gbase, voff) do { _Pragma("unroll") for (int _i = 0; _i < 2; ++_i) \
;         __builtin_amdgcn_global_load_lds((const unsigned*)((const char*)(gbase) + (voff)[_i]), (LAS unsigned*)(lds + (bufoff) + ldsw + _i * 8192), 16, 0, 0); } while (0)
; #define PG8_LDA(dst, b, h) do { _Pragma("unroll") for (int m = 0; m < 4; ++m) _Pragma("unroll") for (int k = 0; k < 2; ++k) dst[m][k] = *(const LAS bf16x8*)(lds + PG8_SA(b, h) + aoff + m * 2048 + k * 1024); } while (0)
; #define PG8_LDB(dst, b, h) do { _Pragma("unroll") for (int n = 0; n < 2; ++n) _Pragma("unroll") for (int k = 0; k < 2; ++k) dst[n][k] = *(const LAS bf16x8*)(lds + PG8_SB(b, h) + boff + n * 2048 + k * 1024); } while (0)
; #define PG8_MMA(ai, bj, At, Bt) do { __builtin_amdgcn_s_setprio(1); _Pragma("unroll") for (int m = 0; m < 4; ++m) _Pragma("unroll") for (int n = 0; n < 2; ++n) _Pragma("unroll") for (int k = 0; k < 2; ++k) \
;         acc[ai][bj][m][n] = __builtin_amdgcn_mfma_f32_16x16x32_bf16(Bt[n][k], At[m][k], acc[ai][bj][m][n], 0, 0, 0); __builtin_amdgcn_s_setprio(0); } while (0)
; #define PG8_WAIT_V(n) asm volatile("s_waitcnt vmcnt(" #n ")" ::: "memory")
; #define PG8_WAIT_L(n) asm volatile("s_waitcnt lgkmcnt(" #n ")" ::: "memory")
; #define PG8_BAR __builtin_amdgcn_s_barrier()
; #define PG8_SCHED __builtin_amdgcn_sched_barrier(0)
; template <class Epi, class Sched>
; DI void gemm_phase(LAS unsigned char* lds, const Gemm g, const Sched& S, const Epi& E) {
;     ...
;             PG8_LDB(B1, 1, 1); PG8_STAGE(PG8_SB(1, 0), b3, voffB);
;             PG8_BAR; PG8_WAIT_L(0); PG8_MMA(0, 1, At, B1); PG8_BAR;
;             PG8_LDA(At, 1, 1); PG8_STAGE(PG8_SA(1, 0), a3, voffA);
;             PG8_BAR; PG8_WAIT_L(0); PG8_MMA(1, 0, At, B0); PG8_BAR; PG8_SCHED;
;             PG8_STAGE(PG8_SB(1, 1), b3 + hstep, voffB);
;             PG8_WAIT_V(6); PG8_BAR; PG8_MMA(1, 1, At, B1); PG8_BAR;
	s_waitcnt lgkmcnt(0)
	s_setprio 1
	s_waitcnt lgkmcnt(0)
	v_mfma_f32_16x16x32_bf16 v[116:119], v[222:225], v[172:175], v[116:119]
	v_mfma_f32_16x16x32_bf16 v[112:115], v[230:233], v[172:175], v[112:115]
	v_mfma_f32_16x16x32_bf16 v[100:103], v[222:225], v[180:183], v[100:103]
	v_mfma_f32_16x16x32_bf16 v[96:99], v[230:233], v[180:183], v[96:99]
	v_mfma_f32_16x16x32_bf16 v[84:87], v[222:225], v[206:209], v[84:87]
	v_mfma_f32_16x16x32_bf16 v[80:83], v[230:233], v[206:209], v[80:83]
	v_mfma_f32_16x16x32_bf16 v[68:71], v[222:225], v[214:217], v[68:71]
	v_mfma_f32_16x16x32_bf16 v[64:67], v[230:233], v[214:217], v[64:67]
	v_mfma_f32_16x16x32_bf16 v[116:119], v[226:229], v[176:179], v[116:119]
	v_mfma_f32_16x16x32_bf16 v[112:115], v[234:237], v[176:179], v[112:115]
	v_mfma_f32_16x16x32_bf16 v[100:103], v[226:229], v[188:191], v[100:103]
	v_mfma_f32_16x16x32_bf16 v[96:99], v[234:237], v[188:191], v[96:99]
	v_mfma_f32_16x16x32_bf16 v[84:87], v[226:229], v[210:213], v[84:87]
	v_mfma_f32_16x16x32_bf16 v[80:83], v[234:237], v[210:213], v[80:83]
	v_mfma_f32_16x16x32_bf16 v[68:71], v[226:229], v[218:221], v[68:71]
	v_mfma_f32_16x16x32_bf16 v[64:67], v[234:237], v[218:221], v[64:67]
	s_setprio 0
	s_mov_b32 m0, s59
	v_lshl_add_u64 v[202:203], v[240:241], 0, s[36:37]
	s_barrier
	ds_read_b128 v[172:175], v156 offset:49152
	ds_read_b128 v[176:179], v156 offset:50176
	ds_read_b128 v[180:183], v156 offset:51200
	ds_read_b128 v[188:191], v156 offset:52224
	ds_read_b128 v[206:209], v156 offset:53248
	ds_read_b128 v[210:213], v156 offset:54272
	ds_read_b128 v[214:217], v156 offset:55296
	ds_read_b128 v[218:221], v156 offset:56320
	global_load_lds_dwordx4 v[202:203], off
	v_lshl_add_u64 v[202:203], v[242:243], 0, s[36:37]
	s_mov_b32 m0, s60
	s_nop 0
	global_load_lds_dwordx4 v[202:203], off
	s_barrier
	s_waitcnt lgkmcnt(0)
	s_setprio 1
	s_waitcnt lgkmcnt(0)
	v_mfma_f32_16x16x32_bf16 v[60:63], v[144:147], v[172:175], v[60:63]
	v_mfma_f32_16x16x32_bf16 v[56:59], v[164:167], v[172:175], v[56:59]
	v_mfma_f32_16x16x32_bf16 v[44:47], v[144:147], v[180:183], v[44:47]
	v_mfma_f32_16x16x32_bf16 v[40:43], v[164:167], v[180:183], v[40:43]
	v_mfma_f32_16x16x32_bf16 v[28:31], v[144:147], v[206:209], v[28:31]
	v_mfma_f32_16x16x32_bf16 v[24:27], v[164:167], v[206:209], v[24:27]
	v_mfma_f32_16x16x32_bf16 v[12:15], v[144:147], v[214:217], v[12:15]
	v_mfma_f32_16x16x32_bf16 v[8:11], v[164:167], v[214:217], v[8:11]
	v_mfma_f32_16x16x32_bf16 v[60:63], v[160:163], v[176:179], v[60:63]
	v_mfma_f32_16x16x32_bf16 v[56:59], v[168:171], v[176:179], v[56:59]
	v_mfma_f32_16x16x32_bf16 v[44:47], v[160:163], v[188:191], v[44:47]
	v_mfma_f32_16x16x32_bf16 v[40:43], v[168:171], v[188:191], v[40:43]
	v_mfma_f32_16x16x32_bf16 v[28:31], v[160:163], v[210:213], v[28:31]
	v_mfma_f32_16x16x32_bf16 v[24:27], v[168:171], v[210:213], v[24:27]
	v_mfma_f32_16x16x32_bf16 v[12:15], v[160:163], v[218:221], v[12:15]
	v_mfma_f32_16x16x32_bf16 v[8:11], v[168:171], v[218:221], v[8:11]
	s_setprio 0
	s_barrier
	s_add_u32 s0, s40, 0x160080
	s_addc_u32 s1, s41, 0
	s_add_i32 s4, s5, s51
	v_lshl_add_u64 v[144:145], s[0:1], 0, v[130:131]
	s_mov_b32 m0, s4
	s_nop 0
	global_load_lds_dwordx4 v[144:145], off
	v_lshl_add_u64 v[144:145], s[0:1], 0, v[134:135]
	s_add_i32 m0, s4, 0x2000
	s_nop 0
	global_load_lds_dwordx4 v[144:145], off
	s_waitcnt vmcnt(6)
	s_barrier
	s_setprio 1
	v_mfma_f32_16x16x32_bf16 v[52:55], v[222:225], v[172:175], v[52:55]
	v_mfma_f32_16x16x32_bf16 v[48:51], v[230:233], v[172:175], v[48:51]
	v_mfma_f32_16x16x32_bf16 v[36:39], v[222:225], v[180:183], v[36:39]
	v_mfma_f32_16x16x32_bf16 v[32:35], v[230:233], v[180:183], v[32:35]
	v_mfma_f32_16x16x32_bf16 v[20:23], v[222:225], v[206:209], v[20:23]
	v_mfma_f32_16x16x32_bf16 v[16:19], v[230:233], v[206:209], v[16:19]
	v_mfma_f32_16x16x32_bf16 v[4:7], v[222:225], v[214:217], v[4:7]
	v_mfma_f32_16x16x32_bf16 v[0:3], v[230:233], v[214:217], v[0:3]
	v_mfma_f32_16x16x32_bf16 v[52:55], v[226:229], v[176:179], v[52:55]
	v_mfma_f32_16x16x32_bf16 v[48:51], v[234:237], v[176:179], v[48:51]
	v_mfma_f32_16x16x32_bf16 v[36:39], v[226:229], v[188:191], v[36:39]
	v_mfma_f32_16x16x32_bf16 v[32:35], v[234:237], v[188:191], v[32:35]
	v_mfma_f32_16x16x32_bf16 v[20:23], v[226:229], v[210:213], v[20:23]
	v_mfma_f32_16x16x32_bf16 v[16:19], v[234:237], v[210:213], v[16:19]
	v_mfma_f32_16x16x32_bf16 v[4:7], v[226:229], v[218:221], v[4:7]
	v_mfma_f32_16x16x32_bf16 v[0:3], v[234:237], v[218:221], v[0:3]
	s_setprio 0
	s_add_i32 s68, s68, 2
	s_add_u32 s38, s38, 0x100
	s_addc_u32 s39, s39, 0
	s_add_u32 s35, s35, 0x100
	s_addc_u32 s67, s67, 0
	s_cmpk_gt_u32 s68, 0x55
	s_barrier
	s_cbranch_scc0 .LBB0_1746
	s_branch .Lpeel_done_1746

; DI float bf_lo(unsigned u) { return __uint_as_float(u << 16); }
; DI float bf_hi(unsigned u) { return __uint_as_float(u & 0xffff0000u); }
; DI u32x4 pack8(f32x4 a, f32x4 b) { u32x4 w; w.x = cvt_pk_bf16(a[0], a[1]); w.y = cvt_pk_bf16(a[2], a[3]); w.z = cvt_pk_bf16(b[0], b[1]); w.w = cvt_pk_bf16(b[2], b[3]); return w; }
;     DI void operator()(AccRef acc, const Unit& u, int wr, int wc, int fr, int fq) const {
;         const int col0 = u.pn * 256 + wc * 32 + 8 * fq;
; #pragma unroll
;         for (int ai = 0; ai < 2; ++ai)
; #pragma unroll
;             for (int m = 0; m < 4; ++m) { const int row = u.pm * 256 + ai * 128 + wr * 64 + m * 16 + fr; const size_t off = (size_t)row * DM + col0; float q = 0.f;
; #pragma unroll
;                 for (int bj = 0; bj < 2; ++bj) {
;                     f32x4 b0, b1;
;                     if (F32BASE) { b0 = *(const f32x4*)(bp + off + bj * 128); b1 = *(const f32x4*)(bp + off + bj * 128 + 4); }
;                     else { const u32x4 uv = *(const u32x4*)(Ui + off + bj * 128); b0 = (f32x4){bf_lo(uv.x), bf_hi(uv.x), bf_lo(uv.y), bf_hi(uv.y)}; b1 = (f32x4){bf_lo(uv.z), bf_hi(uv.z), bf_lo(uv.w), bf_hi(uv.w)}; }
;                     const u32x4 w = pack8(b0 + acc[ai][bj][m][0] * (0.5f * S2), b1 + acc[ai][bj][m][1] * (0.5f * S2));
;                     *(u32x4*)(Uo + (size_t)row * ldo + col0 + bj * 128) = w;
;                     const float r0 = bf_lo(w.x), r1 = bf_hi(w.x), r2 = bf_lo(w.y), r3 = bf_hi(w.y), r4 = bf_lo(w.z), r5 = bf_hi(w.z), r6 = bf_lo(w.w), r7 = bf_hi(w.w);
;                     q += (r0 * r0 + r1 * r1) + (r2 * r2 + r3 * r3) + (r4 * r4 + r5 * r5) + (r6 * r6 + r7 * r7); }
;                 q += __shfl_xor(q, 16); q += __shfl_xor(q, 32); if (fq == 0) ssp[(size_t)row * 32 + u.pn * 4 + wc] = q; }
.Lpeel_done_1746:
	s_lshl_b32 s0, s16, 8
	v_mov_b32_e32 v145, v194
	v_mov_b32_e32 v159, v192
	s_or_b32 s0, s0, s58
	s_lshl_b32 s38, s16, 2
	v_lshl_add_u32 v144, v159, 3, s0
	s_lshl_b32 s0, s34, 8
	s_add_i32 s0, s0, s57
	v_add_u32_e32 v146, s0, v145
	v_ashrrev_i32_e32 v147, 31, v146
	v_ashrrev_i32_e32 v145, 31, v144
	v_lshlrev_b64 v[160:161], 12, v[146:147]
	v_lshl_add_u64 v[160:161], s[18:19], 0, v[160:161]
	v_lshlrev_b64 v[144:145], 1, v[144:145]
	v_lshl_add_u64 v[164:165], v[160:161], 0, v[144:145]
	v_mov_b64_e32 v[182:183], v[164:165]
	s_mov_b32 s43, 0
	global_load_dwordx4 v[170:173], v[182:183], off
	global_load_dwordx4 v[174:177], v[182:183], off offset:256
	s_mov_b32 s42, 0x10000
	v_lshl_add_u64 v[182:183], v[182:183], 0, s[42:43]
	global_load_dwordx4 v[178:181], v[182:183], off
	global_load_dwordx4 v[188:191], v[182:183], off offset:256
	s_mov_b32 s42, 0x10000
	v_lshl_add_u64 v[182:183], v[182:183], 0, s[42:43]
	global_load_dwordx4 v[206:209], v[182:183], off
	global_load_dwordx4 v[210:213], v[182:183], off offset:256
	s_mov_b32 s42, 0x10000
	v_lshl_add_u64 v[182:183], v[182:183], 0, s[42:43]
	global_load_dwordx4 v[214:217], v[182:183], off
	global_load_dwordx4 v[218:221], v[182:183], off offset:256
	s_mov_b32 s42, 0x50000
	v_lshl_add_u64 v[182:183], v[182:183], 0, s[42:43]
	global_load_dwordx4 v[222:225], v[182:183], off
	global_load_dwordx4 v[226:229], v[182:183], off offset:256
	s_mov_b32 s42, 0x10000
	v_lshl_add_u64 v[182:183], v[182:183], 0, s[42:43]
	global_load_dwordx4 v[230:233], v[182:183], off
	global_load_dwordx4 v[234:237], v[182:183], off offset:256
	s_mov_b32 s42, 0x10000
	v_lshl_add_u64 v[182:183], v[182:183], 0, s[42:43]
	global_load_dwordx4 v[238:241], v[182:183], off
	v_mov_b64_e32 v[202:203], v[182:183]
	s_mov_b32 s42, 0x10000
	v_lshl_add_u64 v[202:203], v[202:203], 0, s[42:43]
	global_load_dword v201, v[202:203], off
	global_load_dword v201, v[202:203], off offset:256
	s_waitcnt vmcnt(14)
	v_mov_b64_e32 v[160:161], v[170:171]
	v_mov_b64_e32 v[162:163], v[172:173]
	global_load_dwordx4 v[170:173], v[182:183], off offset:256
	s_ashr_i32 s39, s38, 31
	v_lshlrev_b32_e32 v166, 16, v160
	v_and_b32_e32 v167, 0xffff0000, v160
	v_lshlrev_b32_e32 v160, 16, v161
	v_and_b32_e32 v161, 0xffff0000, v161
	v_lshlrev_b32_e32 v168, 16, v162
	v_and_b32_e32 v169, 0xffff0000, v162
	v_lshlrev_b32_e32 v162, 16, v163
	v_and_b32_e32 v163, 0xffff0000, v163
	v_pk_fma_f32 v[126:127], v[126:127], 0.5, v[160:161] op_sel_hi:[1,0,1]
	v_pk_fma_f32 v[124:125], v[124:125], 0.5, v[166:167] op_sel_hi:[1,0,1]
	v_pk_fma_f32 v[160:161], v[122:123], 0.5, v[162:163] op_sel_hi:[1,0,1]
	v_pk_fma_f32 v[120:121], v[120:121], 0.5, v[168:169] op_sel_hi:[1,0,1]
	v_cvt_pk_bf16_f32 v122, v124, v125
	v_cvt_pk_bf16_f32 v123, v126, v127
	v_and_b32_e32 v127, 64, v158
	v_cvt_pk_bf16_f32 v124, v120, v121
	v_cvt_pk_bf16_f32 v125, v160, v161
	s_waitcnt vmcnt(14)
	v_mov_b64_e32 v[160:161], v[174:175]
	v_mov_b64_e32 v[162:163], v[176:177]
	s_mov_b32 s42, 0x10000
	v_lshl_add_u64 v[182:183], v[182:183], 0, s[42:43]
	global_load_dwordx4 v[174:177], v[182:183], off
	v_xor_b32_e32 v126, 16, v158
	v_add_u32_e32 v164, 64, v127
	v_mov_b64_e32 v[120:121], s[28:29]
	v_cmp_lt_i32_e32 vcc, v126, v164
	v_lshlrev_b32_e32 v166, 16, v124
	v_lshlrev_b32_e32 v167, 16, v125
	v_cndmask_b32_e32 v165, v158, v126, vcc
	v_mad_i64_i32 v[126:127], s[0:1], v146, s63, v[120:121]
	v_lshl_add_u64 v[126:127], v[126:127], 0, v[144:145]
	v_lshlrev_b32_e32 v120, 2, v165
	global_store_dwordx4 v[126:127], v[122:125], off
	v_lshlrev_b32_e32 v121, 16, v122
	v_lshlrev_b32_e32 v165, 16, v123
	v_and_b32_e32 v122, 0xffff0000, v122
	v_and_b32_e32 v123, 0xffff0000, v123
	v_and_b32_e32 v124, 0xffff0000, v124
	v_mul_f32_e32 v122, v122, v122
	v_mul_f32_e32 v123, v123, v123
	v_and_b32_e32 v125, 0xffff0000, v125
	v_mul_f32_e32 v124, v124, v124
	v_fmac_f32_e32 v122, v121, v121
	v_fmac_f32_e32 v123, v165, v165
	v_mul_f32_e32 v125, v125, v125
	v_fmac_f32_e32 v124, v166, v166
	v_add_f32_e32 v121, v122, v123
	v_fmac_f32_e32 v125, v167, v167
	v_add_f32_e32 v121, v121, v124
	v_add_f32_e32 v121, v121, v125
	v_lshlrev_b32_e32 v122, 16, v160
	v_and_b32_e32 v123, 0xffff0000, v160
	v_lshlrev_b32_e32 v124, 16, v161
	v_and_b32_e32 v125, 0xffff0000, v161
	v_lshlrev_b32_e32 v160, 16, v162
	v_and_b32_e32 v161, 0xffff0000, v162
	v_lshlrev_b32_e32 v162, 16, v163
	v_and_b32_e32 v163, 0xffff0000, v163
	v_pk_fma_f32 v[118:119], v[118:119], 0.5, v[124:125] op_sel_hi:[1,0,1]
	v_pk_fma_f32 v[116:117], v[116:117], 0.5, v[122:123] op_sel_hi:[1,0,1]
	v_pk_fma_f32 v[114:115], v[114:115], 0.5, v[162:163] op_sel_hi:[1,0,1]
	v_pk_fma_f32 v[112:113], v[112:113], 0.5, v[160:161] op_sel_hi:[1,0,1]
	v_cvt_pk_bf16_f32 v116, v116, v117
	v_cvt_pk_bf16_f32 v117, v118, v119
	s_nop 0
	v_cvt_pk_bf16_f32 v118, v112, v113
	v_cvt_pk_bf16_f32 v119, v114, v115
	v_and_b32_e32 v113, 0xffff0000, v116
	v_and_b32_e32 v115, 0xffff0000, v117
	v_lshlrev_b32_e32 v112, 16, v116
	v_lshlrev_b32_e32 v114, 16, v117
	v_and_b32_e32 v123, 0xffff0000, v118
	v_mul_f32_e32 v113, v113, v113
	v_mul_f32_e32 v115, v115, v115
	v_lshlrev_b32_e32 v122, 16, v118
	v_and_b32_e32 v125, 0xffff0000, v119
	v_mul_f32_e32 v123, v123, v123
	v_fmac_f32_e32 v113, v112, v112
	v_fmac_f32_e32 v115, v114, v114
	v_lshlrev_b32_e32 v124, 16, v119
	v_mul_f32_e32 v125, v125, v125
	v_fmac_f32_e32 v123, v122, v122
	v_add_f32_e32 v112, v113, v115
	v_fmac_f32_e32 v125, v124, v124
	v_add_f32_e32 v112, v112, v123
	v_add_f32_e32 v112, v112, v125
	v_add_f32_e32 v112, v121, v112
	ds_bpermute_b32 v113, v120, v112
	v_xor_b32_e32 v114, 32, v158
	v_cmp_lt_i32_e32 vcc, v114, v164
	global_store_dwordx4 v[126:127], v[116:119], off offset:256
	s_waitcnt lgkmcnt(0)
	v_add_f32_e32 v112, v112, v113
	v_cndmask_b32_e32 v114, v158, v114, vcc
	v_lshlrev_b32_e32 v114, 2, v114
	ds_bpermute_b32 v113, v114, v112
	v_cmp_eq_u32_e32 vcc, 0, v159
	s_and_saveexec_b64 s[40:41], vcc
	s_cbranch_execz .LBB0_1749
	v_lshlrev_b64 v[116:117], 7, v[146:147]
	v_lshl_add_u64 v[116:117], s[30:31], 0, v[116:117]
	v_lshl_add_u64 v[116:117], s[38:39], 2, v[116:117]
	s_lshl_b32 s16, s56, 2
	v_lshl_add_u64 v[116:117], v[116:117], 0, s[16:17]
	s_waitcnt lgkmcnt(0)
	v_add_f32_e32 v112, v112, v113
	global_store_dword v[116:117], v112, off

;     DI size_t aoff(const Unit& u, size_t tstep) const { return (size_t)u.pm * tstep; }
;     DI size_t boff(const Unit& u, size_t tstep) const { return (size_t)u.pn * tstep; }
;     DI size_t aoff(const Unit& u, size_t) const { return (size_t)u.ks * kbytes; }
; template <class Epi, class Sched>
; DI void gemm_phase(LAS unsigned char* lds, const Gemm g, const Sched& S, const Epi& E) {
;     ...
;         const bool has_next = S.next(ui + 1, nxt);
;         const char* nA = has_next ? (const char*)g.A + S.aoff(nxt, tstep) : cA; const char* nB = has_next ? (const char*)g.Bt + S.boff(nxt, tstep) : cB;
;         for (int t = 0; t < nt; t += 2) {
;             if constexpr (Epi::HAS_MID) { if (t == E.mid_t(nt)) { int fr3 = fr, fq3 = fq; asm volatile("" : "+v"(fr3), "+v"(fq3)); E.mid(acc, cur, wr, wc, fr3, fq3); } }
;             const bool last = (t == nt - 2);
;             const char* a1 = cA + (size_t)(t + 1) * kstep;
;             const char* a2 = last ? nA : cA + (size_t)(t + 2) * kstep; const char* b2 = last ? nB : cB + (size_t)(t + 2) * kstep;
;             const char* a3 = a2 + kstep; const char* b3 = b2 + kstep;
;             PG8_LDB(B0, 0, 0); PG8_SCHED; PG8_LDA(At, 0, 0); PG8_STAGE(PG8_SA(1, 1), a1 + hstep, voffA);
;             PG8_WAIT_L(8); PG8_BAR; PG8_WAIT_L(0); PG8_MMA(0, 0, At, B0); PG8_BAR; PG8_SCHED;
;             PG8_LDB(B1, 0, 1); PG8_STAGE(PG8_SB(0, 0), b2, voffB);
;             PG8_BAR; PG8_WAIT_L(0); PG8_MMA(0, 1, At, B1); PG8_BAR;
;             PG8_LDA(At, 0, 1); PG8_STAGE(PG8_SA(0, 0), a2, voffA);
;             PG8_BAR; PG8_WAIT_L(0); PG8_MMA(1, 0, At, B0); PG8_BAR; PG8_SCHED;
;             PG8_STAGE(PG8_SB(0, 1), b2 + hstep, voffB);
;             PG8_WAIT_V(6); PG8_BAR; PG8_MMA(1, 1, At, B1); PG8_BAR;
;             PG8_LDB(B0, 1, 0); PG8_SCHED; PG8_LDA(At, 1, 0); PG8_STAGE(PG8_SA(0, 1), a2 + hstep, voffA);
;             PG8_WAIT_L(8); PG8_BAR; PG8_WAIT_L(0); PG8_MMA(0, 0, At, B0); PG8_BAR; PG8_SCHED;
;             PG8_LDB(B1, 1, 1); PG8_STAGE(PG8_SB(1, 0), b3, voffB);
;             PG8_BAR; PG8_WAIT_L(0); PG8_MMA(0, 1, At, B1); PG8_BAR;
;             PG8_LDA(At, 1, 1); PG8_STAGE(PG8_SA(1, 0), a3, voffA);
;             PG8_BAR; PG8_WAIT_L(0); PG8_MMA(1, 0, At, B0); PG8_BAR; PG8_SCHED;
;             PG8_STAGE(PG8_SB(1, 1), b3 + hstep, voffB);
;             PG8_WAIT_V(6); PG8_BAR; PG8_MMA(1, 1, At, B1); PG8_BAR;
.LBB0_1774:
	s_add_u32 s28, s38, s28
	s_addc_u32 s29, s39, s29
	s_and_b64 s[0:1], s[8:9], exec
	s_cselect_b32 s15, s29, s37
	s_cselect_b32 s17, s28, s36
	s_add_u32 s8, s36, 0x160080
	s_addc_u32 s9, s37, 0
	s_add_u32 s64, s30, 0x100
	v_mov_b32_e32 v0, 0
	s_addc_u32 s65, s31, 0
	s_mov_b32 s66, -2
	ds_read_b128 v[146:149], v141
	ds_read_b128 v[154:157], v141 offset:1024
	ds_read_b128 v[158:161], v141 offset:2048
	ds_read_b128 v[162:165], v141 offset:3072
	s_add_u32 s0, s8, 0xffea0080
	s_addc_u32 s1, s9, -1
	s_cmp_eq_u32 s66, 4
	s_cselect_b32 s37, s15, s1
	s_cselect_b32 s36, s17, s0
	s_cselect_b32 s31, s19, s65
	s_cselect_b32 s30, s18, s64
	s_mov_b32 m0, s56
	v_lshl_add_u64 v[150:151], s[8:9], 0, v[132:133]
	ds_read_b128 v[166:169], v142
	ds_read_b128 v[170:173], v142 offset:1024
	ds_read_b128 v[174:177], v142 offset:2048
	ds_read_b128 v[178:181], v142 offset:3072
	ds_read_b128 v[188:191], v142 offset:4096
	ds_read_b128 v[206:209], v142 offset:5120
	ds_read_b128 v[210:213], v142 offset:6144
	ds_read_b128 v[214:217], v142 offset:7168
	global_load_lds_dwordx4 v[150:151], off
	v_lshl_add_u64 v[150:151], s[8:9], 0, v[134:135]
	s_mov_b32 m0, s57
	s_nop 0
	global_load_lds_dwordx4 v[150:151], off
	s_waitcnt lgkmcnt(8)
	s_barrier
	s_waitcnt lgkmcnt(0)
	s_setprio 1
	s_waitcnt lgkmcnt(0)
	v_mfma_f32_16x16x32_bf16 v[124:127], v[146:149], v[166:169], 0
	v_mfma_f32_16x16x32_bf16 v[120:123], v[158:161], v[166:169], 0
	v_mfma_f32_16x16x32_bf16 v[116:119], v[146:149], v[174:177], 0
	v_mfma_f32_16x16x32_bf16 v[112:115], v[158:161], v[174:177], 0
	v_mfma_f32_16x16x32_bf16 v[104:107], v[146:149], v[188:191], 0
	v_mfma_f32_16x16x32_bf16 v[96:99], v[158:161], v[188:191], 0
	v_mfma_f32_16x16x32_bf16 v[88:91], v[146:149], v[210:213], 0
	v_mfma_f32_16x16x32_bf16 v[80:83], v[158:161], v[210:213], 0
	v_mfma_f32_16x16x32_bf16 v[124:127], v[154:157], v[170:173], v[124:127]
	v_mfma_f32_16x16x32_bf16 v[120:123], v[162:165], v[170:173], v[120:123]
	v_mfma_f32_16x16x32_bf16 v[116:119], v[154:157], v[178:181], v[116:119]
	v_mfma_f32_16x16x32_bf16 v[112:115], v[162:165], v[178:181], v[112:115]
	v_mfma_f32_16x16x32_bf16 v[104:107], v[154:157], v[206:209], v[104:107]
	v_mfma_f32_16x16x32_bf16 v[96:99], v[162:165], v[206:209], v[96:99]
	v_mfma_f32_16x16x32_bf16 v[88:91], v[154:157], v[214:217], v[88:91]
	v_mfma_f32_16x16x32_bf16 v[80:83], v[162:165], v[214:217], v[80:83]
	s_setprio 0
	s_barrier
	s_mov_b32 m0, s58
	v_lshl_add_u64 v[150:151], s[30:31], 0, v[130:131]
	ds_read_b128 v[218:221], v143
	ds_read_b128 v[222:225], v143 offset:1024
	ds_read_b128 v[226:229], v143 offset:2048
	ds_read_b128 v[230:233], v143 offset:3072
	global_load_lds_dwordx4 v[150:151], off
	v_lshl_add_u64 v[182:183], s[30:31], 0, v[128:129]
	s_mov_b32 m0, s59
	s_nop 0
	global_load_lds_dwordx4 v[182:183], off
	s_barrier
	s_waitcnt lgkmcnt(0)
	s_setprio 1
	s_waitcnt lgkmcnt(0)
	v_mfma_f32_16x16x32_bf16 v[108:111], v[218:221], v[166:169], 0
	v_mfma_f32_16x16x32_bf16 v[100:103], v[226:229], v[166:169], 0
	v_mfma_f32_16x16x32_bf16 v[92:95], v[218:221], v[174:177], 0
	v_mfma_f32_16x16x32_bf16 v[84:87], v[226:229], v[174:177], 0
	v_mfma_f32_16x16x32_bf16 v[76:79], v[218:221], v[188:191], 0
	v_mfma_f32_16x16x32_bf16 v[72:75], v[226:229], v[188:191], 0
	v_mfma_f32_16x16x32_bf16 v[68:71], v[218:221], v[210:213], 0
	v_mfma_f32_16x16x32_bf16 v[64:67], v[226:229], v[210:213], 0
	v_mfma_f32_16x16x32_bf16 v[108:111], v[222:225], v[170:173], v[108:111]
	v_mfma_f32_16x16x32_bf16 v[100:103], v[230:233], v[170:173], v[100:103]
	v_mfma_f32_16x16x32_bf16 v[92:95], v[222:225], v[178:181], v[92:95]
	v_mfma_f32_16x16x32_bf16 v[84:87], v[230:233], v[178:181], v[84:87]
	v_mfma_f32_16x16x32_bf16 v[76:79], v[222:225], v[206:209], v[76:79]
	v_mfma_f32_16x16x32_bf16 v[72:75], v[230:233], v[206:209], v[72:75]
	v_mfma_f32_16x16x32_bf16 v[68:71], v[222:225], v[214:217], v[68:71]
	v_mfma_f32_16x16x32_bf16 v[64:67], v[230:233], v[214:217], v[64:67]
	s_setprio 0
	s_mov_b32 m0, s40
	v_lshl_add_u64 v[202:203], s[36:37], 0, v[130:131]
	s_barrier
	ds_read_b128 v[166:169], v142 offset:16384
	ds_read_b128 v[170:173], v142 offset:17408
	ds_read_b128 v[174:177], v142 offset:18432
	ds_read_b128 v[178:181], v142 offset:19456
	ds_read_b128 v[188:191], v142 offset:20480
	ds_read_b128 v[206:209], v142 offset:21504
	ds_read_b128 v[210:213], v142 offset:22528
	ds_read_b128 v[214:217], v142 offset:23552
	global_load_lds_dwordx4 v[202:203], off
	v_lshl_add_u64 v[234:235], s[36:37], 0, v[128:129]
	s_mov_b32 m0, s41
	s_nop 0
	global_load_lds_dwordx4 v[234:235], off
	s_barrier
	s_waitcnt lgkmcnt(0)
	s_setprio 1
	s_waitcnt lgkmcnt(0)
	v_mfma_f32_16x16x32_bf16 v[60:63], v[146:149], v[166:169], 0
	v_mfma_f32_16x16x32_bf16 v[56:59], v[158:161], v[166:169], 0
	v_mfma_f32_16x16x32_bf16 v[52:55], v[146:149], v[174:177], 0
	v_mfma_f32_16x16x32_bf16 v[48:51], v[158:161], v[174:177], 0
	v_mfma_f32_16x16x32_bf16 v[40:43], v[146:149], v[188:191], 0
	v_mfma_f32_16x16x32_bf16 v[32:35], v[158:161], v[188:191], 0
	v_mfma_f32_16x16x32_bf16 v[24:27], v[146:149], v[210:213], 0
	v_mfma_f32_16x16x32_bf16 v[16:19], v[158:161], v[210:213], 0
	v_mfma_f32_16x16x32_bf16 v[60:63], v[154:157], v[170:173], v[60:63]
	v_mfma_f32_16x16x32_bf16 v[56:59], v[162:165], v[170:173], v[56:59]
	v_mfma_f32_16x16x32_bf16 v[52:55], v[154:157], v[178:181], v[52:55]
	v_mfma_f32_16x16x32_bf16 v[48:51], v[162:165], v[178:181], v[48:51]
	v_mfma_f32_16x16x32_bf16 v[40:43], v[154:157], v[206:209], v[40:43]
	v_mfma_f32_16x16x32_bf16 v[32:35], v[162:165], v[206:209], v[32:35]
	v_mfma_f32_16x16x32_bf16 v[24:27], v[154:157], v[214:217], v[24:27]
	v_mfma_f32_16x16x32_bf16 v[16:19], v[162:165], v[214:217], v[16:19]
	s_setprio 0
	s_barrier
; #define PG8_STAGE(bufoff, gbase, voff) do { _Pragma("unroll") for (int _i = 0; _i < 2; ++_i) \
;         __builtin_amdgcn_global_load_lds((const unsigned*)((const char*)(gbase) + (voff)[_i]), (LAS unsigned*)(lds + (bufoff) + ldsw + _i * 8192), 16, 0, 0); } while (0)
; #define PG8_LDA(dst, b, h) do { _Pragma("unroll") for (int m = 0; m < 4; ++m) _Pragma("unroll") for (int k = 0; k < 2; ++k) dst[m][k] = *(const LAS bf16x8*)(lds + PG8_SA(b, h) + aoff + m * 2048 + k * 1024); } while (0)
; #define PG8_LDB(dst, b, h) do { _Pragma("unroll") for (int n = 0; n < 2; ++n) _Pragma("unroll") for (int k = 0; k < 2; ++k) dst[n][k] = *(const LAS bf16x8*)(lds + PG8_SB(b, h) + boff + n * 2048 + k * 1024); } while (0)
; #define PG8_WAIT_V(n) asm volatile("s_waitcnt vmcnt(" #n ")" ::: "memory")
; #define PG8_WAIT_L(n) asm volatile("s_waitcnt lgkmcnt(" #n ")" ::: "memory")
; #define PG8_BAR __builtin_amdgcn_s_barrier()
; #define PG8_SCHED __builtin_amdgcn_sched_barrier(0)
; template <class Epi, class Sched>
; DI void gemm_phase(LAS unsigned char* lds, const Gemm g, const Sched& S, const Epi& E) {
;     ...
;             PG8_LDB(B0, 0, 0); PG8_SCHED; PG8_LDA(At, 0, 0); PG8_STAGE(PG8_SA(1, 1), a1 + hstep, voffA);
;             PG8_WAIT_L(8); PG8_BAR; PG8_WAIT_L(0); PG8_MMA(0, 0, At, B0); PG8_BAR; PG8_SCHED;
;             PG8_LDB(B1, 0, 1); PG8_STAGE(PG8_SB(0, 0), b2, voffB);
;             PG8_BAR; PG8_WAIT_L(0); PG8_MMA(0, 1, At, B1); PG8_BAR;
;             PG8_LDA(At, 0, 1); PG8_STAGE(PG8_SA(0, 0), a2, voffA);
;             PG8_BAR; PG8_WAIT_L(0); PG8_MMA(1, 0, At, B0); PG8_BAR; PG8_SCHED;
;             PG8_STAGE(PG8_SB(0, 1), b2 + hstep, voffB);
;             PG8_WAIT_V(6); PG8_BAR; PG8_MMA(1, 1, At, B1); PG8_BAR;
;             PG8_LDB(B0, 1, 0); PG8_SCHED; PG8_LDA(At, 1, 0); PG8_STAGE(PG8_SA(0, 1), a2 + hstep, voffA);
;             PG8_WAIT_L(8); PG8_BAR; PG8_WAIT_L(0); PG8_MMA(0, 0, At, B0); PG8_BAR; PG8_SCHED;
;             PG8_LDB(B1, 1, 1); PG8_STAGE(PG8_SB(1, 0), b3, voffB);
;             PG8_BAR; PG8_WAIT_L(0); PG8_MMA(0, 1, At, B1); PG8_BAR;
;             PG8_LDA(At, 1, 1); PG8_STAGE(PG8_SA(1, 0), a3, voffA);
;             PG8_BAR; PG8_WAIT_L(0); PG8_MMA(1, 0, At, B0); PG8_BAR; PG8_SCHED;
;             PG8_STAGE(PG8_SB(1, 1), b3 + hstep, voffB);
;             PG8_WAIT_V(6); PG8_BAR; PG8_MMA(1, 1, At, B1); PG8_BAR;
	s_add_u32 s0, s30, 0x160000
	s_addc_u32 s1, s31, 0
	s_mov_b32 m0, s60
	v_lshl_add_u64 v[146:147], s[0:1], 0, v[130:131]
	global_load_lds_dwordx4 v[146:147], off
	v_lshl_add_u64 v[146:147], s[0:1], 0, v[128:129]
	s_mov_b32 m0, s61
	s_nop 0
	global_load_lds_dwordx4 v[146:147], off
	s_waitcnt vmcnt(6)
	s_barrier
	s_setprio 1
	v_mfma_f32_16x16x32_bf16 v[44:47], v[218:221], v[166:169], 0
	v_mfma_f32_16x16x32_bf16 v[36:39], v[226:229], v[166:169], 0
	v_mfma_f32_16x16x32_bf16 v[28:31], v[218:221], v[174:177], 0
	v_mfma_f32_16x16x32_bf16 v[20:23], v[226:229], v[174:177], 0
	v_mfma_f32_16x16x32_bf16 v[12:15], v[218:221], v[188:191], 0
	v_mfma_f32_16x16x32_bf16 v[8:11], v[226:229], v[188:191], 0
	v_mfma_f32_16x16x32_bf16 v[4:7], v[218:221], v[210:213], 0
	v_mfma_f32_16x16x32_bf16 v[0:3], v[226:229], v[210:213], 0
	v_mfma_f32_16x16x32_bf16 v[44:47], v[222:225], v[170:173], v[44:47]
	v_mfma_f32_16x16x32_bf16 v[36:39], v[230:233], v[170:173], v[36:39]
	v_mfma_f32_16x16x32_bf16 v[28:31], v[222:225], v[178:181], v[28:31]
	v_mfma_f32_16x16x32_bf16 v[20:23], v[230:233], v[178:181], v[20:23]
	v_mfma_f32_16x16x32_bf16 v[12:15], v[222:225], v[206:209], v[12:15]
	v_mfma_f32_16x16x32_bf16 v[8:11], v[230:233], v[206:209], v[8:11]
	v_mfma_f32_16x16x32_bf16 v[4:7], v[222:225], v[214:217], v[4:7]
	v_mfma_f32_16x16x32_bf16 v[0:3], v[230:233], v[214:217], v[0:3]
	s_setprio 0
	s_barrier
	ds_read_b128 v[146:149], v144
	ds_read_b128 v[154:157], v144 offset:1024
	ds_read_b128 v[158:161], v144 offset:2048
	ds_read_b128 v[162:165], v144 offset:3072
	s_add_u32 s0, s36, 0x160000
	s_addc_u32 s1, s37, 0
	s_mov_b32 m0, s42
	v_lshl_add_u64 v[218:219], s[0:1], 0, v[130:131]
	ds_read_b128 v[166:169], v142 offset:32768
	ds_read_b128 v[170:173], v142 offset:33792
	ds_read_b128 v[174:177], v142 offset:34816
	ds_read_b128 v[178:181], v142 offset:35840
	ds_read_b128 v[188:191], v142 offset:36864
	ds_read_b128 v[206:209], v142 offset:37888
	ds_read_b128 v[210:213], v142 offset:38912
	ds_read_b128 v[214:217], v142 offset:39936
	global_load_lds_dwordx4 v[218:219], off
	v_lshl_add_u64 v[218:219], s[0:1], 0, v[128:129]
	s_mov_b32 m0, s43
	s_nop 0
	global_load_lds_dwordx4 v[218:219], off
	s_waitcnt lgkmcnt(8)
	s_barrier
	s_waitcnt lgkmcnt(0)
	s_setprio 1
	s_waitcnt lgkmcnt(0)
	v_mfma_f32_16x16x32_bf16 v[124:127], v[146:149], v[166:169], v[124:127]
	v_mfma_f32_16x16x32_bf16 v[120:123], v[158:161], v[166:169], v[120:123]
	v_mfma_f32_16x16x32_bf16 v[116:119], v[146:149], v[174:177], v[116:119]
	v_mfma_f32_16x16x32_bf16 v[112:115], v[158:161], v[174:177], v[112:115]
	v_mfma_f32_16x16x32_bf16 v[104:107], v[146:149], v[188:191], v[104:107]
	v_mfma_f32_16x16x32_bf16 v[96:99], v[158:161], v[188:191], v[96:99]
	v_mfma_f32_16x16x32_bf16 v[88:91], v[146:149], v[210:213], v[88:91]
	v_mfma_f32_16x16x32_bf16 v[80:83], v[158:161], v[210:213], v[80:83]
	v_mfma_f32_16x16x32_bf16 v[124:127], v[154:157], v[170:173], v[124:127]
	v_mfma_f32_16x16x32_bf16 v[120:123], v[162:165], v[170:173], v[120:123]
	v_mfma_f32_16x16x32_bf16 v[116:119], v[154:157], v[178:181], v[116:119]
	v_mfma_f32_16x16x32_bf16 v[112:115], v[162:165], v[178:181], v[112:115]
	v_mfma_f32_16x16x32_bf16 v[104:107], v[154:157], v[206:209], v[104:107]
	v_mfma_f32_16x16x32_bf16 v[96:99], v[162:165], v[206:209], v[96:99]
	v_mfma_f32_16x16x32_bf16 v[88:91], v[154:157], v[214:217], v[88:91]
	v_mfma_f32_16x16x32_bf16 v[80:83], v[162:165], v[214:217], v[80:83]
	s_setprio 0
	s_barrier
	s_add_i32 s4, 0, 0x1c000
	s_add_i32 s0, s62, s35
	v_add_u32_e32 v145, s4, v140
	v_lshl_add_u64 v[150:151], v[150:151], 0, s[10:11]
	s_mov_b32 m0, s0
	ds_read_b128 v[218:221], v145
	ds_read_b128 v[222:225], v145 offset:1024
	ds_read_b128 v[226:229], v145 offset:2048
	ds_read_b128 v[230:233], v145 offset:3072
	global_load_lds_dwordx4 v[150:151], off
	v_lshl_add_u64 v[150:151], v[182:183], 0, s[10:11]
	s_add_i32 m0, s0, 0x2000
	s_nop 0
	global_load_lds_dwordx4 v[150:151], off
	s_barrier
; #define PG8_STAGE(bufoff, gbase, voff) do { _Pragma("unroll") for (int _i = 0; _i < 2; ++_i) \
;         __builtin_amdgcn_global_load_lds((const unsigned*)((const char*)(gbase) + (voff)[_i]), (LAS unsigned*)(lds + (bufoff) + ldsw + _i * 8192), 16, 0, 0); } while (0)
; #define PG8_LDA(dst, b, h) do { _Pragma("unroll") for (int m = 0; m < 4; ++m) _Pragma("unroll") for (int k = 0; k < 2; ++k) dst[m][k] = *(const LAS bf16x8*)(lds + PG8_SA(b, h) + aoff + m * 2048 + k * 1024); } while (0)
; #define PG8_LDB(dst, b, h) do { _Pragma("unroll") for (int n = 0; n < 2; ++n) _Pragma("unroll") for (int k = 0; k < 2; ++k) dst[n][k] = *(const LAS bf16x8*)(lds + PG8_SB(b, h) + boff + n * 2048 + k * 1024); } while (0)
; #define PG8_MMA(ai, bj, At, Bt) do { __builtin_amdgcn_s_setprio(1); _Pragma("unroll") for (int m = 0; m < 4; ++m) _Pragma("unroll") for (int n = 0; n < 2; ++n) _Pragma("unroll") for (int k = 0; k < 2; ++k) \
;         acc[ai][bj][m][n] = __builtin_amdgcn_mfma_f32_16x16x32_bf16(Bt[n][k], At[m][k], acc[ai][bj][m][n], 0, 0, 0); __builtin_amdgcn_s_setprio(0); } while (0)
; #define PG8_WAIT_V(n) asm volatile("s_waitcnt vmcnt(" #n ")" ::: "memory")
; #define PG8_WAIT_L(n) asm volatile("s_waitcnt lgkmcnt(" #n ")" ::: "memory")
; #define PG8_BAR __builtin_amdgcn_s_barrier()
; #define PG8_SCHED __builtin_amdgcn_sched_barrier(0)
; template <class Epi, class Sched>
; DI void gemm_phase(LAS unsigned char* lds, const Gemm g, const Sched& S, const Epi& E) {
;     ...
;             PG8_LDB(B1, 1, 1); PG8_STAGE(PG8_SB(1, 0), b3, voffB);
;             PG8_BAR; PG8_WAIT_L(0); PG8_MMA(0, 1, At, B1); PG8_BAR;
;             PG8_LDA(At, 1, 1); PG8_STAGE(PG8_SA(1, 0), a3, voffA);
;             PG8_BAR; PG8_WAIT_L(0); PG8_MMA(1, 0, At, B0); PG8_BAR; PG8_SCHED;
;             PG8_STAGE(PG8_SB(1, 1), b3 + hstep, voffB);
;             PG8_WAIT_V(6); PG8_BAR; PG8_MMA(1, 1, At, B1); PG8_BAR;
	s_waitcnt lgkmcnt(0)
	s_setprio 1
	s_waitcnt lgkmcnt(0)
	v_mfma_f32_16x16x32_bf16 v[108:111], v[218:221], v[166:169], v[108:111]
	v_mfma_f32_16x16x32_bf16 v[100:103], v[226:229], v[166:169], v[100:103]
	v_mfma_f32_16x16x32_bf16 v[92:95], v[218:221], v[174:177], v[92:95]
	v_mfma_f32_16x16x32_bf16 v[84:87], v[226:229], v[174:177], v[84:87]
	v_mfma_f32_16x16x32_bf16 v[76:79], v[218:221], v[188:191], v[76:79]
	v_mfma_f32_16x16x32_bf16 v[72:75], v[226:229], v[188:191], v[72:75]
	v_mfma_f32_16x16x32_bf16 v[68:71], v[218:221], v[210:213], v[68:71]
	v_mfma_f32_16x16x32_bf16 v[64:67], v[226:229], v[210:213], v[64:67]
	v_mfma_f32_16x16x32_bf16 v[108:111], v[222:225], v[170:173], v[108:111]
	v_mfma_f32_16x16x32_bf16 v[100:103], v[230:233], v[170:173], v[100:103]
	v_mfma_f32_16x16x32_bf16 v[92:95], v[222:225], v[178:181], v[92:95]
	v_mfma_f32_16x16x32_bf16 v[84:87], v[230:233], v[178:181], v[84:87]
	v_mfma_f32_16x16x32_bf16 v[76:79], v[222:225], v[206:209], v[76:79]
	v_mfma_f32_16x16x32_bf16 v[72:75], v[230:233], v[206:209], v[72:75]
	v_mfma_f32_16x16x32_bf16 v[68:71], v[222:225], v[214:217], v[68:71]
	v_mfma_f32_16x16x32_bf16 v[64:67], v[230:233], v[214:217], v[64:67]
	s_setprio 0
	s_mov_b32 m0, s54
	v_lshl_add_u64 v[150:151], v[202:203], 0, s[10:11]
	s_barrier
	ds_read_b128 v[166:169], v142 offset:49152
	ds_read_b128 v[170:173], v142 offset:50176
	ds_read_b128 v[174:177], v142 offset:51200
	ds_read_b128 v[178:181], v142 offset:52224
	ds_read_b128 v[188:191], v142 offset:53248
	ds_read_b128 v[206:209], v142 offset:54272
	ds_read_b128 v[210:213], v142 offset:55296
	ds_read_b128 v[214:217], v142 offset:56320
	global_load_lds_dwordx4 v[150:151], off
	v_lshl_add_u64 v[150:151], v[234:235], 0, s[10:11]
	s_mov_b32 m0, s55
	s_nop 0
	global_load_lds_dwordx4 v[150:151], off
	s_barrier
	s_waitcnt lgkmcnt(0)
	s_setprio 1
	s_waitcnt lgkmcnt(0)
	v_mfma_f32_16x16x32_bf16 v[60:63], v[146:149], v[166:169], v[60:63]
	v_mfma_f32_16x16x32_bf16 v[56:59], v[158:161], v[166:169], v[56:59]
	v_mfma_f32_16x16x32_bf16 v[52:55], v[146:149], v[174:177], v[52:55]
	v_mfma_f32_16x16x32_bf16 v[48:51], v[158:161], v[174:177], v[48:51]
	v_mfma_f32_16x16x32_bf16 v[40:43], v[146:149], v[188:191], v[40:43]
	v_mfma_f32_16x16x32_bf16 v[32:35], v[158:161], v[188:191], v[32:35]
	v_mfma_f32_16x16x32_bf16 v[24:27], v[146:149], v[210:213], v[24:27]
	v_mfma_f32_16x16x32_bf16 v[16:19], v[158:161], v[210:213], v[16:19]
	v_mfma_f32_16x16x32_bf16 v[60:63], v[154:157], v[170:173], v[60:63]
	v_mfma_f32_16x16x32_bf16 v[56:59], v[162:165], v[170:173], v[56:59]
	v_mfma_f32_16x16x32_bf16 v[52:55], v[154:157], v[178:181], v[52:55]
	v_mfma_f32_16x16x32_bf16 v[48:51], v[162:165], v[178:181], v[48:51]
	v_mfma_f32_16x16x32_bf16 v[40:43], v[154:157], v[206:209], v[40:43]
	v_mfma_f32_16x16x32_bf16 v[32:35], v[162:165], v[206:209], v[32:35]
	v_mfma_f32_16x16x32_bf16 v[24:27], v[154:157], v[214:217], v[24:27]
	v_mfma_f32_16x16x32_bf16 v[16:19], v[162:165], v[214:217], v[16:19]
	s_setprio 0
	s_barrier
	s_add_u32 s0, s30, 0x160080
	s_addc_u32 s1, s31, 0
	s_add_i32 s4, s4, s35
	v_lshl_add_u64 v[146:147], s[0:1], 0, v[130:131]
	s_mov_b32 m0, s4
	s_nop 0
	global_load_lds_dwordx4 v[146:147], off
	v_lshl_add_u64 v[146:147], s[0:1], 0, v[128:129]
	s_add_i32 m0, s4, 0x2000
	s_nop 0
	global_load_lds_dwordx4 v[146:147], off
	s_waitcnt vmcnt(6)
	s_barrier
	s_setprio 1
	v_mfma_f32_16x16x32_bf16 v[44:47], v[218:221], v[166:169], v[44:47]
	v_mfma_f32_16x16x32_bf16 v[36:39], v[226:229], v[166:169], v[36:39]
	v_mfma_f32_16x16x32_bf16 v[28:31], v[218:221], v[174:177], v[28:31]
	v_mfma_f32_16x16x32_bf16 v[20:23], v[226:229], v[174:177], v[20:23]
	v_mfma_f32_16x16x32_bf16 v[12:15], v[218:221], v[188:191], v[12:15]
	v_mfma_f32_16x16x32_bf16 v[8:11], v[226:229], v[188:191], v[8:11]
	v_mfma_f32_16x16x32_bf16 v[4:7], v[218:221], v[210:213], v[4:7]
	v_mfma_f32_16x16x32_bf16 v[0:3], v[226:229], v[210:213], v[0:3]
	v_mfma_f32_16x16x32_bf16 v[44:47], v[222:225], v[170:173], v[44:47]
	v_mfma_f32_16x16x32_bf16 v[36:39], v[230:233], v[170:173], v[36:39]
	v_mfma_f32_16x16x32_bf16 v[28:31], v[222:225], v[178:181], v[28:31]
	v_mfma_f32_16x16x32_bf16 v[20:23], v[230:233], v[178:181], v[20:23]
	v_mfma_f32_16x16x32_bf16 v[12:15], v[222:225], v[206:209], v[12:15]
	v_mfma_f32_16x16x32_bf16 v[8:11], v[230:233], v[206:209], v[8:11]
	v_mfma_f32_16x16x32_bf16 v[4:7], v[222:225], v[214:217], v[4:7]
	v_mfma_f32_16x16x32_bf16 v[0:3], v[230:233], v[214:217], v[0:3]
	s_setprio 0
	s_add_i32 s66, s66, 2
	s_add_u32 s8, s8, 0x100
	s_addc_u32 s9, s9, 0
	s_add_u32 s64, s64, 0x100
	s_addc_u32 s65, s65, 0
	s_cmp_gt_u32 s66, 5
	s_barrier
	s_cbranch_scc0 .LBB0_1775
	s_branch .Lpeel_done_1775

;     DI void operator()(AccRef acc, const Unit& u, int wr, int wc, int fr, int fq) const {
;         float* base = P + (size_t)slot0 * 256 * DM + (size_t)u.ks * 256 * ld; const int col0 = u.pn * 256 + wc * 32 + 4 * fq;
; #pragma unroll
;         for (int ai = 0; ai < 2; ++ai)
; #pragma unroll
;             for (int m = 0; m < 4; ++m) { const size_t off = (size_t)(ai * 128 + wr * 64 + m * 16 + fr) * ld + col0;
; #pragma unroll
;                 for (int bj = 0; bj < 2; ++bj)
; #pragma unroll
;                     for (int n = 0; n < 2; ++n) *(f32x4*)(base + off + bj * 128 + n * 16) = acc[ai][bj][m][n]; }
;     }
.Lpeel_done_1775:
	s_ashr_i32 s15, s14, 31
	s_lshl_b64 s[0:1], s[14:15], 21
	s_add_u32 s0, s52, s0
	s_addc_u32 s1, s53, s1
	s_lshl_b32 s4, s48, 8
	v_mov_b32_e32 v145, v192
	v_mov_b32_e32 v147, v194
	s_or_b32 s4, s4, s51
	s_and_b64 vcc, exec, s[6:7]
	v_lshl_add_u32 v146, v145, 2, s4
	v_add_u32_e32 v148, s50, v147
	v_ashrrev_i32_e32 v147, 31, v146
	v_ashrrev_i32_e32 v149, 31, v148
	v_lshl_add_u64 v[146:147], v[146:147], 2, s[0:1]
	v_lshlrev_b64 v[150:151], 13, v[148:149]
	v_lshl_add_u64 v[150:151], v[146:147], 0, v[150:151]
	global_store_dwordx4 v[150:151], v[124:127], off
	global_store_dwordx4 v[150:151], v[120:123], off offset:64
	global_store_dwordx4 v[150:151], v[108:111], off offset:512
	global_store_dwordx4 v[150:151], v[100:103], off offset:576
	s_mov_b32 s14, s16
	s_mov_b32 s48, s63
	v_add_u32_e32 v100, 16, v148
	v_ashrrev_i32_e32 v101, 31, v100
	v_lshlrev_b64 v[100:101], 13, v[100:101]
	v_lshl_add_u64 v[100:101], v[146:147], 0, v[100:101]
	global_store_dwordx4 v[100:101], v[116:119], off
	global_store_dwordx4 v[100:101], v[112:115], off offset:64
	global_store_dwordx4 v[100:101], v[92:95], off offset:512
	global_store_dwordx4 v[100:101], v[84:87], off offset:576
	s_mov_b64 s[30:31], s[18:19]
	s_mov_b64 s[36:37], s[28:29]
	v_add_u32_e32 v84, 32, v148
	v_ashrrev_i32_e32 v85, 31, v84
	v_lshlrev_b64 v[84:85], 13, v[84:85]
	v_lshl_add_u64 v[84:85], v[146:147], 0, v[84:85]
	global_store_dwordx4 v[84:85], v[104:107], off
	global_store_dwordx4 v[84:85], v[96:99], off offset:64
	global_store_dwordx4 v[84:85], v[76:79], off offset:512
	global_store_dwordx4 v[84:85], v[72:75], off offset:576
	s_nop 1
	v_add_u32_e32 v72, 48, v148
	v_ashrrev_i32_e32 v73, 31, v72
	v_lshlrev_b64 v[72:73], 13, v[72:73]
	v_lshl_add_u64 v[72:73], v[146:147], 0, v[72:73]
	global_store_dwordx4 v[72:73], v[88:91], off
	global_store_dwordx4 v[72:73], v[80:83], off offset:64
	global_store_dwordx4 v[72:73], v[68:71], off offset:512
	global_store_dwordx4 v[72:73], v[64:67], off offset:576
	s_nop 1
	v_add_u32_e32 v64, 0x80, v148
	v_ashrrev_i32_e32 v65, 31, v64
	v_lshlrev_b64 v[64:65], 13, v[64:65]
	v_lshl_add_u64 v[64:65], v[146:147], 0, v[64:65]
	global_store_dwordx4 v[64:65], v[60:63], off
	global_store_dwordx4 v[64:65], v[56:59], off offset:64
	global_store_dwordx4 v[64:65], v[44:47], off offset:512
	global_store_dwordx4 v[64:65], v[36:39], off offset:576
	s_nop 1
	v_add_u32_e32 v36, 0x90, v148
	v_ashrrev_i32_e32 v37, 31, v36
	v_lshlrev_b64 v[36:37], 13, v[36:37]
	v_lshl_add_u64 v[36:37], v[146:147], 0, v[36:37]
	global_store_dwordx4 v[36:37], v[52:55], off
	global_store_dwordx4 v[36:37], v[48:51], off offset:64
	global_store_dwordx4 v[36:37], v[28:31], off offset:512
	global_store_dwordx4 v[36:37], v[20:23], off offset:576
	s_nop 1
	v_add_u32_e32 v20, 0xa0, v148
	v_ashrrev_i32_e32 v21, 31, v20
	v_lshlrev_b64 v[20:21], 13, v[20:21]
	v_lshl_add_u64 v[20:21], v[146:147], 0, v[20:21]
	global_store_dwordx4 v[20:21], v[40:43], off
	global_store_dwordx4 v[20:21], v[32:35], off offset:64
	global_store_dwordx4 v[20:21], v[12:15], off offset:512
	global_store_dwordx4 v[20:21], v[8:11], off offset:576
	s_nop 1
	v_add_u32_e32 v8, 0xb0, v148
	v_ashrrev_i32_e32 v9, 31, v8
	v_lshlrev_b64 v[8:9], 13, v[8:9]
	v_lshl_add_u64 v[8:9], v[146:147], 0, v[8:9]
	global_store_dwordx4 v[8:9], v[24:27], off
	global_store_dwordx4 v[8:9], v[16:19], off offset:64
	global_store_dwordx4 v[8:9], v[4:7], off offset:512
	global_store_dwordx4 v[8:9], v[0:3], off offset:576
	s_cbranch_vccz .LBB0_1770
	s_waitcnt vmcnt(0)
	s_cmpk_gt_u32 s34, 0xff
	s_cbranch_scc1 .LBB0_1779
	s_barrier
